# plus K-loops without the mid-block s_setprio 0/1 flip (priority stays raised across each 32-MFMA block)
# baseline (speedup 1.0000x reference)
; #define PG8_STAGE(bufoff, gbase, voff) do { _Pragma("unroll") for (int _i = 0; _i < 2; ++_i) \
;         __builtin_amdgcn_global_load_lds((const unsigned*)((const char*)(gbase) + (voff)[_i]), (PG8_LAS unsigned*)(lds + (bufoff) + ldsw + _i * 8192), 16, 0, 0); } while (0)
; #define PG8_LDA(dst, b, h) do { _Pragma("unroll") for (int m = 0; m < 4; ++m) _Pragma("unroll") for (int k = 0; k < 2; ++k) dst[m][k] = *(const PG8_LAS bf16x8*)(lds + PG8_SA(b, h) + aoff + m * 2048 + k * 1024); } while (0)
; #define PG8_LDB(dst, b, h) do { _Pragma("unroll") for (int n = 0; n < 2; ++n) _Pragma("unroll") for (int k = 0; k < 2; ++k) dst[n][k] = *(const PG8_LAS bf16x8*)(lds + PG8_SB(b, h) + boff + n * 2048 + k * 1024); } while (0)
; #define PG8_MMA(ai, bj, At, Bt) do { __builtin_amdgcn_s_setprio(1); _Pragma("unroll") for (int m = 0; m < 4; ++m) _Pragma("unroll") for (int n = 0; n < 2; ++n) _Pragma("unroll") for (int k = 0; k < 2; ++k) \
;         acc[ai][bj][m][n] = __builtin_amdgcn_mfma_f32_16x16x32_bf16(Bt[n][k], At[m][k], acc[ai][bj][m][n], 0, 0, 0); __builtin_amdgcn_s_setprio(0); } while (0)
; #define PG8_WAIT_V(n) asm volatile("s_waitcnt vmcnt(" #n ")" ::: "memory")
; #define PG8_WAIT_L(n) asm volatile("s_waitcnt lgkmcnt(" #n ")" ::: "memory")
; #define PG8_BAR __builtin_amdgcn_s_barrier()
; #define PG8_SCHED __builtin_amdgcn_sched_barrier(0)
; template <class Epi, class Sched, bool ALIGN_EPI = false, bool SP2 = false>
; __device__ __forceinline__ void gemm_phase(PG8_LAS unsigned char* lds, const Gemm g, const Sched& S, const Epi& E, const int tid) {
;     ...
;             PG8_LDB(B0, 0, 0); PG8_LDB(B1, 0, 1); PG8_SCHED; PG8_LDA(At, 0, 0); PG8_STAGE(PG8_SA(1, 1), a1 + hstep, voffA);
;             PG8_WAIT_V(8); PG8_WAIT_L(0); PG8_BAR; PG8_MMA(0, 0, At, B0); PG8_MMA(0, 1, At, B1); PG8_BAR; PG8_SCHED;
;             PG8_LDA(At, 0, 1); PG8_STAGE(PG8_SB(0, 0), b2, voffB); PG8_STAGE(PG8_SB(0, 1), b2 + hstep, voffB); PG8_STAGE(PG8_SA(0, 0), a2, voffA);
;             PG8_WAIT_V(8); PG8_WAIT_L(0); PG8_BAR; PG8_MMA(1, 0, At, B0); PG8_MMA(1, 1, At, B1); PG8_BAR; PG8_SCHED;
.Lmy_nobar_341:
	s_add_u32 s12, s10, 0xfff80080
	s_addc_u32 s13, s11, -1
	s_add_i32 s47, 0, 0x10000
	v_add_u32_e32 v28, s47, v197
	s_waitcnt vmcnt(0)
	v_add_u32_e32 v60, s33, v197
	ds_read_b128 v[16:19], v28
	ds_read_b128 v[20:23], v28 offset:1024
	ds_read_b128 v[24:27], v28 offset:2048
	ds_read_b128 v[28:31], v28 offset:3072
	ds_read_b128 v[40:43], v60
	ds_read_b128 v[44:47], v60 offset:1024
	ds_read_b128 v[56:59], v60 offset:2048
	ds_read_b128 v[60:63], v60 offset:3072
	s_cmp_eq_u32 s46, 28
	s_cselect_b32 s43, s1, s13
	s_cselect_b32 s42, s9, s12
	s_cselect_b32 s13, s35, s45
	s_cselect_b32 s12, s37, s44
	v_lshl_add_u64 v[194:195], s[10:11], 0, v[190:191]
	s_add_i32 m0, s63, 0xc000
	ds_read_b128 v[80:83], v240
	ds_read_b128 v[84:87], v240 offset:1024
	ds_read_b128 v[104:107], v240 offset:2048
	ds_read_b128 v[108:111], v240 offset:3072
	ds_read_b128 v[198:201], v240 offset:4096
	ds_read_b128 v[202:205], v240 offset:5120
	ds_read_b128 v[214:217], v240 offset:6144
	ds_read_b128 v[218:221], v240 offset:7168
	global_load_lds_dwordx4 v[194:195], off
	v_lshl_add_u64 v[194:195], s[10:11], 0, v[192:193]
	s_add_i32 m0, s63, 0xe000
	s_nop 0
	global_load_lds_dwordx4 v[194:195], off
	s_waitcnt vmcnt(8)
	s_waitcnt lgkmcnt(0)
	s_barrier
	s_setprio 1
	s_waitcnt lgkmcnt(0)
	v_mfma_f32_16x16x32_bf16 v[172:175], v[16:19], v[80:83], 0
	v_mfma_f32_16x16x32_bf16 v[168:171], v[24:27], v[80:83], 0
	v_mfma_f32_16x16x32_bf16 v[156:159], v[16:19], v[104:107], 0
	v_mfma_f32_16x16x32_bf16 v[152:155], v[24:27], v[104:107], 0
	v_mfma_f32_16x16x32_bf16 v[140:143], v[16:19], v[198:201], 0
	v_mfma_f32_16x16x32_bf16 v[136:139], v[24:27], v[198:201], 0
	v_mfma_f32_16x16x32_bf16 v[124:127], v[16:19], v[214:217], 0
	v_mfma_f32_16x16x32_bf16 v[120:123], v[24:27], v[214:217], 0
	v_mfma_f32_16x16x32_bf16 v[172:175], v[20:23], v[84:87], v[172:175]
	v_mfma_f32_16x16x32_bf16 v[168:171], v[28:31], v[84:87], v[168:171]
	v_mfma_f32_16x16x32_bf16 v[156:159], v[20:23], v[108:111], v[156:159]
	v_mfma_f32_16x16x32_bf16 v[152:155], v[28:31], v[108:111], v[152:155]
	v_mfma_f32_16x16x32_bf16 v[140:143], v[20:23], v[202:205], v[140:143]
	v_mfma_f32_16x16x32_bf16 v[136:139], v[28:31], v[202:205], v[136:139]
	v_mfma_f32_16x16x32_bf16 v[124:127], v[20:23], v[218:221], v[124:127]
	v_mfma_f32_16x16x32_bf16 v[120:123], v[28:31], v[218:221], v[120:123]
	v_mfma_f32_16x16x32_bf16 v[164:167], v[40:43], v[80:83], 0
	v_mfma_f32_16x16x32_bf16 v[80:83], v[56:59], v[80:83], 0
	v_mfma_f32_16x16x32_bf16 v[164:167], v[44:47], v[84:87], v[164:167]
	v_mfma_f32_16x16x32_bf16 v[80:83], v[60:63], v[84:87], v[80:83]
	v_mfma_f32_16x16x32_bf16 v[84:87], v[40:43], v[104:107], 0
	v_mfma_f32_16x16x32_bf16 v[104:107], v[56:59], v[104:107], 0
	v_mfma_f32_16x16x32_bf16 v[128:131], v[56:59], v[198:201], 0
	v_mfma_f32_16x16x32_bf16 v[116:119], v[40:43], v[214:217], 0
	v_mfma_f32_16x16x32_bf16 v[112:115], v[56:59], v[214:217], 0
	v_mfma_f32_16x16x32_bf16 v[84:87], v[44:47], v[108:111], v[84:87]
	v_mfma_f32_16x16x32_bf16 v[104:107], v[60:63], v[108:111], v[104:107]
	v_mfma_f32_16x16x32_bf16 v[108:111], v[40:43], v[198:201], 0
	v_mfma_f32_16x16x32_bf16 v[128:131], v[60:63], v[202:205], v[128:131]
	v_mfma_f32_16x16x32_bf16 v[116:119], v[44:47], v[218:221], v[116:119]
	v_mfma_f32_16x16x32_bf16 v[112:115], v[60:63], v[218:221], v[112:115]
	v_mfma_f32_16x16x32_bf16 v[108:111], v[44:47], v[202:205], v[108:111]
	s_setprio 0
	s_barrier
	s_add_i32 s47, s47, s62
	v_lshl_add_u64 v[194:195], s[12:13], 0, v[178:179]
	s_mov_b32 m0, s47
	ds_read_b128 v[132:135], v240 offset:16384
	ds_read_b128 v[144:147], v240 offset:17408
	ds_read_b128 v[148:151], v240 offset:18432
	ds_read_b128 v[160:163], v240 offset:19456
	ds_read_b128 v[198:201], v240 offset:20480
	ds_read_b128 v[202:205], v240 offset:21504
	ds_read_b128 v[214:217], v240 offset:22528
	ds_read_b128 v[218:221], v240 offset:23552
	global_load_lds_dwordx4 v[194:195], off
	s_add_i32 m0, s47, 0x2000
	s_add_u32 s48, s12, 0x80000
	v_lshl_add_u64 v[206:207], s[12:13], 0, v[182:183]
	s_addc_u32 s49, s13, 0
	s_add_i32 s47, s33, s62
	global_load_lds_dwordx4 v[206:207], off
	v_lshl_add_u64 v[210:211], s[48:49], 0, v[178:179]
	s_mov_b32 m0, s47
	v_lshl_add_u64 v[234:235], s[42:43], 0, v[180:181]
	global_load_lds_dwordx4 v[210:211], off
	v_lshl_add_u64 v[210:211], s[48:49], 0, v[182:183]
	s_add_i32 m0, s47, 0x2000
	s_nop 0
	global_load_lds_dwordx4 v[210:211], off
	v_lshl_add_u64 v[210:211], s[42:43], 0, v[176:177]
	s_mov_b32 m0, s63
	s_nop 0
	global_load_lds_dwordx4 v[210:211], off
	s_mov_b32 m0, s64
	s_nop 0
	global_load_lds_dwordx4 v[234:235], off
	s_waitcnt vmcnt(8)
	s_waitcnt lgkmcnt(0)
	s_barrier
	s_setprio 1
	s_waitcnt lgkmcnt(0)
	v_mfma_f32_16x16x32_bf16 v[100:103], v[16:19], v[132:135], 0
	v_mfma_f32_16x16x32_bf16 v[96:99], v[24:27], v[132:135], 0
	v_mfma_f32_16x16x32_bf16 v[76:79], v[16:19], v[148:151], 0
	v_mfma_f32_16x16x32_bf16 v[72:75], v[24:27], v[148:151], 0
	v_mfma_f32_16x16x32_bf16 v[52:55], v[16:19], v[198:201], 0
	v_mfma_f32_16x16x32_bf16 v[48:51], v[24:27], v[198:201], 0
	v_mfma_f32_16x16x32_bf16 v[12:15], v[16:19], v[214:217], 0
	v_mfma_f32_16x16x32_bf16 v[8:11], v[24:27], v[214:217], 0
	v_mfma_f32_16x16x32_bf16 v[100:103], v[20:23], v[144:147], v[100:103]
	v_mfma_f32_16x16x32_bf16 v[96:99], v[28:31], v[144:147], v[96:99]
	v_mfma_f32_16x16x32_bf16 v[76:79], v[20:23], v[160:163], v[76:79]
	v_mfma_f32_16x16x32_bf16 v[72:75], v[28:31], v[160:163], v[72:75]
	v_mfma_f32_16x16x32_bf16 v[52:55], v[20:23], v[202:205], v[52:55]
	v_mfma_f32_16x16x32_bf16 v[48:51], v[28:31], v[202:205], v[48:51]
	v_mfma_f32_16x16x32_bf16 v[12:15], v[20:23], v[218:221], v[12:15]
	v_mfma_f32_16x16x32_bf16 v[8:11], v[28:31], v[218:221], v[8:11]
	v_mfma_f32_16x16x32_bf16 v[36:39], v[40:43], v[198:201], 0
	v_mfma_f32_16x16x32_bf16 v[32:35], v[56:59], v[198:201], 0
	v_mfma_f32_16x16x32_bf16 v[4:7], v[40:43], v[214:217], 0
	v_mfma_f32_16x16x32_bf16 v[0:3], v[56:59], v[214:217], 0
	v_mfma_f32_16x16x32_bf16 v[16:19], v[40:43], v[132:135], 0
	v_mfma_f32_16x16x32_bf16 v[20:23], v[56:59], v[132:135], 0
	v_mfma_f32_16x16x32_bf16 v[24:27], v[40:43], v[148:151], 0
	v_mfma_f32_16x16x32_bf16 v[28:31], v[56:59], v[148:151], 0
	v_mfma_f32_16x16x32_bf16 v[36:39], v[44:47], v[202:205], v[36:39]
	v_mfma_f32_16x16x32_bf16 v[32:35], v[60:63], v[202:205], v[32:35]
	v_mfma_f32_16x16x32_bf16 v[4:7], v[44:47], v[218:221], v[4:7]
	v_mfma_f32_16x16x32_bf16 v[0:3], v[60:63], v[218:221], v[0:3]
	v_mfma_f32_16x16x32_bf16 v[16:19], v[44:47], v[144:147], v[16:19]
	v_mfma_f32_16x16x32_bf16 v[20:23], v[60:63], v[144:147], v[20:23]
	v_mfma_f32_16x16x32_bf16 v[24:27], v[44:47], v[160:163], v[24:27]
	v_mfma_f32_16x16x32_bf16 v[28:31], v[60:63], v[160:163], v[28:31]
	s_setprio 0
	s_barrier
	s_branch .Lmy_mid_341
; #define PG8_STAGE(bufoff, gbase, voff) do { _Pragma("unroll") for (int _i = 0; _i < 2; ++_i) \
;         __builtin_amdgcn_global_load_lds((const unsigned*)((const char*)(gbase) + (voff)[_i]), (PG8_LAS unsigned*)(lds + (bufoff) + ldsw + _i * 8192), 16, 0, 0); } while (0)
; #define PG8_LDA(dst, b, h) do { _Pragma("unroll") for (int m = 0; m < 4; ++m) _Pragma("unroll") for (int k = 0; k < 2; ++k) dst[m][k] = *(const PG8_LAS bf16x8*)(lds + PG8_SA(b, h) + aoff + m * 2048 + k * 1024); } while (0)
; #define PG8_LDB(dst, b, h) do { _Pragma("unroll") for (int n = 0; n < 2; ++n) _Pragma("unroll") for (int k = 0; k < 2; ++k) dst[n][k] = *(const PG8_LAS bf16x8*)(lds + PG8_SB(b, h) + boff + n * 2048 + k * 1024); } while (0)
; #define PG8_MMA(ai, bj, At, Bt) do { __builtin_amdgcn_s_setprio(1); _Pragma("unroll") for (int m = 0; m < 4; ++m) _Pragma("unroll") for (int n = 0; n < 2; ++n) _Pragma("unroll") for (int k = 0; k < 2; ++k) \
;         acc[ai][bj][m][n] = __builtin_amdgcn_mfma_f32_16x16x32_bf16(Bt[n][k], At[m][k], acc[ai][bj][m][n], 0, 0, 0); __builtin_amdgcn_s_setprio(0); } while (0)
; #define PG8_WAIT_V(n) asm volatile("s_waitcnt vmcnt(" #n ")" ::: "memory")
; #define PG8_WAIT_L(n) asm volatile("s_waitcnt lgkmcnt(" #n ")" ::: "memory")
; #define PG8_BAR __builtin_amdgcn_s_barrier()
; #define PG8_SCHED __builtin_amdgcn_sched_barrier(0)
; template <class Epi, class Sched, bool ALIGN_EPI = false, bool SP2 = false>
; __device__ __forceinline__ void gemm_phase(PG8_LAS unsigned char* lds, const Gemm g, const Sched& S, const Epi& E, const int tid) {
;     ...
;             PG8_LDB(B0, 0, 0); PG8_LDB(B1, 0, 1); PG8_SCHED; PG8_LDA(At, 0, 0); PG8_STAGE(PG8_SA(1, 1), a1 + hstep, voffA);
;             PG8_WAIT_V(8); PG8_WAIT_L(0); PG8_BAR; PG8_MMA(0, 0, At, B0); PG8_MMA(0, 1, At, B1); PG8_BAR; PG8_SCHED;
;             PG8_LDA(At, 0, 1); PG8_STAGE(PG8_SB(0, 0), b2, voffB); PG8_STAGE(PG8_SB(0, 1), b2 + hstep, voffB); PG8_STAGE(PG8_SA(0, 0), a2, voffA);
;             PG8_WAIT_V(8); PG8_WAIT_L(0); PG8_BAR; PG8_MMA(1, 0, At, B0); PG8_MMA(1, 1, At, B1); PG8_BAR; PG8_SCHED;
.LBB0_341:
	s_add_u32 s12, s10, 0xfff80080
	s_addc_u32 s13, s11, -1
	s_add_i32 s47, 0, 0x10000
	v_add_u32_e32 v28, s47, v197
	s_waitcnt vmcnt(0)
	v_add_u32_e32 v60, s33, v197
	ds_read_b128 v[16:19], v28
	ds_read_b128 v[20:23], v28 offset:1024
	ds_read_b128 v[24:27], v28 offset:2048
	ds_read_b128 v[28:31], v28 offset:3072
	ds_read_b128 v[40:43], v60
	ds_read_b128 v[44:47], v60 offset:1024
	ds_read_b128 v[56:59], v60 offset:2048
	ds_read_b128 v[60:63], v60 offset:3072
	s_cmp_eq_u32 s46, 28
	s_cselect_b32 s43, s1, s13
	s_cselect_b32 s42, s9, s12
	s_cselect_b32 s13, s35, s45
	s_cselect_b32 s12, s37, s44
	v_lshl_add_u64 v[194:195], s[10:11], 0, v[190:191]
	s_add_i32 m0, s63, 0xc000
	ds_read_b128 v[80:83], v240
	ds_read_b128 v[84:87], v240 offset:1024
	ds_read_b128 v[104:107], v240 offset:2048
	ds_read_b128 v[108:111], v240 offset:3072
	ds_read_b128 v[198:201], v240 offset:4096
	ds_read_b128 v[202:205], v240 offset:5120
	ds_read_b128 v[214:217], v240 offset:6144
	ds_read_b128 v[218:221], v240 offset:7168
	global_load_lds_dwordx4 v[194:195], off
	v_lshl_add_u64 v[194:195], s[10:11], 0, v[192:193]
	s_add_i32 m0, s63, 0xe000
	s_nop 0
	global_load_lds_dwordx4 v[194:195], off
	s_waitcnt vmcnt(8)
	s_waitcnt lgkmcnt(0)
	s_barrier
	s_setprio 1
	s_waitcnt lgkmcnt(0)
	v_mfma_f32_16x16x32_bf16 v[172:175], v[16:19], v[80:83], v[172:175]
	v_mfma_f32_16x16x32_bf16 v[168:171], v[24:27], v[80:83], v[168:171]
	v_mfma_f32_16x16x32_bf16 v[156:159], v[16:19], v[104:107], v[156:159]
	v_mfma_f32_16x16x32_bf16 v[152:155], v[24:27], v[104:107], v[152:155]
	v_mfma_f32_16x16x32_bf16 v[140:143], v[16:19], v[198:201], v[140:143]
	v_mfma_f32_16x16x32_bf16 v[136:139], v[24:27], v[198:201], v[136:139]
	v_mfma_f32_16x16x32_bf16 v[124:127], v[16:19], v[214:217], v[124:127]
	v_mfma_f32_16x16x32_bf16 v[120:123], v[24:27], v[214:217], v[120:123]
	v_mfma_f32_16x16x32_bf16 v[172:175], v[20:23], v[84:87], v[172:175]
	v_mfma_f32_16x16x32_bf16 v[168:171], v[28:31], v[84:87], v[168:171]
	v_mfma_f32_16x16x32_bf16 v[156:159], v[20:23], v[108:111], v[156:159]
	v_mfma_f32_16x16x32_bf16 v[152:155], v[28:31], v[108:111], v[152:155]
	v_mfma_f32_16x16x32_bf16 v[140:143], v[20:23], v[202:205], v[140:143]
	v_mfma_f32_16x16x32_bf16 v[136:139], v[28:31], v[202:205], v[136:139]
	v_mfma_f32_16x16x32_bf16 v[124:127], v[20:23], v[218:221], v[124:127]
	v_mfma_f32_16x16x32_bf16 v[120:123], v[28:31], v[218:221], v[120:123]
	v_mfma_f32_16x16x32_bf16 v[164:167], v[40:43], v[80:83], v[164:167]
	v_mfma_f32_16x16x32_bf16 v[80:83], v[56:59], v[80:83], v[160:163]
	v_mfma_f32_16x16x32_bf16 v[164:167], v[44:47], v[84:87], v[164:167]
	v_mfma_f32_16x16x32_bf16 v[80:83], v[60:63], v[84:87], v[80:83]
	v_mfma_f32_16x16x32_bf16 v[84:87], v[40:43], v[104:107], v[148:151]
	v_mfma_f32_16x16x32_bf16 v[104:107], v[56:59], v[104:107], v[144:147]
	v_mfma_f32_16x16x32_bf16 v[128:131], v[56:59], v[198:201], v[128:131]
	v_mfma_f32_16x16x32_bf16 v[116:119], v[40:43], v[214:217], v[116:119]
	v_mfma_f32_16x16x32_bf16 v[112:115], v[56:59], v[214:217], v[112:115]
	v_mfma_f32_16x16x32_bf16 v[84:87], v[44:47], v[108:111], v[84:87]
	v_mfma_f32_16x16x32_bf16 v[104:107], v[60:63], v[108:111], v[104:107]
	v_mfma_f32_16x16x32_bf16 v[108:111], v[40:43], v[198:201], v[132:135]
	v_mfma_f32_16x16x32_bf16 v[128:131], v[60:63], v[202:205], v[128:131]
	v_mfma_f32_16x16x32_bf16 v[116:119], v[44:47], v[218:221], v[116:119]
	v_mfma_f32_16x16x32_bf16 v[112:115], v[60:63], v[218:221], v[112:115]
	v_mfma_f32_16x16x32_bf16 v[108:111], v[44:47], v[202:205], v[108:111]
	s_setprio 0
	s_barrier
	s_add_i32 s47, s47, s62
	v_lshl_add_u64 v[194:195], s[12:13], 0, v[178:179]
	s_mov_b32 m0, s47
	ds_read_b128 v[132:135], v240 offset:16384
	ds_read_b128 v[144:147], v240 offset:17408
	ds_read_b128 v[148:151], v240 offset:18432
	ds_read_b128 v[160:163], v240 offset:19456
	ds_read_b128 v[198:201], v240 offset:20480
	ds_read_b128 v[202:205], v240 offset:21504
	ds_read_b128 v[214:217], v240 offset:22528
	ds_read_b128 v[218:221], v240 offset:23552
	global_load_lds_dwordx4 v[194:195], off
	s_add_i32 m0, s47, 0x2000
	s_add_u32 s48, s12, 0x80000
	v_lshl_add_u64 v[206:207], s[12:13], 0, v[182:183]
	s_addc_u32 s49, s13, 0
	s_add_i32 s47, s33, s62
	global_load_lds_dwordx4 v[206:207], off
	v_lshl_add_u64 v[210:211], s[48:49], 0, v[178:179]
	s_mov_b32 m0, s47
	v_lshl_add_u64 v[234:235], s[42:43], 0, v[180:181]
	global_load_lds_dwordx4 v[210:211], off
	v_lshl_add_u64 v[210:211], s[48:49], 0, v[182:183]
	s_add_i32 m0, s47, 0x2000
	s_nop 0
	global_load_lds_dwordx4 v[210:211], off
	v_lshl_add_u64 v[210:211], s[42:43], 0, v[176:177]
	s_mov_b32 m0, s63
	s_nop 0
	global_load_lds_dwordx4 v[210:211], off
	s_mov_b32 m0, s64
	s_nop 0
	global_load_lds_dwordx4 v[234:235], off
	s_waitcnt vmcnt(8)
	s_waitcnt lgkmcnt(0)
	s_barrier
	s_setprio 1
	s_waitcnt lgkmcnt(0)
	v_mfma_f32_16x16x32_bf16 v[100:103], v[16:19], v[132:135], v[100:103]
	v_mfma_f32_16x16x32_bf16 v[96:99], v[24:27], v[132:135], v[96:99]
	v_mfma_f32_16x16x32_bf16 v[76:79], v[16:19], v[148:151], v[76:79]
	v_mfma_f32_16x16x32_bf16 v[72:75], v[24:27], v[148:151], v[72:75]
	v_mfma_f32_16x16x32_bf16 v[52:55], v[16:19], v[198:201], v[52:55]
	v_mfma_f32_16x16x32_bf16 v[48:51], v[24:27], v[198:201], v[48:51]
	v_mfma_f32_16x16x32_bf16 v[12:15], v[16:19], v[214:217], v[12:15]
	v_mfma_f32_16x16x32_bf16 v[8:11], v[24:27], v[214:217], v[8:11]
	v_mfma_f32_16x16x32_bf16 v[100:103], v[20:23], v[144:147], v[100:103]
	v_mfma_f32_16x16x32_bf16 v[96:99], v[28:31], v[144:147], v[96:99]
	v_mfma_f32_16x16x32_bf16 v[76:79], v[20:23], v[160:163], v[76:79]
	v_mfma_f32_16x16x32_bf16 v[72:75], v[28:31], v[160:163], v[72:75]
	v_mfma_f32_16x16x32_bf16 v[52:55], v[20:23], v[202:205], v[52:55]
	v_mfma_f32_16x16x32_bf16 v[48:51], v[28:31], v[202:205], v[48:51]
	v_mfma_f32_16x16x32_bf16 v[12:15], v[20:23], v[218:221], v[12:15]
	v_mfma_f32_16x16x32_bf16 v[8:11], v[28:31], v[218:221], v[8:11]
	v_mfma_f32_16x16x32_bf16 v[36:39], v[40:43], v[198:201], v[36:39]
	v_mfma_f32_16x16x32_bf16 v[32:35], v[56:59], v[198:201], v[32:35]
	v_mfma_f32_16x16x32_bf16 v[4:7], v[40:43], v[214:217], v[4:7]
	v_mfma_f32_16x16x32_bf16 v[0:3], v[56:59], v[214:217], v[0:3]
	v_mfma_f32_16x16x32_bf16 v[16:19], v[40:43], v[132:135], v[92:95]
	v_mfma_f32_16x16x32_bf16 v[20:23], v[56:59], v[132:135], v[88:91]
	v_mfma_f32_16x16x32_bf16 v[24:27], v[40:43], v[148:151], v[68:71]
	v_mfma_f32_16x16x32_bf16 v[28:31], v[56:59], v[148:151], v[64:67]
	v_mfma_f32_16x16x32_bf16 v[36:39], v[44:47], v[202:205], v[36:39]
	v_mfma_f32_16x16x32_bf16 v[32:35], v[60:63], v[202:205], v[32:35]
	v_mfma_f32_16x16x32_bf16 v[4:7], v[44:47], v[218:221], v[4:7]
	v_mfma_f32_16x16x32_bf16 v[0:3], v[60:63], v[218:221], v[0:3]
	v_mfma_f32_16x16x32_bf16 v[16:19], v[44:47], v[144:147], v[16:19]
	v_mfma_f32_16x16x32_bf16 v[20:23], v[60:63], v[144:147], v[20:23]
	v_mfma_f32_16x16x32_bf16 v[24:27], v[44:47], v[160:163], v[24:27]
	v_mfma_f32_16x16x32_bf16 v[28:31], v[60:63], v[160:163], v[28:31]
	s_setprio 0
	s_barrier
; #define PG8_STAGE(bufoff, gbase, voff) do { _Pragma("unroll") for (int _i = 0; _i < 2; ++_i) \
;         __builtin_amdgcn_global_load_lds((const unsigned*)((const char*)(gbase) + (voff)[_i]), (PG8_LAS unsigned*)(lds + (bufoff) + ldsw + _i * 8192), 16, 0, 0); } while (0)
; #define PG8_LDA(dst, b, h) do { _Pragma("unroll") for (int m = 0; m < 4; ++m) _Pragma("unroll") for (int k = 0; k < 2; ++k) dst[m][k] = *(const PG8_LAS bf16x8*)(lds + PG8_SA(b, h) + aoff + m * 2048 + k * 1024); } while (0)
; #define PG8_LDB(dst, b, h) do { _Pragma("unroll") for (int n = 0; n < 2; ++n) _Pragma("unroll") for (int k = 0; k < 2; ++k) dst[n][k] = *(const PG8_LAS bf16x8*)(lds + PG8_SB(b, h) + boff + n * 2048 + k * 1024); } while (0)
; #define PG8_MMA(ai, bj, At, Bt) do { __builtin_amdgcn_s_setprio(1); _Pragma("unroll") for (int m = 0; m < 4; ++m) _Pragma("unroll") for (int n = 0; n < 2; ++n) _Pragma("unroll") for (int k = 0; k < 2; ++k) \
;         acc[ai][bj][m][n] = __builtin_amdgcn_mfma_f32_16x16x32_bf16(Bt[n][k], At[m][k], acc[ai][bj][m][n], 0, 0, 0); __builtin_amdgcn_s_setprio(0); } while (0)
; #define PG8_WAIT_V(n) asm volatile("s_waitcnt vmcnt(" #n ")" ::: "memory")
; #define PG8_WAIT_L(n) asm volatile("s_waitcnt lgkmcnt(" #n ")" ::: "memory")
; #define PG8_BAR __builtin_amdgcn_s_barrier()
; #define PG8_SCHED __builtin_amdgcn_sched_barrier(0)
; template <class Epi, class Sched, bool ALIGN_EPI = false, bool SP2 = false>
; __device__ __forceinline__ void gemm_phase(PG8_LAS unsigned char* lds, const Gemm g, const Sched& S, const Epi& E, const int tid) {
;     ...
;             PG8_LDB(B0, 1, 0); PG8_LDB(B1, 1, 1); PG8_SCHED; PG8_LDA(At, 1, 0); PG8_STAGE(PG8_SA(0, 1), a2 + hstep, voffA);
;             PG8_WAIT_V(8); PG8_WAIT_L(0); PG8_BAR; PG8_MMA(0, 0, At, B0); PG8_MMA(0, 1, At, B1); PG8_BAR; PG8_SCHED;
.Lmy_mid_341:
	s_add_i32 s47, 0, 0x18000
	s_add_i32 s48, 0, 0x1c000
	v_add_u32_e32 v60, s47, v197
	v_add_u32_e32 v64, s48, v197
	ds_read_b128 v[40:43], v60
	ds_read_b128 v[44:47], v60 offset:1024
	ds_read_b128 v[56:59], v60 offset:2048
	ds_read_b128 v[60:63], v60 offset:3072
	ds_read_b128 v[198:201], v64
	ds_read_b128 v[202:205], v64 offset:1024
	ds_read_b128 v[214:217], v64 offset:2048
	ds_read_b128 v[218:221], v64 offset:3072
	s_add_u32 s42, s42, 0x80000
	s_addc_u32 s43, s43, 0
	s_mov_b32 m0, s65
	v_lshl_add_u64 v[132:133], s[42:43], 0, v[176:177]
	ds_read_b128 v[64:67], v240 offset:32768
	ds_read_b128 v[68:71], v240 offset:33792
	ds_read_b128 v[88:91], v240 offset:34816
	ds_read_b128 v[92:95], v240 offset:35840
	ds_read_b128 v[222:225], v240 offset:36864
	ds_read_b128 v[226:229], v240 offset:37888
	ds_read_b128 v[230:233], v240 offset:38912
	ds_read_b128 v[242:245], v240 offset:39936
	global_load_lds_dwordx4 v[132:133], off
	v_lshl_add_u64 v[132:133], s[42:43], 0, v[180:181]
	s_mov_b32 m0, s66
	s_nop 0
	global_load_lds_dwordx4 v[132:133], off
	s_waitcnt vmcnt(8)
	s_waitcnt lgkmcnt(0)
	s_barrier
	s_setprio 1
	s_waitcnt lgkmcnt(0)
	v_mfma_f32_16x16x32_bf16 v[132:135], v[40:43], v[64:67], v[172:175]
	v_mfma_f32_16x16x32_bf16 v[172:175], v[44:47], v[68:71], v[132:135]
	v_mfma_f32_16x16x32_bf16 v[132:135], v[56:59], v[64:67], v[168:171]
	v_mfma_f32_16x16x32_bf16 v[168:171], v[60:63], v[68:71], v[132:135]
	v_mfma_f32_16x16x32_bf16 v[132:135], v[40:43], v[88:91], v[156:159]
	v_mfma_f32_16x16x32_bf16 v[156:159], v[44:47], v[92:95], v[132:135]
	v_mfma_f32_16x16x32_bf16 v[132:135], v[56:59], v[88:91], v[152:155]
	v_mfma_f32_16x16x32_bf16 v[152:155], v[60:63], v[92:95], v[132:135]
	v_mfma_f32_16x16x32_bf16 v[132:135], v[40:43], v[222:225], v[140:143]
	v_mfma_f32_16x16x32_bf16 v[140:143], v[44:47], v[226:229], v[132:135]
	v_mfma_f32_16x16x32_bf16 v[132:135], v[56:59], v[222:225], v[136:139]
	v_mfma_f32_16x16x32_bf16 v[124:127], v[40:43], v[230:233], v[124:127]
	v_mfma_f32_16x16x32_bf16 v[120:123], v[56:59], v[230:233], v[120:123]
	v_mfma_f32_16x16x32_bf16 v[136:139], v[60:63], v[226:229], v[132:135]
	v_mfma_f32_16x16x32_bf16 v[124:127], v[44:47], v[242:245], v[124:127]
	v_mfma_f32_16x16x32_bf16 v[120:123], v[60:63], v[242:245], v[120:123]
	v_mfma_f32_16x16x32_bf16 v[132:135], v[198:201], v[64:67], v[164:167]
	v_mfma_f32_16x16x32_bf16 v[64:67], v[214:217], v[64:67], v[80:83]
	v_mfma_f32_16x16x32_bf16 v[160:163], v[218:221], v[68:71], v[64:67]
	v_mfma_f32_16x16x32_bf16 v[64:67], v[198:201], v[88:91], v[84:87]
	v_mfma_f32_16x16x32_bf16 v[148:151], v[202:205], v[92:95], v[64:67]
	v_mfma_f32_16x16x32_bf16 v[64:67], v[214:217], v[88:91], v[104:107]
	v_mfma_f32_16x16x32_bf16 v[144:147], v[218:221], v[92:95], v[64:67]
	v_mfma_f32_16x16x32_bf16 v[64:67], v[198:201], v[222:225], v[108:111]
	v_mfma_f32_16x16x32_bf16 v[164:167], v[202:205], v[68:71], v[132:135]
	v_mfma_f32_16x16x32_bf16 v[132:135], v[202:205], v[226:229], v[64:67]
	v_mfma_f32_16x16x32_bf16 v[64:67], v[214:217], v[222:225], v[128:131]
	v_mfma_f32_16x16x32_bf16 v[128:131], v[218:221], v[226:229], v[64:67]
	v_mfma_f32_16x16x32_bf16 v[64:67], v[198:201], v[230:233], v[116:119]
	v_mfma_f32_16x16x32_bf16 v[116:119], v[202:205], v[242:245], v[64:67]
	v_mfma_f32_16x16x32_bf16 v[64:67], v[214:217], v[230:233], v[112:115]
	v_mfma_f32_16x16x32_bf16 v[112:115], v[218:221], v[242:245], v[64:67]
	s_setprio 0
	s_barrier
; #define PG8_STAGE(bufoff, gbase, voff) do { _Pragma("unroll") for (int _i = 0; _i < 2; ++_i) \
;         __builtin_amdgcn_global_load_lds((const unsigned*)((const char*)(gbase) + (voff)[_i]), (PG8_LAS unsigned*)(lds + (bufoff) + ldsw + _i * 8192), 16, 0, 0); } while (0)
; #define PG8_LDA(dst, b, h) do { _Pragma("unroll") for (int m = 0; m < 4; ++m) _Pragma("unroll") for (int k = 0; k < 2; ++k) dst[m][k] = *(const PG8_LAS bf16x8*)(lds + PG8_SA(b, h) + aoff + m * 2048 + k * 1024); } while (0)
; #define PG8_MMA(ai, bj, At, Bt) do { __builtin_amdgcn_s_setprio(1); _Pragma("unroll") for (int m = 0; m < 4; ++m) _Pragma("unroll") for (int n = 0; n < 2; ++n) _Pragma("unroll") for (int k = 0; k < 2; ++k) \
;         acc[ai][bj][m][n] = __builtin_amdgcn_mfma_f32_16x16x32_bf16(Bt[n][k], At[m][k], acc[ai][bj][m][n], 0, 0, 0); __builtin_amdgcn_s_setprio(0); } while (0)
; #define PG8_WAIT_V(n) asm volatile("s_waitcnt vmcnt(" #n ")" ::: "memory")
; #define PG8_WAIT_L(n) asm volatile("s_waitcnt lgkmcnt(" #n ")" ::: "memory")
; #define PG8_BAR __builtin_amdgcn_s_barrier()
; #define PG8_SCHED __builtin_amdgcn_sched_barrier(0)
; template <class Epi, class Sched, bool ALIGN_EPI = false, bool SP2 = false>
; __device__ __forceinline__ void gemm_phase(PG8_LAS unsigned char* lds, const Gemm g, const Sched& S, const Epi& E, const int tid) {
;     ...
;             PG8_LDA(At, 1, 1); PG8_STAGE(PG8_SB(1, 0), b3, voffB); PG8_STAGE(PG8_SB(1, 1), b3 + hstep, voffB); PG8_STAGE(PG8_SA(1, 0), a3, voffA);
;             PG8_WAIT_V(8); PG8_WAIT_L(0); PG8_BAR; PG8_MMA(1, 0, At, B0); PG8_MMA(1, 1, At, B1); PG8_BAR; PG8_SCHED;
;     __device__ __forceinline__ void operator()(const f32x4 (&acc)[2][2][4][2], const Unit& un, int wr, int wc, int fr, int fq) const {
;         const int pn = un.pn, rbase = un.pm * 256 + wr * 64 + fr, cw = wc * 32 + 8 * fq;
;         const bool lat = un.pm < (NLAT / 256);
;         const float* sw = shw + (size_t)(lat ? (un.pm >> 5) : 4) * INC + pn * 256 + cw;
;         f32x4 s0[2], s1[2]; float rr[2][4];
; #pragma unroll
;         for (int bj = 0; bj < 2; ++bj) { s0[bj] = *(const f32x4*)(sw + bj * 128); s1[bj] = *(const f32x4*)(sw + bj * 128 + 4); }
	s_add_i32 s42, s47, s62
	v_lshl_add_u64 v[88:89], v[194:195], 0, s[2:3]
	s_mov_b32 m0, s42
	s_nop 1
	ds_read_b128 v[64:67], v240 offset:49152
	ds_read_b128 v[68:71], v240 offset:50176
	ds_read_b128 v[80:83], v240 offset:51200
	ds_read_b128 v[84:87], v240 offset:52224
	ds_read_b128 v[104:107], v240 offset:53248
	ds_read_b128 v[108:111], v240 offset:54272
	ds_read_b128 v[222:225], v240 offset:55296
	ds_read_b128 v[226:229], v240 offset:56320
	global_load_lds_dwordx4 v[88:89], off
	s_add_i32 m0, s42, 0x2000
	s_add_u32 s12, s12, 0x80080
	v_lshl_add_u64 v[88:89], v[206:207], 0, s[2:3]
	s_addc_u32 s13, s13, 0
	s_add_i32 s42, s48, s62
	global_load_lds_dwordx4 v[88:89], off
	v_lshl_add_u64 v[88:89], s[12:13], 0, v[178:179]
	s_mov_b32 m0, s42
	s_nop 0
	global_load_lds_dwordx4 v[88:89], off
	v_lshl_add_u64 v[88:89], s[12:13], 0, v[182:183]
	s_add_i32 m0, s42, 0x2000
	s_nop 0
	global_load_lds_dwordx4 v[88:89], off
	v_lshl_add_u64 v[88:89], v[210:211], 0, s[2:3]
	s_mov_b32 m0, s70
	s_nop 0
	global_load_lds_dwordx4 v[88:89], off
	v_lshl_add_u64 v[88:89], v[234:235], 0, s[2:3]
	s_mov_b32 m0, s71
	s_nop 0
	global_load_lds_dwordx4 v[88:89], off
	s_waitcnt vmcnt(8)
	s_waitcnt lgkmcnt(0)
	s_barrier
	s_setprio 1
	s_waitcnt lgkmcnt(0)
	v_mfma_f32_16x16x32_bf16 v[88:91], v[40:43], v[64:67], v[100:103]
	v_mfma_f32_16x16x32_bf16 v[100:103], v[44:47], v[68:71], v[88:91]
	v_mfma_f32_16x16x32_bf16 v[88:91], v[56:59], v[64:67], v[96:99]
	v_mfma_f32_16x16x32_bf16 v[76:79], v[40:43], v[80:83], v[76:79]
	v_mfma_f32_16x16x32_bf16 v[72:75], v[56:59], v[80:83], v[72:75]
	v_mfma_f32_16x16x32_bf16 v[52:55], v[40:43], v[104:107], v[52:55]
	v_mfma_f32_16x16x32_bf16 v[48:51], v[56:59], v[104:107], v[48:51]
	v_mfma_f32_16x16x32_bf16 v[12:15], v[40:43], v[222:225], v[12:15]
	v_mfma_f32_16x16x32_bf16 v[8:11], v[56:59], v[222:225], v[8:11]
	v_mfma_f32_16x16x32_bf16 v[96:99], v[60:63], v[68:71], v[88:91]
	v_mfma_f32_16x16x32_bf16 v[76:79], v[44:47], v[84:87], v[76:79]
	v_mfma_f32_16x16x32_bf16 v[72:75], v[60:63], v[84:87], v[72:75]
	v_mfma_f32_16x16x32_bf16 v[52:55], v[44:47], v[108:111], v[52:55]
	v_mfma_f32_16x16x32_bf16 v[48:51], v[60:63], v[108:111], v[48:51]
	v_mfma_f32_16x16x32_bf16 v[12:15], v[44:47], v[226:229], v[12:15]
	v_mfma_f32_16x16x32_bf16 v[8:11], v[60:63], v[226:229], v[8:11]
	v_mfma_f32_16x16x32_bf16 v[16:19], v[198:201], v[64:67], v[16:19]
	v_mfma_f32_16x16x32_bf16 v[92:95], v[202:205], v[68:71], v[16:19]
	v_mfma_f32_16x16x32_bf16 v[16:19], v[214:217], v[64:67], v[20:23]
	v_mfma_f32_16x16x32_bf16 v[88:91], v[218:221], v[68:71], v[16:19]
	v_mfma_f32_16x16x32_bf16 v[16:19], v[198:201], v[80:83], v[24:27]
	v_mfma_f32_16x16x32_bf16 v[68:71], v[202:205], v[84:87], v[16:19]
	v_mfma_f32_16x16x32_bf16 v[16:19], v[214:217], v[80:83], v[28:31]
	v_mfma_f32_16x16x32_bf16 v[64:67], v[218:221], v[84:87], v[16:19]
	v_mfma_f32_16x16x32_bf16 v[16:19], v[198:201], v[104:107], v[36:39]
	v_mfma_f32_16x16x32_bf16 v[36:39], v[202:205], v[108:111], v[16:19]
	v_mfma_f32_16x16x32_bf16 v[16:19], v[214:217], v[104:107], v[32:35]
	v_mfma_f32_16x16x32_bf16 v[4:7], v[198:201], v[222:225], v[4:7]
	v_mfma_f32_16x16x32_bf16 v[0:3], v[214:217], v[222:225], v[0:3]
	v_mfma_f32_16x16x32_bf16 v[32:35], v[218:221], v[108:111], v[16:19]
	v_mfma_f32_16x16x32_bf16 v[4:7], v[202:205], v[226:229], v[4:7]
	v_mfma_f32_16x16x32_bf16 v[0:3], v[218:221], v[226:229], v[0:3]
	s_setprio 0
	s_barrier
	s_add_i32 s46, s46, 2
	s_add_u32 s10, s10, 0x100
	s_addc_u32 s11, s11, 0
	s_add_u32 s44, s44, 0x100
	s_addc_u32 s45, s45, 0
	s_cmp_gt_u32 s46, 29
	s_cbranch_scc0 .LBB0_341
	s_cmpk_lt_i32 s0, 0x80
	s_cselect_b64 s[42:43], -1, 0
	s_cmpk_gt_i32 s0, 0x7f
	s_cselect_b64 s[44:45], -1, 0
	s_mov_b64 s[10:11], 0x3400
	s_and_b64 vcc, exec, s[44:45]
	s_cbranch_vccnz .LBB0_346
	s_ashr_i32 s1, s0, 5
	s_mul_hi_i32 s11, s1, 0xd00
	s_mul_i32 s10, s1, 0xd00

; #define PG8_STAGE(bufoff, gbase, voff) do { _Pragma("unroll") for (int _i = 0; _i < 2; ++_i) \
;         __builtin_amdgcn_global_load_lds((const unsigned*)((const char*)(gbase) + (voff)[_i]), (PG8_LAS unsigned*)(lds + (bufoff) + ldsw + _i * 8192), 16, 0, 0); } while (0)
; #define PG8_LDA(dst, b, h) do { _Pragma("unroll") for (int m = 0; m < 4; ++m) _Pragma("unroll") for (int k = 0; k < 2; ++k) dst[m][k] = *(const PG8_LAS bf16x8*)(lds + PG8_SA(b, h) + aoff + m * 2048 + k * 1024); } while (0)
; #define PG8_LDB(dst, b, h) do { _Pragma("unroll") for (int n = 0; n < 2; ++n) _Pragma("unroll") for (int k = 0; k < 2; ++k) dst[n][k] = *(const PG8_LAS bf16x8*)(lds + PG8_SB(b, h) + boff + n * 2048 + k * 1024); } while (0)
; #define PG8_MMA(ai, bj, At, Bt) do { __builtin_amdgcn_s_setprio(1); _Pragma("unroll") for (int m = 0; m < 4; ++m) _Pragma("unroll") for (int n = 0; n < 2; ++n) _Pragma("unroll") for (int k = 0; k < 2; ++k) \
;         acc[ai][bj][m][n] = __builtin_amdgcn_mfma_f32_16x16x32_bf16(Bt[n][k], At[m][k], acc[ai][bj][m][n], 0, 0, 0); __builtin_amdgcn_s_setprio(0); } while (0)
; #define PG8_WAIT_V(n) asm volatile("s_waitcnt vmcnt(" #n ")" ::: "memory")
; #define PG8_WAIT_L(n) asm volatile("s_waitcnt lgkmcnt(" #n ")" ::: "memory")
; #define PG8_BAR __builtin_amdgcn_s_barrier()
; #define PG8_SCHED __builtin_amdgcn_sched_barrier(0)
; template <class Epi, class Sched, bool ALIGN_EPI = false, bool SP2 = false>
; __device__ __forceinline__ void gemm_phase(PG8_LAS unsigned char* lds, const Gemm g, const Sched& S, const Epi& E, const int tid) {
;     ...
;             PG8_LDB(B0, 0, 0); PG8_LDB(B1, 0, 1); PG8_SCHED; PG8_LDA(At, 0, 0); PG8_STAGE(PG8_SA(1, 1), a1 + hstep, voffA);
;             PG8_WAIT_V(8); PG8_WAIT_L(0); PG8_BAR; PG8_MMA(0, 0, At, B0); PG8_MMA(0, 1, At, B1); PG8_BAR; PG8_SCHED;
;             PG8_LDA(At, 0, 1); PG8_STAGE(PG8_SB(0, 0), b2, voffB); PG8_STAGE(PG8_SB(0, 1), b2 + hstep, voffB); PG8_STAGE(PG8_SA(0, 0), a2, voffA);
;             PG8_WAIT_V(8); PG8_WAIT_L(0); PG8_BAR; PG8_MMA(1, 0, At, B0); PG8_MMA(1, 1, At, B1); PG8_BAR; PG8_SCHED;
.Lmy_nobar_768:
	s_add_u32 s26, s24, 0xfff80080
	s_addc_u32 s27, s25, -1
	s_add_i32 s52, 0, 0x10000
	v_add_u32_e32 v68, s52, v157
	v_add_u32_e32 v154, s33, v157
	ds_read_b128 v[48:51], v68
	ds_read_b128 v[52:55], v68 offset:1024
	ds_read_b128 v[64:67], v68 offset:2048
	ds_read_b128 v[68:71], v68 offset:3072
	ds_read_b128 v[162:165], v154
	ds_read_b128 v[166:169], v154 offset:1024
	ds_read_b128 v[170:173], v154 offset:2048
	ds_read_b128 v[174:177], v154 offset:3072
	s_cmp_eq_u32 s51, 28
	s_cselect_b32 s29, s15, s27
	s_cselect_b32 s28, s21, s26
	s_cselect_b32 s27, s11, s50
	s_cselect_b32 s26, s48, s49
	v_lshl_add_u64 v[206:207], s[24:25], 0, v[150:151]
	s_add_i32 m0, s23, 0xc000
	ds_read_b128 v[178:181], v161
	ds_read_b128 v[182:185], v161 offset:1024
	ds_read_b128 v[186:189], v161 offset:2048
	ds_read_b128 v[190:193], v161 offset:3072
	ds_read_b128 v[194:197], v161 offset:4096
	ds_read_b128 v[198:201], v161 offset:5120
	ds_read_b128 v[202:205], v161 offset:6144
	ds_read_b128 v[214:217], v161 offset:7168
	global_load_lds_dwordx4 v[206:207], off
	v_lshl_add_u64 v[206:207], s[24:25], 0, v[152:153]
	s_add_i32 m0, s23, 0xe000
	s_nop 0
	global_load_lds_dwordx4 v[206:207], off
	s_waitcnt vmcnt(8)
	s_waitcnt lgkmcnt(0)
	s_barrier
	s_setprio 1
	s_waitcnt lgkmcnt(0)
	v_mfma_f32_16x16x32_bf16 v[140:143], v[48:51], v[178:181], 0
	v_mfma_f32_16x16x32_bf16 v[136:139], v[64:67], v[178:181], 0
	v_mfma_f32_16x16x32_bf16 v[124:127], v[48:51], v[186:189], 0
	v_mfma_f32_16x16x32_bf16 v[120:123], v[64:67], v[186:189], 0
	v_mfma_f32_16x16x32_bf16 v[108:111], v[48:51], v[194:197], 0
	v_mfma_f32_16x16x32_bf16 v[104:107], v[64:67], v[194:197], 0
	v_mfma_f32_16x16x32_bf16 v[92:95], v[48:51], v[202:205], 0
	v_mfma_f32_16x16x32_bf16 v[88:91], v[64:67], v[202:205], 0
	v_mfma_f32_16x16x32_bf16 v[140:143], v[52:55], v[182:185], v[140:143]
	v_mfma_f32_16x16x32_bf16 v[136:139], v[68:71], v[182:185], v[136:139]
	v_mfma_f32_16x16x32_bf16 v[124:127], v[52:55], v[190:193], v[124:127]
	v_mfma_f32_16x16x32_bf16 v[120:123], v[68:71], v[190:193], v[120:123]
	v_mfma_f32_16x16x32_bf16 v[108:111], v[52:55], v[198:201], v[108:111]
	v_mfma_f32_16x16x32_bf16 v[104:107], v[68:71], v[198:201], v[104:107]
	v_mfma_f32_16x16x32_bf16 v[92:95], v[52:55], v[214:217], v[92:95]
	v_mfma_f32_16x16x32_bf16 v[88:91], v[68:71], v[214:217], v[88:91]
	v_mfma_f32_16x16x32_bf16 v[132:135], v[162:165], v[178:181], 0
	v_mfma_f32_16x16x32_bf16 v[128:131], v[170:173], v[178:181], 0
	v_mfma_f32_16x16x32_bf16 v[116:119], v[162:165], v[186:189], 0
	v_mfma_f32_16x16x32_bf16 v[112:115], v[170:173], v[186:189], 0
	v_mfma_f32_16x16x32_bf16 v[100:103], v[162:165], v[194:197], 0
	v_mfma_f32_16x16x32_bf16 v[96:99], v[170:173], v[194:197], 0
	v_mfma_f32_16x16x32_bf16 v[84:87], v[162:165], v[202:205], 0
	v_mfma_f32_16x16x32_bf16 v[80:83], v[170:173], v[202:205], 0
	v_mfma_f32_16x16x32_bf16 v[132:135], v[166:169], v[182:185], v[132:135]
	v_mfma_f32_16x16x32_bf16 v[128:131], v[174:177], v[182:185], v[128:131]
	v_mfma_f32_16x16x32_bf16 v[116:119], v[166:169], v[190:193], v[116:119]
	v_mfma_f32_16x16x32_bf16 v[112:115], v[174:177], v[190:193], v[112:115]
	v_mfma_f32_16x16x32_bf16 v[100:103], v[166:169], v[198:201], v[100:103]
	v_mfma_f32_16x16x32_bf16 v[96:99], v[174:177], v[198:201], v[96:99]
	v_mfma_f32_16x16x32_bf16 v[84:87], v[166:169], v[214:217], v[84:87]
	v_mfma_f32_16x16x32_bf16 v[80:83], v[174:177], v[214:217], v[80:83]
	s_setprio 0
	s_barrier
	s_add_i32 s52, s52, s38
	v_lshl_add_u64 v[206:207], s[26:27], 0, v[208:209]
	s_mov_b32 m0, s52
	ds_read_b128 v[178:181], v161 offset:16384
	ds_read_b128 v[182:185], v161 offset:17408
	ds_read_b128 v[186:189], v161 offset:18432
	ds_read_b128 v[190:193], v161 offset:19456
	ds_read_b128 v[194:197], v161 offset:20480
	ds_read_b128 v[198:201], v161 offset:21504
	ds_read_b128 v[202:205], v161 offset:22528
	ds_read_b128 v[214:217], v161 offset:23552
	global_load_lds_dwordx4 v[206:207], off
	s_add_i32 m0, s52, 0x2000
	s_add_u32 s52, s26, 0x80000
	v_lshl_add_u64 v[210:211], s[26:27], 0, v[144:145]
	s_addc_u32 s53, s27, 0
	s_add_i32 s54, s33, s38
	global_load_lds_dwordx4 v[210:211], off
	v_lshl_add_u64 v[218:219], s[52:53], 0, v[208:209]
	s_mov_b32 m0, s54
	v_lshl_add_u64 v[220:221], s[28:29], 0, v[146:147]
	global_load_lds_dwordx4 v[218:219], off
	v_lshl_add_u64 v[218:219], s[52:53], 0, v[144:145]
	s_add_i32 m0, s54, 0x2000
	s_nop 0
	global_load_lds_dwordx4 v[218:219], off
	v_lshl_add_u64 v[218:219], s[28:29], 0, v[148:149]
	s_mov_b32 m0, s23
	s_nop 0
	global_load_lds_dwordx4 v[218:219], off
	s_mov_b32 m0, s39
	s_nop 0
	global_load_lds_dwordx4 v[220:221], off
	s_waitcnt vmcnt(8)
	s_waitcnt lgkmcnt(0)
	s_barrier
	s_setprio 1
	s_waitcnt lgkmcnt(0)
	v_mfma_f32_16x16x32_bf16 v[76:79], v[48:51], v[178:181], 0
	v_mfma_f32_16x16x32_bf16 v[72:75], v[64:67], v[178:181], 0
	v_mfma_f32_16x16x32_bf16 v[44:47], v[48:51], v[186:189], 0
	v_mfma_f32_16x16x32_bf16 v[40:43], v[64:67], v[186:189], 0
	v_mfma_f32_16x16x32_bf16 v[28:31], v[48:51], v[194:197], 0
	v_mfma_f32_16x16x32_bf16 v[24:27], v[64:67], v[194:197], 0
	v_mfma_f32_16x16x32_bf16 v[12:15], v[48:51], v[202:205], 0
	v_mfma_f32_16x16x32_bf16 v[8:11], v[64:67], v[202:205], 0
	v_mfma_f32_16x16x32_bf16 v[76:79], v[52:55], v[182:185], v[76:79]
	v_mfma_f32_16x16x32_bf16 v[72:75], v[68:71], v[182:185], v[72:75]
	v_mfma_f32_16x16x32_bf16 v[44:47], v[52:55], v[190:193], v[44:47]
	v_mfma_f32_16x16x32_bf16 v[40:43], v[68:71], v[190:193], v[40:43]
	v_mfma_f32_16x16x32_bf16 v[28:31], v[52:55], v[198:201], v[28:31]
	v_mfma_f32_16x16x32_bf16 v[24:27], v[68:71], v[198:201], v[24:27]
	v_mfma_f32_16x16x32_bf16 v[12:15], v[52:55], v[214:217], v[12:15]
	v_mfma_f32_16x16x32_bf16 v[8:11], v[68:71], v[214:217], v[8:11]
	v_mfma_f32_16x16x32_bf16 v[36:39], v[162:165], v[186:189], 0
	v_mfma_f32_16x16x32_bf16 v[32:35], v[170:173], v[186:189], 0
	v_mfma_f32_16x16x32_bf16 v[20:23], v[162:165], v[194:197], 0
	v_mfma_f32_16x16x32_bf16 v[16:19], v[170:173], v[194:197], 0
	v_mfma_f32_16x16x32_bf16 v[4:7], v[162:165], v[202:205], 0
	v_mfma_f32_16x16x32_bf16 v[0:3], v[170:173], v[202:205], 0
	v_mfma_f32_16x16x32_bf16 v[48:51], v[162:165], v[178:181], 0
	v_mfma_f32_16x16x32_bf16 v[52:55], v[170:173], v[178:181], 0
	v_mfma_f32_16x16x32_bf16 v[36:39], v[166:169], v[190:193], v[36:39]
	v_mfma_f32_16x16x32_bf16 v[32:35], v[174:177], v[190:193], v[32:35]
	v_mfma_f32_16x16x32_bf16 v[20:23], v[166:169], v[198:201], v[20:23]
	v_mfma_f32_16x16x32_bf16 v[16:19], v[174:177], v[198:201], v[16:19]
	v_mfma_f32_16x16x32_bf16 v[4:7], v[166:169], v[214:217], v[4:7]
	v_mfma_f32_16x16x32_bf16 v[0:3], v[174:177], v[214:217], v[0:3]
	v_mfma_f32_16x16x32_bf16 v[48:51], v[166:169], v[182:185], v[48:51]
	v_mfma_f32_16x16x32_bf16 v[52:55], v[174:177], v[182:185], v[52:55]
	s_setprio 0
	s_barrier
	s_branch .Lmy_mid_768
; #define PG8_STAGE(bufoff, gbase, voff) do { _Pragma("unroll") for (int _i = 0; _i < 2; ++_i) \
;         __builtin_amdgcn_global_load_lds((const unsigned*)((const char*)(gbase) + (voff)[_i]), (PG8_LAS unsigned*)(lds + (bufoff) + ldsw + _i * 8192), 16, 0, 0); } while (0)
; #define PG8_LDA(dst, b, h) do { _Pragma("unroll") for (int m = 0; m < 4; ++m) _Pragma("unroll") for (int k = 0; k < 2; ++k) dst[m][k] = *(const PG8_LAS bf16x8*)(lds + PG8_SA(b, h) + aoff + m * 2048 + k * 1024); } while (0)
; #define PG8_LDB(dst, b, h) do { _Pragma("unroll") for (int n = 0; n < 2; ++n) _Pragma("unroll") for (int k = 0; k < 2; ++k) dst[n][k] = *(const PG8_LAS bf16x8*)(lds + PG8_SB(b, h) + boff + n * 2048 + k * 1024); } while (0)
; #define PG8_MMA(ai, bj, At, Bt) do { __builtin_amdgcn_s_setprio(1); _Pragma("unroll") for (int m = 0; m < 4; ++m) _Pragma("unroll") for (int n = 0; n < 2; ++n) _Pragma("unroll") for (int k = 0; k < 2; ++k) \
;         acc[ai][bj][m][n] = __builtin_amdgcn_mfma_f32_16x16x32_bf16(Bt[n][k], At[m][k], acc[ai][bj][m][n], 0, 0, 0); __builtin_amdgcn_s_setprio(0); } while (0)
; #define PG8_WAIT_V(n) asm volatile("s_waitcnt vmcnt(" #n ")" ::: "memory")
; #define PG8_WAIT_L(n) asm volatile("s_waitcnt lgkmcnt(" #n ")" ::: "memory")
; #define PG8_BAR __builtin_amdgcn_s_barrier()
; #define PG8_SCHED __builtin_amdgcn_sched_barrier(0)
; template <class Epi, class Sched, bool ALIGN_EPI = false, bool SP2 = false>
; __device__ __forceinline__ void gemm_phase(PG8_LAS unsigned char* lds, const Gemm g, const Sched& S, const Epi& E, const int tid) {
;     ...
;             PG8_LDB(B0, 0, 0); PG8_LDB(B1, 0, 1); PG8_SCHED; PG8_LDA(At, 0, 0); PG8_STAGE(PG8_SA(1, 1), a1 + hstep, voffA);
;             PG8_WAIT_V(8); PG8_WAIT_L(0); PG8_BAR; PG8_MMA(0, 0, At, B0); PG8_MMA(0, 1, At, B1); PG8_BAR; PG8_SCHED;
;             PG8_LDA(At, 0, 1); PG8_STAGE(PG8_SB(0, 0), b2, voffB); PG8_STAGE(PG8_SB(0, 1), b2 + hstep, voffB); PG8_STAGE(PG8_SA(0, 0), a2, voffA);
;             PG8_WAIT_V(8); PG8_WAIT_L(0); PG8_BAR; PG8_MMA(1, 0, At, B0); PG8_MMA(1, 1, At, B1); PG8_BAR; PG8_SCHED;
.LBB0_768:
	s_add_u32 s26, s24, 0xfff80080
	s_addc_u32 s27, s25, -1
	s_add_i32 s52, 0, 0x10000
	v_add_u32_e32 v68, s52, v157
	v_add_u32_e32 v154, s33, v157
	ds_read_b128 v[48:51], v68
	ds_read_b128 v[52:55], v68 offset:1024
	ds_read_b128 v[64:67], v68 offset:2048
	ds_read_b128 v[68:71], v68 offset:3072
	ds_read_b128 v[162:165], v154
	ds_read_b128 v[166:169], v154 offset:1024
	ds_read_b128 v[170:173], v154 offset:2048
	ds_read_b128 v[174:177], v154 offset:3072
	s_cmp_eq_u32 s51, 28
	s_cselect_b32 s29, s15, s27
	s_cselect_b32 s28, s21, s26
	s_cselect_b32 s27, s11, s50
	s_cselect_b32 s26, s48, s49
	v_lshl_add_u64 v[206:207], s[24:25], 0, v[150:151]
	s_add_i32 m0, s23, 0xc000
	ds_read_b128 v[178:181], v161
	ds_read_b128 v[182:185], v161 offset:1024
	ds_read_b128 v[186:189], v161 offset:2048
	ds_read_b128 v[190:193], v161 offset:3072
	ds_read_b128 v[194:197], v161 offset:4096
	ds_read_b128 v[198:201], v161 offset:5120
	ds_read_b128 v[202:205], v161 offset:6144
	ds_read_b128 v[214:217], v161 offset:7168
	global_load_lds_dwordx4 v[206:207], off
	v_lshl_add_u64 v[206:207], s[24:25], 0, v[152:153]
	s_add_i32 m0, s23, 0xe000
	s_nop 0
	global_load_lds_dwordx4 v[206:207], off
	s_waitcnt vmcnt(8)
	s_waitcnt lgkmcnt(0)
	s_barrier
	s_setprio 1
	s_waitcnt lgkmcnt(0)
	v_mfma_f32_16x16x32_bf16 v[140:143], v[48:51], v[178:181], v[140:143]
	v_mfma_f32_16x16x32_bf16 v[136:139], v[64:67], v[178:181], v[136:139]
	v_mfma_f32_16x16x32_bf16 v[124:127], v[48:51], v[186:189], v[124:127]
	v_mfma_f32_16x16x32_bf16 v[120:123], v[64:67], v[186:189], v[120:123]
	v_mfma_f32_16x16x32_bf16 v[108:111], v[48:51], v[194:197], v[108:111]
	v_mfma_f32_16x16x32_bf16 v[104:107], v[64:67], v[194:197], v[104:107]
	v_mfma_f32_16x16x32_bf16 v[92:95], v[48:51], v[202:205], v[92:95]
	v_mfma_f32_16x16x32_bf16 v[88:91], v[64:67], v[202:205], v[88:91]
	v_mfma_f32_16x16x32_bf16 v[140:143], v[52:55], v[182:185], v[140:143]
	v_mfma_f32_16x16x32_bf16 v[136:139], v[68:71], v[182:185], v[136:139]
	v_mfma_f32_16x16x32_bf16 v[124:127], v[52:55], v[190:193], v[124:127]
	v_mfma_f32_16x16x32_bf16 v[120:123], v[68:71], v[190:193], v[120:123]
	v_mfma_f32_16x16x32_bf16 v[108:111], v[52:55], v[198:201], v[108:111]
	v_mfma_f32_16x16x32_bf16 v[104:107], v[68:71], v[198:201], v[104:107]
	v_mfma_f32_16x16x32_bf16 v[92:95], v[52:55], v[214:217], v[92:95]
	v_mfma_f32_16x16x32_bf16 v[88:91], v[68:71], v[214:217], v[88:91]
	v_mfma_f32_16x16x32_bf16 v[132:135], v[162:165], v[178:181], v[132:135]
	v_mfma_f32_16x16x32_bf16 v[128:131], v[170:173], v[178:181], v[128:131]
	v_mfma_f32_16x16x32_bf16 v[116:119], v[162:165], v[186:189], v[116:119]
	v_mfma_f32_16x16x32_bf16 v[112:115], v[170:173], v[186:189], v[112:115]
	v_mfma_f32_16x16x32_bf16 v[100:103], v[162:165], v[194:197], v[100:103]
	v_mfma_f32_16x16x32_bf16 v[96:99], v[170:173], v[194:197], v[96:99]
	v_mfma_f32_16x16x32_bf16 v[84:87], v[162:165], v[202:205], v[84:87]
	v_mfma_f32_16x16x32_bf16 v[80:83], v[170:173], v[202:205], v[80:83]
	v_mfma_f32_16x16x32_bf16 v[132:135], v[166:169], v[182:185], v[132:135]
	v_mfma_f32_16x16x32_bf16 v[128:131], v[174:177], v[182:185], v[128:131]
	v_mfma_f32_16x16x32_bf16 v[116:119], v[166:169], v[190:193], v[116:119]
	v_mfma_f32_16x16x32_bf16 v[112:115], v[174:177], v[190:193], v[112:115]
	v_mfma_f32_16x16x32_bf16 v[100:103], v[166:169], v[198:201], v[100:103]
	v_mfma_f32_16x16x32_bf16 v[96:99], v[174:177], v[198:201], v[96:99]
	v_mfma_f32_16x16x32_bf16 v[84:87], v[166:169], v[214:217], v[84:87]
	v_mfma_f32_16x16x32_bf16 v[80:83], v[174:177], v[214:217], v[80:83]
	s_setprio 0
	s_barrier
	s_add_i32 s52, s52, s38
	v_lshl_add_u64 v[206:207], s[26:27], 0, v[208:209]
	s_mov_b32 m0, s52
	ds_read_b128 v[178:181], v161 offset:16384
	ds_read_b128 v[182:185], v161 offset:17408
	ds_read_b128 v[186:189], v161 offset:18432
	ds_read_b128 v[190:193], v161 offset:19456
	ds_read_b128 v[194:197], v161 offset:20480
	ds_read_b128 v[198:201], v161 offset:21504
	ds_read_b128 v[202:205], v161 offset:22528
	ds_read_b128 v[214:217], v161 offset:23552
	global_load_lds_dwordx4 v[206:207], off
	s_add_i32 m0, s52, 0x2000
	s_add_u32 s52, s26, 0x80000
	v_lshl_add_u64 v[210:211], s[26:27], 0, v[144:145]
	s_addc_u32 s53, s27, 0
	s_add_i32 s54, s33, s38
	global_load_lds_dwordx4 v[210:211], off
	v_lshl_add_u64 v[218:219], s[52:53], 0, v[208:209]
	s_mov_b32 m0, s54
	v_lshl_add_u64 v[220:221], s[28:29], 0, v[146:147]
	global_load_lds_dwordx4 v[218:219], off
	v_lshl_add_u64 v[218:219], s[52:53], 0, v[144:145]
	s_add_i32 m0, s54, 0x2000
	s_nop 0
	global_load_lds_dwordx4 v[218:219], off
	v_lshl_add_u64 v[218:219], s[28:29], 0, v[148:149]
	s_mov_b32 m0, s23
	s_nop 0
	global_load_lds_dwordx4 v[218:219], off
	s_mov_b32 m0, s39
	s_nop 0
	global_load_lds_dwordx4 v[220:221], off
	s_waitcnt vmcnt(8)
	s_waitcnt lgkmcnt(0)
	s_barrier
	s_setprio 1
	s_waitcnt lgkmcnt(0)
	v_mfma_f32_16x16x32_bf16 v[76:79], v[48:51], v[178:181], v[76:79]
	v_mfma_f32_16x16x32_bf16 v[72:75], v[64:67], v[178:181], v[72:75]
	v_mfma_f32_16x16x32_bf16 v[44:47], v[48:51], v[186:189], v[44:47]
	v_mfma_f32_16x16x32_bf16 v[40:43], v[64:67], v[186:189], v[40:43]
	v_mfma_f32_16x16x32_bf16 v[28:31], v[48:51], v[194:197], v[28:31]
	v_mfma_f32_16x16x32_bf16 v[24:27], v[64:67], v[194:197], v[24:27]
	v_mfma_f32_16x16x32_bf16 v[12:15], v[48:51], v[202:205], v[12:15]
	v_mfma_f32_16x16x32_bf16 v[8:11], v[64:67], v[202:205], v[8:11]
	v_mfma_f32_16x16x32_bf16 v[76:79], v[52:55], v[182:185], v[76:79]
	v_mfma_f32_16x16x32_bf16 v[72:75], v[68:71], v[182:185], v[72:75]
	v_mfma_f32_16x16x32_bf16 v[44:47], v[52:55], v[190:193], v[44:47]
	v_mfma_f32_16x16x32_bf16 v[40:43], v[68:71], v[190:193], v[40:43]
	v_mfma_f32_16x16x32_bf16 v[28:31], v[52:55], v[198:201], v[28:31]
	v_mfma_f32_16x16x32_bf16 v[24:27], v[68:71], v[198:201], v[24:27]
	v_mfma_f32_16x16x32_bf16 v[12:15], v[52:55], v[214:217], v[12:15]
	v_mfma_f32_16x16x32_bf16 v[8:11], v[68:71], v[214:217], v[8:11]
	v_mfma_f32_16x16x32_bf16 v[36:39], v[162:165], v[186:189], v[36:39]
	v_mfma_f32_16x16x32_bf16 v[32:35], v[170:173], v[186:189], v[32:35]
	v_mfma_f32_16x16x32_bf16 v[20:23], v[162:165], v[194:197], v[20:23]
	v_mfma_f32_16x16x32_bf16 v[16:19], v[170:173], v[194:197], v[16:19]
	v_mfma_f32_16x16x32_bf16 v[4:7], v[162:165], v[202:205], v[4:7]
	v_mfma_f32_16x16x32_bf16 v[0:3], v[170:173], v[202:205], v[0:3]
	v_mfma_f32_16x16x32_bf16 v[48:51], v[162:165], v[178:181], v[60:63]
	v_mfma_f32_16x16x32_bf16 v[52:55], v[170:173], v[178:181], v[56:59]
	v_mfma_f32_16x16x32_bf16 v[36:39], v[166:169], v[190:193], v[36:39]
	v_mfma_f32_16x16x32_bf16 v[32:35], v[174:177], v[190:193], v[32:35]
	v_mfma_f32_16x16x32_bf16 v[20:23], v[166:169], v[198:201], v[20:23]
	v_mfma_f32_16x16x32_bf16 v[16:19], v[174:177], v[198:201], v[16:19]
	v_mfma_f32_16x16x32_bf16 v[4:7], v[166:169], v[214:217], v[4:7]
	v_mfma_f32_16x16x32_bf16 v[0:3], v[174:177], v[214:217], v[0:3]
	v_mfma_f32_16x16x32_bf16 v[48:51], v[166:169], v[182:185], v[48:51]
	v_mfma_f32_16x16x32_bf16 v[52:55], v[174:177], v[182:185], v[52:55]
	s_setprio 0
	s_barrier
; #define PG8_STAGE(bufoff, gbase, voff) do { _Pragma("unroll") for (int _i = 0; _i < 2; ++_i) \
;         __builtin_amdgcn_global_load_lds((const unsigned*)((const char*)(gbase) + (voff)[_i]), (PG8_LAS unsigned*)(lds + (bufoff) + ldsw + _i * 8192), 16, 0, 0); } while (0)
; #define PG8_LDA(dst, b, h) do { _Pragma("unroll") for (int m = 0; m < 4; ++m) _Pragma("unroll") for (int k = 0; k < 2; ++k) dst[m][k] = *(const PG8_LAS bf16x8*)(lds + PG8_SA(b, h) + aoff + m * 2048 + k * 1024); } while (0)
; #define PG8_LDB(dst, b, h) do { _Pragma("unroll") for (int n = 0; n < 2; ++n) _Pragma("unroll") for (int k = 0; k < 2; ++k) dst[n][k] = *(const PG8_LAS bf16x8*)(lds + PG8_SB(b, h) + boff + n * 2048 + k * 1024); } while (0)
; #define PG8_MMA(ai, bj, At, Bt) do { __builtin_amdgcn_s_setprio(1); _Pragma("unroll") for (int m = 0; m < 4; ++m) _Pragma("unroll") for (int n = 0; n < 2; ++n) _Pragma("unroll") for (int k = 0; k < 2; ++k) \
;         acc[ai][bj][m][n] = __builtin_amdgcn_mfma_f32_16x16x32_bf16(Bt[n][k], At[m][k], acc[ai][bj][m][n], 0, 0, 0); __builtin_amdgcn_s_setprio(0); } while (0)
; #define PG8_WAIT_V(n) asm volatile("s_waitcnt vmcnt(" #n ")" ::: "memory")
; #define PG8_WAIT_L(n) asm volatile("s_waitcnt lgkmcnt(" #n ")" ::: "memory")
; #define PG8_BAR __builtin_amdgcn_s_barrier()
; #define PG8_SCHED __builtin_amdgcn_sched_barrier(0)
; template <class Epi, class Sched, bool ALIGN_EPI = false, bool SP2 = false>
; __device__ __forceinline__ void gemm_phase(PG8_LAS unsigned char* lds, const Gemm g, const Sched& S, const Epi& E, const int tid) {
;     ...
;             PG8_LDB(B0, 1, 0); PG8_LDB(B1, 1, 1); PG8_SCHED; PG8_LDA(At, 1, 0); PG8_STAGE(PG8_SA(0, 1), a2 + hstep, voffA);
;             PG8_WAIT_V(8); PG8_WAIT_L(0); PG8_BAR; PG8_MMA(0, 0, At, B0); PG8_MMA(0, 1, At, B1); PG8_BAR; PG8_SCHED;
;             PG8_LDA(At, 1, 1); PG8_STAGE(PG8_SB(1, 0), b3, voffB); PG8_STAGE(PG8_SB(1, 1), b3 + hstep, voffB); PG8_STAGE(PG8_SA(1, 0), a3, voffA);
;             PG8_WAIT_V(8); PG8_WAIT_L(0); PG8_BAR; PG8_MMA(1, 0, At, B0); PG8_MMA(1, 1, At, B1); PG8_BAR; PG8_SCHED;
.Lmy_mid_768:
	s_add_i32 s52, 0, 0x18000
	s_add_i32 s53, 0, 0x1c000
	v_add_u32_e32 v68, s52, v157
	v_add_u32_e32 v154, s53, v157
	ds_read_b128 v[56:59], v68
	ds_read_b128 v[60:63], v68 offset:1024
	ds_read_b128 v[64:67], v68 offset:2048
	ds_read_b128 v[68:71], v68 offset:3072
	ds_read_b128 v[162:165], v154
	ds_read_b128 v[166:169], v154 offset:1024
	ds_read_b128 v[170:173], v154 offset:2048
	ds_read_b128 v[174:177], v154 offset:3072
	s_add_u32 s28, s28, 0x80000
	s_addc_u32 s29, s29, 0
	s_mov_b32 m0, s40
	v_lshl_add_u64 v[222:223], s[28:29], 0, v[148:149]
	ds_read_b128 v[178:181], v161 offset:32768
	ds_read_b128 v[182:185], v161 offset:33792
	ds_read_b128 v[186:189], v161 offset:34816
	ds_read_b128 v[190:193], v161 offset:35840
	ds_read_b128 v[194:197], v161 offset:36864
	ds_read_b128 v[198:201], v161 offset:37888
	ds_read_b128 v[202:205], v161 offset:38912
	ds_read_b128 v[214:217], v161 offset:39936
	global_load_lds_dwordx4 v[222:223], off
	v_lshl_add_u64 v[222:223], s[28:29], 0, v[146:147]
	s_mov_b32 m0, s41
	s_nop 0
	global_load_lds_dwordx4 v[222:223], off
	s_waitcnt vmcnt(8)
	s_waitcnt lgkmcnt(0)
	s_barrier
	s_setprio 1
	s_waitcnt lgkmcnt(0)
	v_mfma_f32_16x16x32_bf16 v[140:143], v[56:59], v[178:181], v[140:143]
	v_mfma_f32_16x16x32_bf16 v[136:139], v[64:67], v[178:181], v[136:139]
	v_mfma_f32_16x16x32_bf16 v[124:127], v[56:59], v[186:189], v[124:127]
	v_mfma_f32_16x16x32_bf16 v[120:123], v[64:67], v[186:189], v[120:123]
	v_mfma_f32_16x16x32_bf16 v[108:111], v[56:59], v[194:197], v[108:111]
	v_mfma_f32_16x16x32_bf16 v[104:107], v[64:67], v[194:197], v[104:107]
	v_mfma_f32_16x16x32_bf16 v[92:95], v[56:59], v[202:205], v[92:95]
	v_mfma_f32_16x16x32_bf16 v[88:91], v[64:67], v[202:205], v[88:91]
	v_mfma_f32_16x16x32_bf16 v[140:143], v[60:63], v[182:185], v[140:143]
	v_mfma_f32_16x16x32_bf16 v[136:139], v[68:71], v[182:185], v[136:139]
	v_mfma_f32_16x16x32_bf16 v[124:127], v[60:63], v[190:193], v[124:127]
	v_mfma_f32_16x16x32_bf16 v[120:123], v[68:71], v[190:193], v[120:123]
	v_mfma_f32_16x16x32_bf16 v[108:111], v[60:63], v[198:201], v[108:111]
	v_mfma_f32_16x16x32_bf16 v[104:107], v[68:71], v[198:201], v[104:107]
	v_mfma_f32_16x16x32_bf16 v[92:95], v[60:63], v[214:217], v[92:95]
	v_mfma_f32_16x16x32_bf16 v[88:91], v[68:71], v[214:217], v[88:91]
	v_mfma_f32_16x16x32_bf16 v[132:135], v[162:165], v[178:181], v[132:135]
	v_mfma_f32_16x16x32_bf16 v[128:131], v[170:173], v[178:181], v[128:131]
	v_mfma_f32_16x16x32_bf16 v[116:119], v[162:165], v[186:189], v[116:119]
	v_mfma_f32_16x16x32_bf16 v[112:115], v[170:173], v[186:189], v[112:115]
	v_mfma_f32_16x16x32_bf16 v[100:103], v[162:165], v[194:197], v[100:103]
	v_mfma_f32_16x16x32_bf16 v[96:99], v[170:173], v[194:197], v[96:99]
	v_mfma_f32_16x16x32_bf16 v[84:87], v[162:165], v[202:205], v[84:87]
	v_mfma_f32_16x16x32_bf16 v[80:83], v[170:173], v[202:205], v[80:83]
	v_mfma_f32_16x16x32_bf16 v[132:135], v[166:169], v[182:185], v[132:135]
	v_mfma_f32_16x16x32_bf16 v[128:131], v[174:177], v[182:185], v[128:131]
	v_mfma_f32_16x16x32_bf16 v[116:119], v[166:169], v[190:193], v[116:119]
	v_mfma_f32_16x16x32_bf16 v[112:115], v[174:177], v[190:193], v[112:115]
	v_mfma_f32_16x16x32_bf16 v[100:103], v[166:169], v[198:201], v[100:103]
	v_mfma_f32_16x16x32_bf16 v[96:99], v[174:177], v[198:201], v[96:99]
	v_mfma_f32_16x16x32_bf16 v[84:87], v[166:169], v[214:217], v[84:87]
	v_mfma_f32_16x16x32_bf16 v[80:83], v[174:177], v[214:217], v[80:83]
	s_setprio 0
	s_barrier
	s_add_i32 s28, s52, s38
	v_lshl_add_u64 v[206:207], v[206:207], 0, s[2:3]
	s_mov_b32 m0, s28
	ds_read_b128 v[178:181], v161 offset:49152
	ds_read_b128 v[182:185], v161 offset:50176
	ds_read_b128 v[186:189], v161 offset:51200
	ds_read_b128 v[190:193], v161 offset:52224
	ds_read_b128 v[194:197], v161 offset:53248
	ds_read_b128 v[198:201], v161 offset:54272
	ds_read_b128 v[202:205], v161 offset:55296
	ds_read_b128 v[214:217], v161 offset:56320
	global_load_lds_dwordx4 v[206:207], off
	s_add_i32 m0, s28, 0x2000
	s_add_u32 s26, s26, 0x80080
	v_lshl_add_u64 v[206:207], v[210:211], 0, s[2:3]
	s_addc_u32 s27, s27, 0
	s_add_i32 s28, s53, s38
	global_load_lds_dwordx4 v[206:207], off
	v_lshl_add_u64 v[206:207], s[26:27], 0, v[208:209]
	s_mov_b32 m0, s28
	s_nop 0
	global_load_lds_dwordx4 v[206:207], off
	v_lshl_add_u64 v[206:207], s[26:27], 0, v[144:145]
	s_add_i32 m0, s28, 0x2000
	s_nop 0
	global_load_lds_dwordx4 v[206:207], off
	v_lshl_add_u64 v[206:207], v[218:219], 0, s[2:3]
	s_mov_b32 m0, s45
	s_nop 0
	global_load_lds_dwordx4 v[206:207], off
	v_lshl_add_u64 v[206:207], v[220:221], 0, s[2:3]
	s_mov_b32 m0, s46
	s_nop 0
	global_load_lds_dwordx4 v[206:207], off
	s_waitcnt vmcnt(8)
	s_waitcnt lgkmcnt(0)
	s_barrier
; #define PG8_STAGE(bufoff, gbase, voff) do { _Pragma("unroll") for (int _i = 0; _i < 2; ++_i) \
;         __builtin_amdgcn_global_load_lds((const unsigned*)((const char*)(gbase) + (voff)[_i]), (PG8_LAS unsigned*)(lds + (bufoff) + ldsw + _i * 8192), 16, 0, 0); } while (0)
; #define PG8_LDA(dst, b, h) do { _Pragma("unroll") for (int m = 0; m < 4; ++m) _Pragma("unroll") for (int k = 0; k < 2; ++k) dst[m][k] = *(const PG8_LAS bf16x8*)(lds + PG8_SA(b, h) + aoff + m * 2048 + k * 1024); } while (0)
; #define PG8_MMA(ai, bj, At, Bt) do { __builtin_amdgcn_s_setprio(1); _Pragma("unroll") for (int m = 0; m < 4; ++m) _Pragma("unroll") for (int n = 0; n < 2; ++n) _Pragma("unroll") for (int k = 0; k < 2; ++k) \
;         acc[ai][bj][m][n] = __builtin_amdgcn_mfma_f32_16x16x32_bf16(Bt[n][k], At[m][k], acc[ai][bj][m][n], 0, 0, 0); __builtin_amdgcn_s_setprio(0); } while (0)
; #define PG8_WAIT_V(n) asm volatile("s_waitcnt vmcnt(" #n ")" ::: "memory")
; #define PG8_WAIT_L(n) asm volatile("s_waitcnt lgkmcnt(" #n ")" ::: "memory")
; #define PG8_BAR __builtin_amdgcn_s_barrier()
; #define PG8_SCHED __builtin_amdgcn_sched_barrier(0)
; template <class Epi, class Sched, bool ALIGN_EPI = false, bool SP2 = false>
; __device__ __forceinline__ void gemm_phase(PG8_LAS unsigned char* lds, const Gemm g, const Sched& S, const Epi& E, const int tid) {
;     ...
;             PG8_LDA(At, 1, 1); PG8_STAGE(PG8_SB(1, 0), b3, voffB); PG8_STAGE(PG8_SB(1, 1), b3 + hstep, voffB); PG8_STAGE(PG8_SA(1, 0), a3, voffA);
;             PG8_WAIT_V(8); PG8_WAIT_L(0); PG8_BAR; PG8_MMA(1, 0, At, B0); PG8_MMA(1, 1, At, B1); PG8_BAR; PG8_SCHED;
;     __device__ __forceinline__ void operator()(const f32x4 (&acc)[2][2][4][2], const Unit& un, int wr, int wc, int fr, int fq) const {
;         const int rbase = un.pm * 256 + wr * 64 + fr, cw = un.pn * 256 + wc * 32 + 8 * fq;
;         const int slot = un.pm < (NLAT / 256) ? (un.pm >> 5) : 4; const float* sw = shw + (size_t)slot * DFF;
;         f32x4 s0[2], s1[2]; float rr[2][4];
; #pragma unroll
;         for (int bj = 0; bj < 2; ++bj) { s0[bj] = *(const f32x4*)(sw + cw + bj * 128); s1[bj] = *(const f32x4*)(sw + cw + bj * 128 + 4); }
; #pragma unroll
;         for (int ai = 0; ai < 2; ++ai)
; #pragma unroll
;             for (int m = 0; m < 4; ++m) rr[ai][m] = rs[rbase + ai * 128 + m * 16];
	s_setprio 1
	s_waitcnt lgkmcnt(0)
	v_mfma_f32_16x16x32_bf16 v[76:79], v[56:59], v[178:181], v[76:79]
	v_mfma_f32_16x16x32_bf16 v[72:75], v[64:67], v[178:181], v[72:75]
	v_mfma_f32_16x16x32_bf16 v[44:47], v[56:59], v[186:189], v[44:47]
	v_mfma_f32_16x16x32_bf16 v[40:43], v[64:67], v[186:189], v[40:43]
	v_mfma_f32_16x16x32_bf16 v[28:31], v[56:59], v[194:197], v[28:31]
	v_mfma_f32_16x16x32_bf16 v[24:27], v[64:67], v[194:197], v[24:27]
	v_mfma_f32_16x16x32_bf16 v[12:15], v[56:59], v[202:205], v[12:15]
	v_mfma_f32_16x16x32_bf16 v[8:11], v[64:67], v[202:205], v[8:11]
	v_mfma_f32_16x16x32_bf16 v[76:79], v[60:63], v[182:185], v[76:79]
	v_mfma_f32_16x16x32_bf16 v[72:75], v[68:71], v[182:185], v[72:75]
	v_mfma_f32_16x16x32_bf16 v[44:47], v[60:63], v[190:193], v[44:47]
	v_mfma_f32_16x16x32_bf16 v[40:43], v[68:71], v[190:193], v[40:43]
	v_mfma_f32_16x16x32_bf16 v[28:31], v[60:63], v[198:201], v[28:31]
	v_mfma_f32_16x16x32_bf16 v[24:27], v[68:71], v[198:201], v[24:27]
	v_mfma_f32_16x16x32_bf16 v[12:15], v[60:63], v[214:217], v[12:15]
	v_mfma_f32_16x16x32_bf16 v[8:11], v[68:71], v[214:217], v[8:11]
	v_mfma_f32_16x16x32_bf16 v[48:51], v[162:165], v[178:181], v[48:51]
	v_mfma_f32_16x16x32_bf16 v[60:63], v[166:169], v[182:185], v[48:51]
	v_mfma_f32_16x16x32_bf16 v[48:51], v[170:173], v[178:181], v[52:55]
	v_mfma_f32_16x16x32_bf16 v[36:39], v[162:165], v[186:189], v[36:39]
	v_mfma_f32_16x16x32_bf16 v[32:35], v[170:173], v[186:189], v[32:35]
	v_mfma_f32_16x16x32_bf16 v[20:23], v[162:165], v[194:197], v[20:23]
	v_mfma_f32_16x16x32_bf16 v[16:19], v[170:173], v[194:197], v[16:19]
	v_mfma_f32_16x16x32_bf16 v[4:7], v[162:165], v[202:205], v[4:7]
	v_mfma_f32_16x16x32_bf16 v[0:3], v[170:173], v[202:205], v[0:3]
	v_mfma_f32_16x16x32_bf16 v[56:59], v[174:177], v[182:185], v[48:51]
	v_mfma_f32_16x16x32_bf16 v[36:39], v[166:169], v[190:193], v[36:39]
	v_mfma_f32_16x16x32_bf16 v[32:35], v[174:177], v[190:193], v[32:35]
	v_mfma_f32_16x16x32_bf16 v[20:23], v[166:169], v[198:201], v[20:23]
	v_mfma_f32_16x16x32_bf16 v[16:19], v[174:177], v[198:201], v[16:19]
	v_mfma_f32_16x16x32_bf16 v[4:7], v[166:169], v[214:217], v[4:7]
	v_mfma_f32_16x16x32_bf16 v[0:3], v[174:177], v[214:217], v[0:3]
	s_setprio 0
	s_barrier
	s_add_i32 s51, s51, 2
	s_add_u32 s24, s24, 0x100
	s_addc_u32 s25, s25, 0
	s_add_u32 s49, s49, 0x100
	s_addc_u32 s50, s50, 0
	s_cmp_gt_u32 s51, 29
	s_cbranch_scc0 .LBB0_768
	s_ashr_i32 s24, s20, 5
	s_ashr_i32 s25, s24, 31
	s_lshl_b64 s[24:25], s[24:25], 13
	s_cmpk_lt_i32 s20, 0x80
	s_cselect_b32 s25, s25, 0
	s_cselect_b32 s24, s24, 0x8000
	s_lshl_b64 s[24:25], s[24:25], 2
	v_lshl_or_b32 v176, s22, 8, v159
	s_add_u32 s24, s42, s24
	v_lshl_add_u32 v178, s20, 8, v155
	s_addc_u32 s25, s43, s25
	v_ashrrev_i32_e32 v177, 31, v176
	v_ashrrev_i32_e32 v179, 31, v178
	v_lshl_add_u64 v[52:53], v[176:177], 2, s[24:25]
	v_lshl_add_u64 v[180:181], v[178:179], 2, s[6:7]
	global_load_dwordx4 v[64:67], v[52:53], off offset:16
	global_load_dwordx4 v[68:71], v[52:53], off
	global_load_dwordx4 v[48:51], v[52:53], off offset:528
	s_nop 0
	global_load_dwordx4 v[52:55], v[52:53], off offset:512
	v_or_b32_e32 v172, 16, v178
	global_load_dword v174, v[180:181], off
	v_ashrrev_i32_e32 v173, 31, v172
	v_lshl_add_u64 v[162:163], v[172:173], 2, s[6:7]
	global_load_dword v170, v[162:163], off
	v_or_b32_e32 v168, 32, v178
	v_ashrrev_i32_e32 v169, 31, v168
	v_lshl_add_u64 v[162:163], v[168:169], 2, s[6:7]
	global_load_dword v166, v[162:163], off
	v_or_b32_e32 v164, 48, v178
	v_lshlrev_b64 v[178:179], 14, v[178:179]
	v_ashrrev_i32_e32 v165, 31, v164
	v_lshl_add_u64 v[162:163], v[164:165], 2, s[6:7]
	global_load_dword v162, v[162:163], off
	s_nop 0
	global_load_dword v160, v[180:181], off offset:512
	global_load_dword v158, v[180:181], off offset:576
	global_load_dword v156, v[180:181], off offset:640
	global_load_dword v154, v[180:181], off offset:704
	s_and_b64 vcc, exec, s[8:9]
	s_cbranch_vccz .LBB0_771
	s_barrier

; #define PG8_STAGE(bufoff, gbase, voff) do { _Pragma("unroll") for (int _i = 0; _i < 2; ++_i) \
;         __builtin_amdgcn_global_load_lds((const unsigned*)((const char*)(gbase) + (voff)[_i]), (PG8_LAS unsigned*)(lds + (bufoff) + ldsw + _i * 8192), 16, 0, 0); } while (0)
; #define PG8_LDA(dst, b, h) do { _Pragma("unroll") for (int m = 0; m < 4; ++m) _Pragma("unroll") for (int k = 0; k < 2; ++k) dst[m][k] = *(const PG8_LAS bf16x8*)(lds + PG8_SA(b, h) + aoff + m * 2048 + k * 1024); } while (0)
; #define PG8_LDB(dst, b, h) do { _Pragma("unroll") for (int n = 0; n < 2; ++n) _Pragma("unroll") for (int k = 0; k < 2; ++k) dst[n][k] = *(const PG8_LAS bf16x8*)(lds + PG8_SB(b, h) + boff + n * 2048 + k * 1024); } while (0)
; #define PG8_MMA(ai, bj, At, Bt) do { __builtin_amdgcn_s_setprio(1); _Pragma("unroll") for (int m = 0; m < 4; ++m) _Pragma("unroll") for (int n = 0; n < 2; ++n) _Pragma("unroll") for (int k = 0; k < 2; ++k) \
;         acc[ai][bj][m][n] = __builtin_amdgcn_mfma_f32_16x16x32_bf16(Bt[n][k], At[m][k], acc[ai][bj][m][n], 0, 0, 0); __builtin_amdgcn_s_setprio(0); } while (0)
; #define PG8_WAIT_V(n) asm volatile("s_waitcnt vmcnt(" #n ")" ::: "memory")
; #define PG8_WAIT_L(n) asm volatile("s_waitcnt lgkmcnt(" #n ")" ::: "memory")
; #define PG8_BAR __builtin_amdgcn_s_barrier()
; #define PG8_SCHED __builtin_amdgcn_sched_barrier(0)
; template <class Epi, class Sched, bool ALIGN_EPI = false, bool SP2 = false>
; __device__ __forceinline__ void gemm_phase(PG8_LAS unsigned char* lds, const Gemm g, const Sched& S, const Epi& E, const int tid) {
;     ...
;             PG8_LDB(B0, 0, 0); PG8_LDB(B1, 0, 1); PG8_SCHED; PG8_LDA(At, 0, 0); PG8_STAGE(PG8_SA(1, 1), a1 + hstep, voffA);
;             PG8_WAIT_V(8); PG8_WAIT_L(0); PG8_BAR; PG8_MMA(0, 0, At, B0); PG8_MMA(0, 1, At, B1); PG8_BAR; PG8_SCHED;
;             PG8_LDA(At, 0, 1); PG8_STAGE(PG8_SB(0, 0), b2, voffB); PG8_STAGE(PG8_SB(0, 1), b2 + hstep, voffB); PG8_STAGE(PG8_SA(0, 0), a2, voffA);
;             PG8_WAIT_V(8); PG8_WAIT_L(0); PG8_BAR; PG8_MMA(1, 0, At, B0); PG8_MMA(1, 1, At, B1); PG8_BAR; PG8_SCHED;
.Lmy_nobar_1031:
	s_add_u32 s24, s22, 0xfffe0080
	s_addc_u32 s25, s23, -1
	s_add_i32 s51, 0, 0x10000
	v_add_u32_e32 v138, s51, v141
	ds_read_b128 v[144:147], v138
	ds_read_b128 v[148:151], v138 offset:1024
	ds_read_b128 v[152:155], v138 offset:2048
	ds_read_b128 v[156:159], v138 offset:3072
	v_add_u32_e32 v138, s33, v141
	ds_read_b128 v[160:163], v138
	ds_read_b128 v[164:167], v138 offset:1024
	ds_read_b128 v[168:171], v138 offset:2048
	ds_read_b128 v[172:175], v138 offset:3072
	s_cmp_eq_u32 s50, 4
	s_cselect_b32 s27, s13, s25
	s_cselect_b32 s26, s19, s24
	s_cselect_b32 s25, s11, s49
	s_cselect_b32 s24, s47, s48
	v_lshl_add_u64 v[138:139], s[22:23], 0, v[134:135]
	s_add_i32 m0, s21, 0xc000
	ds_read_b128 v[176:179], v143
	ds_read_b128 v[180:183], v143 offset:1024
	ds_read_b128 v[184:187], v143 offset:2048
	ds_read_b128 v[188:191], v143 offset:3072
	ds_read_b128 v[192:195], v143 offset:4096
	ds_read_b128 v[196:199], v143 offset:5120
	ds_read_b128 v[200:203], v143 offset:6144
	ds_read_b128 v[204:207], v143 offset:7168
	global_load_lds_dwordx4 v[138:139], off
	v_lshl_add_u64 v[138:139], s[22:23], 0, v[136:137]
	s_add_i32 m0, s21, 0xe000
	s_nop 0
	global_load_lds_dwordx4 v[138:139], off
	s_waitcnt vmcnt(8)
	s_waitcnt lgkmcnt(0)
	s_barrier
	s_setprio 1
	s_waitcnt lgkmcnt(0)
	v_mfma_f32_16x16x32_bf16 v[124:127], v[144:147], v[176:179], 0
	v_mfma_f32_16x16x32_bf16 v[120:123], v[152:155], v[176:179], 0
	v_mfma_f32_16x16x32_bf16 v[108:111], v[144:147], v[184:187], 0
	v_mfma_f32_16x16x32_bf16 v[104:107], v[152:155], v[184:187], 0
	v_mfma_f32_16x16x32_bf16 v[92:95], v[144:147], v[192:195], 0
	v_mfma_f32_16x16x32_bf16 v[88:91], v[152:155], v[192:195], 0
	v_mfma_f32_16x16x32_bf16 v[76:79], v[144:147], v[200:203], 0
	v_mfma_f32_16x16x32_bf16 v[72:75], v[152:155], v[200:203], 0
	v_mfma_f32_16x16x32_bf16 v[124:127], v[148:151], v[180:183], v[124:127]
	v_mfma_f32_16x16x32_bf16 v[120:123], v[156:159], v[180:183], v[120:123]
	v_mfma_f32_16x16x32_bf16 v[108:111], v[148:151], v[188:191], v[108:111]
	v_mfma_f32_16x16x32_bf16 v[104:107], v[156:159], v[188:191], v[104:107]
	v_mfma_f32_16x16x32_bf16 v[92:95], v[148:151], v[196:199], v[92:95]
	v_mfma_f32_16x16x32_bf16 v[88:91], v[156:159], v[196:199], v[88:91]
	v_mfma_f32_16x16x32_bf16 v[76:79], v[148:151], v[204:207], v[76:79]
	v_mfma_f32_16x16x32_bf16 v[72:75], v[156:159], v[204:207], v[72:75]
	v_mfma_f32_16x16x32_bf16 v[116:119], v[160:163], v[176:179], 0
	v_mfma_f32_16x16x32_bf16 v[112:115], v[168:171], v[176:179], 0
	v_mfma_f32_16x16x32_bf16 v[100:103], v[160:163], v[184:187], 0
	v_mfma_f32_16x16x32_bf16 v[96:99], v[168:171], v[184:187], 0
	v_mfma_f32_16x16x32_bf16 v[84:87], v[160:163], v[192:195], 0
	v_mfma_f32_16x16x32_bf16 v[80:83], v[168:171], v[192:195], 0
	v_mfma_f32_16x16x32_bf16 v[68:71], v[160:163], v[200:203], 0
	v_mfma_f32_16x16x32_bf16 v[64:67], v[168:171], v[200:203], 0
	v_mfma_f32_16x16x32_bf16 v[116:119], v[164:167], v[180:183], v[116:119]
	v_mfma_f32_16x16x32_bf16 v[112:115], v[172:175], v[180:183], v[112:115]
	v_mfma_f32_16x16x32_bf16 v[100:103], v[164:167], v[188:191], v[100:103]
	v_mfma_f32_16x16x32_bf16 v[96:99], v[172:175], v[188:191], v[96:99]
	v_mfma_f32_16x16x32_bf16 v[84:87], v[164:167], v[196:199], v[84:87]
	v_mfma_f32_16x16x32_bf16 v[80:83], v[172:175], v[196:199], v[80:83]
	v_mfma_f32_16x16x32_bf16 v[68:71], v[164:167], v[204:207], v[68:71]
	v_mfma_f32_16x16x32_bf16 v[64:67], v[172:175], v[204:207], v[64:67]
	s_setprio 0
	s_barrier
	s_add_i32 s51, s51, s36
	v_lshl_add_u64 v[138:139], s[24:25], 0, v[208:209]
	s_mov_b32 m0, s51
	ds_read_b128 v[176:179], v143 offset:16384
	ds_read_b128 v[180:183], v143 offset:17408
	ds_read_b128 v[184:187], v143 offset:18432
	ds_read_b128 v[188:191], v143 offset:19456
	ds_read_b128 v[192:195], v143 offset:20480
	ds_read_b128 v[196:199], v143 offset:21504
	ds_read_b128 v[200:203], v143 offset:22528
	ds_read_b128 v[204:207], v143 offset:23552
	global_load_lds_dwordx4 v[138:139], off
	s_add_i32 m0, s51, 0x2000
	s_add_u32 s52, s24, 0x20000
	v_lshl_add_u64 v[210:211], s[24:25], 0, v[128:129]
	s_addc_u32 s53, s25, 0
	s_add_i32 s51, s33, s36
	global_load_lds_dwordx4 v[210:211], off
	v_lshl_add_u64 v[214:215], s[52:53], 0, v[208:209]
	s_mov_b32 m0, s51
	v_lshl_add_u64 v[216:217], s[26:27], 0, v[130:131]
	global_load_lds_dwordx4 v[214:215], off
	v_lshl_add_u64 v[214:215], s[52:53], 0, v[128:129]
	s_add_i32 m0, s51, 0x2000
	s_nop 0
	global_load_lds_dwordx4 v[214:215], off
	v_lshl_add_u64 v[214:215], s[26:27], 0, v[132:133]
	s_mov_b32 m0, s21
	s_nop 0
	global_load_lds_dwordx4 v[214:215], off
	s_mov_b32 m0, s40
	s_nop 0
	global_load_lds_dwordx4 v[216:217], off
	s_waitcnt vmcnt(8)
	s_waitcnt lgkmcnt(0)
	s_barrier
	s_setprio 1
	s_waitcnt lgkmcnt(0)
	v_mfma_f32_16x16x32_bf16 v[60:63], v[144:147], v[176:179], 0
	v_mfma_f32_16x16x32_bf16 v[56:59], v[152:155], v[176:179], 0
	v_mfma_f32_16x16x32_bf16 v[44:47], v[144:147], v[184:187], 0
	v_mfma_f32_16x16x32_bf16 v[40:43], v[152:155], v[184:187], 0
	v_mfma_f32_16x16x32_bf16 v[28:31], v[144:147], v[192:195], 0
	v_mfma_f32_16x16x32_bf16 v[24:27], v[152:155], v[192:195], 0
	v_mfma_f32_16x16x32_bf16 v[12:15], v[144:147], v[200:203], 0
	v_mfma_f32_16x16x32_bf16 v[8:11], v[152:155], v[200:203], 0
	v_mfma_f32_16x16x32_bf16 v[60:63], v[148:151], v[180:183], v[60:63]
	v_mfma_f32_16x16x32_bf16 v[56:59], v[156:159], v[180:183], v[56:59]
	v_mfma_f32_16x16x32_bf16 v[44:47], v[148:151], v[188:191], v[44:47]
	v_mfma_f32_16x16x32_bf16 v[40:43], v[156:159], v[188:191], v[40:43]
	v_mfma_f32_16x16x32_bf16 v[28:31], v[148:151], v[196:199], v[28:31]
	v_mfma_f32_16x16x32_bf16 v[24:27], v[156:159], v[196:199], v[24:27]
	v_mfma_f32_16x16x32_bf16 v[12:15], v[148:151], v[204:207], v[12:15]
	v_mfma_f32_16x16x32_bf16 v[8:11], v[156:159], v[204:207], v[8:11]
	v_mfma_f32_16x16x32_bf16 v[52:55], v[160:163], v[176:179], 0
	v_mfma_f32_16x16x32_bf16 v[48:51], v[168:171], v[176:179], 0
	v_mfma_f32_16x16x32_bf16 v[36:39], v[160:163], v[184:187], 0
	v_mfma_f32_16x16x32_bf16 v[32:35], v[168:171], v[184:187], 0
	v_mfma_f32_16x16x32_bf16 v[20:23], v[160:163], v[192:195], 0
	v_mfma_f32_16x16x32_bf16 v[16:19], v[168:171], v[192:195], 0
	v_mfma_f32_16x16x32_bf16 v[4:7], v[160:163], v[200:203], 0
	v_mfma_f32_16x16x32_bf16 v[0:3], v[168:171], v[200:203], 0
	v_mfma_f32_16x16x32_bf16 v[52:55], v[164:167], v[180:183], v[52:55]
	v_mfma_f32_16x16x32_bf16 v[48:51], v[172:175], v[180:183], v[48:51]
	v_mfma_f32_16x16x32_bf16 v[36:39], v[164:167], v[188:191], v[36:39]
	v_mfma_f32_16x16x32_bf16 v[32:35], v[172:175], v[188:191], v[32:35]
	v_mfma_f32_16x16x32_bf16 v[20:23], v[164:167], v[196:199], v[20:23]
	v_mfma_f32_16x16x32_bf16 v[16:19], v[172:175], v[196:199], v[16:19]
	v_mfma_f32_16x16x32_bf16 v[4:7], v[164:167], v[204:207], v[4:7]
	v_mfma_f32_16x16x32_bf16 v[0:3], v[172:175], v[204:207], v[0:3]
	s_setprio 0
	s_barrier
	s_branch .Lmy_mid_1031
; #define PG8_STAGE(bufoff, gbase, voff) do { _Pragma("unroll") for (int _i = 0; _i < 2; ++_i) \
;         __builtin_amdgcn_global_load_lds((const unsigned*)((const char*)(gbase) + (voff)[_i]), (PG8_LAS unsigned*)(lds + (bufoff) + ldsw + _i * 8192), 16, 0, 0); } while (0)
; #define PG8_LDA(dst, b, h) do { _Pragma("unroll") for (int m = 0; m < 4; ++m) _Pragma("unroll") for (int k = 0; k < 2; ++k) dst[m][k] = *(const PG8_LAS bf16x8*)(lds + PG8_SA(b, h) + aoff + m * 2048 + k * 1024); } while (0)
; #define PG8_LDB(dst, b, h) do { _Pragma("unroll") for (int n = 0; n < 2; ++n) _Pragma("unroll") for (int k = 0; k < 2; ++k) dst[n][k] = *(const PG8_LAS bf16x8*)(lds + PG8_SB(b, h) + boff + n * 2048 + k * 1024); } while (0)
; #define PG8_MMA(ai, bj, At, Bt) do { __builtin_amdgcn_s_setprio(1); _Pragma("unroll") for (int m = 0; m < 4; ++m) _Pragma("unroll") for (int n = 0; n < 2; ++n) _Pragma("unroll") for (int k = 0; k < 2; ++k) \
;         acc[ai][bj][m][n] = __builtin_amdgcn_mfma_f32_16x16x32_bf16(Bt[n][k], At[m][k], acc[ai][bj][m][n], 0, 0, 0); __builtin_amdgcn_s_setprio(0); } while (0)
; #define PG8_WAIT_V(n) asm volatile("s_waitcnt vmcnt(" #n ")" ::: "memory")
; #define PG8_WAIT_L(n) asm volatile("s_waitcnt lgkmcnt(" #n ")" ::: "memory")
; #define PG8_BAR __builtin_amdgcn_s_barrier()
; #define PG8_SCHED __builtin_amdgcn_sched_barrier(0)
; template <class Epi, class Sched, bool ALIGN_EPI = false, bool SP2 = false>
; __device__ __forceinline__ void gemm_phase(PG8_LAS unsigned char* lds, const Gemm g, const Sched& S, const Epi& E, const int tid) {
;     ...
;             PG8_LDB(B0, 0, 0); PG8_LDB(B1, 0, 1); PG8_SCHED; PG8_LDA(At, 0, 0); PG8_STAGE(PG8_SA(1, 1), a1 + hstep, voffA);
;             PG8_WAIT_V(8); PG8_WAIT_L(0); PG8_BAR; PG8_MMA(0, 0, At, B0); PG8_MMA(0, 1, At, B1); PG8_BAR; PG8_SCHED;
;             PG8_LDA(At, 0, 1); PG8_STAGE(PG8_SB(0, 0), b2, voffB); PG8_STAGE(PG8_SB(0, 1), b2 + hstep, voffB); PG8_STAGE(PG8_SA(0, 0), a2, voffA);
;             PG8_WAIT_V(8); PG8_WAIT_L(0); PG8_BAR; PG8_MMA(1, 0, At, B0); PG8_MMA(1, 1, At, B1); PG8_BAR; PG8_SCHED;
.LBB0_1031:
	s_add_u32 s24, s22, 0xfffe0080
	s_addc_u32 s25, s23, -1
	s_add_i32 s51, 0, 0x10000
	v_add_u32_e32 v138, s51, v141
	ds_read_b128 v[144:147], v138
	ds_read_b128 v[148:151], v138 offset:1024
	ds_read_b128 v[152:155], v138 offset:2048
	ds_read_b128 v[156:159], v138 offset:3072
	v_add_u32_e32 v138, s33, v141
	ds_read_b128 v[160:163], v138
	ds_read_b128 v[164:167], v138 offset:1024
	ds_read_b128 v[168:171], v138 offset:2048
	ds_read_b128 v[172:175], v138 offset:3072
	s_cmp_eq_u32 s50, 4
	s_cselect_b32 s27, s13, s25
	s_cselect_b32 s26, s19, s24
	s_cselect_b32 s25, s11, s49
	s_cselect_b32 s24, s47, s48
	v_lshl_add_u64 v[138:139], s[22:23], 0, v[134:135]
	s_add_i32 m0, s21, 0xc000
	ds_read_b128 v[176:179], v143
	ds_read_b128 v[180:183], v143 offset:1024
	ds_read_b128 v[184:187], v143 offset:2048
	ds_read_b128 v[188:191], v143 offset:3072
	ds_read_b128 v[192:195], v143 offset:4096
	ds_read_b128 v[196:199], v143 offset:5120
	ds_read_b128 v[200:203], v143 offset:6144
	ds_read_b128 v[204:207], v143 offset:7168
	global_load_lds_dwordx4 v[138:139], off
	v_lshl_add_u64 v[138:139], s[22:23], 0, v[136:137]
	s_add_i32 m0, s21, 0xe000
	s_nop 0
	global_load_lds_dwordx4 v[138:139], off
	s_waitcnt vmcnt(8)
	s_waitcnt lgkmcnt(0)
	s_barrier
	s_setprio 1
	s_waitcnt lgkmcnt(0)
	v_mfma_f32_16x16x32_bf16 v[124:127], v[144:147], v[176:179], v[124:127]
	v_mfma_f32_16x16x32_bf16 v[120:123], v[152:155], v[176:179], v[120:123]
	v_mfma_f32_16x16x32_bf16 v[108:111], v[144:147], v[184:187], v[108:111]
	v_mfma_f32_16x16x32_bf16 v[104:107], v[152:155], v[184:187], v[104:107]
	v_mfma_f32_16x16x32_bf16 v[92:95], v[144:147], v[192:195], v[92:95]
	v_mfma_f32_16x16x32_bf16 v[88:91], v[152:155], v[192:195], v[88:91]
	v_mfma_f32_16x16x32_bf16 v[76:79], v[144:147], v[200:203], v[76:79]
	v_mfma_f32_16x16x32_bf16 v[72:75], v[152:155], v[200:203], v[72:75]
	v_mfma_f32_16x16x32_bf16 v[124:127], v[148:151], v[180:183], v[124:127]
	v_mfma_f32_16x16x32_bf16 v[120:123], v[156:159], v[180:183], v[120:123]
	v_mfma_f32_16x16x32_bf16 v[108:111], v[148:151], v[188:191], v[108:111]
	v_mfma_f32_16x16x32_bf16 v[104:107], v[156:159], v[188:191], v[104:107]
	v_mfma_f32_16x16x32_bf16 v[92:95], v[148:151], v[196:199], v[92:95]
	v_mfma_f32_16x16x32_bf16 v[88:91], v[156:159], v[196:199], v[88:91]
	v_mfma_f32_16x16x32_bf16 v[76:79], v[148:151], v[204:207], v[76:79]
	v_mfma_f32_16x16x32_bf16 v[72:75], v[156:159], v[204:207], v[72:75]
	v_mfma_f32_16x16x32_bf16 v[116:119], v[160:163], v[176:179], v[116:119]
	v_mfma_f32_16x16x32_bf16 v[112:115], v[168:171], v[176:179], v[112:115]
	v_mfma_f32_16x16x32_bf16 v[100:103], v[160:163], v[184:187], v[100:103]
	v_mfma_f32_16x16x32_bf16 v[96:99], v[168:171], v[184:187], v[96:99]
	v_mfma_f32_16x16x32_bf16 v[84:87], v[160:163], v[192:195], v[84:87]
	v_mfma_f32_16x16x32_bf16 v[80:83], v[168:171], v[192:195], v[80:83]
	v_mfma_f32_16x16x32_bf16 v[68:71], v[160:163], v[200:203], v[68:71]
	v_mfma_f32_16x16x32_bf16 v[64:67], v[168:171], v[200:203], v[64:67]
	v_mfma_f32_16x16x32_bf16 v[116:119], v[164:167], v[180:183], v[116:119]
	v_mfma_f32_16x16x32_bf16 v[112:115], v[172:175], v[180:183], v[112:115]
	v_mfma_f32_16x16x32_bf16 v[100:103], v[164:167], v[188:191], v[100:103]
	v_mfma_f32_16x16x32_bf16 v[96:99], v[172:175], v[188:191], v[96:99]
	v_mfma_f32_16x16x32_bf16 v[84:87], v[164:167], v[196:199], v[84:87]
	v_mfma_f32_16x16x32_bf16 v[80:83], v[172:175], v[196:199], v[80:83]
	v_mfma_f32_16x16x32_bf16 v[68:71], v[164:167], v[204:207], v[68:71]
	v_mfma_f32_16x16x32_bf16 v[64:67], v[172:175], v[204:207], v[64:67]
	s_setprio 0
	s_barrier
	s_add_i32 s51, s51, s36
	v_lshl_add_u64 v[138:139], s[24:25], 0, v[208:209]
	s_mov_b32 m0, s51
	ds_read_b128 v[176:179], v143 offset:16384
	ds_read_b128 v[180:183], v143 offset:17408
	ds_read_b128 v[184:187], v143 offset:18432
	ds_read_b128 v[188:191], v143 offset:19456
	ds_read_b128 v[192:195], v143 offset:20480
	ds_read_b128 v[196:199], v143 offset:21504
	ds_read_b128 v[200:203], v143 offset:22528
	ds_read_b128 v[204:207], v143 offset:23552
	global_load_lds_dwordx4 v[138:139], off
	s_add_i32 m0, s51, 0x2000
	s_add_u32 s52, s24, 0x20000
	v_lshl_add_u64 v[210:211], s[24:25], 0, v[128:129]
	s_addc_u32 s53, s25, 0
	s_add_i32 s51, s33, s36
	global_load_lds_dwordx4 v[210:211], off
	v_lshl_add_u64 v[214:215], s[52:53], 0, v[208:209]
	s_mov_b32 m0, s51
	v_lshl_add_u64 v[216:217], s[26:27], 0, v[130:131]
	global_load_lds_dwordx4 v[214:215], off
	v_lshl_add_u64 v[214:215], s[52:53], 0, v[128:129]
	s_add_i32 m0, s51, 0x2000
	s_nop 0
	global_load_lds_dwordx4 v[214:215], off
	v_lshl_add_u64 v[214:215], s[26:27], 0, v[132:133]
	s_mov_b32 m0, s21
	s_nop 0
	global_load_lds_dwordx4 v[214:215], off
	s_mov_b32 m0, s40
	s_nop 0
	global_load_lds_dwordx4 v[216:217], off
	s_waitcnt vmcnt(8)
	s_waitcnt lgkmcnt(0)
	s_barrier
	s_setprio 1
	s_waitcnt lgkmcnt(0)
	v_mfma_f32_16x16x32_bf16 v[60:63], v[144:147], v[176:179], v[60:63]
	v_mfma_f32_16x16x32_bf16 v[56:59], v[152:155], v[176:179], v[56:59]
	v_mfma_f32_16x16x32_bf16 v[44:47], v[144:147], v[184:187], v[44:47]
	v_mfma_f32_16x16x32_bf16 v[40:43], v[152:155], v[184:187], v[40:43]
	v_mfma_f32_16x16x32_bf16 v[28:31], v[144:147], v[192:195], v[28:31]
	v_mfma_f32_16x16x32_bf16 v[24:27], v[152:155], v[192:195], v[24:27]
	v_mfma_f32_16x16x32_bf16 v[12:15], v[144:147], v[200:203], v[12:15]
	v_mfma_f32_16x16x32_bf16 v[8:11], v[152:155], v[200:203], v[8:11]
	v_mfma_f32_16x16x32_bf16 v[60:63], v[148:151], v[180:183], v[60:63]
	v_mfma_f32_16x16x32_bf16 v[56:59], v[156:159], v[180:183], v[56:59]
	v_mfma_f32_16x16x32_bf16 v[44:47], v[148:151], v[188:191], v[44:47]
	v_mfma_f32_16x16x32_bf16 v[40:43], v[156:159], v[188:191], v[40:43]
	v_mfma_f32_16x16x32_bf16 v[28:31], v[148:151], v[196:199], v[28:31]
	v_mfma_f32_16x16x32_bf16 v[24:27], v[156:159], v[196:199], v[24:27]
	v_mfma_f32_16x16x32_bf16 v[12:15], v[148:151], v[204:207], v[12:15]
	v_mfma_f32_16x16x32_bf16 v[8:11], v[156:159], v[204:207], v[8:11]
	v_mfma_f32_16x16x32_bf16 v[52:55], v[160:163], v[176:179], v[52:55]
	v_mfma_f32_16x16x32_bf16 v[48:51], v[168:171], v[176:179], v[48:51]
	v_mfma_f32_16x16x32_bf16 v[36:39], v[160:163], v[184:187], v[36:39]
	v_mfma_f32_16x16x32_bf16 v[32:35], v[168:171], v[184:187], v[32:35]
	v_mfma_f32_16x16x32_bf16 v[20:23], v[160:163], v[192:195], v[20:23]
	v_mfma_f32_16x16x32_bf16 v[16:19], v[168:171], v[192:195], v[16:19]
	v_mfma_f32_16x16x32_bf16 v[4:7], v[160:163], v[200:203], v[4:7]
	v_mfma_f32_16x16x32_bf16 v[0:3], v[168:171], v[200:203], v[0:3]
	v_mfma_f32_16x16x32_bf16 v[52:55], v[164:167], v[180:183], v[52:55]
	v_mfma_f32_16x16x32_bf16 v[48:51], v[172:175], v[180:183], v[48:51]
	v_mfma_f32_16x16x32_bf16 v[36:39], v[164:167], v[188:191], v[36:39]
	v_mfma_f32_16x16x32_bf16 v[32:35], v[172:175], v[188:191], v[32:35]
	v_mfma_f32_16x16x32_bf16 v[20:23], v[164:167], v[196:199], v[20:23]
	v_mfma_f32_16x16x32_bf16 v[16:19], v[172:175], v[196:199], v[16:19]
	v_mfma_f32_16x16x32_bf16 v[4:7], v[164:167], v[204:207], v[4:7]
	v_mfma_f32_16x16x32_bf16 v[0:3], v[172:175], v[204:207], v[0:3]
	s_setprio 0
	s_barrier
; #define PG8_STAGE(bufoff, gbase, voff) do { _Pragma("unroll") for (int _i = 0; _i < 2; ++_i) \
;         __builtin_amdgcn_global_load_lds((const unsigned*)((const char*)(gbase) + (voff)[_i]), (PG8_LAS unsigned*)(lds + (bufoff) + ldsw + _i * 8192), 16, 0, 0); } while (0)
; #define PG8_LDA(dst, b, h) do { _Pragma("unroll") for (int m = 0; m < 4; ++m) _Pragma("unroll") for (int k = 0; k < 2; ++k) dst[m][k] = *(const PG8_LAS bf16x8*)(lds + PG8_SA(b, h) + aoff + m * 2048 + k * 1024); } while (0)
; #define PG8_LDB(dst, b, h) do { _Pragma("unroll") for (int n = 0; n < 2; ++n) _Pragma("unroll") for (int k = 0; k < 2; ++k) dst[n][k] = *(const PG8_LAS bf16x8*)(lds + PG8_SB(b, h) + boff + n * 2048 + k * 1024); } while (0)
; #define PG8_MMA(ai, bj, At, Bt) do { __builtin_amdgcn_s_setprio(1); _Pragma("unroll") for (int m = 0; m < 4; ++m) _Pragma("unroll") for (int n = 0; n < 2; ++n) _Pragma("unroll") for (int k = 0; k < 2; ++k) \
;         acc[ai][bj][m][n] = __builtin_amdgcn_mfma_f32_16x16x32_bf16(Bt[n][k], At[m][k], acc[ai][bj][m][n], 0, 0, 0); __builtin_amdgcn_s_setprio(0); } while (0)
; #define PG8_WAIT_V(n) asm volatile("s_waitcnt vmcnt(" #n ")" ::: "memory")
; #define PG8_WAIT_L(n) asm volatile("s_waitcnt lgkmcnt(" #n ")" ::: "memory")
; #define PG8_BAR __builtin_amdgcn_s_barrier()
; #define PG8_SCHED __builtin_amdgcn_sched_barrier(0)
; template <class Epi, class Sched, bool ALIGN_EPI = false, bool SP2 = false>
; __device__ __forceinline__ void gemm_phase(PG8_LAS unsigned char* lds, const Gemm g, const Sched& S, const Epi& E, const int tid) {
;     ...
;             PG8_LDB(B0, 1, 0); PG8_LDB(B1, 1, 1); PG8_SCHED; PG8_LDA(At, 1, 0); PG8_STAGE(PG8_SA(0, 1), a2 + hstep, voffA);
;             PG8_WAIT_V(8); PG8_WAIT_L(0); PG8_BAR; PG8_MMA(0, 0, At, B0); PG8_MMA(0, 1, At, B1); PG8_BAR; PG8_SCHED;
.Lmy_mid_1031:
	s_add_i32 s51, 0, 0x18000
	s_add_i32 s52, 0, 0x1c000
	v_add_u32_e32 v156, s51, v141
	v_add_u32_e32 v172, s52, v141
	ds_read_b128 v[144:147], v156
	ds_read_b128 v[148:151], v156 offset:1024
	ds_read_b128 v[152:155], v156 offset:2048
	ds_read_b128 v[156:159], v156 offset:3072
	ds_read_b128 v[160:163], v172
	ds_read_b128 v[164:167], v172 offset:1024
	ds_read_b128 v[168:171], v172 offset:2048
	ds_read_b128 v[172:175], v172 offset:3072
	s_add_u32 s26, s26, 0x20000
	s_addc_u32 s27, s27, 0
	s_mov_b32 m0, s41
	v_lshl_add_u64 v[218:219], s[26:27], 0, v[132:133]
	ds_read_b128 v[176:179], v143 offset:32768
	ds_read_b128 v[180:183], v143 offset:33792
	ds_read_b128 v[184:187], v143 offset:34816
	ds_read_b128 v[188:191], v143 offset:35840
	ds_read_b128 v[192:195], v143 offset:36864
	ds_read_b128 v[196:199], v143 offset:37888
	ds_read_b128 v[200:203], v143 offset:38912
	ds_read_b128 v[204:207], v143 offset:39936
	global_load_lds_dwordx4 v[218:219], off
	v_lshl_add_u64 v[218:219], s[26:27], 0, v[130:131]
	s_mov_b32 m0, s42
	s_nop 0
	global_load_lds_dwordx4 v[218:219], off
	s_waitcnt vmcnt(8)
	s_waitcnt lgkmcnt(0)
	s_barrier
	s_setprio 1
	s_waitcnt lgkmcnt(0)
	v_mfma_f32_16x16x32_bf16 v[124:127], v[144:147], v[176:179], v[124:127]
	v_mfma_f32_16x16x32_bf16 v[120:123], v[152:155], v[176:179], v[120:123]
	v_mfma_f32_16x16x32_bf16 v[108:111], v[144:147], v[184:187], v[108:111]
	v_mfma_f32_16x16x32_bf16 v[104:107], v[152:155], v[184:187], v[104:107]
	v_mfma_f32_16x16x32_bf16 v[92:95], v[144:147], v[192:195], v[92:95]
	v_mfma_f32_16x16x32_bf16 v[88:91], v[152:155], v[192:195], v[88:91]
	v_mfma_f32_16x16x32_bf16 v[76:79], v[144:147], v[200:203], v[76:79]
	v_mfma_f32_16x16x32_bf16 v[72:75], v[152:155], v[200:203], v[72:75]
	v_mfma_f32_16x16x32_bf16 v[124:127], v[148:151], v[180:183], v[124:127]
	v_mfma_f32_16x16x32_bf16 v[120:123], v[156:159], v[180:183], v[120:123]
	v_mfma_f32_16x16x32_bf16 v[108:111], v[148:151], v[188:191], v[108:111]
	v_mfma_f32_16x16x32_bf16 v[104:107], v[156:159], v[188:191], v[104:107]
	v_mfma_f32_16x16x32_bf16 v[92:95], v[148:151], v[196:199], v[92:95]
	v_mfma_f32_16x16x32_bf16 v[88:91], v[156:159], v[196:199], v[88:91]
	v_mfma_f32_16x16x32_bf16 v[76:79], v[148:151], v[204:207], v[76:79]
	v_mfma_f32_16x16x32_bf16 v[72:75], v[156:159], v[204:207], v[72:75]
	v_mfma_f32_16x16x32_bf16 v[116:119], v[160:163], v[176:179], v[116:119]
	v_mfma_f32_16x16x32_bf16 v[112:115], v[168:171], v[176:179], v[112:115]
	v_mfma_f32_16x16x32_bf16 v[100:103], v[160:163], v[184:187], v[100:103]
	v_mfma_f32_16x16x32_bf16 v[96:99], v[168:171], v[184:187], v[96:99]
	v_mfma_f32_16x16x32_bf16 v[84:87], v[160:163], v[192:195], v[84:87]
	v_mfma_f32_16x16x32_bf16 v[80:83], v[168:171], v[192:195], v[80:83]
	v_mfma_f32_16x16x32_bf16 v[68:71], v[160:163], v[200:203], v[68:71]
	v_mfma_f32_16x16x32_bf16 v[64:67], v[168:171], v[200:203], v[64:67]
	v_mfma_f32_16x16x32_bf16 v[116:119], v[164:167], v[180:183], v[116:119]
	v_mfma_f32_16x16x32_bf16 v[112:115], v[172:175], v[180:183], v[112:115]
	v_mfma_f32_16x16x32_bf16 v[100:103], v[164:167], v[188:191], v[100:103]
	v_mfma_f32_16x16x32_bf16 v[96:99], v[172:175], v[188:191], v[96:99]
	v_mfma_f32_16x16x32_bf16 v[84:87], v[164:167], v[196:199], v[84:87]
	v_mfma_f32_16x16x32_bf16 v[80:83], v[172:175], v[196:199], v[80:83]
	v_mfma_f32_16x16x32_bf16 v[68:71], v[164:167], v[204:207], v[68:71]
	v_mfma_f32_16x16x32_bf16 v[64:67], v[172:175], v[204:207], v[64:67]
	s_setprio 0
	s_barrier
; #define PG8_STAGE(bufoff, gbase, voff) do { _Pragma("unroll") for (int _i = 0; _i < 2; ++_i) \
;         __builtin_amdgcn_global_load_lds((const unsigned*)((const char*)(gbase) + (voff)[_i]), (PG8_LAS unsigned*)(lds + (bufoff) + ldsw + _i * 8192), 16, 0, 0); } while (0)
; #define PG8_LDA(dst, b, h) do { _Pragma("unroll") for (int m = 0; m < 4; ++m) _Pragma("unroll") for (int k = 0; k < 2; ++k) dst[m][k] = *(const PG8_LAS bf16x8*)(lds + PG8_SA(b, h) + aoff + m * 2048 + k * 1024); } while (0)
; #define PG8_MMA(ai, bj, At, Bt) do { __builtin_amdgcn_s_setprio(1); _Pragma("unroll") for (int m = 0; m < 4; ++m) _Pragma("unroll") for (int n = 0; n < 2; ++n) _Pragma("unroll") for (int k = 0; k < 2; ++k) \
;         acc[ai][bj][m][n] = __builtin_amdgcn_mfma_f32_16x16x32_bf16(Bt[n][k], At[m][k], acc[ai][bj][m][n], 0, 0, 0); __builtin_amdgcn_s_setprio(0); } while (0)
; #define PG8_WAIT_V(n) asm volatile("s_waitcnt vmcnt(" #n ")" ::: "memory")
; #define PG8_WAIT_L(n) asm volatile("s_waitcnt lgkmcnt(" #n ")" ::: "memory")
; #define PG8_BAR __builtin_amdgcn_s_barrier()
; #define PG8_SCHED __builtin_amdgcn_sched_barrier(0)
; template <class Epi, class Sched, bool ALIGN_EPI = false, bool SP2 = false>
; __device__ __forceinline__ void gemm_phase(PG8_LAS unsigned char* lds, const Gemm g, const Sched& S, const Epi& E, const int tid) {
;     ...
;         for (int t = 0; t < nt; t += 2) {
;             const bool last = (t == nt - 2);
;             const char* a1 = cA + (size_t)(t + 1) * kstep;
;             const char* a2 = last ? nA : cA + (size_t)(t + 2) * kstep; const char* b2 = last ? nB : cB + (size_t)(t + 2) * kstep;
;             const char* a3 = a2 + kstep; const char* b3 = b2 + kstep;
;             if (last && has_next) S.a_ready(nxt);
;     ...
;             PG8_LDA(At, 1, 1); PG8_STAGE(PG8_SB(1, 0), b3, voffB); PG8_STAGE(PG8_SB(1, 1), b3 + hstep, voffB); PG8_STAGE(PG8_SA(1, 0), a3, voffA);
;             PG8_WAIT_V(8); PG8_WAIT_L(0); PG8_BAR; PG8_MMA(1, 0, At, B0); PG8_MMA(1, 1, At, B1); PG8_BAR; PG8_SCHED;
	s_add_i32 s26, s51, s36
	v_lshl_add_u64 v[138:139], v[138:139], 0, s[2:3]
	s_mov_b32 m0, s26
	ds_read_b128 v[176:179], v143 offset:49152
	ds_read_b128 v[180:183], v143 offset:50176
	ds_read_b128 v[184:187], v143 offset:51200
	ds_read_b128 v[188:191], v143 offset:52224
	ds_read_b128 v[192:195], v143 offset:53248
	ds_read_b128 v[196:199], v143 offset:54272
	ds_read_b128 v[200:203], v143 offset:55296
	ds_read_b128 v[204:207], v143 offset:56320
	global_load_lds_dwordx4 v[138:139], off
	s_add_i32 m0, s26, 0x2000
	s_add_u32 s24, s24, 0x20080
	v_lshl_add_u64 v[138:139], v[210:211], 0, s[2:3]
	s_addc_u32 s25, s25, 0
	s_add_i32 s26, s52, s36
	global_load_lds_dwordx4 v[138:139], off
	v_lshl_add_u64 v[138:139], s[24:25], 0, v[208:209]
	s_mov_b32 m0, s26
	s_nop 0
	global_load_lds_dwordx4 v[138:139], off
	v_lshl_add_u64 v[138:139], s[24:25], 0, v[128:129]
	s_add_i32 m0, s26, 0x2000
	s_nop 0
	global_load_lds_dwordx4 v[138:139], off
	v_lshl_add_u64 v[138:139], v[214:215], 0, s[2:3]
	s_mov_b32 m0, s43
	s_nop 0
	global_load_lds_dwordx4 v[138:139], off
	v_lshl_add_u64 v[138:139], v[216:217], 0, s[2:3]
	s_mov_b32 m0, s44
	s_nop 0
	global_load_lds_dwordx4 v[138:139], off
	s_waitcnt vmcnt(8)
	s_waitcnt lgkmcnt(0)
	s_barrier
	s_setprio 1
	s_waitcnt lgkmcnt(0)
	v_mfma_f32_16x16x32_bf16 v[60:63], v[144:147], v[176:179], v[60:63]
	v_mfma_f32_16x16x32_bf16 v[56:59], v[152:155], v[176:179], v[56:59]
	v_mfma_f32_16x16x32_bf16 v[44:47], v[144:147], v[184:187], v[44:47]
	v_mfma_f32_16x16x32_bf16 v[40:43], v[152:155], v[184:187], v[40:43]
	v_mfma_f32_16x16x32_bf16 v[28:31], v[144:147], v[192:195], v[28:31]
	v_mfma_f32_16x16x32_bf16 v[24:27], v[152:155], v[192:195], v[24:27]
	v_mfma_f32_16x16x32_bf16 v[12:15], v[144:147], v[200:203], v[12:15]
	v_mfma_f32_16x16x32_bf16 v[8:11], v[152:155], v[200:203], v[8:11]
	v_mfma_f32_16x16x32_bf16 v[60:63], v[148:151], v[180:183], v[60:63]
	v_mfma_f32_16x16x32_bf16 v[56:59], v[156:159], v[180:183], v[56:59]
	v_mfma_f32_16x16x32_bf16 v[44:47], v[148:151], v[188:191], v[44:47]
	v_mfma_f32_16x16x32_bf16 v[40:43], v[156:159], v[188:191], v[40:43]
	v_mfma_f32_16x16x32_bf16 v[28:31], v[148:151], v[196:199], v[28:31]
	v_mfma_f32_16x16x32_bf16 v[24:27], v[156:159], v[196:199], v[24:27]
	v_mfma_f32_16x16x32_bf16 v[12:15], v[148:151], v[204:207], v[12:15]
	v_mfma_f32_16x16x32_bf16 v[8:11], v[156:159], v[204:207], v[8:11]
	v_mfma_f32_16x16x32_bf16 v[52:55], v[160:163], v[176:179], v[52:55]
	v_mfma_f32_16x16x32_bf16 v[48:51], v[168:171], v[176:179], v[48:51]
	v_mfma_f32_16x16x32_bf16 v[36:39], v[160:163], v[184:187], v[36:39]
	v_mfma_f32_16x16x32_bf16 v[32:35], v[168:171], v[184:187], v[32:35]
	v_mfma_f32_16x16x32_bf16 v[20:23], v[160:163], v[192:195], v[20:23]
	v_mfma_f32_16x16x32_bf16 v[16:19], v[168:171], v[192:195], v[16:19]
	v_mfma_f32_16x16x32_bf16 v[4:7], v[160:163], v[200:203], v[4:7]
	v_mfma_f32_16x16x32_bf16 v[0:3], v[168:171], v[200:203], v[0:3]
	v_mfma_f32_16x16x32_bf16 v[52:55], v[164:167], v[180:183], v[52:55]
	v_mfma_f32_16x16x32_bf16 v[48:51], v[172:175], v[180:183], v[48:51]
	v_mfma_f32_16x16x32_bf16 v[36:39], v[164:167], v[188:191], v[36:39]
	v_mfma_f32_16x16x32_bf16 v[32:35], v[172:175], v[188:191], v[32:35]
	v_mfma_f32_16x16x32_bf16 v[20:23], v[164:167], v[196:199], v[20:23]
	v_mfma_f32_16x16x32_bf16 v[16:19], v[172:175], v[196:199], v[16:19]
	v_mfma_f32_16x16x32_bf16 v[4:7], v[164:167], v[204:207], v[4:7]
	v_mfma_f32_16x16x32_bf16 v[0:3], v[172:175], v[204:207], v[0:3]
	s_setprio 0
	s_barrier
	s_add_i32 s50, s50, 2
	s_add_u32 s22, s22, 0x100
	s_addc_u32 s23, s23, 0
	s_add_u32 s48, s48, 0x100
	s_addc_u32 s49, s49, 0
	s_cmp_gt_u32 s50, 5
	s_cbranch_scc0 .LBB0_1031
	s_and_b64 vcc, exec, s[8:9]
	s_cbranch_vccz .LBB0_1034
	s_barrier

; #define PG8_STAGE(bufoff, gbase, voff) do { _Pragma("unroll") for (int _i = 0; _i < 2; ++_i) \
;         __builtin_amdgcn_global_load_lds((const unsigned*)((const char*)(gbase) + (voff)[_i]), (PG8_LAS unsigned*)(lds + (bufoff) + ldsw + _i * 8192), 16, 0, 0); } while (0)
; #define PG8_LDA(dst, b, h) do { _Pragma("unroll") for (int m = 0; m < 4; ++m) _Pragma("unroll") for (int k = 0; k < 2; ++k) dst[m][k] = *(const PG8_LAS bf16x8*)(lds + PG8_SA(b, h) + aoff + m * 2048 + k * 1024); } while (0)
; #define PG8_LDB(dst, b, h) do { _Pragma("unroll") for (int n = 0; n < 2; ++n) _Pragma("unroll") for (int k = 0; k < 2; ++k) dst[n][k] = *(const PG8_LAS bf16x8*)(lds + PG8_SB(b, h) + boff + n * 2048 + k * 1024); } while (0)
; #define PG8_MMA(ai, bj, At, Bt) do { __builtin_amdgcn_s_setprio(1); _Pragma("unroll") for (int m = 0; m < 4; ++m) _Pragma("unroll") for (int n = 0; n < 2; ++n) _Pragma("unroll") for (int k = 0; k < 2; ++k) \
;         acc[ai][bj][m][n] = __builtin_amdgcn_mfma_f32_16x16x32_bf16(Bt[n][k], At[m][k], acc[ai][bj][m][n], 0, 0, 0); __builtin_amdgcn_s_setprio(0); } while (0)
; #define PG8_WAIT_V(n) asm volatile("s_waitcnt vmcnt(" #n ")" ::: "memory")
; #define PG8_WAIT_L(n) asm volatile("s_waitcnt lgkmcnt(" #n ")" ::: "memory")
; #define PG8_BAR __builtin_amdgcn_s_barrier()
; #define PG8_SCHED __builtin_amdgcn_sched_barrier(0)
; template <class Epi, class Sched, bool ALIGN_EPI = false, bool SP2 = false>
; __device__ __forceinline__ void gemm_phase(PG8_LAS unsigned char* lds, const Gemm g, const Sched& S, const Epi& E, const int tid) {
;     ...
;             PG8_LDB(B0, 0, 0); PG8_LDB(B1, 0, 1); PG8_SCHED; PG8_LDA(At, 0, 0); PG8_STAGE(PG8_SA(1, 1), a1 + hstep, voffA);
;             PG8_WAIT_V(8); PG8_WAIT_L(0); PG8_BAR; PG8_MMA(0, 0, At, B0); PG8_MMA(0, 1, At, B1); PG8_BAR; PG8_SCHED;
;             PG8_LDA(At, 0, 1); PG8_STAGE(PG8_SB(0, 0), b2, voffB); PG8_STAGE(PG8_SB(0, 1), b2 + hstep, voffB); PG8_STAGE(PG8_SA(0, 0), a2, voffA);
;             PG8_WAIT_V(8); PG8_WAIT_L(0); PG8_BAR; PG8_MMA(1, 0, At, B0); PG8_MMA(1, 1, At, B1); PG8_BAR; PG8_SCHED;
.Lmy_nobar_1047:
	s_add_u32 s26, s24, 0xfff80080
	s_addc_u32 s27, s25, -1
	s_add_i32 s51, 0, 0x10000
	v_add_u32_e32 v68, s51, v157
	v_add_u32_e32 v154, s33, v157
	ds_read_b128 v[48:51], v68
	ds_read_b128 v[52:55], v68 offset:1024
	ds_read_b128 v[64:67], v68 offset:2048
	ds_read_b128 v[68:71], v68 offset:3072
	ds_read_b128 v[162:165], v154
	ds_read_b128 v[166:169], v154 offset:1024
	ds_read_b128 v[170:173], v154 offset:2048
	ds_read_b128 v[174:177], v154 offset:3072
	s_cmp_eq_u32 s50, 28
	s_cselect_b32 s29, s15, s27
	s_cselect_b32 s28, s21, s26
	s_cselect_b32 s27, s11, s49
	s_cselect_b32 s26, s47, s48
	v_lshl_add_u64 v[206:207], s[24:25], 0, v[150:151]
	s_add_i32 m0, s23, 0xc000
	ds_read_b128 v[178:181], v161
	ds_read_b128 v[182:185], v161 offset:1024
	ds_read_b128 v[186:189], v161 offset:2048
	ds_read_b128 v[190:193], v161 offset:3072
	ds_read_b128 v[194:197], v161 offset:4096
	ds_read_b128 v[198:201], v161 offset:5120
	ds_read_b128 v[202:205], v161 offset:6144
	ds_read_b128 v[214:217], v161 offset:7168
	global_load_lds_dwordx4 v[206:207], off
	v_lshl_add_u64 v[206:207], s[24:25], 0, v[152:153]
	s_add_i32 m0, s23, 0xe000
	s_nop 0
	global_load_lds_dwordx4 v[206:207], off
	s_waitcnt vmcnt(8)
	s_waitcnt lgkmcnt(0)
	s_barrier
	s_setprio 1
	s_waitcnt lgkmcnt(0)
	v_mfma_f32_16x16x32_bf16 v[140:143], v[48:51], v[178:181], 0
	v_mfma_f32_16x16x32_bf16 v[136:139], v[64:67], v[178:181], 0
	v_mfma_f32_16x16x32_bf16 v[124:127], v[48:51], v[186:189], 0
	v_mfma_f32_16x16x32_bf16 v[120:123], v[64:67], v[186:189], 0
	v_mfma_f32_16x16x32_bf16 v[108:111], v[48:51], v[194:197], 0
	v_mfma_f32_16x16x32_bf16 v[104:107], v[64:67], v[194:197], 0
	v_mfma_f32_16x16x32_bf16 v[92:95], v[48:51], v[202:205], 0
	v_mfma_f32_16x16x32_bf16 v[88:91], v[64:67], v[202:205], 0
	v_mfma_f32_16x16x32_bf16 v[140:143], v[52:55], v[182:185], v[140:143]
	v_mfma_f32_16x16x32_bf16 v[136:139], v[68:71], v[182:185], v[136:139]
	v_mfma_f32_16x16x32_bf16 v[124:127], v[52:55], v[190:193], v[124:127]
	v_mfma_f32_16x16x32_bf16 v[120:123], v[68:71], v[190:193], v[120:123]
	v_mfma_f32_16x16x32_bf16 v[108:111], v[52:55], v[198:201], v[108:111]
	v_mfma_f32_16x16x32_bf16 v[104:107], v[68:71], v[198:201], v[104:107]
	v_mfma_f32_16x16x32_bf16 v[92:95], v[52:55], v[214:217], v[92:95]
	v_mfma_f32_16x16x32_bf16 v[88:91], v[68:71], v[214:217], v[88:91]
	v_mfma_f32_16x16x32_bf16 v[132:135], v[162:165], v[178:181], 0
	v_mfma_f32_16x16x32_bf16 v[128:131], v[170:173], v[178:181], 0
	v_mfma_f32_16x16x32_bf16 v[116:119], v[162:165], v[186:189], 0
	v_mfma_f32_16x16x32_bf16 v[112:115], v[170:173], v[186:189], 0
	v_mfma_f32_16x16x32_bf16 v[100:103], v[162:165], v[194:197], 0
	v_mfma_f32_16x16x32_bf16 v[96:99], v[170:173], v[194:197], 0
	v_mfma_f32_16x16x32_bf16 v[84:87], v[162:165], v[202:205], 0
	v_mfma_f32_16x16x32_bf16 v[80:83], v[170:173], v[202:205], 0
	v_mfma_f32_16x16x32_bf16 v[132:135], v[166:169], v[182:185], v[132:135]
	v_mfma_f32_16x16x32_bf16 v[128:131], v[174:177], v[182:185], v[128:131]
	v_mfma_f32_16x16x32_bf16 v[116:119], v[166:169], v[190:193], v[116:119]
	v_mfma_f32_16x16x32_bf16 v[112:115], v[174:177], v[190:193], v[112:115]
	v_mfma_f32_16x16x32_bf16 v[100:103], v[166:169], v[198:201], v[100:103]
	v_mfma_f32_16x16x32_bf16 v[96:99], v[174:177], v[198:201], v[96:99]
	v_mfma_f32_16x16x32_bf16 v[84:87], v[166:169], v[214:217], v[84:87]
	v_mfma_f32_16x16x32_bf16 v[80:83], v[174:177], v[214:217], v[80:83]
	s_setprio 0
	s_barrier
	s_add_i32 s51, s51, s38
	v_lshl_add_u64 v[206:207], s[26:27], 0, v[208:209]
	s_mov_b32 m0, s51
	ds_read_b128 v[178:181], v161 offset:16384
	ds_read_b128 v[182:185], v161 offset:17408
	ds_read_b128 v[186:189], v161 offset:18432
	ds_read_b128 v[190:193], v161 offset:19456
	ds_read_b128 v[194:197], v161 offset:20480
	ds_read_b128 v[198:201], v161 offset:21504
	ds_read_b128 v[202:205], v161 offset:22528
	ds_read_b128 v[214:217], v161 offset:23552
	global_load_lds_dwordx4 v[206:207], off
	s_add_i32 m0, s51, 0x2000
	s_add_u32 s52, s26, 0x80000
	v_lshl_add_u64 v[210:211], s[26:27], 0, v[144:145]
	s_addc_u32 s53, s27, 0
	s_add_i32 s51, s33, s38
	global_load_lds_dwordx4 v[210:211], off
	v_lshl_add_u64 v[218:219], s[52:53], 0, v[208:209]
	s_mov_b32 m0, s51
	v_lshl_add_u64 v[220:221], s[28:29], 0, v[146:147]
	global_load_lds_dwordx4 v[218:219], off
	v_lshl_add_u64 v[218:219], s[52:53], 0, v[144:145]
	s_add_i32 m0, s51, 0x2000
	s_nop 0
	global_load_lds_dwordx4 v[218:219], off
	v_lshl_add_u64 v[218:219], s[28:29], 0, v[148:149]
	s_mov_b32 m0, s23
	s_nop 0
	global_load_lds_dwordx4 v[218:219], off
	s_mov_b32 m0, s39
	s_nop 0
	global_load_lds_dwordx4 v[220:221], off
	s_waitcnt vmcnt(8)
	s_waitcnt lgkmcnt(0)
	s_barrier
	s_setprio 1
	s_waitcnt lgkmcnt(0)
	v_mfma_f32_16x16x32_bf16 v[76:79], v[48:51], v[178:181], 0
	v_mfma_f32_16x16x32_bf16 v[72:75], v[64:67], v[178:181], 0
	v_mfma_f32_16x16x32_bf16 v[44:47], v[48:51], v[186:189], 0
	v_mfma_f32_16x16x32_bf16 v[40:43], v[64:67], v[186:189], 0
	v_mfma_f32_16x16x32_bf16 v[28:31], v[48:51], v[194:197], 0
	v_mfma_f32_16x16x32_bf16 v[24:27], v[64:67], v[194:197], 0
	v_mfma_f32_16x16x32_bf16 v[12:15], v[48:51], v[202:205], 0
	v_mfma_f32_16x16x32_bf16 v[8:11], v[64:67], v[202:205], 0
	v_mfma_f32_16x16x32_bf16 v[76:79], v[52:55], v[182:185], v[76:79]
	v_mfma_f32_16x16x32_bf16 v[72:75], v[68:71], v[182:185], v[72:75]
	v_mfma_f32_16x16x32_bf16 v[44:47], v[52:55], v[190:193], v[44:47]
	v_mfma_f32_16x16x32_bf16 v[40:43], v[68:71], v[190:193], v[40:43]
	v_mfma_f32_16x16x32_bf16 v[28:31], v[52:55], v[198:201], v[28:31]
	v_mfma_f32_16x16x32_bf16 v[24:27], v[68:71], v[198:201], v[24:27]
	v_mfma_f32_16x16x32_bf16 v[12:15], v[52:55], v[214:217], v[12:15]
	v_mfma_f32_16x16x32_bf16 v[8:11], v[68:71], v[214:217], v[8:11]
	v_mfma_f32_16x16x32_bf16 v[36:39], v[162:165], v[186:189], 0
	v_mfma_f32_16x16x32_bf16 v[32:35], v[170:173], v[186:189], 0
	v_mfma_f32_16x16x32_bf16 v[20:23], v[162:165], v[194:197], 0
	v_mfma_f32_16x16x32_bf16 v[16:19], v[170:173], v[194:197], 0
	v_mfma_f32_16x16x32_bf16 v[4:7], v[162:165], v[202:205], 0
	v_mfma_f32_16x16x32_bf16 v[0:3], v[170:173], v[202:205], 0
	v_mfma_f32_16x16x32_bf16 v[48:51], v[162:165], v[178:181], 0
	v_mfma_f32_16x16x32_bf16 v[52:55], v[170:173], v[178:181], 0
	v_mfma_f32_16x16x32_bf16 v[36:39], v[166:169], v[190:193], v[36:39]
	v_mfma_f32_16x16x32_bf16 v[32:35], v[174:177], v[190:193], v[32:35]
	v_mfma_f32_16x16x32_bf16 v[20:23], v[166:169], v[198:201], v[20:23]
	v_mfma_f32_16x16x32_bf16 v[16:19], v[174:177], v[198:201], v[16:19]
	v_mfma_f32_16x16x32_bf16 v[4:7], v[166:169], v[214:217], v[4:7]
	v_mfma_f32_16x16x32_bf16 v[0:3], v[174:177], v[214:217], v[0:3]
	v_mfma_f32_16x16x32_bf16 v[48:51], v[166:169], v[182:185], v[48:51]
	v_mfma_f32_16x16x32_bf16 v[52:55], v[174:177], v[182:185], v[52:55]
	s_setprio 0
	s_barrier
	s_branch .Lmy_mid_1047
; #define PG8_STAGE(bufoff, gbase, voff) do { _Pragma("unroll") for (int _i = 0; _i < 2; ++_i) \
;         __builtin_amdgcn_global_load_lds((const unsigned*)((const char*)(gbase) + (voff)[_i]), (PG8_LAS unsigned*)(lds + (bufoff) + ldsw + _i * 8192), 16, 0, 0); } while (0)
; #define PG8_LDA(dst, b, h) do { _Pragma("unroll") for (int m = 0; m < 4; ++m) _Pragma("unroll") for (int k = 0; k < 2; ++k) dst[m][k] = *(const PG8_LAS bf16x8*)(lds + PG8_SA(b, h) + aoff + m * 2048 + k * 1024); } while (0)
; #define PG8_LDB(dst, b, h) do { _Pragma("unroll") for (int n = 0; n < 2; ++n) _Pragma("unroll") for (int k = 0; k < 2; ++k) dst[n][k] = *(const PG8_LAS bf16x8*)(lds + PG8_SB(b, h) + boff + n * 2048 + k * 1024); } while (0)
; #define PG8_MMA(ai, bj, At, Bt) do { __builtin_amdgcn_s_setprio(1); _Pragma("unroll") for (int m = 0; m < 4; ++m) _Pragma("unroll") for (int n = 0; n < 2; ++n) _Pragma("unroll") for (int k = 0; k < 2; ++k) \
;         acc[ai][bj][m][n] = __builtin_amdgcn_mfma_f32_16x16x32_bf16(Bt[n][k], At[m][k], acc[ai][bj][m][n], 0, 0, 0); __builtin_amdgcn_s_setprio(0); } while (0)
; #define PG8_WAIT_V(n) asm volatile("s_waitcnt vmcnt(" #n ")" ::: "memory")
; #define PG8_WAIT_L(n) asm volatile("s_waitcnt lgkmcnt(" #n ")" ::: "memory")
; #define PG8_BAR __builtin_amdgcn_s_barrier()
; #define PG8_SCHED __builtin_amdgcn_sched_barrier(0)
; template <class Epi, class Sched, bool ALIGN_EPI = false, bool SP2 = false>
; __device__ __forceinline__ void gemm_phase(PG8_LAS unsigned char* lds, const Gemm g, const Sched& S, const Epi& E, const int tid) {
;     ...
;             PG8_LDB(B0, 0, 0); PG8_LDB(B1, 0, 1); PG8_SCHED; PG8_LDA(At, 0, 0); PG8_STAGE(PG8_SA(1, 1), a1 + hstep, voffA);
;             PG8_WAIT_V(8); PG8_WAIT_L(0); PG8_BAR; PG8_MMA(0, 0, At, B0); PG8_MMA(0, 1, At, B1); PG8_BAR; PG8_SCHED;
;             PG8_LDA(At, 0, 1); PG8_STAGE(PG8_SB(0, 0), b2, voffB); PG8_STAGE(PG8_SB(0, 1), b2 + hstep, voffB); PG8_STAGE(PG8_SA(0, 0), a2, voffA);
;             PG8_WAIT_V(8); PG8_WAIT_L(0); PG8_BAR; PG8_MMA(1, 0, At, B0); PG8_MMA(1, 1, At, B1); PG8_BAR; PG8_SCHED;
.LBB0_1047:
	s_add_u32 s26, s24, 0xfff80080
	s_addc_u32 s27, s25, -1
	s_add_i32 s51, 0, 0x10000
	v_add_u32_e32 v68, s51, v157
	v_add_u32_e32 v154, s33, v157
	ds_read_b128 v[48:51], v68
	ds_read_b128 v[52:55], v68 offset:1024
	ds_read_b128 v[64:67], v68 offset:2048
	ds_read_b128 v[68:71], v68 offset:3072
	ds_read_b128 v[162:165], v154
	ds_read_b128 v[166:169], v154 offset:1024
	ds_read_b128 v[170:173], v154 offset:2048
	ds_read_b128 v[174:177], v154 offset:3072
	s_cmp_eq_u32 s50, 28
	s_cselect_b32 s29, s15, s27
	s_cselect_b32 s28, s21, s26
	s_cselect_b32 s27, s11, s49
	s_cselect_b32 s26, s47, s48
	v_lshl_add_u64 v[206:207], s[24:25], 0, v[150:151]
	s_add_i32 m0, s23, 0xc000
	ds_read_b128 v[178:181], v161
	ds_read_b128 v[182:185], v161 offset:1024
	ds_read_b128 v[186:189], v161 offset:2048
	ds_read_b128 v[190:193], v161 offset:3072
	ds_read_b128 v[194:197], v161 offset:4096
	ds_read_b128 v[198:201], v161 offset:5120
	ds_read_b128 v[202:205], v161 offset:6144
	ds_read_b128 v[214:217], v161 offset:7168
	global_load_lds_dwordx4 v[206:207], off
	v_lshl_add_u64 v[206:207], s[24:25], 0, v[152:153]
	s_add_i32 m0, s23, 0xe000
	s_nop 0
	global_load_lds_dwordx4 v[206:207], off
	s_waitcnt vmcnt(8)
	s_waitcnt lgkmcnt(0)
	s_barrier
	s_setprio 1
	s_waitcnt lgkmcnt(0)
	v_mfma_f32_16x16x32_bf16 v[140:143], v[48:51], v[178:181], v[140:143]
	v_mfma_f32_16x16x32_bf16 v[136:139], v[64:67], v[178:181], v[136:139]
	v_mfma_f32_16x16x32_bf16 v[124:127], v[48:51], v[186:189], v[124:127]
	v_mfma_f32_16x16x32_bf16 v[120:123], v[64:67], v[186:189], v[120:123]
	v_mfma_f32_16x16x32_bf16 v[108:111], v[48:51], v[194:197], v[108:111]
	v_mfma_f32_16x16x32_bf16 v[104:107], v[64:67], v[194:197], v[104:107]
	v_mfma_f32_16x16x32_bf16 v[92:95], v[48:51], v[202:205], v[92:95]
	v_mfma_f32_16x16x32_bf16 v[88:91], v[64:67], v[202:205], v[88:91]
	v_mfma_f32_16x16x32_bf16 v[140:143], v[52:55], v[182:185], v[140:143]
	v_mfma_f32_16x16x32_bf16 v[136:139], v[68:71], v[182:185], v[136:139]
	v_mfma_f32_16x16x32_bf16 v[124:127], v[52:55], v[190:193], v[124:127]
	v_mfma_f32_16x16x32_bf16 v[120:123], v[68:71], v[190:193], v[120:123]
	v_mfma_f32_16x16x32_bf16 v[108:111], v[52:55], v[198:201], v[108:111]
	v_mfma_f32_16x16x32_bf16 v[104:107], v[68:71], v[198:201], v[104:107]
	v_mfma_f32_16x16x32_bf16 v[92:95], v[52:55], v[214:217], v[92:95]
	v_mfma_f32_16x16x32_bf16 v[88:91], v[68:71], v[214:217], v[88:91]
	v_mfma_f32_16x16x32_bf16 v[132:135], v[162:165], v[178:181], v[132:135]
	v_mfma_f32_16x16x32_bf16 v[128:131], v[170:173], v[178:181], v[128:131]
	v_mfma_f32_16x16x32_bf16 v[116:119], v[162:165], v[186:189], v[116:119]
	v_mfma_f32_16x16x32_bf16 v[112:115], v[170:173], v[186:189], v[112:115]
	v_mfma_f32_16x16x32_bf16 v[100:103], v[162:165], v[194:197], v[100:103]
	v_mfma_f32_16x16x32_bf16 v[96:99], v[170:173], v[194:197], v[96:99]
	v_mfma_f32_16x16x32_bf16 v[84:87], v[162:165], v[202:205], v[84:87]
	v_mfma_f32_16x16x32_bf16 v[80:83], v[170:173], v[202:205], v[80:83]
	v_mfma_f32_16x16x32_bf16 v[132:135], v[166:169], v[182:185], v[132:135]
	v_mfma_f32_16x16x32_bf16 v[128:131], v[174:177], v[182:185], v[128:131]
	v_mfma_f32_16x16x32_bf16 v[116:119], v[166:169], v[190:193], v[116:119]
	v_mfma_f32_16x16x32_bf16 v[112:115], v[174:177], v[190:193], v[112:115]
	v_mfma_f32_16x16x32_bf16 v[100:103], v[166:169], v[198:201], v[100:103]
	v_mfma_f32_16x16x32_bf16 v[96:99], v[174:177], v[198:201], v[96:99]
	v_mfma_f32_16x16x32_bf16 v[84:87], v[166:169], v[214:217], v[84:87]
	v_mfma_f32_16x16x32_bf16 v[80:83], v[174:177], v[214:217], v[80:83]
	s_setprio 0
	s_barrier
	s_add_i32 s51, s51, s38
	v_lshl_add_u64 v[206:207], s[26:27], 0, v[208:209]
	s_mov_b32 m0, s51
	ds_read_b128 v[178:181], v161 offset:16384
	ds_read_b128 v[182:185], v161 offset:17408
	ds_read_b128 v[186:189], v161 offset:18432
	ds_read_b128 v[190:193], v161 offset:19456
	ds_read_b128 v[194:197], v161 offset:20480
	ds_read_b128 v[198:201], v161 offset:21504
	ds_read_b128 v[202:205], v161 offset:22528
	ds_read_b128 v[214:217], v161 offset:23552
	global_load_lds_dwordx4 v[206:207], off
	s_add_i32 m0, s51, 0x2000
	s_add_u32 s52, s26, 0x80000
	v_lshl_add_u64 v[210:211], s[26:27], 0, v[144:145]
	s_addc_u32 s53, s27, 0
	s_add_i32 s51, s33, s38
	global_load_lds_dwordx4 v[210:211], off
	v_lshl_add_u64 v[218:219], s[52:53], 0, v[208:209]
	s_mov_b32 m0, s51
	v_lshl_add_u64 v[220:221], s[28:29], 0, v[146:147]
	global_load_lds_dwordx4 v[218:219], off
	v_lshl_add_u64 v[218:219], s[52:53], 0, v[144:145]
	s_add_i32 m0, s51, 0x2000
	s_nop 0
	global_load_lds_dwordx4 v[218:219], off
	v_lshl_add_u64 v[218:219], s[28:29], 0, v[148:149]
	s_mov_b32 m0, s23
	s_nop 0
	global_load_lds_dwordx4 v[218:219], off
	s_mov_b32 m0, s39
	s_nop 0
	global_load_lds_dwordx4 v[220:221], off
	s_waitcnt vmcnt(8)
	s_waitcnt lgkmcnt(0)
	s_barrier
	s_setprio 1
	s_waitcnt lgkmcnt(0)
	v_mfma_f32_16x16x32_bf16 v[76:79], v[48:51], v[178:181], v[76:79]
	v_mfma_f32_16x16x32_bf16 v[72:75], v[64:67], v[178:181], v[72:75]
	v_mfma_f32_16x16x32_bf16 v[44:47], v[48:51], v[186:189], v[44:47]
	v_mfma_f32_16x16x32_bf16 v[40:43], v[64:67], v[186:189], v[40:43]
	v_mfma_f32_16x16x32_bf16 v[28:31], v[48:51], v[194:197], v[28:31]
	v_mfma_f32_16x16x32_bf16 v[24:27], v[64:67], v[194:197], v[24:27]
	v_mfma_f32_16x16x32_bf16 v[12:15], v[48:51], v[202:205], v[12:15]
	v_mfma_f32_16x16x32_bf16 v[8:11], v[64:67], v[202:205], v[8:11]
	v_mfma_f32_16x16x32_bf16 v[76:79], v[52:55], v[182:185], v[76:79]
	v_mfma_f32_16x16x32_bf16 v[72:75], v[68:71], v[182:185], v[72:75]
	v_mfma_f32_16x16x32_bf16 v[44:47], v[52:55], v[190:193], v[44:47]
	v_mfma_f32_16x16x32_bf16 v[40:43], v[68:71], v[190:193], v[40:43]
	v_mfma_f32_16x16x32_bf16 v[28:31], v[52:55], v[198:201], v[28:31]
	v_mfma_f32_16x16x32_bf16 v[24:27], v[68:71], v[198:201], v[24:27]
	v_mfma_f32_16x16x32_bf16 v[12:15], v[52:55], v[214:217], v[12:15]
	v_mfma_f32_16x16x32_bf16 v[8:11], v[68:71], v[214:217], v[8:11]
	v_mfma_f32_16x16x32_bf16 v[36:39], v[162:165], v[186:189], v[36:39]
	v_mfma_f32_16x16x32_bf16 v[32:35], v[170:173], v[186:189], v[32:35]
	v_mfma_f32_16x16x32_bf16 v[20:23], v[162:165], v[194:197], v[20:23]
	v_mfma_f32_16x16x32_bf16 v[16:19], v[170:173], v[194:197], v[16:19]
	v_mfma_f32_16x16x32_bf16 v[4:7], v[162:165], v[202:205], v[4:7]
	v_mfma_f32_16x16x32_bf16 v[0:3], v[170:173], v[202:205], v[0:3]
	v_mfma_f32_16x16x32_bf16 v[48:51], v[162:165], v[178:181], v[60:63]
	v_mfma_f32_16x16x32_bf16 v[52:55], v[170:173], v[178:181], v[56:59]
	v_mfma_f32_16x16x32_bf16 v[36:39], v[166:169], v[190:193], v[36:39]
	v_mfma_f32_16x16x32_bf16 v[32:35], v[174:177], v[190:193], v[32:35]
	v_mfma_f32_16x16x32_bf16 v[20:23], v[166:169], v[198:201], v[20:23]
	v_mfma_f32_16x16x32_bf16 v[16:19], v[174:177], v[198:201], v[16:19]
	v_mfma_f32_16x16x32_bf16 v[4:7], v[166:169], v[214:217], v[4:7]
	v_mfma_f32_16x16x32_bf16 v[0:3], v[174:177], v[214:217], v[0:3]
	v_mfma_f32_16x16x32_bf16 v[48:51], v[166:169], v[182:185], v[48:51]
	v_mfma_f32_16x16x32_bf16 v[52:55], v[174:177], v[182:185], v[52:55]
	s_setprio 0
	s_barrier
; #define PG8_STAGE(bufoff, gbase, voff) do { _Pragma("unroll") for (int _i = 0; _i < 2; ++_i) \
;         __builtin_amdgcn_global_load_lds((const unsigned*)((const char*)(gbase) + (voff)[_i]), (PG8_LAS unsigned*)(lds + (bufoff) + ldsw + _i * 8192), 16, 0, 0); } while (0)
; #define PG8_LDA(dst, b, h) do { _Pragma("unroll") for (int m = 0; m < 4; ++m) _Pragma("unroll") for (int k = 0; k < 2; ++k) dst[m][k] = *(const PG8_LAS bf16x8*)(lds + PG8_SA(b, h) + aoff + m * 2048 + k * 1024); } while (0)
; #define PG8_LDB(dst, b, h) do { _Pragma("unroll") for (int n = 0; n < 2; ++n) _Pragma("unroll") for (int k = 0; k < 2; ++k) dst[n][k] = *(const PG8_LAS bf16x8*)(lds + PG8_SB(b, h) + boff + n * 2048 + k * 1024); } while (0)
; #define PG8_MMA(ai, bj, At, Bt) do { __builtin_amdgcn_s_setprio(1); _Pragma("unroll") for (int m = 0; m < 4; ++m) _Pragma("unroll") for (int n = 0; n < 2; ++n) _Pragma("unroll") for (int k = 0; k < 2; ++k) \
;         acc[ai][bj][m][n] = __builtin_amdgcn_mfma_f32_16x16x32_bf16(Bt[n][k], At[m][k], acc[ai][bj][m][n], 0, 0, 0); __builtin_amdgcn_s_setprio(0); } while (0)
; #define PG8_WAIT_V(n) asm volatile("s_waitcnt vmcnt(" #n ")" ::: "memory")
; #define PG8_WAIT_L(n) asm volatile("s_waitcnt lgkmcnt(" #n ")" ::: "memory")
; #define PG8_BAR __builtin_amdgcn_s_barrier()
; #define PG8_SCHED __builtin_amdgcn_sched_barrier(0)
; template <class Epi, class Sched, bool ALIGN_EPI = false, bool SP2 = false>
; __device__ __forceinline__ void gemm_phase(PG8_LAS unsigned char* lds, const Gemm g, const Sched& S, const Epi& E, const int tid) {
;     ...
;             PG8_LDB(B0, 1, 0); PG8_LDB(B1, 1, 1); PG8_SCHED; PG8_LDA(At, 1, 0); PG8_STAGE(PG8_SA(0, 1), a2 + hstep, voffA);
;             PG8_WAIT_V(8); PG8_WAIT_L(0); PG8_BAR; PG8_MMA(0, 0, At, B0); PG8_MMA(0, 1, At, B1); PG8_BAR; PG8_SCHED;
;             PG8_LDA(At, 1, 1); PG8_STAGE(PG8_SB(1, 0), b3, voffB); PG8_STAGE(PG8_SB(1, 1), b3 + hstep, voffB); PG8_STAGE(PG8_SA(1, 0), a3, voffA);
.Lmy_mid_1047:
	s_add_i32 s51, 0, 0x18000
	s_add_i32 s52, 0, 0x1c000
	v_add_u32_e32 v68, s51, v157
	v_add_u32_e32 v154, s52, v157
	ds_read_b128 v[56:59], v68
	ds_read_b128 v[60:63], v68 offset:1024
	ds_read_b128 v[64:67], v68 offset:2048
	ds_read_b128 v[68:71], v68 offset:3072
	ds_read_b128 v[162:165], v154
	ds_read_b128 v[166:169], v154 offset:1024
	ds_read_b128 v[170:173], v154 offset:2048
	ds_read_b128 v[174:177], v154 offset:3072
	s_add_u32 s28, s28, 0x80000
	s_addc_u32 s29, s29, 0
	s_mov_b32 m0, s40
	v_lshl_add_u64 v[222:223], s[28:29], 0, v[148:149]
	ds_read_b128 v[178:181], v161 offset:32768
	ds_read_b128 v[182:185], v161 offset:33792
	ds_read_b128 v[186:189], v161 offset:34816
	ds_read_b128 v[190:193], v161 offset:35840
	ds_read_b128 v[194:197], v161 offset:36864
	ds_read_b128 v[198:201], v161 offset:37888
	ds_read_b128 v[202:205], v161 offset:38912
	ds_read_b128 v[214:217], v161 offset:39936
	global_load_lds_dwordx4 v[222:223], off
	v_lshl_add_u64 v[222:223], s[28:29], 0, v[146:147]
	s_mov_b32 m0, s41
	s_nop 0
	global_load_lds_dwordx4 v[222:223], off
	s_waitcnt vmcnt(8)
	s_waitcnt lgkmcnt(0)
	s_barrier
	s_setprio 1
	s_waitcnt lgkmcnt(0)
	v_mfma_f32_16x16x32_bf16 v[140:143], v[56:59], v[178:181], v[140:143]
	v_mfma_f32_16x16x32_bf16 v[136:139], v[64:67], v[178:181], v[136:139]
	v_mfma_f32_16x16x32_bf16 v[124:127], v[56:59], v[186:189], v[124:127]
	v_mfma_f32_16x16x32_bf16 v[120:123], v[64:67], v[186:189], v[120:123]
	v_mfma_f32_16x16x32_bf16 v[108:111], v[56:59], v[194:197], v[108:111]
	v_mfma_f32_16x16x32_bf16 v[104:107], v[64:67], v[194:197], v[104:107]
	v_mfma_f32_16x16x32_bf16 v[92:95], v[56:59], v[202:205], v[92:95]
	v_mfma_f32_16x16x32_bf16 v[88:91], v[64:67], v[202:205], v[88:91]
	v_mfma_f32_16x16x32_bf16 v[140:143], v[60:63], v[182:185], v[140:143]
	v_mfma_f32_16x16x32_bf16 v[136:139], v[68:71], v[182:185], v[136:139]
	v_mfma_f32_16x16x32_bf16 v[124:127], v[60:63], v[190:193], v[124:127]
	v_mfma_f32_16x16x32_bf16 v[120:123], v[68:71], v[190:193], v[120:123]
	v_mfma_f32_16x16x32_bf16 v[108:111], v[60:63], v[198:201], v[108:111]
	v_mfma_f32_16x16x32_bf16 v[104:107], v[68:71], v[198:201], v[104:107]
	v_mfma_f32_16x16x32_bf16 v[92:95], v[60:63], v[214:217], v[92:95]
	v_mfma_f32_16x16x32_bf16 v[88:91], v[68:71], v[214:217], v[88:91]
	v_mfma_f32_16x16x32_bf16 v[132:135], v[162:165], v[178:181], v[132:135]
	v_mfma_f32_16x16x32_bf16 v[128:131], v[170:173], v[178:181], v[128:131]
	v_mfma_f32_16x16x32_bf16 v[116:119], v[162:165], v[186:189], v[116:119]
	v_mfma_f32_16x16x32_bf16 v[112:115], v[170:173], v[186:189], v[112:115]
	v_mfma_f32_16x16x32_bf16 v[100:103], v[162:165], v[194:197], v[100:103]
	v_mfma_f32_16x16x32_bf16 v[96:99], v[170:173], v[194:197], v[96:99]
	v_mfma_f32_16x16x32_bf16 v[84:87], v[162:165], v[202:205], v[84:87]
	v_mfma_f32_16x16x32_bf16 v[80:83], v[170:173], v[202:205], v[80:83]
	v_mfma_f32_16x16x32_bf16 v[132:135], v[166:169], v[182:185], v[132:135]
	v_mfma_f32_16x16x32_bf16 v[128:131], v[174:177], v[182:185], v[128:131]
	v_mfma_f32_16x16x32_bf16 v[116:119], v[166:169], v[190:193], v[116:119]
	v_mfma_f32_16x16x32_bf16 v[112:115], v[174:177], v[190:193], v[112:115]
	v_mfma_f32_16x16x32_bf16 v[100:103], v[166:169], v[198:201], v[100:103]
	v_mfma_f32_16x16x32_bf16 v[96:99], v[174:177], v[198:201], v[96:99]
	v_mfma_f32_16x16x32_bf16 v[84:87], v[166:169], v[214:217], v[84:87]
	v_mfma_f32_16x16x32_bf16 v[80:83], v[174:177], v[214:217], v[80:83]
	s_setprio 0
	s_barrier
	s_add_i32 s28, s51, s38
	v_lshl_add_u64 v[206:207], v[206:207], 0, s[2:3]
	s_mov_b32 m0, s28
	ds_read_b128 v[178:181], v161 offset:49152
	ds_read_b128 v[182:185], v161 offset:50176
	ds_read_b128 v[186:189], v161 offset:51200
	ds_read_b128 v[190:193], v161 offset:52224
	ds_read_b128 v[194:197], v161 offset:53248
	ds_read_b128 v[198:201], v161 offset:54272
	ds_read_b128 v[202:205], v161 offset:55296
	ds_read_b128 v[214:217], v161 offset:56320
	global_load_lds_dwordx4 v[206:207], off
	s_add_i32 m0, s28, 0x2000
	s_add_u32 s26, s26, 0x80080
	v_lshl_add_u64 v[206:207], v[210:211], 0, s[2:3]
	s_addc_u32 s27, s27, 0
	s_add_i32 s28, s52, s38
	global_load_lds_dwordx4 v[206:207], off
	v_lshl_add_u64 v[206:207], s[26:27], 0, v[208:209]
	s_mov_b32 m0, s28
	s_nop 0
	global_load_lds_dwordx4 v[206:207], off
	v_lshl_add_u64 v[206:207], s[26:27], 0, v[144:145]
	s_add_i32 m0, s28, 0x2000
	s_nop 0
	global_load_lds_dwordx4 v[206:207], off
	v_lshl_add_u64 v[206:207], v[218:219], 0, s[2:3]
	s_mov_b32 m0, s44
	s_nop 0
	global_load_lds_dwordx4 v[206:207], off
	v_lshl_add_u64 v[206:207], v[220:221], 0, s[2:3]
	s_mov_b32 m0, s45
	s_nop 0
	global_load_lds_dwordx4 v[206:207], off
	s_waitcnt vmcnt(8)
	s_waitcnt lgkmcnt(0)
	s_barrier
; #define PG8_MMA(ai, bj, At, Bt) do { __builtin_amdgcn_s_setprio(1); _Pragma("unroll") for (int m = 0; m < 4; ++m) _Pragma("unroll") for (int n = 0; n < 2; ++n) _Pragma("unroll") for (int k = 0; k < 2; ++k) \
;         acc[ai][bj][m][n] = __builtin_amdgcn_mfma_f32_16x16x32_bf16(Bt[n][k], At[m][k], acc[ai][bj][m][n], 0, 0, 0); __builtin_amdgcn_s_setprio(0); } while (0)
; #define PG8_WAIT_V(n) asm volatile("s_waitcnt vmcnt(" #n ")" ::: "memory")
; #define PG8_WAIT_L(n) asm volatile("s_waitcnt lgkmcnt(" #n ")" ::: "memory")
; #define PG8_BAR __builtin_amdgcn_s_barrier()
; #define PG8_SCHED __builtin_amdgcn_sched_barrier(0)
; template <class Epi, class Sched, bool ALIGN_EPI = false, bool SP2 = false>
; __device__ __forceinline__ void gemm_phase(PG8_LAS unsigned char* lds, const Gemm g, const Sched& S, const Epi& E, const int tid) {
;     ...
;             PG8_WAIT_V(8); PG8_WAIT_L(0); PG8_BAR; PG8_MMA(1, 0, At, B0); PG8_MMA(1, 1, At, B1); PG8_BAR; PG8_SCHED;
;     __device__ __forceinline__ void operator()(const f32x4 (&acc)[2][2][4][2], const Unit& un, int wr, int wc, int fr, int fq) const {
;         const int rbase = un.pm * 256 + wr * 64 + fr, cw = un.pn * 256 + wc * 32 + 8 * fq;
;         const int slot = un.pm < (NLAT / 256) ? (un.pm >> 5) : 4; const float* sw = shw + (size_t)slot * DFF;
;         f32x4 s0[2], s1[2]; float rr[2][4];
; #pragma unroll
;         for (int bj = 0; bj < 2; ++bj) { s0[bj] = *(const f32x4*)(sw + cw + bj * 128); s1[bj] = *(const f32x4*)(sw + cw + bj * 128 + 4); }
; #pragma unroll
;         for (int ai = 0; ai < 2; ++ai)
; #pragma unroll
;             for (int m = 0; m < 4; ++m) rr[ai][m] = rs[rbase + ai * 128 + m * 16];
	s_setprio 1
	s_waitcnt lgkmcnt(0)
	v_mfma_f32_16x16x32_bf16 v[76:79], v[56:59], v[178:181], v[76:79]
	v_mfma_f32_16x16x32_bf16 v[72:75], v[64:67], v[178:181], v[72:75]
	v_mfma_f32_16x16x32_bf16 v[44:47], v[56:59], v[186:189], v[44:47]
	v_mfma_f32_16x16x32_bf16 v[40:43], v[64:67], v[186:189], v[40:43]
	v_mfma_f32_16x16x32_bf16 v[28:31], v[56:59], v[194:197], v[28:31]
	v_mfma_f32_16x16x32_bf16 v[24:27], v[64:67], v[194:197], v[24:27]
	v_mfma_f32_16x16x32_bf16 v[12:15], v[56:59], v[202:205], v[12:15]
	v_mfma_f32_16x16x32_bf16 v[8:11], v[64:67], v[202:205], v[8:11]
	v_mfma_f32_16x16x32_bf16 v[76:79], v[60:63], v[182:185], v[76:79]
	v_mfma_f32_16x16x32_bf16 v[72:75], v[68:71], v[182:185], v[72:75]
	v_mfma_f32_16x16x32_bf16 v[44:47], v[60:63], v[190:193], v[44:47]
	v_mfma_f32_16x16x32_bf16 v[40:43], v[68:71], v[190:193], v[40:43]
	v_mfma_f32_16x16x32_bf16 v[28:31], v[60:63], v[198:201], v[28:31]
	v_mfma_f32_16x16x32_bf16 v[24:27], v[68:71], v[198:201], v[24:27]
	v_mfma_f32_16x16x32_bf16 v[12:15], v[60:63], v[214:217], v[12:15]
	v_mfma_f32_16x16x32_bf16 v[8:11], v[68:71], v[214:217], v[8:11]
	v_mfma_f32_16x16x32_bf16 v[48:51], v[162:165], v[178:181], v[48:51]
	v_mfma_f32_16x16x32_bf16 v[60:63], v[166:169], v[182:185], v[48:51]
	v_mfma_f32_16x16x32_bf16 v[48:51], v[170:173], v[178:181], v[52:55]
	v_mfma_f32_16x16x32_bf16 v[36:39], v[162:165], v[186:189], v[36:39]
	v_mfma_f32_16x16x32_bf16 v[32:35], v[170:173], v[186:189], v[32:35]
	v_mfma_f32_16x16x32_bf16 v[20:23], v[162:165], v[194:197], v[20:23]
	v_mfma_f32_16x16x32_bf16 v[16:19], v[170:173], v[194:197], v[16:19]
	v_mfma_f32_16x16x32_bf16 v[4:7], v[162:165], v[202:205], v[4:7]
	v_mfma_f32_16x16x32_bf16 v[0:3], v[170:173], v[202:205], v[0:3]
	v_mfma_f32_16x16x32_bf16 v[56:59], v[174:177], v[182:185], v[48:51]
	v_mfma_f32_16x16x32_bf16 v[36:39], v[166:169], v[190:193], v[36:39]
	v_mfma_f32_16x16x32_bf16 v[32:35], v[174:177], v[190:193], v[32:35]
	v_mfma_f32_16x16x32_bf16 v[20:23], v[166:169], v[198:201], v[20:23]
	v_mfma_f32_16x16x32_bf16 v[16:19], v[174:177], v[198:201], v[16:19]
	v_mfma_f32_16x16x32_bf16 v[4:7], v[166:169], v[214:217], v[4:7]
	v_mfma_f32_16x16x32_bf16 v[0:3], v[174:177], v[214:217], v[0:3]
	s_setprio 0
	s_barrier
	s_add_i32 s50, s50, 2
	s_add_u32 s24, s24, 0x100
	s_addc_u32 s25, s25, 0
	s_add_u32 s48, s48, 0x100
	s_addc_u32 s49, s49, 0
	s_cmp_gt_u32 s50, 29
	s_cbranch_scc0 .LBB0_1047
	s_ashr_i32 s24, s20, 5
	s_ashr_i32 s25, s24, 31
	s_lshl_b64 s[24:25], s[24:25], 13
	s_cmpk_lt_i32 s20, 0x80
	s_cselect_b32 s25, s25, 0
	s_cselect_b32 s24, s24, 0x8000
	s_lshl_b64 s[24:25], s[24:25], 2
	v_lshl_or_b32 v176, s22, 8, v159
	s_add_u32 s24, s42, s24
	v_lshl_add_u32 v178, s20, 8, v155
	s_addc_u32 s25, s43, s25
	v_ashrrev_i32_e32 v177, 31, v176
	v_ashrrev_i32_e32 v179, 31, v178
	v_lshl_add_u64 v[52:53], v[176:177], 2, s[24:25]
	v_lshl_add_u64 v[180:181], v[178:179], 2, s[6:7]
	global_load_dwordx4 v[64:67], v[52:53], off offset:16
	global_load_dwordx4 v[68:71], v[52:53], off
	global_load_dwordx4 v[48:51], v[52:53], off offset:528
	s_nop 0
	global_load_dwordx4 v[52:55], v[52:53], off offset:512
	v_or_b32_e32 v172, 16, v178
	global_load_dword v174, v[180:181], off
	v_ashrrev_i32_e32 v173, 31, v172
	v_lshl_add_u64 v[162:163], v[172:173], 2, s[6:7]
	global_load_dword v170, v[162:163], off
	v_or_b32_e32 v168, 32, v178
	v_ashrrev_i32_e32 v169, 31, v168
	v_lshl_add_u64 v[162:163], v[168:169], 2, s[6:7]
	global_load_dword v166, v[162:163], off
	v_or_b32_e32 v164, 48, v178
	v_lshlrev_b64 v[178:179], 14, v[178:179]
	v_ashrrev_i32_e32 v165, 31, v164
	v_lshl_add_u64 v[162:163], v[164:165], 2, s[6:7]
	global_load_dword v162, v[162:163], off
	s_nop 0
	global_load_dword v160, v[180:181], off offset:512
	global_load_dword v158, v[180:181], off offset:576
	global_load_dword v156, v[180:181], off offset:640
	global_load_dword v154, v[180:181], off offset:704
	s_and_b64 vcc, exec, s[8:9]
	s_cbranch_vccz .LBB0_1050
	s_barrier

; #define PG8_STAGE(bufoff, gbase, voff) do { _Pragma("unroll") for (int _i = 0; _i < 2; ++_i) \
;         __builtin_amdgcn_global_load_lds((const unsigned*)((const char*)(gbase) + (voff)[_i]), (PG8_LAS unsigned*)(lds + (bufoff) + ldsw + _i * 8192), 16, 0, 0); } while (0)
; #define PG8_LDA(dst, b, h) do { _Pragma("unroll") for (int m = 0; m < 4; ++m) _Pragma("unroll") for (int k = 0; k < 2; ++k) dst[m][k] = *(const PG8_LAS bf16x8*)(lds + PG8_SA(b, h) + aoff + m * 2048 + k * 1024); } while (0)
; #define PG8_LDB(dst, b, h) do { _Pragma("unroll") for (int n = 0; n < 2; ++n) _Pragma("unroll") for (int k = 0; k < 2; ++k) dst[n][k] = *(const PG8_LAS bf16x8*)(lds + PG8_SB(b, h) + boff + n * 2048 + k * 1024); } while (0)
; #define PG8_MMA(ai, bj, At, Bt) do { __builtin_amdgcn_s_setprio(1); _Pragma("unroll") for (int m = 0; m < 4; ++m) _Pragma("unroll") for (int n = 0; n < 2; ++n) _Pragma("unroll") for (int k = 0; k < 2; ++k) \
;         acc[ai][bj][m][n] = __builtin_amdgcn_mfma_f32_16x16x32_bf16(Bt[n][k], At[m][k], acc[ai][bj][m][n], 0, 0, 0); __builtin_amdgcn_s_setprio(0); } while (0)
; #define PG8_WAIT_V(n) asm volatile("s_waitcnt vmcnt(" #n ")" ::: "memory")
; #define PG8_WAIT_L(n) asm volatile("s_waitcnt lgkmcnt(" #n ")" ::: "memory")
; #define PG8_BAR __builtin_amdgcn_s_barrier()
; #define PG8_SCHED __builtin_amdgcn_sched_barrier(0)
; template <class Epi, class Sched, bool ALIGN_EPI = false, bool SP2 = false>
; __device__ __forceinline__ void gemm_phase(PG8_LAS unsigned char* lds, const Gemm g, const Sched& S, const Epi& E, const int tid) {
;     ...
;             PG8_LDB(B0, 0, 0); PG8_LDB(B1, 0, 1); PG8_SCHED; PG8_LDA(At, 0, 0); PG8_STAGE(PG8_SA(1, 1), a1 + hstep, voffA);
;             PG8_WAIT_V(8); PG8_WAIT_L(0); PG8_BAR; PG8_MMA(0, 0, At, B0); PG8_MMA(0, 1, At, B1); PG8_BAR; PG8_SCHED;
;             PG8_LDA(At, 0, 1); PG8_STAGE(PG8_SB(0, 0), b2, voffB); PG8_STAGE(PG8_SB(0, 1), b2 + hstep, voffB); PG8_STAGE(PG8_SA(0, 0), a2, voffA);
;             PG8_WAIT_V(8); PG8_WAIT_L(0); PG8_BAR; PG8_MMA(1, 0, At, B0); PG8_MMA(1, 1, At, B1); PG8_BAR; PG8_SCHED;
.Lmy_nobar_1128:
	s_add_u32 s24, s4, 0xfffe0080
	s_addc_u32 s25, s5, -1
	s_add_i32 s50, 0, 0x10000
	v_add_u32_e32 v140, s50, v211
	v_add_u32_e32 v156, s33, v211
	ds_read_b128 v[128:131], v140
	ds_read_b128 v[132:135], v140 offset:1024
	ds_read_b128 v[136:139], v140 offset:2048
	ds_read_b128 v[140:143], v140 offset:3072
	ds_read_b128 v[144:147], v156
	ds_read_b128 v[148:151], v156 offset:1024
	ds_read_b128 v[152:155], v156 offset:2048
	ds_read_b128 v[156:159], v156 offset:3072
	s_cmp_eq_u32 s49, 4
	s_cselect_b32 s27, s17, s25
	s_cselect_b32 s26, s16, s24
	s_cselect_b32 s25, s13, s23
	s_cselect_b32 s24, s15, s21
	v_lshl_add_u64 v[192:193], s[4:5], 0, v[200:201]
	s_add_i32 m0, s37, 0xc000
	ds_read_b128 v[160:163], v225
	ds_read_b128 v[164:167], v225 offset:1024
	ds_read_b128 v[168:171], v225 offset:2048
	ds_read_b128 v[172:175], v225 offset:3072
	ds_read_b128 v[176:179], v225 offset:4096
	ds_read_b128 v[180:183], v225 offset:5120
	ds_read_b128 v[184:187], v225 offset:6144
	ds_read_b128 v[188:191], v225 offset:7168
	global_load_lds_dwordx4 v[192:193], off
	v_lshl_add_u64 v[192:193], s[4:5], 0, v[202:203]
	s_add_i32 m0, s37, 0xe000
	s_nop 0
	global_load_lds_dwordx4 v[192:193], off
	s_waitcnt vmcnt(8)
	s_waitcnt lgkmcnt(0)
	s_barrier
	s_setprio 1
	s_waitcnt lgkmcnt(0)
	v_mfma_f32_16x16x32_bf16 v[124:127], v[128:131], v[160:163], 0
	v_mfma_f32_16x16x32_bf16 v[120:123], v[136:139], v[160:163], 0
	v_mfma_f32_16x16x32_bf16 v[108:111], v[128:131], v[168:171], 0
	v_mfma_f32_16x16x32_bf16 v[104:107], v[136:139], v[168:171], 0
	v_mfma_f32_16x16x32_bf16 v[100:103], v[128:131], v[176:179], 0
	v_mfma_f32_16x16x32_bf16 v[96:99], v[136:139], v[176:179], 0
	v_mfma_f32_16x16x32_bf16 v[92:95], v[128:131], v[184:187], 0
	v_mfma_f32_16x16x32_bf16 v[88:91], v[136:139], v[184:187], 0
	v_mfma_f32_16x16x32_bf16 v[124:127], v[132:135], v[164:167], v[124:127]
	v_mfma_f32_16x16x32_bf16 v[120:123], v[140:143], v[164:167], v[120:123]
	v_mfma_f32_16x16x32_bf16 v[108:111], v[132:135], v[172:175], v[108:111]
	v_mfma_f32_16x16x32_bf16 v[104:107], v[140:143], v[172:175], v[104:107]
	v_mfma_f32_16x16x32_bf16 v[100:103], v[132:135], v[180:183], v[100:103]
	v_mfma_f32_16x16x32_bf16 v[96:99], v[140:143], v[180:183], v[96:99]
	v_mfma_f32_16x16x32_bf16 v[92:95], v[132:135], v[188:191], v[92:95]
	v_mfma_f32_16x16x32_bf16 v[88:91], v[140:143], v[188:191], v[88:91]
	v_mfma_f32_16x16x32_bf16 v[116:119], v[144:147], v[160:163], 0
	v_mfma_f32_16x16x32_bf16 v[112:115], v[152:155], v[160:163], 0
	v_mfma_f32_16x16x32_bf16 v[84:87], v[144:147], v[168:171], 0
	v_mfma_f32_16x16x32_bf16 v[80:83], v[152:155], v[168:171], 0
	v_mfma_f32_16x16x32_bf16 v[76:79], v[144:147], v[176:179], 0
	v_mfma_f32_16x16x32_bf16 v[72:75], v[152:155], v[176:179], 0
	v_mfma_f32_16x16x32_bf16 v[68:71], v[144:147], v[184:187], 0
	v_mfma_f32_16x16x32_bf16 v[64:67], v[152:155], v[184:187], 0
	v_mfma_f32_16x16x32_bf16 v[116:119], v[148:151], v[164:167], v[116:119]
	v_mfma_f32_16x16x32_bf16 v[112:115], v[156:159], v[164:167], v[112:115]
	v_mfma_f32_16x16x32_bf16 v[84:87], v[148:151], v[172:175], v[84:87]
	v_mfma_f32_16x16x32_bf16 v[80:83], v[156:159], v[172:175], v[80:83]
	v_mfma_f32_16x16x32_bf16 v[76:79], v[148:151], v[180:183], v[76:79]
	v_mfma_f32_16x16x32_bf16 v[72:75], v[156:159], v[180:183], v[72:75]
	v_mfma_f32_16x16x32_bf16 v[68:71], v[148:151], v[188:191], v[68:71]
	v_mfma_f32_16x16x32_bf16 v[64:67], v[156:159], v[188:191], v[64:67]
	s_setprio 0
	s_barrier
	s_add_i32 s50, s50, s36
	v_lshl_add_u64 v[192:193], s[24:25], 0, v[208:209]
	s_mov_b32 m0, s50
	ds_read_b128 v[160:163], v225 offset:16384
	ds_read_b128 v[164:167], v225 offset:17408
	ds_read_b128 v[168:171], v225 offset:18432
	ds_read_b128 v[172:175], v225 offset:19456
	ds_read_b128 v[176:179], v225 offset:20480
	ds_read_b128 v[180:183], v225 offset:21504
	ds_read_b128 v[184:187], v225 offset:22528
	ds_read_b128 v[188:191], v225 offset:23552
	global_load_lds_dwordx4 v[192:193], off
	s_add_i32 m0, s50, 0x2000
	s_add_u32 s50, s24, 0x20000
	v_lshl_add_u64 v[204:205], s[24:25], 0, v[198:199]
	s_addc_u32 s51, s25, 0
	s_add_i32 s52, s33, s36
	global_load_lds_dwordx4 v[204:205], off
	v_lshl_add_u64 v[206:207], s[50:51], 0, v[208:209]
	s_mov_b32 m0, s52
	v_lshl_add_u64 v[214:215], s[26:27], 0, v[196:197]
	global_load_lds_dwordx4 v[206:207], off
	v_lshl_add_u64 v[206:207], s[50:51], 0, v[198:199]
	s_add_i32 m0, s52, 0x2000
	s_nop 0
	global_load_lds_dwordx4 v[206:207], off
	v_lshl_add_u64 v[206:207], s[26:27], 0, v[194:195]
	s_mov_b32 m0, s37
	s_nop 0
	global_load_lds_dwordx4 v[206:207], off
	s_mov_b32 m0, s38
	s_nop 0
	global_load_lds_dwordx4 v[214:215], off
	s_waitcnt vmcnt(8)
	s_waitcnt lgkmcnt(0)
	s_barrier
	s_setprio 1
	s_waitcnt lgkmcnt(0)
	v_mfma_f32_16x16x32_bf16 v[60:63], v[128:131], v[160:163], 0
	v_mfma_f32_16x16x32_bf16 v[56:59], v[136:139], v[160:163], 0
	v_mfma_f32_16x16x32_bf16 v[44:47], v[128:131], v[168:171], 0
	v_mfma_f32_16x16x32_bf16 v[40:43], v[136:139], v[168:171], 0
	v_mfma_f32_16x16x32_bf16 v[28:31], v[128:131], v[176:179], 0
	v_mfma_f32_16x16x32_bf16 v[24:27], v[136:139], v[176:179], 0
	v_mfma_f32_16x16x32_bf16 v[12:15], v[128:131], v[184:187], 0
	v_mfma_f32_16x16x32_bf16 v[8:11], v[136:139], v[184:187], 0
	v_mfma_f32_16x16x32_bf16 v[60:63], v[132:135], v[164:167], v[60:63]
	v_mfma_f32_16x16x32_bf16 v[56:59], v[140:143], v[164:167], v[56:59]
	v_mfma_f32_16x16x32_bf16 v[44:47], v[132:135], v[172:175], v[44:47]
	v_mfma_f32_16x16x32_bf16 v[40:43], v[140:143], v[172:175], v[40:43]
	v_mfma_f32_16x16x32_bf16 v[28:31], v[132:135], v[180:183], v[28:31]
	v_mfma_f32_16x16x32_bf16 v[24:27], v[140:143], v[180:183], v[24:27]
	v_mfma_f32_16x16x32_bf16 v[12:15], v[132:135], v[188:191], v[12:15]
	v_mfma_f32_16x16x32_bf16 v[8:11], v[140:143], v[188:191], v[8:11]
	v_mfma_f32_16x16x32_bf16 v[52:55], v[144:147], v[160:163], 0
	v_mfma_f32_16x16x32_bf16 v[48:51], v[152:155], v[160:163], 0
	v_mfma_f32_16x16x32_bf16 v[36:39], v[144:147], v[168:171], 0
	v_mfma_f32_16x16x32_bf16 v[32:35], v[152:155], v[168:171], 0
	v_mfma_f32_16x16x32_bf16 v[20:23], v[144:147], v[176:179], 0
	v_mfma_f32_16x16x32_bf16 v[16:19], v[152:155], v[176:179], 0
	v_mfma_f32_16x16x32_bf16 v[4:7], v[144:147], v[184:187], 0
	v_mfma_f32_16x16x32_bf16 v[0:3], v[152:155], v[184:187], 0
	v_mfma_f32_16x16x32_bf16 v[52:55], v[148:151], v[164:167], v[52:55]
	v_mfma_f32_16x16x32_bf16 v[48:51], v[156:159], v[164:167], v[48:51]
	v_mfma_f32_16x16x32_bf16 v[36:39], v[148:151], v[172:175], v[36:39]
	v_mfma_f32_16x16x32_bf16 v[32:35], v[156:159], v[172:175], v[32:35]
	v_mfma_f32_16x16x32_bf16 v[20:23], v[148:151], v[180:183], v[20:23]
	v_mfma_f32_16x16x32_bf16 v[16:19], v[156:159], v[180:183], v[16:19]
	v_mfma_f32_16x16x32_bf16 v[4:7], v[148:151], v[188:191], v[4:7]
	v_mfma_f32_16x16x32_bf16 v[0:3], v[156:159], v[188:191], v[0:3]
	s_setprio 0
	s_barrier
	s_branch .Lmy_mid_1128
; #define PG8_STAGE(bufoff, gbase, voff) do { _Pragma("unroll") for (int _i = 0; _i < 2; ++_i) \
;         __builtin_amdgcn_global_load_lds((const unsigned*)((const char*)(gbase) + (voff)[_i]), (PG8_LAS unsigned*)(lds + (bufoff) + ldsw + _i * 8192), 16, 0, 0); } while (0)
; #define PG8_LDA(dst, b, h) do { _Pragma("unroll") for (int m = 0; m < 4; ++m) _Pragma("unroll") for (int k = 0; k < 2; ++k) dst[m][k] = *(const PG8_LAS bf16x8*)(lds + PG8_SA(b, h) + aoff + m * 2048 + k * 1024); } while (0)
; #define PG8_LDB(dst, b, h) do { _Pragma("unroll") for (int n = 0; n < 2; ++n) _Pragma("unroll") for (int k = 0; k < 2; ++k) dst[n][k] = *(const PG8_LAS bf16x8*)(lds + PG8_SB(b, h) + boff + n * 2048 + k * 1024); } while (0)
; #define PG8_MMA(ai, bj, At, Bt) do { __builtin_amdgcn_s_setprio(1); _Pragma("unroll") for (int m = 0; m < 4; ++m) _Pragma("unroll") for (int n = 0; n < 2; ++n) _Pragma("unroll") for (int k = 0; k < 2; ++k) \
;         acc[ai][bj][m][n] = __builtin_amdgcn_mfma_f32_16x16x32_bf16(Bt[n][k], At[m][k], acc[ai][bj][m][n], 0, 0, 0); __builtin_amdgcn_s_setprio(0); } while (0)
; #define PG8_WAIT_V(n) asm volatile("s_waitcnt vmcnt(" #n ")" ::: "memory")
; #define PG8_WAIT_L(n) asm volatile("s_waitcnt lgkmcnt(" #n ")" ::: "memory")
; #define PG8_BAR __builtin_amdgcn_s_barrier()
; #define PG8_SCHED __builtin_amdgcn_sched_barrier(0)
; template <class Epi, class Sched, bool ALIGN_EPI = false, bool SP2 = false>
; __device__ __forceinline__ void gemm_phase(PG8_LAS unsigned char* lds, const Gemm g, const Sched& S, const Epi& E, const int tid) {
;     ...
;             PG8_LDB(B0, 0, 0); PG8_LDB(B1, 0, 1); PG8_SCHED; PG8_LDA(At, 0, 0); PG8_STAGE(PG8_SA(1, 1), a1 + hstep, voffA);
;             PG8_WAIT_V(8); PG8_WAIT_L(0); PG8_BAR; PG8_MMA(0, 0, At, B0); PG8_MMA(0, 1, At, B1); PG8_BAR; PG8_SCHED;
;             PG8_LDA(At, 0, 1); PG8_STAGE(PG8_SB(0, 0), b2, voffB); PG8_STAGE(PG8_SB(0, 1), b2 + hstep, voffB); PG8_STAGE(PG8_SA(0, 0), a2, voffA);
;             PG8_WAIT_V(8); PG8_WAIT_L(0); PG8_BAR; PG8_MMA(1, 0, At, B0); PG8_MMA(1, 1, At, B1); PG8_BAR; PG8_SCHED;
.LBB0_1128:
	s_add_u32 s24, s4, 0xfffe0080
	s_addc_u32 s25, s5, -1
	s_add_i32 s50, 0, 0x10000
	v_add_u32_e32 v140, s50, v211
	v_add_u32_e32 v156, s33, v211
	ds_read_b128 v[128:131], v140
	ds_read_b128 v[132:135], v140 offset:1024
	ds_read_b128 v[136:139], v140 offset:2048
	ds_read_b128 v[140:143], v140 offset:3072
	ds_read_b128 v[144:147], v156
	ds_read_b128 v[148:151], v156 offset:1024
	ds_read_b128 v[152:155], v156 offset:2048
	ds_read_b128 v[156:159], v156 offset:3072
	s_cmp_eq_u32 s49, 4
	s_cselect_b32 s27, s17, s25
	s_cselect_b32 s26, s16, s24
	s_cselect_b32 s25, s13, s23
	s_cselect_b32 s24, s15, s21
	v_lshl_add_u64 v[192:193], s[4:5], 0, v[200:201]
	s_add_i32 m0, s37, 0xc000
	ds_read_b128 v[160:163], v225
	ds_read_b128 v[164:167], v225 offset:1024
	ds_read_b128 v[168:171], v225 offset:2048
	ds_read_b128 v[172:175], v225 offset:3072
	ds_read_b128 v[176:179], v225 offset:4096
	ds_read_b128 v[180:183], v225 offset:5120
	ds_read_b128 v[184:187], v225 offset:6144
	ds_read_b128 v[188:191], v225 offset:7168
	global_load_lds_dwordx4 v[192:193], off
	v_lshl_add_u64 v[192:193], s[4:5], 0, v[202:203]
	s_add_i32 m0, s37, 0xe000
	s_nop 0
	global_load_lds_dwordx4 v[192:193], off
	s_waitcnt vmcnt(8)
	s_waitcnt lgkmcnt(0)
	s_barrier
	s_setprio 1
	s_waitcnt lgkmcnt(0)
	v_mfma_f32_16x16x32_bf16 v[124:127], v[128:131], v[160:163], v[124:127]
	v_mfma_f32_16x16x32_bf16 v[120:123], v[136:139], v[160:163], v[120:123]
	v_mfma_f32_16x16x32_bf16 v[108:111], v[128:131], v[168:171], v[108:111]
	v_mfma_f32_16x16x32_bf16 v[104:107], v[136:139], v[168:171], v[104:107]
	v_mfma_f32_16x16x32_bf16 v[100:103], v[128:131], v[176:179], v[100:103]
	v_mfma_f32_16x16x32_bf16 v[96:99], v[136:139], v[176:179], v[96:99]
	v_mfma_f32_16x16x32_bf16 v[92:95], v[128:131], v[184:187], v[92:95]
	v_mfma_f32_16x16x32_bf16 v[88:91], v[136:139], v[184:187], v[88:91]
	v_mfma_f32_16x16x32_bf16 v[124:127], v[132:135], v[164:167], v[124:127]
	v_mfma_f32_16x16x32_bf16 v[120:123], v[140:143], v[164:167], v[120:123]
	v_mfma_f32_16x16x32_bf16 v[108:111], v[132:135], v[172:175], v[108:111]
	v_mfma_f32_16x16x32_bf16 v[104:107], v[140:143], v[172:175], v[104:107]
	v_mfma_f32_16x16x32_bf16 v[100:103], v[132:135], v[180:183], v[100:103]
	v_mfma_f32_16x16x32_bf16 v[96:99], v[140:143], v[180:183], v[96:99]
	v_mfma_f32_16x16x32_bf16 v[92:95], v[132:135], v[188:191], v[92:95]
	v_mfma_f32_16x16x32_bf16 v[88:91], v[140:143], v[188:191], v[88:91]
	v_mfma_f32_16x16x32_bf16 v[116:119], v[144:147], v[160:163], v[116:119]
	v_mfma_f32_16x16x32_bf16 v[112:115], v[152:155], v[160:163], v[112:115]
	v_mfma_f32_16x16x32_bf16 v[84:87], v[144:147], v[168:171], v[84:87]
	v_mfma_f32_16x16x32_bf16 v[80:83], v[152:155], v[168:171], v[80:83]
	v_mfma_f32_16x16x32_bf16 v[76:79], v[144:147], v[176:179], v[76:79]
	v_mfma_f32_16x16x32_bf16 v[72:75], v[152:155], v[176:179], v[72:75]
	v_mfma_f32_16x16x32_bf16 v[68:71], v[144:147], v[184:187], v[68:71]
	v_mfma_f32_16x16x32_bf16 v[64:67], v[152:155], v[184:187], v[64:67]
	v_mfma_f32_16x16x32_bf16 v[116:119], v[148:151], v[164:167], v[116:119]
	v_mfma_f32_16x16x32_bf16 v[112:115], v[156:159], v[164:167], v[112:115]
	v_mfma_f32_16x16x32_bf16 v[84:87], v[148:151], v[172:175], v[84:87]
	v_mfma_f32_16x16x32_bf16 v[80:83], v[156:159], v[172:175], v[80:83]
	v_mfma_f32_16x16x32_bf16 v[76:79], v[148:151], v[180:183], v[76:79]
	v_mfma_f32_16x16x32_bf16 v[72:75], v[156:159], v[180:183], v[72:75]
	v_mfma_f32_16x16x32_bf16 v[68:71], v[148:151], v[188:191], v[68:71]
	v_mfma_f32_16x16x32_bf16 v[64:67], v[156:159], v[188:191], v[64:67]
	s_setprio 0
	s_barrier
	s_add_i32 s50, s50, s36
	v_lshl_add_u64 v[192:193], s[24:25], 0, v[208:209]
	s_mov_b32 m0, s50
	ds_read_b128 v[160:163], v225 offset:16384
	ds_read_b128 v[164:167], v225 offset:17408
	ds_read_b128 v[168:171], v225 offset:18432
	ds_read_b128 v[172:175], v225 offset:19456
	ds_read_b128 v[176:179], v225 offset:20480
	ds_read_b128 v[180:183], v225 offset:21504
	ds_read_b128 v[184:187], v225 offset:22528
	ds_read_b128 v[188:191], v225 offset:23552
	global_load_lds_dwordx4 v[192:193], off
	s_add_i32 m0, s50, 0x2000
	s_add_u32 s50, s24, 0x20000
	v_lshl_add_u64 v[204:205], s[24:25], 0, v[198:199]
	s_addc_u32 s51, s25, 0
	s_add_i32 s52, s33, s36
	global_load_lds_dwordx4 v[204:205], off
	v_lshl_add_u64 v[206:207], s[50:51], 0, v[208:209]
	s_mov_b32 m0, s52
	v_lshl_add_u64 v[214:215], s[26:27], 0, v[196:197]
	global_load_lds_dwordx4 v[206:207], off
	v_lshl_add_u64 v[206:207], s[50:51], 0, v[198:199]
	s_add_i32 m0, s52, 0x2000
	s_nop 0
	global_load_lds_dwordx4 v[206:207], off
	v_lshl_add_u64 v[206:207], s[26:27], 0, v[194:195]
	s_mov_b32 m0, s37
	s_nop 0
	global_load_lds_dwordx4 v[206:207], off
	s_mov_b32 m0, s38
	s_nop 0
	global_load_lds_dwordx4 v[214:215], off
	s_waitcnt vmcnt(8)
	s_waitcnt lgkmcnt(0)
	s_barrier
	s_setprio 1
	s_waitcnt lgkmcnt(0)
	v_mfma_f32_16x16x32_bf16 v[60:63], v[128:131], v[160:163], v[60:63]
	v_mfma_f32_16x16x32_bf16 v[56:59], v[136:139], v[160:163], v[56:59]
	v_mfma_f32_16x16x32_bf16 v[44:47], v[128:131], v[168:171], v[44:47]
	v_mfma_f32_16x16x32_bf16 v[40:43], v[136:139], v[168:171], v[40:43]
	v_mfma_f32_16x16x32_bf16 v[28:31], v[128:131], v[176:179], v[28:31]
	v_mfma_f32_16x16x32_bf16 v[24:27], v[136:139], v[176:179], v[24:27]
	v_mfma_f32_16x16x32_bf16 v[12:15], v[128:131], v[184:187], v[12:15]
	v_mfma_f32_16x16x32_bf16 v[8:11], v[136:139], v[184:187], v[8:11]
	v_mfma_f32_16x16x32_bf16 v[60:63], v[132:135], v[164:167], v[60:63]
	v_mfma_f32_16x16x32_bf16 v[56:59], v[140:143], v[164:167], v[56:59]
	v_mfma_f32_16x16x32_bf16 v[44:47], v[132:135], v[172:175], v[44:47]
	v_mfma_f32_16x16x32_bf16 v[40:43], v[140:143], v[172:175], v[40:43]
	v_mfma_f32_16x16x32_bf16 v[28:31], v[132:135], v[180:183], v[28:31]
	v_mfma_f32_16x16x32_bf16 v[24:27], v[140:143], v[180:183], v[24:27]
	v_mfma_f32_16x16x32_bf16 v[12:15], v[132:135], v[188:191], v[12:15]
	v_mfma_f32_16x16x32_bf16 v[8:11], v[140:143], v[188:191], v[8:11]
	v_mfma_f32_16x16x32_bf16 v[52:55], v[144:147], v[160:163], v[52:55]
	v_mfma_f32_16x16x32_bf16 v[48:51], v[152:155], v[160:163], v[48:51]
	v_mfma_f32_16x16x32_bf16 v[36:39], v[144:147], v[168:171], v[36:39]
	v_mfma_f32_16x16x32_bf16 v[32:35], v[152:155], v[168:171], v[32:35]
	v_mfma_f32_16x16x32_bf16 v[20:23], v[144:147], v[176:179], v[20:23]
	v_mfma_f32_16x16x32_bf16 v[16:19], v[152:155], v[176:179], v[16:19]
	v_mfma_f32_16x16x32_bf16 v[4:7], v[144:147], v[184:187], v[4:7]
	v_mfma_f32_16x16x32_bf16 v[0:3], v[152:155], v[184:187], v[0:3]
	v_mfma_f32_16x16x32_bf16 v[52:55], v[148:151], v[164:167], v[52:55]
	v_mfma_f32_16x16x32_bf16 v[48:51], v[156:159], v[164:167], v[48:51]
	v_mfma_f32_16x16x32_bf16 v[36:39], v[148:151], v[172:175], v[36:39]
	v_mfma_f32_16x16x32_bf16 v[32:35], v[156:159], v[172:175], v[32:35]
	v_mfma_f32_16x16x32_bf16 v[20:23], v[148:151], v[180:183], v[20:23]
	v_mfma_f32_16x16x32_bf16 v[16:19], v[156:159], v[180:183], v[16:19]
	v_mfma_f32_16x16x32_bf16 v[4:7], v[148:151], v[188:191], v[4:7]
	v_mfma_f32_16x16x32_bf16 v[0:3], v[156:159], v[188:191], v[0:3]
	s_setprio 0
	s_barrier
; #define PG8_STAGE(bufoff, gbase, voff) do { _Pragma("unroll") for (int _i = 0; _i < 2; ++_i) \
;         __builtin_amdgcn_global_load_lds((const unsigned*)((const char*)(gbase) + (voff)[_i]), (PG8_LAS unsigned*)(lds + (bufoff) + ldsw + _i * 8192), 16, 0, 0); } while (0)
; #define PG8_LDA(dst, b, h) do { _Pragma("unroll") for (int m = 0; m < 4; ++m) _Pragma("unroll") for (int k = 0; k < 2; ++k) dst[m][k] = *(const PG8_LAS bf16x8*)(lds + PG8_SA(b, h) + aoff + m * 2048 + k * 1024); } while (0)
; #define PG8_LDB(dst, b, h) do { _Pragma("unroll") for (int n = 0; n < 2; ++n) _Pragma("unroll") for (int k = 0; k < 2; ++k) dst[n][k] = *(const PG8_LAS bf16x8*)(lds + PG8_SB(b, h) + boff + n * 2048 + k * 1024); } while (0)
; #define PG8_MMA(ai, bj, At, Bt) do { __builtin_amdgcn_s_setprio(1); _Pragma("unroll") for (int m = 0; m < 4; ++m) _Pragma("unroll") for (int n = 0; n < 2; ++n) _Pragma("unroll") for (int k = 0; k < 2; ++k) \
;         acc[ai][bj][m][n] = __builtin_amdgcn_mfma_f32_16x16x32_bf16(Bt[n][k], At[m][k], acc[ai][bj][m][n], 0, 0, 0); __builtin_amdgcn_s_setprio(0); } while (0)
; #define PG8_WAIT_V(n) asm volatile("s_waitcnt vmcnt(" #n ")" ::: "memory")
; #define PG8_WAIT_L(n) asm volatile("s_waitcnt lgkmcnt(" #n ")" ::: "memory")
; #define PG8_BAR __builtin_amdgcn_s_barrier()
; #define PG8_SCHED __builtin_amdgcn_sched_barrier(0)
; template <class Epi, class Sched, bool ALIGN_EPI = false, bool SP2 = false>
; __device__ __forceinline__ void gemm_phase(PG8_LAS unsigned char* lds, const Gemm g, const Sched& S, const Epi& E, const int tid) {
;     ...
;             PG8_LDB(B0, 1, 0); PG8_LDB(B1, 1, 1); PG8_SCHED; PG8_LDA(At, 1, 0); PG8_STAGE(PG8_SA(0, 1), a2 + hstep, voffA);
;             PG8_WAIT_V(8); PG8_WAIT_L(0); PG8_BAR; PG8_MMA(0, 0, At, B0); PG8_MMA(0, 1, At, B1); PG8_BAR; PG8_SCHED;
.Lmy_mid_1128:
	s_add_i32 s50, 0, 0x18000
	s_add_i32 s51, 0, 0x1c000
	v_add_u32_e32 v140, s50, v211
	v_add_u32_e32 v156, s51, v211
	ds_read_b128 v[128:131], v140
	ds_read_b128 v[132:135], v140 offset:1024
	ds_read_b128 v[136:139], v140 offset:2048
	ds_read_b128 v[140:143], v140 offset:3072
	ds_read_b128 v[144:147], v156
	ds_read_b128 v[148:151], v156 offset:1024
	ds_read_b128 v[152:155], v156 offset:2048
	ds_read_b128 v[156:159], v156 offset:3072
	s_add_u32 s26, s26, 0x20000
	s_addc_u32 s27, s27, 0
	s_mov_b32 m0, s39
	v_lshl_add_u64 v[216:217], s[26:27], 0, v[194:195]
	ds_read_b128 v[160:163], v225 offset:32768
	ds_read_b128 v[164:167], v225 offset:33792
	ds_read_b128 v[168:171], v225 offset:34816
	ds_read_b128 v[172:175], v225 offset:35840
	ds_read_b128 v[176:179], v225 offset:36864
	ds_read_b128 v[180:183], v225 offset:37888
	ds_read_b128 v[184:187], v225 offset:38912
	ds_read_b128 v[188:191], v225 offset:39936
	global_load_lds_dwordx4 v[216:217], off
	v_lshl_add_u64 v[216:217], s[26:27], 0, v[196:197]
	s_mov_b32 m0, s40
	s_nop 0
	global_load_lds_dwordx4 v[216:217], off
	s_waitcnt vmcnt(8)
	s_waitcnt lgkmcnt(0)
	s_barrier
	s_setprio 1
	s_waitcnt lgkmcnt(0)
	v_mfma_f32_16x16x32_bf16 v[124:127], v[128:131], v[160:163], v[124:127]
	v_mfma_f32_16x16x32_bf16 v[120:123], v[136:139], v[160:163], v[120:123]
	v_mfma_f32_16x16x32_bf16 v[108:111], v[128:131], v[168:171], v[108:111]
	v_mfma_f32_16x16x32_bf16 v[104:107], v[136:139], v[168:171], v[104:107]
	v_mfma_f32_16x16x32_bf16 v[100:103], v[128:131], v[176:179], v[100:103]
	v_mfma_f32_16x16x32_bf16 v[96:99], v[136:139], v[176:179], v[96:99]
	v_mfma_f32_16x16x32_bf16 v[92:95], v[128:131], v[184:187], v[92:95]
	v_mfma_f32_16x16x32_bf16 v[88:91], v[136:139], v[184:187], v[88:91]
	v_mfma_f32_16x16x32_bf16 v[124:127], v[132:135], v[164:167], v[124:127]
	v_mfma_f32_16x16x32_bf16 v[120:123], v[140:143], v[164:167], v[120:123]
	v_mfma_f32_16x16x32_bf16 v[108:111], v[132:135], v[172:175], v[108:111]
	v_mfma_f32_16x16x32_bf16 v[104:107], v[140:143], v[172:175], v[104:107]
	v_mfma_f32_16x16x32_bf16 v[100:103], v[132:135], v[180:183], v[100:103]
	v_mfma_f32_16x16x32_bf16 v[96:99], v[140:143], v[180:183], v[96:99]
	v_mfma_f32_16x16x32_bf16 v[92:95], v[132:135], v[188:191], v[92:95]
	v_mfma_f32_16x16x32_bf16 v[88:91], v[140:143], v[188:191], v[88:91]
	v_mfma_f32_16x16x32_bf16 v[116:119], v[144:147], v[160:163], v[116:119]
	v_mfma_f32_16x16x32_bf16 v[112:115], v[152:155], v[160:163], v[112:115]
	v_mfma_f32_16x16x32_bf16 v[84:87], v[144:147], v[168:171], v[84:87]
	v_mfma_f32_16x16x32_bf16 v[80:83], v[152:155], v[168:171], v[80:83]
	v_mfma_f32_16x16x32_bf16 v[76:79], v[144:147], v[176:179], v[76:79]
	v_mfma_f32_16x16x32_bf16 v[72:75], v[152:155], v[176:179], v[72:75]
	v_mfma_f32_16x16x32_bf16 v[68:71], v[144:147], v[184:187], v[68:71]
	v_mfma_f32_16x16x32_bf16 v[64:67], v[152:155], v[184:187], v[64:67]
	v_mfma_f32_16x16x32_bf16 v[116:119], v[148:151], v[164:167], v[116:119]
	v_mfma_f32_16x16x32_bf16 v[112:115], v[156:159], v[164:167], v[112:115]
	v_mfma_f32_16x16x32_bf16 v[84:87], v[148:151], v[172:175], v[84:87]
	v_mfma_f32_16x16x32_bf16 v[80:83], v[156:159], v[172:175], v[80:83]
	v_mfma_f32_16x16x32_bf16 v[76:79], v[148:151], v[180:183], v[76:79]
	v_mfma_f32_16x16x32_bf16 v[72:75], v[156:159], v[180:183], v[72:75]
	v_mfma_f32_16x16x32_bf16 v[68:71], v[148:151], v[188:191], v[68:71]
	v_mfma_f32_16x16x32_bf16 v[64:67], v[156:159], v[188:191], v[64:67]
	s_setprio 0
	s_barrier
; #define PG8_STAGE(bufoff, gbase, voff) do { _Pragma("unroll") for (int _i = 0; _i < 2; ++_i) \
;         __builtin_amdgcn_global_load_lds((const unsigned*)((const char*)(gbase) + (voff)[_i]), (PG8_LAS unsigned*)(lds + (bufoff) + ldsw + _i * 8192), 16, 0, 0); } while (0)
; #define PG8_LDA(dst, b, h) do { _Pragma("unroll") for (int m = 0; m < 4; ++m) _Pragma("unroll") for (int k = 0; k < 2; ++k) dst[m][k] = *(const PG8_LAS bf16x8*)(lds + PG8_SA(b, h) + aoff + m * 2048 + k * 1024); } while (0)
; #define PG8_MMA(ai, bj, At, Bt) do { __builtin_amdgcn_s_setprio(1); _Pragma("unroll") for (int m = 0; m < 4; ++m) _Pragma("unroll") for (int n = 0; n < 2; ++n) _Pragma("unroll") for (int k = 0; k < 2; ++k) \
;         acc[ai][bj][m][n] = __builtin_amdgcn_mfma_f32_16x16x32_bf16(Bt[n][k], At[m][k], acc[ai][bj][m][n], 0, 0, 0); __builtin_amdgcn_s_setprio(0); } while (0)
; #define PG8_WAIT_V(n) asm volatile("s_waitcnt vmcnt(" #n ")" ::: "memory")
; #define PG8_WAIT_L(n) asm volatile("s_waitcnt lgkmcnt(" #n ")" ::: "memory")
; #define PG8_BAR __builtin_amdgcn_s_barrier()
; #define PG8_SCHED __builtin_amdgcn_sched_barrier(0)
; template <class Epi, class Sched, bool ALIGN_EPI = false, bool SP2 = false>
; __device__ __forceinline__ void gemm_phase(PG8_LAS unsigned char* lds, const Gemm g, const Sched& S, const Epi& E, const int tid) {
;     ...
;             PG8_LDA(At, 1, 1); PG8_STAGE(PG8_SB(1, 0), b3, voffB); PG8_STAGE(PG8_SB(1, 1), b3 + hstep, voffB); PG8_STAGE(PG8_SA(1, 0), a3, voffA);
;             PG8_WAIT_V(8); PG8_WAIT_L(0); PG8_BAR; PG8_MMA(1, 0, At, B0); PG8_MMA(1, 1, At, B1); PG8_BAR; PG8_SCHED;
;     __device__ __forceinline__ void operator()(const f32x4 (&acc)[2][2][4][2], const Unit& un, int wr, int wc, int fr, int fq) const {
;         const int rbase = un.pm * 256 + wr * 64 + fr, cw = un.pn * 256 + wc * 32 + 8 * fq, kb = un.kb;
; #pragma unroll
;         for (int ai = 0; ai < 2; ++ai) {
;             u32x4 ga_[4][2], pa_[4][2];
; #pragma unroll
;             for (int m = 0; m < 4; ++m)
; #pragma unroll
;                 for (int bj = 0; bj < 2; ++bj) { const int row = rbase + ai * 128 + m * 16, col = cw + bj * 128; ga_[m][bj] = *(const u32x4*)(gate + (size_t)row * DFF + kb * D + col);
;                     pa_[m][bj] = kb > 0 ? *(const u32x4*)(mg + (size_t)row * D + col) : (u32x4){0u, 0u, 0u, 0u}; }
	s_add_i32 s26, s50, s36
	v_lshl_add_u64 v[192:193], v[192:193], 0, s[2:3]
	s_mov_b32 m0, s26
	ds_read_b128 v[160:163], v225 offset:49152
	ds_read_b128 v[164:167], v225 offset:50176
	ds_read_b128 v[168:171], v225 offset:51200
	ds_read_b128 v[172:175], v225 offset:52224
	ds_read_b128 v[176:179], v225 offset:53248
	ds_read_b128 v[180:183], v225 offset:54272
	ds_read_b128 v[184:187], v225 offset:55296
	ds_read_b128 v[188:191], v225 offset:56320
	global_load_lds_dwordx4 v[192:193], off
	s_add_i32 m0, s26, 0x2000
	s_add_u32 s24, s24, 0x20080
	v_lshl_add_u64 v[192:193], v[204:205], 0, s[2:3]
	s_addc_u32 s25, s25, 0
	s_add_i32 s26, s51, s36
	global_load_lds_dwordx4 v[192:193], off
	v_lshl_add_u64 v[192:193], s[24:25], 0, v[208:209]
	s_mov_b32 m0, s26
	s_nop 0
	global_load_lds_dwordx4 v[192:193], off
	v_lshl_add_u64 v[192:193], s[24:25], 0, v[198:199]
	s_add_i32 m0, s26, 0x2000
	s_nop 0
	global_load_lds_dwordx4 v[192:193], off
	v_lshl_add_u64 v[192:193], v[206:207], 0, s[2:3]
	s_mov_b32 m0, s43
	s_nop 0
	global_load_lds_dwordx4 v[192:193], off
	v_lshl_add_u64 v[192:193], v[214:215], 0, s[2:3]
	s_mov_b32 m0, s44
	s_nop 0
	global_load_lds_dwordx4 v[192:193], off
	s_waitcnt vmcnt(8)
	s_waitcnt lgkmcnt(0)
	s_barrier
	s_setprio 1
	s_waitcnt lgkmcnt(0)
	v_mfma_f32_16x16x32_bf16 v[60:63], v[128:131], v[160:163], v[60:63]
	v_mfma_f32_16x16x32_bf16 v[56:59], v[136:139], v[160:163], v[56:59]
	v_mfma_f32_16x16x32_bf16 v[44:47], v[128:131], v[168:171], v[44:47]
	v_mfma_f32_16x16x32_bf16 v[40:43], v[136:139], v[168:171], v[40:43]
	v_mfma_f32_16x16x32_bf16 v[28:31], v[128:131], v[176:179], v[28:31]
	v_mfma_f32_16x16x32_bf16 v[24:27], v[136:139], v[176:179], v[24:27]
	v_mfma_f32_16x16x32_bf16 v[12:15], v[128:131], v[184:187], v[12:15]
	v_mfma_f32_16x16x32_bf16 v[8:11], v[136:139], v[184:187], v[8:11]
	v_mfma_f32_16x16x32_bf16 v[60:63], v[132:135], v[164:167], v[60:63]
	v_mfma_f32_16x16x32_bf16 v[56:59], v[140:143], v[164:167], v[56:59]
	v_mfma_f32_16x16x32_bf16 v[44:47], v[132:135], v[172:175], v[44:47]
	v_mfma_f32_16x16x32_bf16 v[40:43], v[140:143], v[172:175], v[40:43]
	v_mfma_f32_16x16x32_bf16 v[28:31], v[132:135], v[180:183], v[28:31]
	v_mfma_f32_16x16x32_bf16 v[24:27], v[140:143], v[180:183], v[24:27]
	v_mfma_f32_16x16x32_bf16 v[12:15], v[132:135], v[188:191], v[12:15]
	v_mfma_f32_16x16x32_bf16 v[8:11], v[140:143], v[188:191], v[8:11]
	v_mfma_f32_16x16x32_bf16 v[52:55], v[144:147], v[160:163], v[52:55]
	v_mfma_f32_16x16x32_bf16 v[48:51], v[152:155], v[160:163], v[48:51]
	v_mfma_f32_16x16x32_bf16 v[36:39], v[144:147], v[168:171], v[36:39]
	v_mfma_f32_16x16x32_bf16 v[32:35], v[152:155], v[168:171], v[32:35]
	v_mfma_f32_16x16x32_bf16 v[20:23], v[144:147], v[176:179], v[20:23]
	v_mfma_f32_16x16x32_bf16 v[16:19], v[152:155], v[176:179], v[16:19]
	v_mfma_f32_16x16x32_bf16 v[4:7], v[144:147], v[184:187], v[4:7]
	v_mfma_f32_16x16x32_bf16 v[0:3], v[152:155], v[184:187], v[0:3]
	v_mfma_f32_16x16x32_bf16 v[52:55], v[148:151], v[164:167], v[52:55]
	v_mfma_f32_16x16x32_bf16 v[48:51], v[156:159], v[164:167], v[48:51]
	v_mfma_f32_16x16x32_bf16 v[36:39], v[148:151], v[172:175], v[36:39]
	v_mfma_f32_16x16x32_bf16 v[32:35], v[156:159], v[172:175], v[32:35]
	v_mfma_f32_16x16x32_bf16 v[20:23], v[148:151], v[180:183], v[20:23]
	v_mfma_f32_16x16x32_bf16 v[16:19], v[156:159], v[180:183], v[16:19]
	v_mfma_f32_16x16x32_bf16 v[4:7], v[148:151], v[188:191], v[4:7]
	v_mfma_f32_16x16x32_bf16 v[0:3], v[156:159], v[188:191], v[0:3]
	s_setprio 0
	s_barrier
	s_add_i32 s49, s49, 2
	s_add_u32 s4, s4, 0x100
	s_addc_u32 s5, s5, 0
	s_add_u32 s21, s21, 0x100
	s_addc_u32 s23, s23, 0
	s_cmp_gt_u32 s49, 5
	s_cbranch_scc0 .LBB0_1128
	s_cmp_lg_u32 s48, 0
	v_lshl_add_u32 v206, s20, 8, v210
	v_lshl_or_b32 v204, s22, 8, v224
	s_cselect_b64 s[22:23], -1, 0
	s_lshl_b32 s4, s48, 12
	s_add_u32 s20, s41, s4
	v_ashrrev_i32_e32 v207, 31, v206
	s_addc_u32 s21, s42, 0
	v_lshlrev_b64 v[128:129], 14, v[206:207]
	v_lshl_add_u64 v[128:129], s[20:21], 0, v[128:129]
	v_ashrrev_i32_e32 v205, 31, v204
	v_lshl_add_u64 v[130:131], v[204:205], 1, v[128:129]
	global_load_dwordx4 v[186:189], v[130:131], off
	v_lshlrev_b64 v[128:129], 12, v[206:207]
	v_lshl_add_u64 v[220:221], s[8:9], 0, v[128:129]
	s_cmp_eq_u32 s48, 0
	v_lshl_add_u64 v[128:129], v[204:205], 1, v[220:221]
	s_cbranch_scc1 .LBB0_1133
	global_load_dwordx4 v[190:193], v[128:129], off
	s_branch .LBB0_1134

; #define PG8_STAGE(bufoff, gbase, voff) do { _Pragma("unroll") for (int _i = 0; _i < 2; ++_i) \
;         __builtin_amdgcn_global_load_lds((const unsigned*)((const char*)(gbase) + (voff)[_i]), (PG8_LAS unsigned*)(lds + (bufoff) + ldsw + _i * 8192), 16, 0, 0); } while (0)
; #define PG8_LDA(dst, b, h) do { _Pragma("unroll") for (int m = 0; m < 4; ++m) _Pragma("unroll") for (int k = 0; k < 2; ++k) dst[m][k] = *(const PG8_LAS bf16x8*)(lds + PG8_SA(b, h) + aoff + m * 2048 + k * 1024); } while (0)
; #define PG8_LDB(dst, b, h) do { _Pragma("unroll") for (int n = 0; n < 2; ++n) _Pragma("unroll") for (int k = 0; k < 2; ++k) dst[n][k] = *(const PG8_LAS bf16x8*)(lds + PG8_SB(b, h) + boff + n * 2048 + k * 1024); } while (0)
; #define PG8_MMA(ai, bj, At, Bt) do { __builtin_amdgcn_s_setprio(1); _Pragma("unroll") for (int m = 0; m < 4; ++m) _Pragma("unroll") for (int n = 0; n < 2; ++n) _Pragma("unroll") for (int k = 0; k < 2; ++k) \
;         acc[ai][bj][m][n] = __builtin_amdgcn_mfma_f32_16x16x32_bf16(Bt[n][k], At[m][k], acc[ai][bj][m][n], 0, 0, 0); __builtin_amdgcn_s_setprio(0); } while (0)
; #define PG8_WAIT_V(n) asm volatile("s_waitcnt vmcnt(" #n ")" ::: "memory")
; #define PG8_WAIT_L(n) asm volatile("s_waitcnt lgkmcnt(" #n ")" ::: "memory")
; #define PG8_BAR __builtin_amdgcn_s_barrier()
; #define PG8_SCHED __builtin_amdgcn_sched_barrier(0)
; template <class Epi, class Sched, bool ALIGN_EPI = false, bool SP2 = false>
; __device__ __forceinline__ void gemm_phase(PG8_LAS unsigned char* lds, const Gemm g, const Sched& S, const Epi& E, const int tid) {
;     ...
;             PG8_LDB(B0, 0, 0); PG8_LDB(B1, 0, 1); PG8_SCHED; PG8_LDA(At, 0, 0); PG8_STAGE(PG8_SA(1, 1), a1 + hstep, voffA);
;             PG8_WAIT_V(8); PG8_WAIT_L(0); PG8_BAR; PG8_MMA(0, 0, At, B0); PG8_MMA(0, 1, At, B1); PG8_BAR; PG8_SCHED;
;             PG8_LDA(At, 0, 1); PG8_STAGE(PG8_SB(0, 0), b2, voffB); PG8_STAGE(PG8_SB(0, 1), b2 + hstep, voffB); PG8_STAGE(PG8_SA(0, 0), a2, voffA);
;             PG8_WAIT_V(8); PG8_WAIT_L(0); PG8_BAR; PG8_MMA(1, 0, At, B0); PG8_MMA(1, 1, At, B1); PG8_BAR; PG8_SCHED;
.LBB0_1174:
	s_add_u32 s8, s26, s6
	s_addc_u32 s9, s27, s7
	s_add_u32 s8, s8, 0x20200100
	s_addc_u32 s9, s9, 0
	s_add_u32 s31, s28, s6
	s_addc_u32 s34, s29, s7
	s_add_i32 s35, 0, 0x10000
	v_add_u32_e32 v154, s35, v140
	v_add_u32_e32 v170, s33, v140
	ds_read_b128 v[142:145], v154
	ds_read_b128 v[146:149], v154 offset:1024
	ds_read_b128 v[150:153], v154 offset:2048
	ds_read_b128 v[154:157], v154 offset:3072
	ds_read_b128 v[158:161], v170
	ds_read_b128 v[162:165], v170 offset:1024
	ds_read_b128 v[166:169], v170 offset:2048
	ds_read_b128 v[170:173], v170 offset:3072
	s_cmpk_eq_i32 s6, 0x300
	s_cselect_b32 s11, s5, s9
	s_cselect_b32 s10, s4, s8
	s_cselect_b32 s9, s1, s34
	s_cselect_b32 s8, s0, s31
	v_lshl_add_u64 v[206:207], v[134:135], 0, s[6:7]
	s_add_i32 m0, s19, 0xc000
	ds_read_b128 v[174:177], v141
	ds_read_b128 v[178:181], v141 offset:1024
	ds_read_b128 v[182:185], v141 offset:2048
	ds_read_b128 v[186:189], v141 offset:3072
	ds_read_b128 v[190:193], v141 offset:4096
	ds_read_b128 v[194:197], v141 offset:5120
	ds_read_b128 v[198:201], v141 offset:6144
	ds_read_b128 v[202:205], v141 offset:7168
	global_load_lds_dwordx4 v[206:207], off
	v_lshl_add_u64 v[206:207], v[136:137], 0, s[6:7]
	s_add_i32 m0, s19, 0xe000
	s_nop 0
	global_load_lds_dwordx4 v[206:207], off
	s_waitcnt vmcnt(8)
	s_waitcnt lgkmcnt(0)
	s_barrier
	s_setprio 1
	s_waitcnt lgkmcnt(0)
	v_mfma_f32_16x16x32_bf16 v[124:127], v[142:145], v[174:177], v[124:127]
	v_mfma_f32_16x16x32_bf16 v[120:123], v[150:153], v[174:177], v[120:123]
	v_mfma_f32_16x16x32_bf16 v[108:111], v[142:145], v[182:185], v[108:111]
	v_mfma_f32_16x16x32_bf16 v[104:107], v[150:153], v[182:185], v[104:107]
	v_mfma_f32_16x16x32_bf16 v[96:99], v[142:145], v[190:193], v[96:99]
	v_mfma_f32_16x16x32_bf16 v[88:91], v[150:153], v[190:193], v[88:91]
	v_mfma_f32_16x16x32_bf16 v[80:83], v[142:145], v[198:201], v[80:83]
	v_mfma_f32_16x16x32_bf16 v[72:75], v[150:153], v[198:201], v[72:75]
	v_mfma_f32_16x16x32_bf16 v[124:127], v[146:149], v[178:181], v[124:127]
	v_mfma_f32_16x16x32_bf16 v[120:123], v[154:157], v[178:181], v[120:123]
	v_mfma_f32_16x16x32_bf16 v[108:111], v[146:149], v[186:189], v[108:111]
	v_mfma_f32_16x16x32_bf16 v[104:107], v[154:157], v[186:189], v[104:107]
	v_mfma_f32_16x16x32_bf16 v[96:99], v[146:149], v[194:197], v[96:99]
	v_mfma_f32_16x16x32_bf16 v[88:91], v[154:157], v[194:197], v[88:91]
	v_mfma_f32_16x16x32_bf16 v[80:83], v[146:149], v[202:205], v[80:83]
	v_mfma_f32_16x16x32_bf16 v[72:75], v[154:157], v[202:205], v[72:75]
	v_mfma_f32_16x16x32_bf16 v[116:119], v[158:161], v[174:177], v[116:119]
	v_mfma_f32_16x16x32_bf16 v[112:115], v[166:169], v[174:177], v[112:115]
	v_mfma_f32_16x16x32_bf16 v[100:103], v[158:161], v[182:185], v[100:103]
	v_mfma_f32_16x16x32_bf16 v[92:95], v[166:169], v[182:185], v[92:95]
	v_mfma_f32_16x16x32_bf16 v[84:87], v[158:161], v[190:193], v[84:87]
	v_mfma_f32_16x16x32_bf16 v[76:79], v[166:169], v[190:193], v[76:79]
	v_mfma_f32_16x16x32_bf16 v[68:71], v[158:161], v[198:201], v[68:71]
	v_mfma_f32_16x16x32_bf16 v[64:67], v[166:169], v[198:201], v[64:67]
	v_mfma_f32_16x16x32_bf16 v[116:119], v[162:165], v[178:181], v[116:119]
	v_mfma_f32_16x16x32_bf16 v[112:115], v[170:173], v[178:181], v[112:115]
	v_mfma_f32_16x16x32_bf16 v[100:103], v[162:165], v[186:189], v[100:103]
	v_mfma_f32_16x16x32_bf16 v[92:95], v[170:173], v[186:189], v[92:95]
	v_mfma_f32_16x16x32_bf16 v[84:87], v[162:165], v[194:197], v[84:87]
	v_mfma_f32_16x16x32_bf16 v[76:79], v[170:173], v[194:197], v[76:79]
	v_mfma_f32_16x16x32_bf16 v[68:71], v[162:165], v[202:205], v[68:71]
	v_mfma_f32_16x16x32_bf16 v[64:67], v[170:173], v[202:205], v[64:67]
	s_setprio 0
	s_barrier
	s_add_i32 s31, s35, s15
	v_lshl_add_u64 v[206:207], s[8:9], 0, v[208:209]
	s_mov_b32 m0, s31
	ds_read_b128 v[174:177], v141 offset:16384
	ds_read_b128 v[178:181], v141 offset:17408
	ds_read_b128 v[182:185], v141 offset:18432
	ds_read_b128 v[186:189], v141 offset:19456
	ds_read_b128 v[190:193], v141 offset:20480
	ds_read_b128 v[194:197], v141 offset:21504
	ds_read_b128 v[198:201], v141 offset:22528
	ds_read_b128 v[202:205], v141 offset:23552
	global_load_lds_dwordx4 v[206:207], off
	s_add_i32 m0, s31, 0x2000
	s_add_u32 s34, s8, 0x20000
	v_lshl_add_u64 v[210:211], s[8:9], 0, v[128:129]
	s_addc_u32 s35, s9, 0
	s_add_i32 s31, s33, s15
	global_load_lds_dwordx4 v[210:211], off
	v_lshl_add_u64 v[214:215], s[34:35], 0, v[208:209]
	s_mov_b32 m0, s31
	v_lshl_add_u64 v[216:217], s[10:11], 0, v[130:131]
	global_load_lds_dwordx4 v[214:215], off
	v_lshl_add_u64 v[214:215], s[34:35], 0, v[128:129]
	s_add_i32 m0, s31, 0x2000
	s_nop 0
	global_load_lds_dwordx4 v[214:215], off
	v_lshl_add_u64 v[214:215], s[10:11], 0, v[132:133]
	s_mov_b32 m0, s19
	s_nop 0
	global_load_lds_dwordx4 v[214:215], off
	s_mov_b32 m0, s20
	s_nop 0
	global_load_lds_dwordx4 v[216:217], off
	s_waitcnt vmcnt(8)
	s_waitcnt lgkmcnt(0)
	s_barrier
; #define PG8_STAGE(bufoff, gbase, voff) do { _Pragma("unroll") for (int _i = 0; _i < 2; ++_i) \
;         __builtin_amdgcn_global_load_lds((const unsigned*)((const char*)(gbase) + (voff)[_i]), (PG8_LAS unsigned*)(lds + (bufoff) + ldsw + _i * 8192), 16, 0, 0); } while (0)
; #define PG8_LDA(dst, b, h) do { _Pragma("unroll") for (int m = 0; m < 4; ++m) _Pragma("unroll") for (int k = 0; k < 2; ++k) dst[m][k] = *(const PG8_LAS bf16x8*)(lds + PG8_SA(b, h) + aoff + m * 2048 + k * 1024); } while (0)
; #define PG8_LDB(dst, b, h) do { _Pragma("unroll") for (int n = 0; n < 2; ++n) _Pragma("unroll") for (int k = 0; k < 2; ++k) dst[n][k] = *(const PG8_LAS bf16x8*)(lds + PG8_SB(b, h) + boff + n * 2048 + k * 1024); } while (0)
; #define PG8_MMA(ai, bj, At, Bt) do { __builtin_amdgcn_s_setprio(1); _Pragma("unroll") for (int m = 0; m < 4; ++m) _Pragma("unroll") for (int n = 0; n < 2; ++n) _Pragma("unroll") for (int k = 0; k < 2; ++k) \
;         acc[ai][bj][m][n] = __builtin_amdgcn_mfma_f32_16x16x32_bf16(Bt[n][k], At[m][k], acc[ai][bj][m][n], 0, 0, 0); __builtin_amdgcn_s_setprio(0); } while (0)
; #define PG8_WAIT_V(n) asm volatile("s_waitcnt vmcnt(" #n ")" ::: "memory")
; #define PG8_WAIT_L(n) asm volatile("s_waitcnt lgkmcnt(" #n ")" ::: "memory")
; #define PG8_BAR __builtin_amdgcn_s_barrier()
; #define PG8_SCHED __builtin_amdgcn_sched_barrier(0)
; template <class Epi, class Sched, bool ALIGN_EPI = false, bool SP2 = false>
; __device__ __forceinline__ void gemm_phase(PG8_LAS unsigned char* lds, const Gemm g, const Sched& S, const Epi& E, const int tid) {
;     ...
;             PG8_WAIT_V(8); PG8_WAIT_L(0); PG8_BAR; PG8_MMA(1, 0, At, B0); PG8_MMA(1, 1, At, B1); PG8_BAR; PG8_SCHED;
;             PG8_LDB(B0, 1, 0); PG8_LDB(B1, 1, 1); PG8_SCHED; PG8_LDA(At, 1, 0); PG8_STAGE(PG8_SA(0, 1), a2 + hstep, voffA);
;             PG8_WAIT_V(8); PG8_WAIT_L(0); PG8_BAR; PG8_MMA(0, 0, At, B0); PG8_MMA(0, 1, At, B1); PG8_BAR; PG8_SCHED;
	s_setprio 1
	s_waitcnt lgkmcnt(0)
	v_mfma_f32_16x16x32_bf16 v[60:63], v[142:145], v[174:177], v[60:63]
	v_mfma_f32_16x16x32_bf16 v[56:59], v[150:153], v[174:177], v[56:59]
	v_mfma_f32_16x16x32_bf16 v[48:51], v[142:145], v[182:185], v[48:51]
	v_mfma_f32_16x16x32_bf16 v[40:43], v[150:153], v[182:185], v[40:43]
	v_mfma_f32_16x16x32_bf16 v[32:35], v[142:145], v[190:193], v[32:35]
	v_mfma_f32_16x16x32_bf16 v[24:27], v[150:153], v[190:193], v[24:27]
	v_mfma_f32_16x16x32_bf16 v[16:19], v[142:145], v[198:201], v[16:19]
	v_mfma_f32_16x16x32_bf16 v[8:11], v[150:153], v[198:201], v[8:11]
	v_mfma_f32_16x16x32_bf16 v[60:63], v[146:149], v[178:181], v[60:63]
	v_mfma_f32_16x16x32_bf16 v[56:59], v[154:157], v[178:181], v[56:59]
	v_mfma_f32_16x16x32_bf16 v[48:51], v[146:149], v[186:189], v[48:51]
	v_mfma_f32_16x16x32_bf16 v[40:43], v[154:157], v[186:189], v[40:43]
	v_mfma_f32_16x16x32_bf16 v[32:35], v[146:149], v[194:197], v[32:35]
	v_mfma_f32_16x16x32_bf16 v[24:27], v[154:157], v[194:197], v[24:27]
	v_mfma_f32_16x16x32_bf16 v[16:19], v[146:149], v[202:205], v[16:19]
	v_mfma_f32_16x16x32_bf16 v[8:11], v[154:157], v[202:205], v[8:11]
	v_mfma_f32_16x16x32_bf16 v[52:55], v[158:161], v[174:177], v[52:55]
	v_mfma_f32_16x16x32_bf16 v[44:47], v[166:169], v[174:177], v[44:47]
	v_mfma_f32_16x16x32_bf16 v[36:39], v[158:161], v[182:185], v[36:39]
	v_mfma_f32_16x16x32_bf16 v[28:31], v[166:169], v[182:185], v[28:31]
	v_mfma_f32_16x16x32_bf16 v[20:23], v[158:161], v[190:193], v[20:23]
	v_mfma_f32_16x16x32_bf16 v[12:15], v[166:169], v[190:193], v[12:15]
	v_mfma_f32_16x16x32_bf16 v[4:7], v[158:161], v[198:201], v[4:7]
	v_mfma_f32_16x16x32_bf16 v[0:3], v[166:169], v[198:201], v[0:3]
	v_mfma_f32_16x16x32_bf16 v[52:55], v[162:165], v[178:181], v[52:55]
	v_mfma_f32_16x16x32_bf16 v[44:47], v[170:173], v[178:181], v[44:47]
	v_mfma_f32_16x16x32_bf16 v[36:39], v[162:165], v[186:189], v[36:39]
	v_mfma_f32_16x16x32_bf16 v[28:31], v[170:173], v[186:189], v[28:31]
	v_mfma_f32_16x16x32_bf16 v[20:23], v[162:165], v[194:197], v[20:23]
	v_mfma_f32_16x16x32_bf16 v[12:15], v[170:173], v[194:197], v[12:15]
	v_mfma_f32_16x16x32_bf16 v[4:7], v[162:165], v[202:205], v[4:7]
	v_mfma_f32_16x16x32_bf16 v[0:3], v[170:173], v[202:205], v[0:3]
	s_setprio 0
	s_barrier
	s_add_i32 s31, 0, 0x18000
	s_add_i32 s34, 0, 0x1c000
	v_add_u32_e32 v154, s31, v140
	v_add_u32_e32 v170, s34, v140
	ds_read_b128 v[142:145], v154
	ds_read_b128 v[146:149], v154 offset:1024
	ds_read_b128 v[150:153], v154 offset:2048
	ds_read_b128 v[154:157], v154 offset:3072
	ds_read_b128 v[158:161], v170
	ds_read_b128 v[162:165], v170 offset:1024
	ds_read_b128 v[166:169], v170 offset:2048
	ds_read_b128 v[170:173], v170 offset:3072
	s_add_u32 s10, s10, 0x20000
	s_addc_u32 s11, s11, 0
	s_mov_b32 m0, s21
	v_lshl_add_u64 v[218:219], s[10:11], 0, v[132:133]
	ds_read_b128 v[174:177], v141 offset:32768
	ds_read_b128 v[178:181], v141 offset:33792
	ds_read_b128 v[182:185], v141 offset:34816
	ds_read_b128 v[186:189], v141 offset:35840
	ds_read_b128 v[190:193], v141 offset:36864
	ds_read_b128 v[194:197], v141 offset:37888
	ds_read_b128 v[198:201], v141 offset:38912
	ds_read_b128 v[202:205], v141 offset:39936
	global_load_lds_dwordx4 v[218:219], off
	v_lshl_add_u64 v[218:219], s[10:11], 0, v[130:131]
	s_mov_b32 m0, s22
	s_nop 0
	global_load_lds_dwordx4 v[218:219], off
	s_waitcnt vmcnt(8)
	s_waitcnt lgkmcnt(0)
	s_barrier
	s_setprio 1
	s_waitcnt lgkmcnt(0)
	v_mfma_f32_16x16x32_bf16 v[124:127], v[142:145], v[174:177], v[124:127]
	v_mfma_f32_16x16x32_bf16 v[120:123], v[150:153], v[174:177], v[120:123]
	v_mfma_f32_16x16x32_bf16 v[108:111], v[142:145], v[182:185], v[108:111]
	v_mfma_f32_16x16x32_bf16 v[104:107], v[150:153], v[182:185], v[104:107]
	v_mfma_f32_16x16x32_bf16 v[96:99], v[142:145], v[190:193], v[96:99]
	v_mfma_f32_16x16x32_bf16 v[88:91], v[150:153], v[190:193], v[88:91]
	v_mfma_f32_16x16x32_bf16 v[80:83], v[142:145], v[198:201], v[80:83]
	v_mfma_f32_16x16x32_bf16 v[72:75], v[150:153], v[198:201], v[72:75]
	v_mfma_f32_16x16x32_bf16 v[124:127], v[146:149], v[178:181], v[124:127]
	v_mfma_f32_16x16x32_bf16 v[120:123], v[154:157], v[178:181], v[120:123]
	v_mfma_f32_16x16x32_bf16 v[108:111], v[146:149], v[186:189], v[108:111]
	v_mfma_f32_16x16x32_bf16 v[104:107], v[154:157], v[186:189], v[104:107]
	v_mfma_f32_16x16x32_bf16 v[96:99], v[146:149], v[194:197], v[96:99]
	v_mfma_f32_16x16x32_bf16 v[88:91], v[154:157], v[194:197], v[88:91]
	v_mfma_f32_16x16x32_bf16 v[80:83], v[146:149], v[202:205], v[80:83]
	v_mfma_f32_16x16x32_bf16 v[72:75], v[154:157], v[202:205], v[72:75]
	v_mfma_f32_16x16x32_bf16 v[116:119], v[158:161], v[174:177], v[116:119]
	v_mfma_f32_16x16x32_bf16 v[112:115], v[166:169], v[174:177], v[112:115]
	v_mfma_f32_16x16x32_bf16 v[100:103], v[158:161], v[182:185], v[100:103]
	v_mfma_f32_16x16x32_bf16 v[92:95], v[166:169], v[182:185], v[92:95]
	v_mfma_f32_16x16x32_bf16 v[84:87], v[158:161], v[190:193], v[84:87]
	v_mfma_f32_16x16x32_bf16 v[76:79], v[166:169], v[190:193], v[76:79]
	v_mfma_f32_16x16x32_bf16 v[68:71], v[158:161], v[198:201], v[68:71]
	v_mfma_f32_16x16x32_bf16 v[64:67], v[166:169], v[198:201], v[64:67]
	v_mfma_f32_16x16x32_bf16 v[116:119], v[162:165], v[178:181], v[116:119]
	v_mfma_f32_16x16x32_bf16 v[112:115], v[170:173], v[178:181], v[112:115]
	v_mfma_f32_16x16x32_bf16 v[100:103], v[162:165], v[186:189], v[100:103]
	v_mfma_f32_16x16x32_bf16 v[92:95], v[170:173], v[186:189], v[92:95]
	v_mfma_f32_16x16x32_bf16 v[84:87], v[162:165], v[194:197], v[84:87]
	v_mfma_f32_16x16x32_bf16 v[76:79], v[170:173], v[194:197], v[76:79]
	v_mfma_f32_16x16x32_bf16 v[68:71], v[162:165], v[202:205], v[68:71]
	v_mfma_f32_16x16x32_bf16 v[64:67], v[170:173], v[202:205], v[64:67]
	s_setprio 0
	s_barrier
; #define PG8_STAGE(bufoff, gbase, voff) do { _Pragma("unroll") for (int _i = 0; _i < 2; ++_i) \
;         __builtin_amdgcn_global_load_lds((const unsigned*)((const char*)(gbase) + (voff)[_i]), (PG8_LAS unsigned*)(lds + (bufoff) + ldsw + _i * 8192), 16, 0, 0); } while (0)
; #define PG8_LDA(dst, b, h) do { _Pragma("unroll") for (int m = 0; m < 4; ++m) _Pragma("unroll") for (int k = 0; k < 2; ++k) dst[m][k] = *(const PG8_LAS bf16x8*)(lds + PG8_SA(b, h) + aoff + m * 2048 + k * 1024); } while (0)
; #define PG8_MMA(ai, bj, At, Bt) do { __builtin_amdgcn_s_setprio(1); _Pragma("unroll") for (int m = 0; m < 4; ++m) _Pragma("unroll") for (int n = 0; n < 2; ++n) _Pragma("unroll") for (int k = 0; k < 2; ++k) \
;         acc[ai][bj][m][n] = __builtin_amdgcn_mfma_f32_16x16x32_bf16(Bt[n][k], At[m][k], acc[ai][bj][m][n], 0, 0, 0); __builtin_amdgcn_s_setprio(0); } while (0)
; #define PG8_WAIT_V(n) asm volatile("s_waitcnt vmcnt(" #n ")" ::: "memory")
; #define PG8_WAIT_L(n) asm volatile("s_waitcnt lgkmcnt(" #n ")" ::: "memory")
; #define PG8_BAR __builtin_amdgcn_s_barrier()
; #define PG8_SCHED __builtin_amdgcn_sched_barrier(0)
; template <class Epi, class Sched, bool ALIGN_EPI = false, bool SP2 = false>
; __device__ __forceinline__ void gemm_phase(PG8_LAS unsigned char* lds, const Gemm g, const Sched& S, const Epi& E, const int tid) {
;     ...
;             PG8_LDA(At, 1, 1); PG8_STAGE(PG8_SB(1, 0), b3, voffB); PG8_STAGE(PG8_SB(1, 1), b3 + hstep, voffB); PG8_STAGE(PG8_SA(1, 0), a3, voffA);
;             PG8_WAIT_V(8); PG8_WAIT_L(0); PG8_BAR; PG8_MMA(1, 0, At, B0); PG8_MMA(1, 1, At, B1); PG8_BAR; PG8_SCHED;
	s_add_i32 s10, s31, s15
	v_lshl_add_u64 v[206:207], v[206:207], 0, s[2:3]
	s_mov_b32 m0, s10
	ds_read_b128 v[174:177], v141 offset:49152
	ds_read_b128 v[178:181], v141 offset:50176
	ds_read_b128 v[182:185], v141 offset:51200
	ds_read_b128 v[186:189], v141 offset:52224
	ds_read_b128 v[190:193], v141 offset:53248
	ds_read_b128 v[194:197], v141 offset:54272
	ds_read_b128 v[198:201], v141 offset:55296
	ds_read_b128 v[202:205], v141 offset:56320
	global_load_lds_dwordx4 v[206:207], off
	s_add_i32 m0, s10, 0x2000
	s_add_u32 s8, s8, 0x20080
	v_lshl_add_u64 v[206:207], v[210:211], 0, s[2:3]
	s_addc_u32 s9, s9, 0
	s_add_i32 s10, s34, s15
	global_load_lds_dwordx4 v[206:207], off
	v_lshl_add_u64 v[206:207], s[8:9], 0, v[208:209]
	s_mov_b32 m0, s10
	s_nop 0
	global_load_lds_dwordx4 v[206:207], off
	v_lshl_add_u64 v[206:207], s[8:9], 0, v[128:129]
	s_add_i32 m0, s10, 0x2000
	s_nop 0
	global_load_lds_dwordx4 v[206:207], off
	v_lshl_add_u64 v[206:207], v[214:215], 0, s[2:3]
	s_mov_b32 m0, s24
	s_nop 0
	global_load_lds_dwordx4 v[206:207], off
	v_lshl_add_u64 v[206:207], v[216:217], 0, s[2:3]
	s_mov_b32 m0, s25
	s_nop 0
	global_load_lds_dwordx4 v[206:207], off
	s_waitcnt vmcnt(8)
	s_waitcnt lgkmcnt(0)
	s_barrier
	s_setprio 1
	s_waitcnt lgkmcnt(0)
	v_mfma_f32_16x16x32_bf16 v[60:63], v[142:145], v[174:177], v[60:63]
	v_mfma_f32_16x16x32_bf16 v[56:59], v[150:153], v[174:177], v[56:59]
	v_mfma_f32_16x16x32_bf16 v[48:51], v[142:145], v[182:185], v[48:51]
	v_mfma_f32_16x16x32_bf16 v[40:43], v[150:153], v[182:185], v[40:43]
	v_mfma_f32_16x16x32_bf16 v[32:35], v[142:145], v[190:193], v[32:35]
	v_mfma_f32_16x16x32_bf16 v[24:27], v[150:153], v[190:193], v[24:27]
	v_mfma_f32_16x16x32_bf16 v[16:19], v[142:145], v[198:201], v[16:19]
	v_mfma_f32_16x16x32_bf16 v[8:11], v[150:153], v[198:201], v[8:11]
	v_mfma_f32_16x16x32_bf16 v[60:63], v[146:149], v[178:181], v[60:63]
	v_mfma_f32_16x16x32_bf16 v[56:59], v[154:157], v[178:181], v[56:59]
	v_mfma_f32_16x16x32_bf16 v[48:51], v[146:149], v[186:189], v[48:51]
	v_mfma_f32_16x16x32_bf16 v[40:43], v[154:157], v[186:189], v[40:43]
	v_mfma_f32_16x16x32_bf16 v[32:35], v[146:149], v[194:197], v[32:35]
	v_mfma_f32_16x16x32_bf16 v[24:27], v[154:157], v[194:197], v[24:27]
	v_mfma_f32_16x16x32_bf16 v[16:19], v[146:149], v[202:205], v[16:19]
	v_mfma_f32_16x16x32_bf16 v[8:11], v[154:157], v[202:205], v[8:11]
	v_mfma_f32_16x16x32_bf16 v[52:55], v[158:161], v[174:177], v[52:55]
	v_mfma_f32_16x16x32_bf16 v[44:47], v[166:169], v[174:177], v[44:47]
	v_mfma_f32_16x16x32_bf16 v[36:39], v[158:161], v[182:185], v[36:39]
	v_mfma_f32_16x16x32_bf16 v[28:31], v[166:169], v[182:185], v[28:31]
	v_mfma_f32_16x16x32_bf16 v[20:23], v[158:161], v[190:193], v[20:23]
	v_mfma_f32_16x16x32_bf16 v[12:15], v[166:169], v[190:193], v[12:15]
	v_mfma_f32_16x16x32_bf16 v[4:7], v[158:161], v[198:201], v[4:7]
	v_mfma_f32_16x16x32_bf16 v[0:3], v[166:169], v[198:201], v[0:3]
	v_mfma_f32_16x16x32_bf16 v[52:55], v[162:165], v[178:181], v[52:55]
	v_mfma_f32_16x16x32_bf16 v[44:47], v[170:173], v[178:181], v[44:47]
	v_mfma_f32_16x16x32_bf16 v[36:39], v[162:165], v[186:189], v[36:39]
	v_mfma_f32_16x16x32_bf16 v[28:31], v[170:173], v[186:189], v[28:31]
	v_mfma_f32_16x16x32_bf16 v[20:23], v[162:165], v[194:197], v[20:23]
	v_mfma_f32_16x16x32_bf16 v[12:15], v[170:173], v[194:197], v[12:15]
	v_mfma_f32_16x16x32_bf16 v[4:7], v[162:165], v[202:205], v[4:7]
	v_mfma_f32_16x16x32_bf16 v[0:3], v[170:173], v[202:205], v[0:3]
	s_setprio 0
	s_barrier
	s_add_i32 s30, s30, 2
	s_add_u32 s6, s6, 0x100
	s_addc_u32 s7, s7, 0
	s_cmp_gt_u32 s30, 5
	s_cbranch_scc0 .LBB0_1174
	s_cmpk_lt_u32 s14, 0x100
	s_movk_i32 s30, 0x41
	s_cbranch_scc0 .LBB0_1177
	s_barrier

; #define PG8_STAGE(bufoff, gbase, voff) do { _Pragma("unroll") for (int _i = 0; _i < 2; ++_i) \
;         __builtin_amdgcn_global_load_lds((const unsigned*)((const char*)(gbase) + (voff)[_i]), (PG8_LAS unsigned*)(lds + (bufoff) + ldsw + _i * 8192), 16, 0, 0); } while (0)
; #define PG8_LDA(dst, b, h) do { _Pragma("unroll") for (int m = 0; m < 4; ++m) _Pragma("unroll") for (int k = 0; k < 2; ++k) dst[m][k] = *(const PG8_LAS bf16x8*)(lds + PG8_SA(b, h) + aoff + m * 2048 + k * 1024); } while (0)
; #define PG8_LDB(dst, b, h) do { _Pragma("unroll") for (int n = 0; n < 2; ++n) _Pragma("unroll") for (int k = 0; k < 2; ++k) dst[n][k] = *(const PG8_LAS bf16x8*)(lds + PG8_SB(b, h) + boff + n * 2048 + k * 1024); } while (0)
; #define PG8_MMA(ai, bj, At, Bt) do { __builtin_amdgcn_s_setprio(1); _Pragma("unroll") for (int m = 0; m < 4; ++m) _Pragma("unroll") for (int n = 0; n < 2; ++n) _Pragma("unroll") for (int k = 0; k < 2; ++k) \
;         acc[ai][bj][m][n] = __builtin_amdgcn_mfma_f32_16x16x32_bf16(Bt[n][k], At[m][k], acc[ai][bj][m][n], 0, 0, 0); __builtin_amdgcn_s_setprio(0); } while (0)
; #define PG8_WAIT_V(n) asm volatile("s_waitcnt vmcnt(" #n ")" ::: "memory")
; #define PG8_WAIT_L(n) asm volatile("s_waitcnt lgkmcnt(" #n ")" ::: "memory")
; #define PG8_BAR __builtin_amdgcn_s_barrier()
; #define PG8_SCHED __builtin_amdgcn_sched_barrier(0)
; template <class Epi, class Sched, bool ALIGN_EPI = false, bool SP2 = false>
; __device__ __forceinline__ void gemm_phase(PG8_LAS unsigned char* lds, const Gemm g, const Sched& S, const Epi& E, const int tid) {
;     ...
;             PG8_LDB(B0, 0, 0); PG8_LDB(B1, 0, 1); PG8_SCHED; PG8_LDA(At, 0, 0); PG8_STAGE(PG8_SA(1, 1), a1 + hstep, voffA);
;             PG8_WAIT_V(8); PG8_WAIT_L(0); PG8_BAR; PG8_MMA(0, 0, At, B0); PG8_MMA(0, 1, At, B1); PG8_BAR; PG8_SCHED;
;             PG8_LDA(At, 0, 1); PG8_STAGE(PG8_SB(0, 0), b2, voffB); PG8_STAGE(PG8_SB(0, 1), b2 + hstep, voffB); PG8_STAGE(PG8_SA(0, 0), a2, voffA);
;             PG8_WAIT_V(8); PG8_WAIT_L(0); PG8_BAR; PG8_MMA(1, 0, At, B0); PG8_MMA(1, 1, At, B1); PG8_BAR; PG8_SCHED;
.Lmy_nobar_1316:
	s_add_u32 s44, s42, 0xfff80080
	s_addc_u32 s45, s43, -1
	s_add_i32 s74, 0, 0x10000
	v_add_u32_e32 v132, s74, v252
	v_add_u32_e32 v156, s33, v252
	ds_read_b128 v[116:119], v132
	ds_read_b128 v[124:127], v132 offset:1024
	ds_read_b128 v[128:131], v132 offset:2048
	ds_read_b128 v[132:135], v132 offset:3072
	ds_read_b128 v[144:147], v156
	ds_read_b128 v[148:151], v156 offset:1024
	ds_read_b128 v[152:155], v156 offset:2048
	ds_read_b128 v[156:159], v156 offset:3072
	s_cmp_eq_u32 s73, 28
	s_cselect_b32 s47, s31, s45
	s_cselect_b32 s46, s39, s44
	s_cselect_b32 s45, s29, s72
	s_cselect_b32 s44, s41, s71
	v_lshl_add_u64 v[192:193], s[42:43], 0, v[220:221]
	s_add_i32 m0, s55, 0xc000
	ds_read_b128 v[160:163], v210
	ds_read_b128 v[164:167], v210 offset:1024
	ds_read_b128 v[168:171], v210 offset:2048
	ds_read_b128 v[172:175], v210 offset:3072
	ds_read_b128 v[176:179], v210 offset:4096
	ds_read_b128 v[180:183], v210 offset:5120
	ds_read_b128 v[184:187], v210 offset:6144
	ds_read_b128 v[188:191], v210 offset:7168
	global_load_lds_dwordx4 v[192:193], off
	v_lshl_add_u64 v[192:193], s[42:43], 0, v[222:223]
	s_add_i32 m0, s55, 0xe000
	s_nop 0
	global_load_lds_dwordx4 v[192:193], off
	s_waitcnt vmcnt(8)
	s_waitcnt lgkmcnt(0)
	s_barrier
	s_setprio 1
	s_waitcnt lgkmcnt(0)
	v_mfma_f32_16x16x32_bf16 v[140:143], v[116:119], v[160:163], 0
	v_mfma_f32_16x16x32_bf16 v[136:139], v[128:131], v[160:163], 0
	v_mfma_f32_16x16x32_bf16 v[108:111], v[116:119], v[168:171], 0
	v_mfma_f32_16x16x32_bf16 v[104:107], v[128:131], v[168:171], 0
	v_mfma_f32_16x16x32_bf16 v[92:95], v[116:119], v[176:179], 0
	v_mfma_f32_16x16x32_bf16 v[88:91], v[128:131], v[176:179], 0
	v_mfma_f32_16x16x32_bf16 v[76:79], v[116:119], v[184:187], 0
	v_mfma_f32_16x16x32_bf16 v[72:75], v[128:131], v[184:187], 0
	v_mfma_f32_16x16x32_bf16 v[140:143], v[124:127], v[164:167], v[140:143]
	v_mfma_f32_16x16x32_bf16 v[136:139], v[132:135], v[164:167], v[136:139]
	v_mfma_f32_16x16x32_bf16 v[108:111], v[124:127], v[172:175], v[108:111]
	v_mfma_f32_16x16x32_bf16 v[104:107], v[132:135], v[172:175], v[104:107]
	v_mfma_f32_16x16x32_bf16 v[92:95], v[124:127], v[180:183], v[92:95]
	v_mfma_f32_16x16x32_bf16 v[88:91], v[132:135], v[180:183], v[88:91]
	v_mfma_f32_16x16x32_bf16 v[76:79], v[124:127], v[188:191], v[76:79]
	v_mfma_f32_16x16x32_bf16 v[72:75], v[132:135], v[188:191], v[72:75]
	v_mfma_f32_16x16x32_bf16 v[120:123], v[144:147], v[160:163], 0
	v_mfma_f32_16x16x32_bf16 v[112:115], v[152:155], v[160:163], 0
	v_mfma_f32_16x16x32_bf16 v[100:103], v[144:147], v[168:171], 0
	v_mfma_f32_16x16x32_bf16 v[96:99], v[152:155], v[168:171], 0
	v_mfma_f32_16x16x32_bf16 v[84:87], v[144:147], v[176:179], 0
	v_mfma_f32_16x16x32_bf16 v[80:83], v[152:155], v[176:179], 0
	v_mfma_f32_16x16x32_bf16 v[68:71], v[144:147], v[184:187], 0
	v_mfma_f32_16x16x32_bf16 v[64:67], v[152:155], v[184:187], 0
	v_mfma_f32_16x16x32_bf16 v[120:123], v[148:151], v[164:167], v[120:123]
	v_mfma_f32_16x16x32_bf16 v[112:115], v[156:159], v[164:167], v[112:115]
	v_mfma_f32_16x16x32_bf16 v[100:103], v[148:151], v[172:175], v[100:103]
	v_mfma_f32_16x16x32_bf16 v[96:99], v[156:159], v[172:175], v[96:99]
	v_mfma_f32_16x16x32_bf16 v[84:87], v[148:151], v[180:183], v[84:87]
	v_mfma_f32_16x16x32_bf16 v[80:83], v[156:159], v[180:183], v[80:83]
	v_mfma_f32_16x16x32_bf16 v[68:71], v[148:151], v[188:191], v[68:71]
	v_mfma_f32_16x16x32_bf16 v[64:67], v[156:159], v[188:191], v[64:67]
	s_setprio 0
	s_barrier
	s_add_i32 s74, s74, s54
	v_lshl_add_u64 v[192:193], s[44:45], 0, v[208:209]
	s_mov_b32 m0, s74
	ds_read_b128 v[160:163], v210 offset:16384
	ds_read_b128 v[164:167], v210 offset:17408
	ds_read_b128 v[168:171], v210 offset:18432
	ds_read_b128 v[172:175], v210 offset:19456
	ds_read_b128 v[176:179], v210 offset:20480
	ds_read_b128 v[180:183], v210 offset:21504
	ds_read_b128 v[184:187], v210 offset:22528
	ds_read_b128 v[188:191], v210 offset:23552
	global_load_lds_dwordx4 v[192:193], off
	s_add_i32 m0, s74, 0x2000
	s_add_u32 s74, s44, 0x80000
	v_lshl_add_u64 v[194:195], s[44:45], 0, v[218:219]
	s_addc_u32 s75, s45, 0
	s_add_i32 s76, s33, s54
	global_load_lds_dwordx4 v[194:195], off
	v_lshl_add_u64 v[196:197], s[74:75], 0, v[208:209]
	s_mov_b32 m0, s76
	v_lshl_add_u64 v[198:199], s[46:47], 0, v[216:217]
	global_load_lds_dwordx4 v[196:197], off
	v_lshl_add_u64 v[196:197], s[74:75], 0, v[218:219]
	s_add_i32 m0, s76, 0x2000
	s_nop 0
	global_load_lds_dwordx4 v[196:197], off
	v_lshl_add_u64 v[196:197], s[46:47], 0, v[214:215]
	s_mov_b32 m0, s55
	s_nop 0
	global_load_lds_dwordx4 v[196:197], off
	s_mov_b32 m0, s56
	s_nop 0
	global_load_lds_dwordx4 v[198:199], off
	s_waitcnt vmcnt(8)
	s_waitcnt lgkmcnt(0)
	s_barrier
	s_setprio 1
	s_waitcnt lgkmcnt(0)
	v_mfma_f32_16x16x32_bf16 v[60:63], v[116:119], v[160:163], 0
	v_mfma_f32_16x16x32_bf16 v[56:59], v[128:131], v[160:163], 0
	v_mfma_f32_16x16x32_bf16 v[44:47], v[116:119], v[168:171], 0
	v_mfma_f32_16x16x32_bf16 v[40:43], v[128:131], v[168:171], 0
	v_mfma_f32_16x16x32_bf16 v[28:31], v[116:119], v[176:179], 0
	v_mfma_f32_16x16x32_bf16 v[24:27], v[128:131], v[176:179], 0
	v_mfma_f32_16x16x32_bf16 v[12:15], v[116:119], v[184:187], 0
	v_mfma_f32_16x16x32_bf16 v[8:11], v[128:131], v[184:187], 0
	v_mfma_f32_16x16x32_bf16 v[60:63], v[124:127], v[164:167], v[60:63]
	v_mfma_f32_16x16x32_bf16 v[56:59], v[132:135], v[164:167], v[56:59]
	v_mfma_f32_16x16x32_bf16 v[44:47], v[124:127], v[172:175], v[44:47]
	v_mfma_f32_16x16x32_bf16 v[40:43], v[132:135], v[172:175], v[40:43]
	v_mfma_f32_16x16x32_bf16 v[28:31], v[124:127], v[180:183], v[28:31]
	v_mfma_f32_16x16x32_bf16 v[24:27], v[132:135], v[180:183], v[24:27]
	v_mfma_f32_16x16x32_bf16 v[12:15], v[124:127], v[188:191], v[12:15]
	v_mfma_f32_16x16x32_bf16 v[8:11], v[132:135], v[188:191], v[8:11]
	v_mfma_f32_16x16x32_bf16 v[52:55], v[144:147], v[160:163], 0
	v_mfma_f32_16x16x32_bf16 v[48:51], v[152:155], v[160:163], 0
	v_mfma_f32_16x16x32_bf16 v[36:39], v[144:147], v[168:171], 0
	v_mfma_f32_16x16x32_bf16 v[32:35], v[152:155], v[168:171], 0
	v_mfma_f32_16x16x32_bf16 v[20:23], v[144:147], v[176:179], 0
	v_mfma_f32_16x16x32_bf16 v[16:19], v[152:155], v[176:179], 0
	v_mfma_f32_16x16x32_bf16 v[4:7], v[144:147], v[184:187], 0
	v_mfma_f32_16x16x32_bf16 v[0:3], v[152:155], v[184:187], 0
	v_mfma_f32_16x16x32_bf16 v[52:55], v[148:151], v[164:167], v[52:55]
	v_mfma_f32_16x16x32_bf16 v[48:51], v[156:159], v[164:167], v[48:51]
	v_mfma_f32_16x16x32_bf16 v[36:39], v[148:151], v[172:175], v[36:39]
	v_mfma_f32_16x16x32_bf16 v[32:35], v[156:159], v[172:175], v[32:35]
	v_mfma_f32_16x16x32_bf16 v[20:23], v[148:151], v[180:183], v[20:23]
	v_mfma_f32_16x16x32_bf16 v[16:19], v[156:159], v[180:183], v[16:19]
	v_mfma_f32_16x16x32_bf16 v[4:7], v[148:151], v[188:191], v[4:7]
	v_mfma_f32_16x16x32_bf16 v[0:3], v[156:159], v[188:191], v[0:3]
	s_setprio 0
	s_barrier
	s_branch .Lmy_mid_1316
; #define PG8_STAGE(bufoff, gbase, voff) do { _Pragma("unroll") for (int _i = 0; _i < 2; ++_i) \
;         __builtin_amdgcn_global_load_lds((const unsigned*)((const char*)(gbase) + (voff)[_i]), (PG8_LAS unsigned*)(lds + (bufoff) + ldsw + _i * 8192), 16, 0, 0); } while (0)
; #define PG8_LDA(dst, b, h) do { _Pragma("unroll") for (int m = 0; m < 4; ++m) _Pragma("unroll") for (int k = 0; k < 2; ++k) dst[m][k] = *(const PG8_LAS bf16x8*)(lds + PG8_SA(b, h) + aoff + m * 2048 + k * 1024); } while (0)
; #define PG8_LDB(dst, b, h) do { _Pragma("unroll") for (int n = 0; n < 2; ++n) _Pragma("unroll") for (int k = 0; k < 2; ++k) dst[n][k] = *(const PG8_LAS bf16x8*)(lds + PG8_SB(b, h) + boff + n * 2048 + k * 1024); } while (0)
; #define PG8_MMA(ai, bj, At, Bt) do { __builtin_amdgcn_s_setprio(1); _Pragma("unroll") for (int m = 0; m < 4; ++m) _Pragma("unroll") for (int n = 0; n < 2; ++n) _Pragma("unroll") for (int k = 0; k < 2; ++k) \
;         acc[ai][bj][m][n] = __builtin_amdgcn_mfma_f32_16x16x32_bf16(Bt[n][k], At[m][k], acc[ai][bj][m][n], 0, 0, 0); __builtin_amdgcn_s_setprio(0); } while (0)
; #define PG8_WAIT_V(n) asm volatile("s_waitcnt vmcnt(" #n ")" ::: "memory")
; #define PG8_WAIT_L(n) asm volatile("s_waitcnt lgkmcnt(" #n ")" ::: "memory")
; #define PG8_BAR __builtin_amdgcn_s_barrier()
; #define PG8_SCHED __builtin_amdgcn_sched_barrier(0)
; template <class Epi, class Sched, bool ALIGN_EPI = false, bool SP2 = false>
; __device__ __forceinline__ void gemm_phase(PG8_LAS unsigned char* lds, const Gemm g, const Sched& S, const Epi& E, const int tid) {
;     ...
;             PG8_LDB(B0, 0, 0); PG8_LDB(B1, 0, 1); PG8_SCHED; PG8_LDA(At, 0, 0); PG8_STAGE(PG8_SA(1, 1), a1 + hstep, voffA);
;             PG8_WAIT_V(8); PG8_WAIT_L(0); PG8_BAR; PG8_MMA(0, 0, At, B0); PG8_MMA(0, 1, At, B1); PG8_BAR; PG8_SCHED;
;             PG8_LDA(At, 0, 1); PG8_STAGE(PG8_SB(0, 0), b2, voffB); PG8_STAGE(PG8_SB(0, 1), b2 + hstep, voffB); PG8_STAGE(PG8_SA(0, 0), a2, voffA);
;             PG8_WAIT_V(8); PG8_WAIT_L(0); PG8_BAR; PG8_MMA(1, 0, At, B0); PG8_MMA(1, 1, At, B1); PG8_BAR; PG8_SCHED;
.LBB0_1316:
	s_add_u32 s44, s42, 0xfff80080
	s_addc_u32 s45, s43, -1
	s_add_i32 s74, 0, 0x10000
	v_add_u32_e32 v132, s74, v252
	v_add_u32_e32 v156, s33, v252
	ds_read_b128 v[116:119], v132
	ds_read_b128 v[124:127], v132 offset:1024
	ds_read_b128 v[128:131], v132 offset:2048
	ds_read_b128 v[132:135], v132 offset:3072
	ds_read_b128 v[144:147], v156
	ds_read_b128 v[148:151], v156 offset:1024
	ds_read_b128 v[152:155], v156 offset:2048
	ds_read_b128 v[156:159], v156 offset:3072
	s_cmp_eq_u32 s73, 28
	s_cselect_b32 s47, s31, s45
	s_cselect_b32 s46, s39, s44
	s_cselect_b32 s45, s29, s72
	s_cselect_b32 s44, s41, s71
	v_lshl_add_u64 v[192:193], s[42:43], 0, v[220:221]
	s_add_i32 m0, s55, 0xc000
	ds_read_b128 v[160:163], v210
	ds_read_b128 v[164:167], v210 offset:1024
	ds_read_b128 v[168:171], v210 offset:2048
	ds_read_b128 v[172:175], v210 offset:3072
	ds_read_b128 v[176:179], v210 offset:4096
	ds_read_b128 v[180:183], v210 offset:5120
	ds_read_b128 v[184:187], v210 offset:6144
	ds_read_b128 v[188:191], v210 offset:7168
	global_load_lds_dwordx4 v[192:193], off
	v_lshl_add_u64 v[192:193], s[42:43], 0, v[222:223]
	s_add_i32 m0, s55, 0xe000
	s_nop 0
	global_load_lds_dwordx4 v[192:193], off
	s_waitcnt vmcnt(8)
	s_waitcnt lgkmcnt(0)
	s_barrier
	s_setprio 1
	s_waitcnt lgkmcnt(0)
	v_mfma_f32_16x16x32_bf16 v[140:143], v[116:119], v[160:163], v[140:143]
	v_mfma_f32_16x16x32_bf16 v[136:139], v[128:131], v[160:163], v[136:139]
	v_mfma_f32_16x16x32_bf16 v[108:111], v[116:119], v[168:171], v[108:111]
	v_mfma_f32_16x16x32_bf16 v[104:107], v[128:131], v[168:171], v[104:107]
	v_mfma_f32_16x16x32_bf16 v[92:95], v[116:119], v[176:179], v[92:95]
	v_mfma_f32_16x16x32_bf16 v[88:91], v[128:131], v[176:179], v[88:91]
	v_mfma_f32_16x16x32_bf16 v[76:79], v[116:119], v[184:187], v[76:79]
	v_mfma_f32_16x16x32_bf16 v[72:75], v[128:131], v[184:187], v[72:75]
	v_mfma_f32_16x16x32_bf16 v[140:143], v[124:127], v[164:167], v[140:143]
	v_mfma_f32_16x16x32_bf16 v[136:139], v[132:135], v[164:167], v[136:139]
	v_mfma_f32_16x16x32_bf16 v[108:111], v[124:127], v[172:175], v[108:111]
	v_mfma_f32_16x16x32_bf16 v[104:107], v[132:135], v[172:175], v[104:107]
	v_mfma_f32_16x16x32_bf16 v[92:95], v[124:127], v[180:183], v[92:95]
	v_mfma_f32_16x16x32_bf16 v[88:91], v[132:135], v[180:183], v[88:91]
	v_mfma_f32_16x16x32_bf16 v[76:79], v[124:127], v[188:191], v[76:79]
	v_mfma_f32_16x16x32_bf16 v[72:75], v[132:135], v[188:191], v[72:75]
	v_mfma_f32_16x16x32_bf16 v[120:123], v[144:147], v[160:163], v[120:123]
	v_mfma_f32_16x16x32_bf16 v[112:115], v[152:155], v[160:163], v[112:115]
	v_mfma_f32_16x16x32_bf16 v[100:103], v[144:147], v[168:171], v[100:103]
	v_mfma_f32_16x16x32_bf16 v[96:99], v[152:155], v[168:171], v[96:99]
	v_mfma_f32_16x16x32_bf16 v[84:87], v[144:147], v[176:179], v[84:87]
	v_mfma_f32_16x16x32_bf16 v[80:83], v[152:155], v[176:179], v[80:83]
	v_mfma_f32_16x16x32_bf16 v[68:71], v[144:147], v[184:187], v[68:71]
	v_mfma_f32_16x16x32_bf16 v[64:67], v[152:155], v[184:187], v[64:67]
	v_mfma_f32_16x16x32_bf16 v[120:123], v[148:151], v[164:167], v[120:123]
	v_mfma_f32_16x16x32_bf16 v[112:115], v[156:159], v[164:167], v[112:115]
	v_mfma_f32_16x16x32_bf16 v[100:103], v[148:151], v[172:175], v[100:103]
	v_mfma_f32_16x16x32_bf16 v[96:99], v[156:159], v[172:175], v[96:99]
	v_mfma_f32_16x16x32_bf16 v[84:87], v[148:151], v[180:183], v[84:87]
	v_mfma_f32_16x16x32_bf16 v[80:83], v[156:159], v[180:183], v[80:83]
	v_mfma_f32_16x16x32_bf16 v[68:71], v[148:151], v[188:191], v[68:71]
	v_mfma_f32_16x16x32_bf16 v[64:67], v[156:159], v[188:191], v[64:67]
	s_setprio 0
	s_barrier
	s_add_i32 s74, s74, s54
	v_lshl_add_u64 v[192:193], s[44:45], 0, v[208:209]
	s_mov_b32 m0, s74
	ds_read_b128 v[160:163], v210 offset:16384
	ds_read_b128 v[164:167], v210 offset:17408
	ds_read_b128 v[168:171], v210 offset:18432
	ds_read_b128 v[172:175], v210 offset:19456
	ds_read_b128 v[176:179], v210 offset:20480
	ds_read_b128 v[180:183], v210 offset:21504
	ds_read_b128 v[184:187], v210 offset:22528
	ds_read_b128 v[188:191], v210 offset:23552
	global_load_lds_dwordx4 v[192:193], off
	s_add_i32 m0, s74, 0x2000
	s_add_u32 s74, s44, 0x80000
	v_lshl_add_u64 v[194:195], s[44:45], 0, v[218:219]
	s_addc_u32 s75, s45, 0
	s_add_i32 s76, s33, s54
	global_load_lds_dwordx4 v[194:195], off
	v_lshl_add_u64 v[196:197], s[74:75], 0, v[208:209]
	s_mov_b32 m0, s76
	v_lshl_add_u64 v[198:199], s[46:47], 0, v[216:217]
	global_load_lds_dwordx4 v[196:197], off
	v_lshl_add_u64 v[196:197], s[74:75], 0, v[218:219]
	s_add_i32 m0, s76, 0x2000
	s_nop 0
	global_load_lds_dwordx4 v[196:197], off
	v_lshl_add_u64 v[196:197], s[46:47], 0, v[214:215]
	s_mov_b32 m0, s55
	s_nop 0
	global_load_lds_dwordx4 v[196:197], off
	s_mov_b32 m0, s56
	s_nop 0
	global_load_lds_dwordx4 v[198:199], off
	s_waitcnt vmcnt(8)
	s_waitcnt lgkmcnt(0)
	s_barrier
	s_setprio 1
	s_waitcnt lgkmcnt(0)
	v_mfma_f32_16x16x32_bf16 v[60:63], v[116:119], v[160:163], v[60:63]
	v_mfma_f32_16x16x32_bf16 v[56:59], v[128:131], v[160:163], v[56:59]
	v_mfma_f32_16x16x32_bf16 v[44:47], v[116:119], v[168:171], v[44:47]
	v_mfma_f32_16x16x32_bf16 v[40:43], v[128:131], v[168:171], v[40:43]
	v_mfma_f32_16x16x32_bf16 v[28:31], v[116:119], v[176:179], v[28:31]
	v_mfma_f32_16x16x32_bf16 v[24:27], v[128:131], v[176:179], v[24:27]
	v_mfma_f32_16x16x32_bf16 v[12:15], v[116:119], v[184:187], v[12:15]
	v_mfma_f32_16x16x32_bf16 v[8:11], v[128:131], v[184:187], v[8:11]
	v_mfma_f32_16x16x32_bf16 v[60:63], v[124:127], v[164:167], v[60:63]
	v_mfma_f32_16x16x32_bf16 v[56:59], v[132:135], v[164:167], v[56:59]
	v_mfma_f32_16x16x32_bf16 v[44:47], v[124:127], v[172:175], v[44:47]
	v_mfma_f32_16x16x32_bf16 v[40:43], v[132:135], v[172:175], v[40:43]
	v_mfma_f32_16x16x32_bf16 v[28:31], v[124:127], v[180:183], v[28:31]
	v_mfma_f32_16x16x32_bf16 v[24:27], v[132:135], v[180:183], v[24:27]
	v_mfma_f32_16x16x32_bf16 v[12:15], v[124:127], v[188:191], v[12:15]
	v_mfma_f32_16x16x32_bf16 v[8:11], v[132:135], v[188:191], v[8:11]
	v_mfma_f32_16x16x32_bf16 v[52:55], v[144:147], v[160:163], v[52:55]
	v_mfma_f32_16x16x32_bf16 v[48:51], v[152:155], v[160:163], v[48:51]
	v_mfma_f32_16x16x32_bf16 v[36:39], v[144:147], v[168:171], v[36:39]
	v_mfma_f32_16x16x32_bf16 v[32:35], v[152:155], v[168:171], v[32:35]
	v_mfma_f32_16x16x32_bf16 v[20:23], v[144:147], v[176:179], v[20:23]
	v_mfma_f32_16x16x32_bf16 v[16:19], v[152:155], v[176:179], v[16:19]
	v_mfma_f32_16x16x32_bf16 v[4:7], v[144:147], v[184:187], v[4:7]
	v_mfma_f32_16x16x32_bf16 v[0:3], v[152:155], v[184:187], v[0:3]
	v_mfma_f32_16x16x32_bf16 v[52:55], v[148:151], v[164:167], v[52:55]
	v_mfma_f32_16x16x32_bf16 v[48:51], v[156:159], v[164:167], v[48:51]
	v_mfma_f32_16x16x32_bf16 v[36:39], v[148:151], v[172:175], v[36:39]
	v_mfma_f32_16x16x32_bf16 v[32:35], v[156:159], v[172:175], v[32:35]
	v_mfma_f32_16x16x32_bf16 v[20:23], v[148:151], v[180:183], v[20:23]
	v_mfma_f32_16x16x32_bf16 v[16:19], v[156:159], v[180:183], v[16:19]
	v_mfma_f32_16x16x32_bf16 v[4:7], v[148:151], v[188:191], v[4:7]
	v_mfma_f32_16x16x32_bf16 v[0:3], v[156:159], v[188:191], v[0:3]
	s_setprio 0
	s_barrier
; #define PG8_STAGE(bufoff, gbase, voff) do { _Pragma("unroll") for (int _i = 0; _i < 2; ++_i) \
;         __builtin_amdgcn_global_load_lds((const unsigned*)((const char*)(gbase) + (voff)[_i]), (PG8_LAS unsigned*)(lds + (bufoff) + ldsw + _i * 8192), 16, 0, 0); } while (0)
; #define PG8_LDA(dst, b, h) do { _Pragma("unroll") for (int m = 0; m < 4; ++m) _Pragma("unroll") for (int k = 0; k < 2; ++k) dst[m][k] = *(const PG8_LAS bf16x8*)(lds + PG8_SA(b, h) + aoff + m * 2048 + k * 1024); } while (0)
; #define PG8_LDB(dst, b, h) do { _Pragma("unroll") for (int n = 0; n < 2; ++n) _Pragma("unroll") for (int k = 0; k < 2; ++k) dst[n][k] = *(const PG8_LAS bf16x8*)(lds + PG8_SB(b, h) + boff + n * 2048 + k * 1024); } while (0)
; #define PG8_MMA(ai, bj, At, Bt) do { __builtin_amdgcn_s_setprio(1); _Pragma("unroll") for (int m = 0; m < 4; ++m) _Pragma("unroll") for (int n = 0; n < 2; ++n) _Pragma("unroll") for (int k = 0; k < 2; ++k) \
;         acc[ai][bj][m][n] = __builtin_amdgcn_mfma_f32_16x16x32_bf16(Bt[n][k], At[m][k], acc[ai][bj][m][n], 0, 0, 0); __builtin_amdgcn_s_setprio(0); } while (0)
; #define PG8_WAIT_V(n) asm volatile("s_waitcnt vmcnt(" #n ")" ::: "memory")
; #define PG8_WAIT_L(n) asm volatile("s_waitcnt lgkmcnt(" #n ")" ::: "memory")
; #define PG8_BAR __builtin_amdgcn_s_barrier()
; #define PG8_SCHED __builtin_amdgcn_sched_barrier(0)
; template <class Epi, class Sched, bool ALIGN_EPI = false, bool SP2 = false>
; __device__ __forceinline__ void gemm_phase(PG8_LAS unsigned char* lds, const Gemm g, const Sched& S, const Epi& E, const int tid) {
;     ...
;             PG8_LDB(B0, 1, 0); PG8_LDB(B1, 1, 1); PG8_SCHED; PG8_LDA(At, 1, 0); PG8_STAGE(PG8_SA(0, 1), a2 + hstep, voffA);
;             PG8_WAIT_V(8); PG8_WAIT_L(0); PG8_BAR; PG8_MMA(0, 0, At, B0); PG8_MMA(0, 1, At, B1); PG8_BAR; PG8_SCHED;
.Lmy_mid_1316:
	s_add_i32 s74, 0, 0x18000
	s_add_i32 s75, 0, 0x1c000
	v_add_u32_e32 v132, s74, v252
	v_add_u32_e32 v156, s75, v252
	ds_read_b128 v[116:119], v132
	ds_read_b128 v[124:127], v132 offset:1024
	ds_read_b128 v[128:131], v132 offset:2048
	ds_read_b128 v[132:135], v132 offset:3072
	ds_read_b128 v[144:147], v156
	ds_read_b128 v[148:151], v156 offset:1024
	ds_read_b128 v[152:155], v156 offset:2048
	ds_read_b128 v[156:159], v156 offset:3072
	s_add_u32 s46, s46, 0x80000
	s_addc_u32 s47, s47, 0
	s_mov_b32 m0, s57
	v_lshl_add_u64 v[200:201], s[46:47], 0, v[214:215]
	ds_read_b128 v[160:163], v210 offset:32768
	ds_read_b128 v[164:167], v210 offset:33792
	ds_read_b128 v[168:171], v210 offset:34816
	ds_read_b128 v[172:175], v210 offset:35840
	ds_read_b128 v[176:179], v210 offset:36864
	ds_read_b128 v[180:183], v210 offset:37888
	ds_read_b128 v[184:187], v210 offset:38912
	ds_read_b128 v[188:191], v210 offset:39936
	global_load_lds_dwordx4 v[200:201], off
	v_lshl_add_u64 v[200:201], s[46:47], 0, v[216:217]
	s_mov_b32 m0, s58
	s_nop 0
	global_load_lds_dwordx4 v[200:201], off
	s_waitcnt vmcnt(8)
	s_waitcnt lgkmcnt(0)
	s_barrier
	s_setprio 1
	s_waitcnt lgkmcnt(0)
	v_mfma_f32_16x16x32_bf16 v[140:143], v[116:119], v[160:163], v[140:143]
	v_mfma_f32_16x16x32_bf16 v[136:139], v[128:131], v[160:163], v[136:139]
	v_mfma_f32_16x16x32_bf16 v[108:111], v[116:119], v[168:171], v[108:111]
	v_mfma_f32_16x16x32_bf16 v[104:107], v[128:131], v[168:171], v[104:107]
	v_mfma_f32_16x16x32_bf16 v[92:95], v[116:119], v[176:179], v[92:95]
	v_mfma_f32_16x16x32_bf16 v[88:91], v[128:131], v[176:179], v[88:91]
	v_mfma_f32_16x16x32_bf16 v[76:79], v[116:119], v[184:187], v[76:79]
	v_mfma_f32_16x16x32_bf16 v[72:75], v[128:131], v[184:187], v[72:75]
	v_mfma_f32_16x16x32_bf16 v[140:143], v[124:127], v[164:167], v[140:143]
	v_mfma_f32_16x16x32_bf16 v[136:139], v[132:135], v[164:167], v[136:139]
	v_mfma_f32_16x16x32_bf16 v[108:111], v[124:127], v[172:175], v[108:111]
	v_mfma_f32_16x16x32_bf16 v[104:107], v[132:135], v[172:175], v[104:107]
	v_mfma_f32_16x16x32_bf16 v[92:95], v[124:127], v[180:183], v[92:95]
	v_mfma_f32_16x16x32_bf16 v[88:91], v[132:135], v[180:183], v[88:91]
	v_mfma_f32_16x16x32_bf16 v[76:79], v[124:127], v[188:191], v[76:79]
	v_mfma_f32_16x16x32_bf16 v[72:75], v[132:135], v[188:191], v[72:75]
	v_mfma_f32_16x16x32_bf16 v[120:123], v[144:147], v[160:163], v[120:123]
	v_mfma_f32_16x16x32_bf16 v[112:115], v[152:155], v[160:163], v[112:115]
	v_mfma_f32_16x16x32_bf16 v[100:103], v[144:147], v[168:171], v[100:103]
	v_mfma_f32_16x16x32_bf16 v[96:99], v[152:155], v[168:171], v[96:99]
	v_mfma_f32_16x16x32_bf16 v[84:87], v[144:147], v[176:179], v[84:87]
	v_mfma_f32_16x16x32_bf16 v[80:83], v[152:155], v[176:179], v[80:83]
	v_mfma_f32_16x16x32_bf16 v[68:71], v[144:147], v[184:187], v[68:71]
	v_mfma_f32_16x16x32_bf16 v[64:67], v[152:155], v[184:187], v[64:67]
	v_mfma_f32_16x16x32_bf16 v[120:123], v[148:151], v[164:167], v[120:123]
	v_mfma_f32_16x16x32_bf16 v[112:115], v[156:159], v[164:167], v[112:115]
	v_mfma_f32_16x16x32_bf16 v[100:103], v[148:151], v[172:175], v[100:103]
	v_mfma_f32_16x16x32_bf16 v[96:99], v[156:159], v[172:175], v[96:99]
	v_mfma_f32_16x16x32_bf16 v[84:87], v[148:151], v[180:183], v[84:87]
	v_mfma_f32_16x16x32_bf16 v[80:83], v[156:159], v[180:183], v[80:83]
	v_mfma_f32_16x16x32_bf16 v[68:71], v[148:151], v[188:191], v[68:71]
	v_mfma_f32_16x16x32_bf16 v[64:67], v[156:159], v[188:191], v[64:67]
	s_setprio 0
	s_barrier
; #define PG8_STAGE(bufoff, gbase, voff) do { _Pragma("unroll") for (int _i = 0; _i < 2; ++_i) \
;         __builtin_amdgcn_global_load_lds((const unsigned*)((const char*)(gbase) + (voff)[_i]), (PG8_LAS unsigned*)(lds + (bufoff) + ldsw + _i * 8192), 16, 0, 0); } while (0)
; #define PG8_LDA(dst, b, h) do { _Pragma("unroll") for (int m = 0; m < 4; ++m) _Pragma("unroll") for (int k = 0; k < 2; ++k) dst[m][k] = *(const PG8_LAS bf16x8*)(lds + PG8_SA(b, h) + aoff + m * 2048 + k * 1024); } while (0)
; #define PG8_MMA(ai, bj, At, Bt) do { __builtin_amdgcn_s_setprio(1); _Pragma("unroll") for (int m = 0; m < 4; ++m) _Pragma("unroll") for (int n = 0; n < 2; ++n) _Pragma("unroll") for (int k = 0; k < 2; ++k) \
;         acc[ai][bj][m][n] = __builtin_amdgcn_mfma_f32_16x16x32_bf16(Bt[n][k], At[m][k], acc[ai][bj][m][n], 0, 0, 0); __builtin_amdgcn_s_setprio(0); } while (0)
; #define PG8_WAIT_V(n) asm volatile("s_waitcnt vmcnt(" #n ")" ::: "memory")
; #define PG8_WAIT_L(n) asm volatile("s_waitcnt lgkmcnt(" #n ")" ::: "memory")
; #define PG8_BAR __builtin_amdgcn_s_barrier()
; #define PG8_SCHED __builtin_amdgcn_sched_barrier(0)
; template <class Epi, class Sched, bool ALIGN_EPI = false, bool SP2 = false>
; __device__ __forceinline__ void gemm_phase(PG8_LAS unsigned char* lds, const Gemm g, const Sched& S, const Epi& E, const int tid) {
;     ...
;             PG8_LDA(At, 1, 1); PG8_STAGE(PG8_SB(1, 0), b3, voffB); PG8_STAGE(PG8_SB(1, 1), b3 + hstep, voffB); PG8_STAGE(PG8_SA(1, 0), a3, voffA);
;             PG8_WAIT_V(8); PG8_WAIT_L(0); PG8_BAR; PG8_MMA(1, 0, At, B0); PG8_MMA(1, 1, At, B1); PG8_BAR; PG8_SCHED;
;     __device__ __forceinline__ void operator()(const f32x4 (&acc)[2][2][4][2], const Unit& un, int wr, int wc, int fr_, int fq_) const {
;         const int ln_ = lane_fresh(), fr = ln_ & 15, fq = ln_ >> 4; (void)fr_; (void)fq_;
;         const int rbase = un.pm * 256 + wr * 64 + fr, cw = un.pn * 256 + wc * 32 + 8 * fq;
;         const bool lat = un.pm < (NLAT / 256);
;         const int slot = lat ? (un.pm >> 5) : 4;
;         const float* src = lat ? srcl : srcc; float* dst = lat ? dstl : dstc; const int radj = lat ? 0 : NLAT;
;         const float* gp = modg + (size_t)slot * 12288; const float* sp2 = sc2 + (size_t)slot * 12288;
	s_add_i32 s46, s74, s54
	v_lshl_add_u64 v[192:193], v[192:193], 0, s[2:3]
	s_mov_b32 m0, s46
	ds_read_b128 v[160:163], v210 offset:49152
	ds_read_b128 v[164:167], v210 offset:50176
	ds_read_b128 v[168:171], v210 offset:51200
	ds_read_b128 v[172:175], v210 offset:52224
	ds_read_b128 v[176:179], v210 offset:53248
	ds_read_b128 v[180:183], v210 offset:54272
	ds_read_b128 v[184:187], v210 offset:55296
	ds_read_b128 v[188:191], v210 offset:56320
	global_load_lds_dwordx4 v[192:193], off
	s_add_i32 m0, s46, 0x2000
	s_add_u32 s44, s44, 0x80080
	v_lshl_add_u64 v[192:193], v[194:195], 0, s[2:3]
	s_addc_u32 s45, s45, 0
	s_add_i32 s46, s75, s54
	global_load_lds_dwordx4 v[192:193], off
	v_lshl_add_u64 v[192:193], s[44:45], 0, v[208:209]
	s_mov_b32 m0, s46
	s_nop 0
	global_load_lds_dwordx4 v[192:193], off
	v_lshl_add_u64 v[192:193], s[44:45], 0, v[218:219]
	s_add_i32 m0, s46, 0x2000
	s_nop 0
	global_load_lds_dwordx4 v[192:193], off
	v_lshl_add_u64 v[192:193], v[196:197], 0, s[2:3]
	s_mov_b32 m0, s66
	s_nop 0
	global_load_lds_dwordx4 v[192:193], off
	v_lshl_add_u64 v[192:193], v[198:199], 0, s[2:3]
	s_mov_b32 m0, s67
	s_nop 0
	global_load_lds_dwordx4 v[192:193], off
	s_waitcnt vmcnt(8)
	s_waitcnt lgkmcnt(0)
	s_barrier
	s_setprio 1
	s_waitcnt lgkmcnt(0)
	v_mfma_f32_16x16x32_bf16 v[60:63], v[116:119], v[160:163], v[60:63]
	v_mfma_f32_16x16x32_bf16 v[56:59], v[128:131], v[160:163], v[56:59]
	v_mfma_f32_16x16x32_bf16 v[44:47], v[116:119], v[168:171], v[44:47]
	v_mfma_f32_16x16x32_bf16 v[40:43], v[128:131], v[168:171], v[40:43]
	v_mfma_f32_16x16x32_bf16 v[28:31], v[116:119], v[176:179], v[28:31]
	v_mfma_f32_16x16x32_bf16 v[24:27], v[128:131], v[176:179], v[24:27]
	v_mfma_f32_16x16x32_bf16 v[12:15], v[116:119], v[184:187], v[12:15]
	v_mfma_f32_16x16x32_bf16 v[8:11], v[128:131], v[184:187], v[8:11]
	v_mfma_f32_16x16x32_bf16 v[60:63], v[124:127], v[164:167], v[60:63]
	v_mfma_f32_16x16x32_bf16 v[56:59], v[132:135], v[164:167], v[56:59]
	v_mfma_f32_16x16x32_bf16 v[44:47], v[124:127], v[172:175], v[44:47]
	v_mfma_f32_16x16x32_bf16 v[40:43], v[132:135], v[172:175], v[40:43]
	v_mfma_f32_16x16x32_bf16 v[28:31], v[124:127], v[180:183], v[28:31]
	v_mfma_f32_16x16x32_bf16 v[24:27], v[132:135], v[180:183], v[24:27]
	v_mfma_f32_16x16x32_bf16 v[12:15], v[124:127], v[188:191], v[12:15]
	v_mfma_f32_16x16x32_bf16 v[8:11], v[132:135], v[188:191], v[8:11]
	v_mfma_f32_16x16x32_bf16 v[52:55], v[144:147], v[160:163], v[52:55]
	v_mfma_f32_16x16x32_bf16 v[48:51], v[152:155], v[160:163], v[48:51]
	v_mfma_f32_16x16x32_bf16 v[36:39], v[144:147], v[168:171], v[36:39]
	v_mfma_f32_16x16x32_bf16 v[32:35], v[152:155], v[168:171], v[32:35]
	v_mfma_f32_16x16x32_bf16 v[20:23], v[144:147], v[176:179], v[20:23]
	v_mfma_f32_16x16x32_bf16 v[16:19], v[152:155], v[176:179], v[16:19]
	v_mfma_f32_16x16x32_bf16 v[4:7], v[144:147], v[184:187], v[4:7]
	v_mfma_f32_16x16x32_bf16 v[0:3], v[152:155], v[184:187], v[0:3]
	v_mfma_f32_16x16x32_bf16 v[52:55], v[148:151], v[164:167], v[52:55]
	v_mfma_f32_16x16x32_bf16 v[48:51], v[156:159], v[164:167], v[48:51]
	v_mfma_f32_16x16x32_bf16 v[36:39], v[148:151], v[172:175], v[36:39]
	v_mfma_f32_16x16x32_bf16 v[32:35], v[156:159], v[172:175], v[32:35]
	v_mfma_f32_16x16x32_bf16 v[20:23], v[148:151], v[180:183], v[20:23]
	v_mfma_f32_16x16x32_bf16 v[16:19], v[156:159], v[180:183], v[16:19]
	v_mfma_f32_16x16x32_bf16 v[4:7], v[148:151], v[188:191], v[4:7]
	v_mfma_f32_16x16x32_bf16 v[0:3], v[156:159], v[188:191], v[0:3]
	s_setprio 0
	s_barrier
	s_add_i32 s73, s73, 2
	s_add_u32 s42, s42, 0x100
	s_addc_u32 s43, s43, 0
	s_add_u32 s71, s71, 0x100
	s_addc_u32 s72, s72, 0
	s_cmp_gt_u32 s73, 29
	s_cbranch_scc0 .LBB0_1316
	s_cmpk_gt_i32 s40, 0x7f
	s_mov_b32 s71, 0x280000
	s_mov_b32 s72, 0x2c0000
	v_mbcnt_lo_u32_b32 v211, -1, 0
	v_mbcnt_hi_u32_b32 v211, -1, v211
	s_cbranch_scc1 .LBB0_1321
	s_ashr_i32 s29, s40, 5
	s_mul_hi_i32 s47, s29, 0x3000
	s_mul_i32 s46, s29, 0x3000
	s_mov_b32 s29, 0
	s_mov_b64 s[42:43], s[14:15]
	s_mov_b64 s[44:45], s[10:11]
	s_branch .LBB0_1322

; #define PG8_STAGE(bufoff, gbase, voff) do { _Pragma("unroll") for (int _i = 0; _i < 2; ++_i) \
;         __builtin_amdgcn_global_load_lds((const unsigned*)((const char*)(gbase) + (voff)[_i]), (PG8_LAS unsigned*)(lds + (bufoff) + ldsw + _i * 8192), 16, 0, 0); } while (0)
; #define PG8_LDA(dst, b, h) do { _Pragma("unroll") for (int m = 0; m < 4; ++m) _Pragma("unroll") for (int k = 0; k < 2; ++k) dst[m][k] = *(const PG8_LAS bf16x8*)(lds + PG8_SA(b, h) + aoff + m * 2048 + k * 1024); } while (0)
; #define PG8_LDB(dst, b, h) do { _Pragma("unroll") for (int n = 0; n < 2; ++n) _Pragma("unroll") for (int k = 0; k < 2; ++k) dst[n][k] = *(const PG8_LAS bf16x8*)(lds + PG8_SB(b, h) + boff + n * 2048 + k * 1024); } while (0)
; #define PG8_MMA(ai, bj, At, Bt) do { __builtin_amdgcn_s_setprio(1); _Pragma("unroll") for (int m = 0; m < 4; ++m) _Pragma("unroll") for (int n = 0; n < 2; ++n) _Pragma("unroll") for (int k = 0; k < 2; ++k) \
;         acc[ai][bj][m][n] = __builtin_amdgcn_mfma_f32_16x16x32_bf16(Bt[n][k], At[m][k], acc[ai][bj][m][n], 0, 0, 0); __builtin_amdgcn_s_setprio(0); } while (0)
; #define PG8_WAIT_V(n) asm volatile("s_waitcnt vmcnt(" #n ")" ::: "memory")
; #define PG8_WAIT_L(n) asm volatile("s_waitcnt lgkmcnt(" #n ")" ::: "memory")
; #define PG8_BAR __builtin_amdgcn_s_barrier()
; #define PG8_SCHED __builtin_amdgcn_sched_barrier(0)
; template <class Epi, class Sched, bool ALIGN_EPI = false, bool SP2 = false>
; __device__ __forceinline__ void gemm_phase(PG8_LAS unsigned char* lds, const Gemm g, const Sched& S, const Epi& E, const int tid) {
;     ...
;             PG8_LDB(B0, 0, 0); PG8_LDB(B1, 0, 1); PG8_SCHED; PG8_LDA(At, 0, 0); PG8_STAGE(PG8_SA(1, 1), a1 + hstep, voffA);
;             PG8_WAIT_V(8); PG8_WAIT_L(0); PG8_BAR; PG8_MMA(0, 0, At, B0); PG8_MMA(0, 1, At, B1); PG8_BAR; PG8_SCHED;
;             PG8_LDA(At, 0, 1); PG8_STAGE(PG8_SB(0, 0), b2, voffB); PG8_STAGE(PG8_SB(0, 1), b2 + hstep, voffB); PG8_STAGE(PG8_SA(0, 0), a2, voffA);
;             PG8_WAIT_V(8); PG8_WAIT_L(0); PG8_BAR; PG8_MMA(1, 0, At, B0); PG8_MMA(1, 1, At, B1); PG8_BAR; PG8_SCHED;
.LBB0_1347:
	s_add_u32 s16, s14, 0x100
	s_addc_u32 s17, s15, 0
	s_cmp_lg_u32 s37, 4
	s_cselect_b32 s18, s16, 0
	s_cselect_b32 s19, s17, 0
	s_add_u32 s20, s12, s18
	s_addc_u32 s21, s13, s19
	s_add_i32 s38, 0, 0x10000
	v_add_u32_e32 v154, s38, v140
	v_add_u32_e32 v170, s33, v140
	ds_read_b128 v[142:145], v154
	ds_read_b128 v[146:149], v154 offset:1024
	ds_read_b128 v[150:153], v154 offset:2048
	ds_read_b128 v[154:157], v154 offset:3072
	ds_read_b128 v[158:161], v170
	ds_read_b128 v[162:165], v170 offset:1024
	ds_read_b128 v[166:169], v170 offset:2048
	ds_read_b128 v[170:173], v170 offset:3072
	s_add_u32 s18, s10, s18
	s_addc_u32 s19, s11, s19
	v_lshl_add_u64 v[206:207], v[134:135], 0, s[14:15]
	s_add_i32 m0, s1, 0xc000
	ds_read_b128 v[174:177], v141
	ds_read_b128 v[178:181], v141 offset:1024
	ds_read_b128 v[182:185], v141 offset:2048
	ds_read_b128 v[186:189], v141 offset:3072
	ds_read_b128 v[190:193], v141 offset:4096
	ds_read_b128 v[194:197], v141 offset:5120
	ds_read_b128 v[198:201], v141 offset:6144
	ds_read_b128 v[202:205], v141 offset:7168
	global_load_lds_dwordx4 v[206:207], off
	v_lshl_add_u64 v[206:207], v[136:137], 0, s[14:15]
	s_add_i32 m0, s1, 0xe000
	s_nop 0
	global_load_lds_dwordx4 v[206:207], off
	s_waitcnt vmcnt(8)
	s_waitcnt lgkmcnt(0)
	s_barrier
	s_setprio 1
	s_waitcnt lgkmcnt(0)
	v_mfma_f32_16x16x32_bf16 v[124:127], v[142:145], v[174:177], v[124:127]
	v_mfma_f32_16x16x32_bf16 v[120:123], v[150:153], v[174:177], v[120:123]
	v_mfma_f32_16x16x32_bf16 v[116:119], v[142:145], v[182:185], v[116:119]
	v_mfma_f32_16x16x32_bf16 v[112:115], v[150:153], v[182:185], v[112:115]
	v_mfma_f32_16x16x32_bf16 v[104:107], v[142:145], v[190:193], v[104:107]
	v_mfma_f32_16x16x32_bf16 v[96:99], v[150:153], v[190:193], v[96:99]
	v_mfma_f32_16x16x32_bf16 v[88:91], v[142:145], v[198:201], v[88:91]
	v_mfma_f32_16x16x32_bf16 v[80:83], v[150:153], v[198:201], v[80:83]
	v_mfma_f32_16x16x32_bf16 v[124:127], v[146:149], v[178:181], v[124:127]
	v_mfma_f32_16x16x32_bf16 v[120:123], v[154:157], v[178:181], v[120:123]
	v_mfma_f32_16x16x32_bf16 v[116:119], v[146:149], v[186:189], v[116:119]
	v_mfma_f32_16x16x32_bf16 v[112:115], v[154:157], v[186:189], v[112:115]
	v_mfma_f32_16x16x32_bf16 v[104:107], v[146:149], v[194:197], v[104:107]
	v_mfma_f32_16x16x32_bf16 v[96:99], v[154:157], v[194:197], v[96:99]
	v_mfma_f32_16x16x32_bf16 v[88:91], v[146:149], v[202:205], v[88:91]
	v_mfma_f32_16x16x32_bf16 v[80:83], v[154:157], v[202:205], v[80:83]
	v_mfma_f32_16x16x32_bf16 v[108:111], v[158:161], v[174:177], v[108:111]
	v_mfma_f32_16x16x32_bf16 v[100:103], v[166:169], v[174:177], v[100:103]
	v_mfma_f32_16x16x32_bf16 v[92:95], v[158:161], v[182:185], v[92:95]
	v_mfma_f32_16x16x32_bf16 v[84:87], v[166:169], v[182:185], v[84:87]
	v_mfma_f32_16x16x32_bf16 v[76:79], v[158:161], v[190:193], v[76:79]
	v_mfma_f32_16x16x32_bf16 v[72:75], v[166:169], v[190:193], v[72:75]
	v_mfma_f32_16x16x32_bf16 v[68:71], v[158:161], v[198:201], v[68:71]
	v_mfma_f32_16x16x32_bf16 v[64:67], v[166:169], v[198:201], v[64:67]
	v_mfma_f32_16x16x32_bf16 v[108:111], v[162:165], v[178:181], v[108:111]
	v_mfma_f32_16x16x32_bf16 v[100:103], v[170:173], v[178:181], v[100:103]
	v_mfma_f32_16x16x32_bf16 v[92:95], v[162:165], v[186:189], v[92:95]
	v_mfma_f32_16x16x32_bf16 v[84:87], v[170:173], v[186:189], v[84:87]
	v_mfma_f32_16x16x32_bf16 v[76:79], v[162:165], v[194:197], v[76:79]
	v_mfma_f32_16x16x32_bf16 v[72:75], v[170:173], v[194:197], v[72:75]
	v_mfma_f32_16x16x32_bf16 v[68:71], v[162:165], v[202:205], v[68:71]
	v_mfma_f32_16x16x32_bf16 v[64:67], v[170:173], v[202:205], v[64:67]
	s_setprio 0
	s_barrier
	s_add_i32 s14, s38, s25
	v_lshl_add_u64 v[206:207], s[18:19], 0, v[208:209]
	s_mov_b32 m0, s14
	ds_read_b128 v[174:177], v141 offset:16384
	ds_read_b128 v[178:181], v141 offset:17408
	ds_read_b128 v[182:185], v141 offset:18432
	ds_read_b128 v[186:189], v141 offset:19456
	ds_read_b128 v[190:193], v141 offset:20480
	ds_read_b128 v[194:197], v141 offset:21504
	ds_read_b128 v[198:201], v141 offset:22528
	ds_read_b128 v[202:205], v141 offset:23552
	global_load_lds_dwordx4 v[206:207], off
	s_add_i32 m0, s14, 0x2000
	s_add_u32 s14, s18, 0x80000
	v_lshl_add_u64 v[210:211], s[18:19], 0, v[128:129]
	s_addc_u32 s15, s19, 0
	s_add_i32 s38, s33, s25
	global_load_lds_dwordx4 v[210:211], off
	v_lshl_add_u64 v[212:213], s[14:15], 0, v[208:209]
	s_mov_b32 m0, s38
	v_lshl_add_u64 v[214:215], s[20:21], 0, v[130:131]
	global_load_lds_dwordx4 v[212:213], off
	v_lshl_add_u64 v[212:213], s[14:15], 0, v[128:129]
	s_add_i32 m0, s38, 0x2000
	s_nop 0
	global_load_lds_dwordx4 v[212:213], off
	v_lshl_add_u64 v[212:213], s[20:21], 0, v[132:133]
	s_mov_b32 m0, s1
	s_nop 0
	global_load_lds_dwordx4 v[212:213], off
	s_mov_b32 m0, s28
	s_nop 0
	global_load_lds_dwordx4 v[214:215], off
	s_waitcnt vmcnt(8)
	s_waitcnt lgkmcnt(0)
	s_barrier
; #define PG8_STAGE(bufoff, gbase, voff) do { _Pragma("unroll") for (int _i = 0; _i < 2; ++_i) \
;         __builtin_amdgcn_global_load_lds((const unsigned*)((const char*)(gbase) + (voff)[_i]), (PG8_LAS unsigned*)(lds + (bufoff) + ldsw + _i * 8192), 16, 0, 0); } while (0)
; #define PG8_LDA(dst, b, h) do { _Pragma("unroll") for (int m = 0; m < 4; ++m) _Pragma("unroll") for (int k = 0; k < 2; ++k) dst[m][k] = *(const PG8_LAS bf16x8*)(lds + PG8_SA(b, h) + aoff + m * 2048 + k * 1024); } while (0)
; #define PG8_LDB(dst, b, h) do { _Pragma("unroll") for (int n = 0; n < 2; ++n) _Pragma("unroll") for (int k = 0; k < 2; ++k) dst[n][k] = *(const PG8_LAS bf16x8*)(lds + PG8_SB(b, h) + boff + n * 2048 + k * 1024); } while (0)
; #define PG8_MMA(ai, bj, At, Bt) do { __builtin_amdgcn_s_setprio(1); _Pragma("unroll") for (int m = 0; m < 4; ++m) _Pragma("unroll") for (int n = 0; n < 2; ++n) _Pragma("unroll") for (int k = 0; k < 2; ++k) \
;         acc[ai][bj][m][n] = __builtin_amdgcn_mfma_f32_16x16x32_bf16(Bt[n][k], At[m][k], acc[ai][bj][m][n], 0, 0, 0); __builtin_amdgcn_s_setprio(0); } while (0)
; #define PG8_WAIT_V(n) asm volatile("s_waitcnt vmcnt(" #n ")" ::: "memory")
; #define PG8_WAIT_L(n) asm volatile("s_waitcnt lgkmcnt(" #n ")" ::: "memory")
; #define PG8_BAR __builtin_amdgcn_s_barrier()
; #define PG8_SCHED __builtin_amdgcn_sched_barrier(0)
; template <class Epi, class Sched, bool ALIGN_EPI = false, bool SP2 = false>
; __device__ __forceinline__ void gemm_phase(PG8_LAS unsigned char* lds, const Gemm g, const Sched& S, const Epi& E, const int tid) {
;     ...
;             PG8_WAIT_V(8); PG8_WAIT_L(0); PG8_BAR; PG8_MMA(1, 0, At, B0); PG8_MMA(1, 1, At, B1); PG8_BAR; PG8_SCHED;
;             PG8_LDB(B0, 1, 0); PG8_LDB(B1, 1, 1); PG8_SCHED; PG8_LDA(At, 1, 0); PG8_STAGE(PG8_SA(0, 1), a2 + hstep, voffA);
;             PG8_WAIT_V(8); PG8_WAIT_L(0); PG8_BAR; PG8_MMA(0, 0, At, B0); PG8_MMA(0, 1, At, B1); PG8_BAR; PG8_SCHED;
	s_setprio 1
	s_waitcnt lgkmcnt(0)
	v_mfma_f32_16x16x32_bf16 v[60:63], v[142:145], v[174:177], v[60:63]
	v_mfma_f32_16x16x32_bf16 v[56:59], v[150:153], v[174:177], v[56:59]
	v_mfma_f32_16x16x32_bf16 v[52:55], v[142:145], v[182:185], v[52:55]
	v_mfma_f32_16x16x32_bf16 v[48:51], v[150:153], v[182:185], v[48:51]
	v_mfma_f32_16x16x32_bf16 v[36:39], v[142:145], v[190:193], v[36:39]
	v_mfma_f32_16x16x32_bf16 v[32:35], v[150:153], v[190:193], v[32:35]
	v_mfma_f32_16x16x32_bf16 v[20:23], v[142:145], v[198:201], v[20:23]
	v_mfma_f32_16x16x32_bf16 v[16:19], v[150:153], v[198:201], v[16:19]
	v_mfma_f32_16x16x32_bf16 v[60:63], v[146:149], v[178:181], v[60:63]
	v_mfma_f32_16x16x32_bf16 v[56:59], v[154:157], v[178:181], v[56:59]
	v_mfma_f32_16x16x32_bf16 v[52:55], v[146:149], v[186:189], v[52:55]
	v_mfma_f32_16x16x32_bf16 v[48:51], v[154:157], v[186:189], v[48:51]
	v_mfma_f32_16x16x32_bf16 v[36:39], v[146:149], v[194:197], v[36:39]
	v_mfma_f32_16x16x32_bf16 v[32:35], v[154:157], v[194:197], v[32:35]
	v_mfma_f32_16x16x32_bf16 v[20:23], v[146:149], v[202:205], v[20:23]
	v_mfma_f32_16x16x32_bf16 v[16:19], v[154:157], v[202:205], v[16:19]
	v_mfma_f32_16x16x32_bf16 v[44:47], v[158:161], v[174:177], v[44:47]
	v_mfma_f32_16x16x32_bf16 v[40:43], v[166:169], v[174:177], v[40:43]
	v_mfma_f32_16x16x32_bf16 v[28:31], v[158:161], v[182:185], v[28:31]
	v_mfma_f32_16x16x32_bf16 v[24:27], v[166:169], v[182:185], v[24:27]
	v_mfma_f32_16x16x32_bf16 v[12:15], v[158:161], v[190:193], v[12:15]
	v_mfma_f32_16x16x32_bf16 v[8:11], v[166:169], v[190:193], v[8:11]
	v_mfma_f32_16x16x32_bf16 v[4:7], v[158:161], v[198:201], v[4:7]
	v_mfma_f32_16x16x32_bf16 v[0:3], v[166:169], v[198:201], v[0:3]
	v_mfma_f32_16x16x32_bf16 v[44:47], v[162:165], v[178:181], v[44:47]
	v_mfma_f32_16x16x32_bf16 v[40:43], v[170:173], v[178:181], v[40:43]
	v_mfma_f32_16x16x32_bf16 v[28:31], v[162:165], v[186:189], v[28:31]
	v_mfma_f32_16x16x32_bf16 v[24:27], v[170:173], v[186:189], v[24:27]
	v_mfma_f32_16x16x32_bf16 v[12:15], v[162:165], v[194:197], v[12:15]
	v_mfma_f32_16x16x32_bf16 v[8:11], v[170:173], v[194:197], v[8:11]
	v_mfma_f32_16x16x32_bf16 v[4:7], v[162:165], v[202:205], v[4:7]
	v_mfma_f32_16x16x32_bf16 v[0:3], v[170:173], v[202:205], v[0:3]
	s_setprio 0
	s_barrier
	s_add_i32 s38, 0, 0x18000
	s_add_i32 s39, 0, 0x1c000
	v_add_u32_e32 v154, s38, v140
	v_add_u32_e32 v170, s39, v140
	ds_read_b128 v[142:145], v154
	ds_read_b128 v[146:149], v154 offset:1024
	ds_read_b128 v[150:153], v154 offset:2048
	ds_read_b128 v[154:157], v154 offset:3072
	ds_read_b128 v[158:161], v170
	ds_read_b128 v[162:165], v170 offset:1024
	ds_read_b128 v[166:169], v170 offset:2048
	ds_read_b128 v[170:173], v170 offset:3072
	s_add_u32 s14, s20, 0x80000
	s_addc_u32 s15, s21, 0
	s_mov_b32 m0, s29
	v_lshl_add_u64 v[216:217], s[14:15], 0, v[132:133]
	ds_read_b128 v[174:177], v141 offset:32768
	ds_read_b128 v[178:181], v141 offset:33792
	ds_read_b128 v[182:185], v141 offset:34816
	ds_read_b128 v[186:189], v141 offset:35840
	ds_read_b128 v[190:193], v141 offset:36864
	ds_read_b128 v[194:197], v141 offset:37888
	ds_read_b128 v[198:201], v141 offset:38912
	ds_read_b128 v[202:205], v141 offset:39936
	global_load_lds_dwordx4 v[216:217], off
	v_lshl_add_u64 v[216:217], s[14:15], 0, v[130:131]
	s_mov_b32 m0, s30
	s_nop 0
	global_load_lds_dwordx4 v[216:217], off
	s_waitcnt vmcnt(8)
	s_waitcnt lgkmcnt(0)
	s_barrier
	s_setprio 1
	s_waitcnt lgkmcnt(0)
	v_mfma_f32_16x16x32_bf16 v[124:127], v[142:145], v[174:177], v[124:127]
	v_mfma_f32_16x16x32_bf16 v[120:123], v[150:153], v[174:177], v[120:123]
	v_mfma_f32_16x16x32_bf16 v[116:119], v[142:145], v[182:185], v[116:119]
	v_mfma_f32_16x16x32_bf16 v[112:115], v[150:153], v[182:185], v[112:115]
	v_mfma_f32_16x16x32_bf16 v[104:107], v[142:145], v[190:193], v[104:107]
	v_mfma_f32_16x16x32_bf16 v[96:99], v[150:153], v[190:193], v[96:99]
	v_mfma_f32_16x16x32_bf16 v[88:91], v[142:145], v[198:201], v[88:91]
	v_mfma_f32_16x16x32_bf16 v[80:83], v[150:153], v[198:201], v[80:83]
	v_mfma_f32_16x16x32_bf16 v[124:127], v[146:149], v[178:181], v[124:127]
	v_mfma_f32_16x16x32_bf16 v[120:123], v[154:157], v[178:181], v[120:123]
	v_mfma_f32_16x16x32_bf16 v[116:119], v[146:149], v[186:189], v[116:119]
	v_mfma_f32_16x16x32_bf16 v[112:115], v[154:157], v[186:189], v[112:115]
	v_mfma_f32_16x16x32_bf16 v[104:107], v[146:149], v[194:197], v[104:107]
	v_mfma_f32_16x16x32_bf16 v[96:99], v[154:157], v[194:197], v[96:99]
	v_mfma_f32_16x16x32_bf16 v[88:91], v[146:149], v[202:205], v[88:91]
	v_mfma_f32_16x16x32_bf16 v[80:83], v[154:157], v[202:205], v[80:83]
	v_mfma_f32_16x16x32_bf16 v[108:111], v[158:161], v[174:177], v[108:111]
	v_mfma_f32_16x16x32_bf16 v[100:103], v[166:169], v[174:177], v[100:103]
	v_mfma_f32_16x16x32_bf16 v[92:95], v[158:161], v[182:185], v[92:95]
	v_mfma_f32_16x16x32_bf16 v[84:87], v[166:169], v[182:185], v[84:87]
	v_mfma_f32_16x16x32_bf16 v[76:79], v[158:161], v[190:193], v[76:79]
	v_mfma_f32_16x16x32_bf16 v[72:75], v[166:169], v[190:193], v[72:75]
	v_mfma_f32_16x16x32_bf16 v[68:71], v[158:161], v[198:201], v[68:71]
	v_mfma_f32_16x16x32_bf16 v[64:67], v[166:169], v[198:201], v[64:67]
	v_mfma_f32_16x16x32_bf16 v[108:111], v[162:165], v[178:181], v[108:111]
	v_mfma_f32_16x16x32_bf16 v[100:103], v[170:173], v[178:181], v[100:103]
	v_mfma_f32_16x16x32_bf16 v[92:95], v[162:165], v[186:189], v[92:95]
	v_mfma_f32_16x16x32_bf16 v[84:87], v[170:173], v[186:189], v[84:87]
	v_mfma_f32_16x16x32_bf16 v[76:79], v[162:165], v[194:197], v[76:79]
	v_mfma_f32_16x16x32_bf16 v[72:75], v[170:173], v[194:197], v[72:75]
	v_mfma_f32_16x16x32_bf16 v[68:71], v[162:165], v[202:205], v[68:71]
	v_mfma_f32_16x16x32_bf16 v[64:67], v[170:173], v[202:205], v[64:67]
	s_setprio 0
	s_barrier
; #define PG8_STAGE(bufoff, gbase, voff) do { _Pragma("unroll") for (int _i = 0; _i < 2; ++_i) \
;         __builtin_amdgcn_global_load_lds((const unsigned*)((const char*)(gbase) + (voff)[_i]), (PG8_LAS unsigned*)(lds + (bufoff) + ldsw + _i * 8192), 16, 0, 0); } while (0)
; #define PG8_LDA(dst, b, h) do { _Pragma("unroll") for (int m = 0; m < 4; ++m) _Pragma("unroll") for (int k = 0; k < 2; ++k) dst[m][k] = *(const PG8_LAS bf16x8*)(lds + PG8_SA(b, h) + aoff + m * 2048 + k * 1024); } while (0)
; #define PG8_MMA(ai, bj, At, Bt) do { __builtin_amdgcn_s_setprio(1); _Pragma("unroll") for (int m = 0; m < 4; ++m) _Pragma("unroll") for (int n = 0; n < 2; ++n) _Pragma("unroll") for (int k = 0; k < 2; ++k) \
;         acc[ai][bj][m][n] = __builtin_amdgcn_mfma_f32_16x16x32_bf16(Bt[n][k], At[m][k], acc[ai][bj][m][n], 0, 0, 0); __builtin_amdgcn_s_setprio(0); } while (0)
; #define PG8_WAIT_V(n) asm volatile("s_waitcnt vmcnt(" #n ")" ::: "memory")
; #define PG8_WAIT_L(n) asm volatile("s_waitcnt lgkmcnt(" #n ")" ::: "memory")
; #define PG8_BAR __builtin_amdgcn_s_barrier()
; #define PG8_SCHED __builtin_amdgcn_sched_barrier(0)
; template <class Epi, class Sched, bool ALIGN_EPI = false, bool SP2 = false>
; __device__ __forceinline__ void gemm_phase(PG8_LAS unsigned char* lds, const Gemm g, const Sched& S, const Epi& E, const int tid) {
;     ...
;             PG8_LDA(At, 1, 1); PG8_STAGE(PG8_SB(1, 0), b3, voffB); PG8_STAGE(PG8_SB(1, 1), b3 + hstep, voffB); PG8_STAGE(PG8_SA(1, 0), a3, voffA);
;             PG8_WAIT_V(8); PG8_WAIT_L(0); PG8_BAR; PG8_MMA(1, 0, At, B0); PG8_MMA(1, 1, At, B1); PG8_BAR; PG8_SCHED;
	s_add_i32 s14, s38, s25
	v_lshl_add_u64 v[206:207], v[206:207], 0, s[2:3]
	s_mov_b32 m0, s14
	ds_read_b128 v[174:177], v141 offset:49152
	ds_read_b128 v[178:181], v141 offset:50176
	ds_read_b128 v[182:185], v141 offset:51200
	ds_read_b128 v[186:189], v141 offset:52224
	ds_read_b128 v[190:193], v141 offset:53248
	ds_read_b128 v[194:197], v141 offset:54272
	ds_read_b128 v[198:201], v141 offset:55296
	ds_read_b128 v[202:205], v141 offset:56320
	global_load_lds_dwordx4 v[206:207], off
	s_add_i32 m0, s14, 0x2000
	s_add_u32 s14, s18, 0x80080
	v_lshl_add_u64 v[206:207], v[210:211], 0, s[2:3]
	s_addc_u32 s15, s19, 0
	s_add_i32 s18, s39, s25
	global_load_lds_dwordx4 v[206:207], off
	v_lshl_add_u64 v[206:207], s[14:15], 0, v[208:209]
	s_mov_b32 m0, s18
	s_nop 0
	global_load_lds_dwordx4 v[206:207], off
	v_lshl_add_u64 v[206:207], s[14:15], 0, v[128:129]
	s_add_i32 m0, s18, 0x2000
	s_nop 0
	global_load_lds_dwordx4 v[206:207], off
	v_lshl_add_u64 v[206:207], v[212:213], 0, s[2:3]
	s_mov_b32 m0, s35
	s_nop 0
	global_load_lds_dwordx4 v[206:207], off
	v_lshl_add_u64 v[206:207], v[214:215], 0, s[2:3]
	s_mov_b32 m0, s36
	s_nop 0
	global_load_lds_dwordx4 v[206:207], off
	s_waitcnt vmcnt(8)
	s_waitcnt lgkmcnt(0)
	s_barrier
	s_setprio 1
	s_waitcnt lgkmcnt(0)
	v_mfma_f32_16x16x32_bf16 v[60:63], v[142:145], v[174:177], v[60:63]
	v_mfma_f32_16x16x32_bf16 v[56:59], v[150:153], v[174:177], v[56:59]
	v_mfma_f32_16x16x32_bf16 v[52:55], v[142:145], v[182:185], v[52:55]
	v_mfma_f32_16x16x32_bf16 v[48:51], v[150:153], v[182:185], v[48:51]
	v_mfma_f32_16x16x32_bf16 v[36:39], v[142:145], v[190:193], v[36:39]
	v_mfma_f32_16x16x32_bf16 v[32:35], v[150:153], v[190:193], v[32:35]
	v_mfma_f32_16x16x32_bf16 v[20:23], v[142:145], v[198:201], v[20:23]
	v_mfma_f32_16x16x32_bf16 v[16:19], v[150:153], v[198:201], v[16:19]
	v_mfma_f32_16x16x32_bf16 v[60:63], v[146:149], v[178:181], v[60:63]
	v_mfma_f32_16x16x32_bf16 v[56:59], v[154:157], v[178:181], v[56:59]
	v_mfma_f32_16x16x32_bf16 v[52:55], v[146:149], v[186:189], v[52:55]
	v_mfma_f32_16x16x32_bf16 v[48:51], v[154:157], v[186:189], v[48:51]
	v_mfma_f32_16x16x32_bf16 v[36:39], v[146:149], v[194:197], v[36:39]
	v_mfma_f32_16x16x32_bf16 v[32:35], v[154:157], v[194:197], v[32:35]
	v_mfma_f32_16x16x32_bf16 v[20:23], v[146:149], v[202:205], v[20:23]
	v_mfma_f32_16x16x32_bf16 v[16:19], v[154:157], v[202:205], v[16:19]
	v_mfma_f32_16x16x32_bf16 v[44:47], v[158:161], v[174:177], v[44:47]
	v_mfma_f32_16x16x32_bf16 v[40:43], v[166:169], v[174:177], v[40:43]
	v_mfma_f32_16x16x32_bf16 v[28:31], v[158:161], v[182:185], v[28:31]
	v_mfma_f32_16x16x32_bf16 v[24:27], v[166:169], v[182:185], v[24:27]
	v_mfma_f32_16x16x32_bf16 v[12:15], v[158:161], v[190:193], v[12:15]
	v_mfma_f32_16x16x32_bf16 v[8:11], v[166:169], v[190:193], v[8:11]
	v_mfma_f32_16x16x32_bf16 v[4:7], v[158:161], v[198:201], v[4:7]
	v_mfma_f32_16x16x32_bf16 v[0:3], v[166:169], v[198:201], v[0:3]
	v_mfma_f32_16x16x32_bf16 v[44:47], v[162:165], v[178:181], v[44:47]
	v_mfma_f32_16x16x32_bf16 v[40:43], v[170:173], v[178:181], v[40:43]
	v_mfma_f32_16x16x32_bf16 v[28:31], v[162:165], v[186:189], v[28:31]
	v_mfma_f32_16x16x32_bf16 v[24:27], v[170:173], v[186:189], v[24:27]
	v_mfma_f32_16x16x32_bf16 v[12:15], v[162:165], v[194:197], v[12:15]
	v_mfma_f32_16x16x32_bf16 v[8:11], v[170:173], v[194:197], v[8:11]
	v_mfma_f32_16x16x32_bf16 v[4:7], v[162:165], v[202:205], v[4:7]
	v_mfma_f32_16x16x32_bf16 v[0:3], v[170:173], v[202:205], v[0:3]
	s_setprio 0
	s_barrier
	s_add_i32 s37, s37, 2
	s_cmp_gt_u32 s37, 5
	s_mov_b64 s[14:15], s[16:17]
	s_cbranch_scc0 .LBB0_1347
	s_cmpk_lt_u32 s24, 0x100
	v_readlane_b32 s58, v254, 51
	s_cbranch_scc0 .LBB0_1350
	s_barrier

; #define PG8_STAGE(bufoff, gbase, voff) do { _Pragma("unroll") for (int _i = 0; _i < 2; ++_i) \
;         __builtin_amdgcn_global_load_lds((const unsigned*)((const char*)(gbase) + (voff)[_i]), (PG8_LAS unsigned*)(lds + (bufoff) + ldsw + _i * 8192), 16, 0, 0); } while (0)
; #define PG8_LDA(dst, b, h) do { _Pragma("unroll") for (int m = 0; m < 4; ++m) _Pragma("unroll") for (int k = 0; k < 2; ++k) dst[m][k] = *(const PG8_LAS bf16x8*)(lds + PG8_SA(b, h) + aoff + m * 2048 + k * 1024); } while (0)
; #define PG8_LDB(dst, b, h) do { _Pragma("unroll") for (int n = 0; n < 2; ++n) _Pragma("unroll") for (int k = 0; k < 2; ++k) dst[n][k] = *(const PG8_LAS bf16x8*)(lds + PG8_SB(b, h) + boff + n * 2048 + k * 1024); } while (0)
; #define PG8_MMA(ai, bj, At, Bt) do { __builtin_amdgcn_s_setprio(1); _Pragma("unroll") for (int m = 0; m < 4; ++m) _Pragma("unroll") for (int n = 0; n < 2; ++n) _Pragma("unroll") for (int k = 0; k < 2; ++k) \
;         acc[ai][bj][m][n] = __builtin_amdgcn_mfma_f32_16x16x32_bf16(Bt[n][k], At[m][k], acc[ai][bj][m][n], 0, 0, 0); __builtin_amdgcn_s_setprio(0); } while (0)
; #define PG8_WAIT_V(n) asm volatile("s_waitcnt vmcnt(" #n ")" ::: "memory")
; #define PG8_WAIT_L(n) asm volatile("s_waitcnt lgkmcnt(" #n ")" ::: "memory")
; #define PG8_BAR __builtin_amdgcn_s_barrier()
; #define PG8_SCHED __builtin_amdgcn_sched_barrier(0)
; template <class Epi, class Sched, bool ALIGN_EPI = false, bool SP2 = false>
; __device__ __forceinline__ void gemm_phase(PG8_LAS unsigned char* lds, const Gemm g, const Sched& S, const Epi& E, const int tid) {
;     ...
;             PG8_LDB(B0, 0, 0); PG8_LDB(B1, 0, 1); PG8_SCHED; PG8_LDA(At, 0, 0); PG8_STAGE(PG8_SA(1, 1), a1 + hstep, voffA);
;             PG8_WAIT_V(8); PG8_WAIT_L(0); PG8_BAR; PG8_MMA(0, 0, At, B0); PG8_MMA(0, 1, At, B1); PG8_BAR; PG8_SCHED;
;             PG8_LDA(At, 0, 1); PG8_STAGE(PG8_SB(0, 0), b2, voffB); PG8_STAGE(PG8_SB(0, 1), b2 + hstep, voffB); PG8_STAGE(PG8_SA(0, 0), a2, voffA);
;             PG8_WAIT_V(8); PG8_WAIT_L(0); PG8_BAR; PG8_MMA(1, 0, At, B0); PG8_MMA(1, 1, At, B1); PG8_BAR; PG8_SCHED;
.Lmy_nobar_1479:
	s_add_u32 s30, s28, 0xfff80080
	s_addc_u32 s31, s29, -1
	s_add_i32 s57, 0, 0x10000
	v_add_u32_e32 v124, s57, v157
	v_add_u32_e32 v154, s33, v157
	ds_read_b128 v[112:115], v124
	ds_read_b128 v[116:119], v124 offset:1024
	ds_read_b128 v[120:123], v124 offset:2048
	ds_read_b128 v[124:127], v124 offset:3072
	ds_read_b128 v[162:165], v154
	ds_read_b128 v[166:169], v154 offset:1024
	ds_read_b128 v[170:173], v154 offset:2048
	ds_read_b128 v[174:177], v154 offset:3072
	s_cmp_eq_u32 s56, 28
	s_cselect_b32 s35, s19, s31
	s_cselect_b32 s34, s25, s30
	s_cselect_b32 s31, s17, s55
	s_cselect_b32 s30, s53, s54
	v_lshl_add_u64 v[206:207], s[28:29], 0, v[150:151]
	s_add_i32 m0, s27, 0xc000
	ds_read_b128 v[178:181], v161
	ds_read_b128 v[182:185], v161 offset:1024
	ds_read_b128 v[186:189], v161 offset:2048
	ds_read_b128 v[190:193], v161 offset:3072
	ds_read_b128 v[194:197], v161 offset:4096
	ds_read_b128 v[198:201], v161 offset:5120
	ds_read_b128 v[202:205], v161 offset:6144
	ds_read_b128 v[214:217], v161 offset:7168
	global_load_lds_dwordx4 v[206:207], off
	v_lshl_add_u64 v[206:207], s[28:29], 0, v[152:153]
	s_add_i32 m0, s27, 0xe000
	s_nop 0
	global_load_lds_dwordx4 v[206:207], off
	s_waitcnt vmcnt(8)
	s_waitcnt lgkmcnt(0)
	s_barrier
	s_setprio 1
	s_waitcnt lgkmcnt(0)
	v_mfma_f32_16x16x32_bf16 v[140:143], v[112:115], v[178:181], 0
	v_mfma_f32_16x16x32_bf16 v[136:139], v[120:123], v[178:181], 0
	v_mfma_f32_16x16x32_bf16 v[108:111], v[112:115], v[186:189], 0
	v_mfma_f32_16x16x32_bf16 v[104:107], v[120:123], v[186:189], 0
	v_mfma_f32_16x16x32_bf16 v[92:95], v[112:115], v[194:197], 0
	v_mfma_f32_16x16x32_bf16 v[88:91], v[120:123], v[194:197], 0
	v_mfma_f32_16x16x32_bf16 v[76:79], v[112:115], v[202:205], 0
	v_mfma_f32_16x16x32_bf16 v[72:75], v[120:123], v[202:205], 0
	v_mfma_f32_16x16x32_bf16 v[140:143], v[116:119], v[182:185], v[140:143]
	v_mfma_f32_16x16x32_bf16 v[136:139], v[124:127], v[182:185], v[136:139]
	v_mfma_f32_16x16x32_bf16 v[108:111], v[116:119], v[190:193], v[108:111]
	v_mfma_f32_16x16x32_bf16 v[104:107], v[124:127], v[190:193], v[104:107]
	v_mfma_f32_16x16x32_bf16 v[92:95], v[116:119], v[198:201], v[92:95]
	v_mfma_f32_16x16x32_bf16 v[88:91], v[124:127], v[198:201], v[88:91]
	v_mfma_f32_16x16x32_bf16 v[76:79], v[116:119], v[214:217], v[76:79]
	v_mfma_f32_16x16x32_bf16 v[72:75], v[124:127], v[214:217], v[72:75]
	v_mfma_f32_16x16x32_bf16 v[132:135], v[162:165], v[178:181], 0
	v_mfma_f32_16x16x32_bf16 v[128:131], v[170:173], v[178:181], 0
	v_mfma_f32_16x16x32_bf16 v[100:103], v[162:165], v[186:189], 0
	v_mfma_f32_16x16x32_bf16 v[96:99], v[170:173], v[186:189], 0
	v_mfma_f32_16x16x32_bf16 v[84:87], v[162:165], v[194:197], 0
	v_mfma_f32_16x16x32_bf16 v[80:83], v[170:173], v[194:197], 0
	v_mfma_f32_16x16x32_bf16 v[68:71], v[162:165], v[202:205], 0
	v_mfma_f32_16x16x32_bf16 v[64:67], v[170:173], v[202:205], 0
	v_mfma_f32_16x16x32_bf16 v[132:135], v[166:169], v[182:185], v[132:135]
	v_mfma_f32_16x16x32_bf16 v[128:131], v[174:177], v[182:185], v[128:131]
	v_mfma_f32_16x16x32_bf16 v[100:103], v[166:169], v[190:193], v[100:103]
	v_mfma_f32_16x16x32_bf16 v[96:99], v[174:177], v[190:193], v[96:99]
	v_mfma_f32_16x16x32_bf16 v[84:87], v[166:169], v[198:201], v[84:87]
	v_mfma_f32_16x16x32_bf16 v[80:83], v[174:177], v[198:201], v[80:83]
	v_mfma_f32_16x16x32_bf16 v[68:71], v[166:169], v[214:217], v[68:71]
	v_mfma_f32_16x16x32_bf16 v[64:67], v[174:177], v[214:217], v[64:67]
	s_setprio 0
	s_barrier
	s_add_i32 s57, s57, s42
	v_lshl_add_u64 v[206:207], s[30:31], 0, v[208:209]
	s_mov_b32 m0, s57
	ds_read_b128 v[178:181], v161 offset:16384
	ds_read_b128 v[182:185], v161 offset:17408
	ds_read_b128 v[186:189], v161 offset:18432
	ds_read_b128 v[190:193], v161 offset:19456
	ds_read_b128 v[194:197], v161 offset:20480
	ds_read_b128 v[198:201], v161 offset:21504
	ds_read_b128 v[202:205], v161 offset:22528
	ds_read_b128 v[214:217], v161 offset:23552
	global_load_lds_dwordx4 v[206:207], off
	s_add_i32 m0, s57, 0x2000
	s_add_u32 s58, s30, 0x80000
	v_lshl_add_u64 v[210:211], s[30:31], 0, v[144:145]
	s_addc_u32 s59, s31, 0
	s_add_i32 s57, s33, s42
	global_load_lds_dwordx4 v[210:211], off
	v_lshl_add_u64 v[212:213], s[58:59], 0, v[208:209]
	s_mov_b32 m0, s57
	v_lshl_add_u64 v[218:219], s[34:35], 0, v[146:147]
	global_load_lds_dwordx4 v[212:213], off
	v_lshl_add_u64 v[212:213], s[58:59], 0, v[144:145]
	s_add_i32 m0, s57, 0x2000
	s_nop 0
	global_load_lds_dwordx4 v[212:213], off
	v_lshl_add_u64 v[212:213], s[34:35], 0, v[148:149]
	s_mov_b32 m0, s27
	s_nop 0
	global_load_lds_dwordx4 v[212:213], off
	s_mov_b32 m0, s44
	s_nop 0
	global_load_lds_dwordx4 v[218:219], off
	s_waitcnt vmcnt(8)
	s_waitcnt lgkmcnt(0)
	s_barrier
	s_setprio 1
	s_waitcnt lgkmcnt(0)
	v_mfma_f32_16x16x32_bf16 v[60:63], v[112:115], v[178:181], 0
	v_mfma_f32_16x16x32_bf16 v[56:59], v[120:123], v[178:181], 0
	v_mfma_f32_16x16x32_bf16 v[44:47], v[112:115], v[186:189], 0
	v_mfma_f32_16x16x32_bf16 v[40:43], v[120:123], v[186:189], 0
	v_mfma_f32_16x16x32_bf16 v[28:31], v[112:115], v[194:197], 0
	v_mfma_f32_16x16x32_bf16 v[24:27], v[120:123], v[194:197], 0
	v_mfma_f32_16x16x32_bf16 v[12:15], v[112:115], v[202:205], 0
	v_mfma_f32_16x16x32_bf16 v[8:11], v[120:123], v[202:205], 0
	v_mfma_f32_16x16x32_bf16 v[60:63], v[116:119], v[182:185], v[60:63]
	v_mfma_f32_16x16x32_bf16 v[56:59], v[124:127], v[182:185], v[56:59]
	v_mfma_f32_16x16x32_bf16 v[44:47], v[116:119], v[190:193], v[44:47]
	v_mfma_f32_16x16x32_bf16 v[40:43], v[124:127], v[190:193], v[40:43]
	v_mfma_f32_16x16x32_bf16 v[28:31], v[116:119], v[198:201], v[28:31]
	v_mfma_f32_16x16x32_bf16 v[24:27], v[124:127], v[198:201], v[24:27]
	v_mfma_f32_16x16x32_bf16 v[12:15], v[116:119], v[214:217], v[12:15]
	v_mfma_f32_16x16x32_bf16 v[8:11], v[124:127], v[214:217], v[8:11]
	v_mfma_f32_16x16x32_bf16 v[52:55], v[162:165], v[178:181], 0
	v_mfma_f32_16x16x32_bf16 v[48:51], v[170:173], v[178:181], 0
	v_mfma_f32_16x16x32_bf16 v[36:39], v[162:165], v[186:189], 0
	v_mfma_f32_16x16x32_bf16 v[32:35], v[170:173], v[186:189], 0
	v_mfma_f32_16x16x32_bf16 v[20:23], v[162:165], v[194:197], 0
	v_mfma_f32_16x16x32_bf16 v[16:19], v[170:173], v[194:197], 0
	v_mfma_f32_16x16x32_bf16 v[4:7], v[162:165], v[202:205], 0
	v_mfma_f32_16x16x32_bf16 v[0:3], v[170:173], v[202:205], 0
	v_mfma_f32_16x16x32_bf16 v[52:55], v[166:169], v[182:185], v[52:55]
	v_mfma_f32_16x16x32_bf16 v[48:51], v[174:177], v[182:185], v[48:51]
	v_mfma_f32_16x16x32_bf16 v[36:39], v[166:169], v[190:193], v[36:39]
	v_mfma_f32_16x16x32_bf16 v[32:35], v[174:177], v[190:193], v[32:35]
	v_mfma_f32_16x16x32_bf16 v[20:23], v[166:169], v[198:201], v[20:23]
	v_mfma_f32_16x16x32_bf16 v[16:19], v[174:177], v[198:201], v[16:19]
	v_mfma_f32_16x16x32_bf16 v[4:7], v[166:169], v[214:217], v[4:7]
	v_mfma_f32_16x16x32_bf16 v[0:3], v[174:177], v[214:217], v[0:3]
	s_setprio 0
	s_barrier
	s_branch .Lmy_mid_1479
; #define PG8_STAGE(bufoff, gbase, voff) do { _Pragma("unroll") for (int _i = 0; _i < 2; ++_i) \
;         __builtin_amdgcn_global_load_lds((const unsigned*)((const char*)(gbase) + (voff)[_i]), (PG8_LAS unsigned*)(lds + (bufoff) + ldsw + _i * 8192), 16, 0, 0); } while (0)
; #define PG8_LDA(dst, b, h) do { _Pragma("unroll") for (int m = 0; m < 4; ++m) _Pragma("unroll") for (int k = 0; k < 2; ++k) dst[m][k] = *(const PG8_LAS bf16x8*)(lds + PG8_SA(b, h) + aoff + m * 2048 + k * 1024); } while (0)
; #define PG8_LDB(dst, b, h) do { _Pragma("unroll") for (int n = 0; n < 2; ++n) _Pragma("unroll") for (int k = 0; k < 2; ++k) dst[n][k] = *(const PG8_LAS bf16x8*)(lds + PG8_SB(b, h) + boff + n * 2048 + k * 1024); } while (0)
; #define PG8_MMA(ai, bj, At, Bt) do { __builtin_amdgcn_s_setprio(1); _Pragma("unroll") for (int m = 0; m < 4; ++m) _Pragma("unroll") for (int n = 0; n < 2; ++n) _Pragma("unroll") for (int k = 0; k < 2; ++k) \
;         acc[ai][bj][m][n] = __builtin_amdgcn_mfma_f32_16x16x32_bf16(Bt[n][k], At[m][k], acc[ai][bj][m][n], 0, 0, 0); __builtin_amdgcn_s_setprio(0); } while (0)
; #define PG8_BAR __builtin_amdgcn_s_barrier()
; template <class Epi, class Sched, bool ALIGN_EPI = false, bool SP2 = false>
; __device__ __forceinline__ void gemm_phase(PG8_LAS unsigned char* lds, const Gemm g, const Sched& S, const Epi& E, const int tid) {
;     ...
;             PG8_LDB(B0, 0, 0); PG8_LDB(B1, 0, 1); PG8_SCHED; PG8_LDA(At, 0, 0); PG8_STAGE(PG8_SA(1, 1), a1 + hstep, voffA);
;             PG8_WAIT_V(8); PG8_WAIT_L(0); PG8_BAR; PG8_MMA(0, 0, At, B0); PG8_MMA(0, 1, At, B1); PG8_BAR; PG8_SCHED;
;             PG8_LDA(At, 0, 1); PG8_STAGE(PG8_SB(0, 0), b2, voffB); PG8_STAGE(PG8_SB(0, 1), b2 + hstep, voffB); PG8_STAGE(PG8_SA(0, 0), a2, voffA);
;             PG8_WAIT_V(8); PG8_WAIT_L(0); PG8_BAR; PG8_MMA(1, 0, At, B0); PG8_MMA(1, 1, At, B1); PG8_BAR; PG8_SCHED;
;             PG8_LDB(B0, 1, 0); PG8_LDB(B1, 1, 1); PG8_SCHED; PG8_LDA(At, 1, 0); PG8_STAGE(PG8_SA(0, 1), a2 + hstep, voffA);
;             PG8_WAIT_V(8); PG8_WAIT_L(0); PG8_BAR; PG8_MMA(0, 0, At, B0); PG8_MMA(0, 1, At, B1); PG8_BAR; PG8_SCHED;
;             PG8_LDA(At, 1, 1); PG8_STAGE(PG8_SB(1, 0), b3, voffB); PG8_STAGE(PG8_SB(1, 1), b3 + hstep, voffB); PG8_STAGE(PG8_SA(1, 0), a3, voffA);
;             PG8_WAIT_V(8); PG8_WAIT_L(0); PG8_BAR; PG8_MMA(1, 0, At, B0); PG8_MMA(1, 1, At, B1); PG8_BAR; PG8_SCHED;
.LBB0_1479:
	s_add_u32 s30, s28, 0xfff80080
	s_addc_u32 s31, s29, -1
	s_add_i32 s57, 0, 0x10000
	v_add_u32_e32 v124, s57, v157
	v_add_u32_e32 v154, s33, v157
	ds_read_b128 v[112:115], v124
	ds_read_b128 v[116:119], v124 offset:1024
	ds_read_b128 v[120:123], v124 offset:2048
	ds_read_b128 v[124:127], v124 offset:3072
	ds_read_b128 v[162:165], v154
	ds_read_b128 v[166:169], v154 offset:1024
	ds_read_b128 v[170:173], v154 offset:2048
	ds_read_b128 v[174:177], v154 offset:3072
	s_cmp_eq_u32 s56, 28
	s_cselect_b32 s35, s19, s31
	s_cselect_b32 s34, s25, s30
	s_cselect_b32 s31, s17, s55
	s_cselect_b32 s30, s53, s54
	v_lshl_add_u64 v[206:207], s[28:29], 0, v[150:151]
	s_add_i32 m0, s27, 0xc000
	ds_read_b128 v[178:181], v161
	ds_read_b128 v[182:185], v161 offset:1024
	ds_read_b128 v[186:189], v161 offset:2048
	ds_read_b128 v[190:193], v161 offset:3072
	ds_read_b128 v[194:197], v161 offset:4096
	ds_read_b128 v[198:201], v161 offset:5120
	ds_read_b128 v[202:205], v161 offset:6144
	ds_read_b128 v[214:217], v161 offset:7168
	global_load_lds_dwordx4 v[206:207], off
	v_lshl_add_u64 v[206:207], s[28:29], 0, v[152:153]
	s_add_i32 m0, s27, 0xe000
	s_nop 0
	global_load_lds_dwordx4 v[206:207], off
	s_waitcnt vmcnt(8)
	s_waitcnt lgkmcnt(0)
	s_barrier
	s_setprio 1
	s_waitcnt lgkmcnt(0)
	v_mfma_f32_16x16x32_bf16 v[140:143], v[112:115], v[178:181], v[140:143]
	v_mfma_f32_16x16x32_bf16 v[136:139], v[120:123], v[178:181], v[136:139]
	v_mfma_f32_16x16x32_bf16 v[108:111], v[112:115], v[186:189], v[108:111]
	v_mfma_f32_16x16x32_bf16 v[104:107], v[120:123], v[186:189], v[104:107]
	v_mfma_f32_16x16x32_bf16 v[92:95], v[112:115], v[194:197], v[92:95]
	v_mfma_f32_16x16x32_bf16 v[88:91], v[120:123], v[194:197], v[88:91]
	v_mfma_f32_16x16x32_bf16 v[76:79], v[112:115], v[202:205], v[76:79]
	v_mfma_f32_16x16x32_bf16 v[72:75], v[120:123], v[202:205], v[72:75]
	v_mfma_f32_16x16x32_bf16 v[140:143], v[116:119], v[182:185], v[140:143]
	v_mfma_f32_16x16x32_bf16 v[136:139], v[124:127], v[182:185], v[136:139]
	v_mfma_f32_16x16x32_bf16 v[108:111], v[116:119], v[190:193], v[108:111]
	v_mfma_f32_16x16x32_bf16 v[104:107], v[124:127], v[190:193], v[104:107]
	v_mfma_f32_16x16x32_bf16 v[92:95], v[116:119], v[198:201], v[92:95]
	v_mfma_f32_16x16x32_bf16 v[88:91], v[124:127], v[198:201], v[88:91]
	v_mfma_f32_16x16x32_bf16 v[76:79], v[116:119], v[214:217], v[76:79]
	v_mfma_f32_16x16x32_bf16 v[72:75], v[124:127], v[214:217], v[72:75]
	v_mfma_f32_16x16x32_bf16 v[132:135], v[162:165], v[178:181], v[132:135]
	v_mfma_f32_16x16x32_bf16 v[128:131], v[170:173], v[178:181], v[128:131]
	v_mfma_f32_16x16x32_bf16 v[100:103], v[162:165], v[186:189], v[100:103]
	v_mfma_f32_16x16x32_bf16 v[96:99], v[170:173], v[186:189], v[96:99]
	v_mfma_f32_16x16x32_bf16 v[84:87], v[162:165], v[194:197], v[84:87]
	v_mfma_f32_16x16x32_bf16 v[80:83], v[170:173], v[194:197], v[80:83]
	v_mfma_f32_16x16x32_bf16 v[68:71], v[162:165], v[202:205], v[68:71]
	v_mfma_f32_16x16x32_bf16 v[64:67], v[170:173], v[202:205], v[64:67]
	v_mfma_f32_16x16x32_bf16 v[132:135], v[166:169], v[182:185], v[132:135]
	v_mfma_f32_16x16x32_bf16 v[128:131], v[174:177], v[182:185], v[128:131]
	v_mfma_f32_16x16x32_bf16 v[100:103], v[166:169], v[190:193], v[100:103]
	v_mfma_f32_16x16x32_bf16 v[96:99], v[174:177], v[190:193], v[96:99]
	v_mfma_f32_16x16x32_bf16 v[84:87], v[166:169], v[198:201], v[84:87]
	v_mfma_f32_16x16x32_bf16 v[80:83], v[174:177], v[198:201], v[80:83]
	v_mfma_f32_16x16x32_bf16 v[68:71], v[166:169], v[214:217], v[68:71]
	v_mfma_f32_16x16x32_bf16 v[64:67], v[174:177], v[214:217], v[64:67]
	s_setprio 0
	s_barrier
	s_add_i32 s57, s57, s42
	v_lshl_add_u64 v[206:207], s[30:31], 0, v[208:209]
	s_mov_b32 m0, s57
	ds_read_b128 v[178:181], v161 offset:16384
	ds_read_b128 v[182:185], v161 offset:17408
	ds_read_b128 v[186:189], v161 offset:18432
	ds_read_b128 v[190:193], v161 offset:19456
	ds_read_b128 v[194:197], v161 offset:20480
	ds_read_b128 v[198:201], v161 offset:21504
	ds_read_b128 v[202:205], v161 offset:22528
	ds_read_b128 v[214:217], v161 offset:23552
	global_load_lds_dwordx4 v[206:207], off
	s_add_i32 m0, s57, 0x2000
	s_add_u32 s58, s30, 0x80000
	v_lshl_add_u64 v[210:211], s[30:31], 0, v[144:145]
	s_addc_u32 s59, s31, 0
	s_add_i32 s57, s33, s42
	global_load_lds_dwordx4 v[210:211], off
	v_lshl_add_u64 v[212:213], s[58:59], 0, v[208:209]
	s_mov_b32 m0, s57
	v_lshl_add_u64 v[218:219], s[34:35], 0, v[146:147]
	global_load_lds_dwordx4 v[212:213], off
	v_lshl_add_u64 v[212:213], s[58:59], 0, v[144:145]
	s_add_i32 m0, s57, 0x2000
	s_nop 0
	global_load_lds_dwordx4 v[212:213], off
	v_lshl_add_u64 v[212:213], s[34:35], 0, v[148:149]
	s_mov_b32 m0, s27
	s_nop 0
	global_load_lds_dwordx4 v[212:213], off
	s_mov_b32 m0, s44
	s_nop 0
	global_load_lds_dwordx4 v[218:219], off
	s_waitcnt vmcnt(8)
	s_waitcnt lgkmcnt(0)
	s_barrier
	s_setprio 1
	s_waitcnt lgkmcnt(0)
	v_mfma_f32_16x16x32_bf16 v[60:63], v[112:115], v[178:181], v[60:63]
	v_mfma_f32_16x16x32_bf16 v[56:59], v[120:123], v[178:181], v[56:59]
	v_mfma_f32_16x16x32_bf16 v[44:47], v[112:115], v[186:189], v[44:47]
	v_mfma_f32_16x16x32_bf16 v[40:43], v[120:123], v[186:189], v[40:43]
	v_mfma_f32_16x16x32_bf16 v[28:31], v[112:115], v[194:197], v[28:31]
	v_mfma_f32_16x16x32_bf16 v[24:27], v[120:123], v[194:197], v[24:27]
	v_mfma_f32_16x16x32_bf16 v[12:15], v[112:115], v[202:205], v[12:15]
	v_mfma_f32_16x16x32_bf16 v[8:11], v[120:123], v[202:205], v[8:11]
	v_mfma_f32_16x16x32_bf16 v[60:63], v[116:119], v[182:185], v[60:63]
	v_mfma_f32_16x16x32_bf16 v[56:59], v[124:127], v[182:185], v[56:59]
	v_mfma_f32_16x16x32_bf16 v[44:47], v[116:119], v[190:193], v[44:47]
	v_mfma_f32_16x16x32_bf16 v[40:43], v[124:127], v[190:193], v[40:43]
	v_mfma_f32_16x16x32_bf16 v[28:31], v[116:119], v[198:201], v[28:31]
	v_mfma_f32_16x16x32_bf16 v[24:27], v[124:127], v[198:201], v[24:27]
	v_mfma_f32_16x16x32_bf16 v[12:15], v[116:119], v[214:217], v[12:15]
	v_mfma_f32_16x16x32_bf16 v[8:11], v[124:127], v[214:217], v[8:11]
	v_mfma_f32_16x16x32_bf16 v[52:55], v[162:165], v[178:181], v[52:55]
	v_mfma_f32_16x16x32_bf16 v[48:51], v[170:173], v[178:181], v[48:51]
	v_mfma_f32_16x16x32_bf16 v[36:39], v[162:165], v[186:189], v[36:39]
	v_mfma_f32_16x16x32_bf16 v[32:35], v[170:173], v[186:189], v[32:35]
	v_mfma_f32_16x16x32_bf16 v[20:23], v[162:165], v[194:197], v[20:23]
	v_mfma_f32_16x16x32_bf16 v[16:19], v[170:173], v[194:197], v[16:19]
	v_mfma_f32_16x16x32_bf16 v[4:7], v[162:165], v[202:205], v[4:7]
	v_mfma_f32_16x16x32_bf16 v[0:3], v[170:173], v[202:205], v[0:3]
	v_mfma_f32_16x16x32_bf16 v[52:55], v[166:169], v[182:185], v[52:55]
	v_mfma_f32_16x16x32_bf16 v[48:51], v[174:177], v[182:185], v[48:51]
	v_mfma_f32_16x16x32_bf16 v[36:39], v[166:169], v[190:193], v[36:39]
	v_mfma_f32_16x16x32_bf16 v[32:35], v[174:177], v[190:193], v[32:35]
	v_mfma_f32_16x16x32_bf16 v[20:23], v[166:169], v[198:201], v[20:23]
	v_mfma_f32_16x16x32_bf16 v[16:19], v[174:177], v[198:201], v[16:19]
	v_mfma_f32_16x16x32_bf16 v[4:7], v[166:169], v[214:217], v[4:7]
	v_mfma_f32_16x16x32_bf16 v[0:3], v[174:177], v[214:217], v[0:3]
	s_setprio 0
	s_barrier
; #define PG8_STAGE(bufoff, gbase, voff) do { _Pragma("unroll") for (int _i = 0; _i < 2; ++_i) \
;         __builtin_amdgcn_global_load_lds((const unsigned*)((const char*)(gbase) + (voff)[_i]), (PG8_LAS unsigned*)(lds + (bufoff) + ldsw + _i * 8192), 16, 0, 0); } while (0)
; #define PG8_LDA(dst, b, h) do { _Pragma("unroll") for (int m = 0; m < 4; ++m) _Pragma("unroll") for (int k = 0; k < 2; ++k) dst[m][k] = *(const PG8_LAS bf16x8*)(lds + PG8_SA(b, h) + aoff + m * 2048 + k * 1024); } while (0)
; #define PG8_LDB(dst, b, h) do { _Pragma("unroll") for (int n = 0; n < 2; ++n) _Pragma("unroll") for (int k = 0; k < 2; ++k) dst[n][k] = *(const PG8_LAS bf16x8*)(lds + PG8_SB(b, h) + boff + n * 2048 + k * 1024); } while (0)
; #define PG8_MMA(ai, bj, At, Bt) do { __builtin_amdgcn_s_setprio(1); _Pragma("unroll") for (int m = 0; m < 4; ++m) _Pragma("unroll") for (int n = 0; n < 2; ++n) _Pragma("unroll") for (int k = 0; k < 2; ++k) \
;         acc[ai][bj][m][n] = __builtin_amdgcn_mfma_f32_16x16x32_bf16(Bt[n][k], At[m][k], acc[ai][bj][m][n], 0, 0, 0); __builtin_amdgcn_s_setprio(0); } while (0)
; #define PG8_WAIT_V(n) asm volatile("s_waitcnt vmcnt(" #n ")" ::: "memory")
; #define PG8_WAIT_L(n) asm volatile("s_waitcnt lgkmcnt(" #n ")" ::: "memory")
; #define PG8_BAR __builtin_amdgcn_s_barrier()
; #define PG8_SCHED __builtin_amdgcn_sched_barrier(0)
; template <class Epi, class Sched, bool ALIGN_EPI = false, bool SP2 = false>
; __device__ __forceinline__ void gemm_phase(PG8_LAS unsigned char* lds, const Gemm g, const Sched& S, const Epi& E, const int tid) {
;     ...
;             PG8_LDB(B0, 1, 0); PG8_LDB(B1, 1, 1); PG8_SCHED; PG8_LDA(At, 1, 0); PG8_STAGE(PG8_SA(0, 1), a2 + hstep, voffA);
;             PG8_WAIT_V(8); PG8_WAIT_L(0); PG8_BAR; PG8_MMA(0, 0, At, B0); PG8_MMA(0, 1, At, B1); PG8_BAR; PG8_SCHED;
;             PG8_LDA(At, 1, 1); PG8_STAGE(PG8_SB(1, 0), b3, voffB); PG8_STAGE(PG8_SB(1, 1), b3 + hstep, voffB); PG8_STAGE(PG8_SA(1, 0), a3, voffA);
;             PG8_WAIT_V(8); PG8_WAIT_L(0); PG8_BAR; PG8_MMA(1, 0, At, B0); PG8_MMA(1, 1, At, B1); PG8_BAR; PG8_SCHED;
.Lmy_mid_1479:
	s_add_i32 s57, 0, 0x18000
	s_add_i32 s58, 0, 0x1c000
	v_add_u32_e32 v124, s57, v157
	v_add_u32_e32 v154, s58, v157
	ds_read_b128 v[112:115], v124
	ds_read_b128 v[116:119], v124 offset:1024
	ds_read_b128 v[120:123], v124 offset:2048
	ds_read_b128 v[124:127], v124 offset:3072
	ds_read_b128 v[162:165], v154
	ds_read_b128 v[166:169], v154 offset:1024
	ds_read_b128 v[170:173], v154 offset:2048
	ds_read_b128 v[174:177], v154 offset:3072
	s_add_u32 s34, s34, 0x80000
	s_addc_u32 s35, s35, 0
	s_mov_b32 m0, s45
	v_lshl_add_u64 v[220:221], s[34:35], 0, v[148:149]
	ds_read_b128 v[178:181], v161 offset:32768
	ds_read_b128 v[182:185], v161 offset:33792
	ds_read_b128 v[186:189], v161 offset:34816
	ds_read_b128 v[190:193], v161 offset:35840
	ds_read_b128 v[194:197], v161 offset:36864
	ds_read_b128 v[198:201], v161 offset:37888
	ds_read_b128 v[202:205], v161 offset:38912
	ds_read_b128 v[214:217], v161 offset:39936
	global_load_lds_dwordx4 v[220:221], off
	v_lshl_add_u64 v[220:221], s[34:35], 0, v[146:147]
	s_mov_b32 m0, s46
	s_nop 0
	global_load_lds_dwordx4 v[220:221], off
	s_waitcnt vmcnt(8)
	s_waitcnt lgkmcnt(0)
	s_barrier
	s_setprio 1
	s_waitcnt lgkmcnt(0)
	v_mfma_f32_16x16x32_bf16 v[140:143], v[112:115], v[178:181], v[140:143]
	v_mfma_f32_16x16x32_bf16 v[136:139], v[120:123], v[178:181], v[136:139]
	v_mfma_f32_16x16x32_bf16 v[108:111], v[112:115], v[186:189], v[108:111]
	v_mfma_f32_16x16x32_bf16 v[104:107], v[120:123], v[186:189], v[104:107]
	v_mfma_f32_16x16x32_bf16 v[92:95], v[112:115], v[194:197], v[92:95]
	v_mfma_f32_16x16x32_bf16 v[88:91], v[120:123], v[194:197], v[88:91]
	v_mfma_f32_16x16x32_bf16 v[76:79], v[112:115], v[202:205], v[76:79]
	v_mfma_f32_16x16x32_bf16 v[72:75], v[120:123], v[202:205], v[72:75]
	v_mfma_f32_16x16x32_bf16 v[140:143], v[116:119], v[182:185], v[140:143]
	v_mfma_f32_16x16x32_bf16 v[136:139], v[124:127], v[182:185], v[136:139]
	v_mfma_f32_16x16x32_bf16 v[108:111], v[116:119], v[190:193], v[108:111]
	v_mfma_f32_16x16x32_bf16 v[104:107], v[124:127], v[190:193], v[104:107]
	v_mfma_f32_16x16x32_bf16 v[92:95], v[116:119], v[198:201], v[92:95]
	v_mfma_f32_16x16x32_bf16 v[88:91], v[124:127], v[198:201], v[88:91]
	v_mfma_f32_16x16x32_bf16 v[76:79], v[116:119], v[214:217], v[76:79]
	v_mfma_f32_16x16x32_bf16 v[72:75], v[124:127], v[214:217], v[72:75]
	v_mfma_f32_16x16x32_bf16 v[132:135], v[162:165], v[178:181], v[132:135]
	v_mfma_f32_16x16x32_bf16 v[128:131], v[170:173], v[178:181], v[128:131]
	v_mfma_f32_16x16x32_bf16 v[100:103], v[162:165], v[186:189], v[100:103]
	v_mfma_f32_16x16x32_bf16 v[96:99], v[170:173], v[186:189], v[96:99]
	v_mfma_f32_16x16x32_bf16 v[84:87], v[162:165], v[194:197], v[84:87]
	v_mfma_f32_16x16x32_bf16 v[80:83], v[170:173], v[194:197], v[80:83]
	v_mfma_f32_16x16x32_bf16 v[68:71], v[162:165], v[202:205], v[68:71]
	v_mfma_f32_16x16x32_bf16 v[64:67], v[170:173], v[202:205], v[64:67]
	v_mfma_f32_16x16x32_bf16 v[132:135], v[166:169], v[182:185], v[132:135]
	v_mfma_f32_16x16x32_bf16 v[128:131], v[174:177], v[182:185], v[128:131]
	v_mfma_f32_16x16x32_bf16 v[100:103], v[166:169], v[190:193], v[100:103]
	v_mfma_f32_16x16x32_bf16 v[96:99], v[174:177], v[190:193], v[96:99]
	v_mfma_f32_16x16x32_bf16 v[84:87], v[166:169], v[198:201], v[84:87]
	v_mfma_f32_16x16x32_bf16 v[80:83], v[174:177], v[198:201], v[80:83]
	v_mfma_f32_16x16x32_bf16 v[68:71], v[166:169], v[214:217], v[68:71]
	v_mfma_f32_16x16x32_bf16 v[64:67], v[174:177], v[214:217], v[64:67]
	s_setprio 0
	s_barrier
	s_add_i32 s34, s57, s42
	v_lshl_add_u64 v[206:207], v[206:207], 0, s[2:3]
	s_mov_b32 m0, s34
	ds_read_b128 v[178:181], v161 offset:49152
	ds_read_b128 v[182:185], v161 offset:50176
	ds_read_b128 v[186:189], v161 offset:51200
	ds_read_b128 v[190:193], v161 offset:52224
	ds_read_b128 v[194:197], v161 offset:53248
	ds_read_b128 v[198:201], v161 offset:54272
	ds_read_b128 v[202:205], v161 offset:55296
	ds_read_b128 v[214:217], v161 offset:56320
	global_load_lds_dwordx4 v[206:207], off
	s_add_i32 m0, s34, 0x2000
	s_add_u32 s30, s30, 0x80080
	v_lshl_add_u64 v[206:207], v[210:211], 0, s[2:3]
	s_addc_u32 s31, s31, 0
	s_add_i32 s34, s58, s42
	global_load_lds_dwordx4 v[206:207], off
	v_lshl_add_u64 v[206:207], s[30:31], 0, v[208:209]
	s_mov_b32 m0, s34
	s_nop 0
	global_load_lds_dwordx4 v[206:207], off
	v_lshl_add_u64 v[206:207], s[30:31], 0, v[144:145]
	s_add_i32 m0, s34, 0x2000
	s_nop 0
	global_load_lds_dwordx4 v[206:207], off
	v_lshl_add_u64 v[206:207], v[212:213], 0, s[2:3]
	s_mov_b32 m0, s49
	s_nop 0
	global_load_lds_dwordx4 v[206:207], off
	v_lshl_add_u64 v[206:207], v[218:219], 0, s[2:3]
	s_mov_b32 m0, s50
	s_nop 0
	global_load_lds_dwordx4 v[206:207], off
	s_waitcnt vmcnt(8)
	s_waitcnt lgkmcnt(0)
	s_barrier
; #define PG8_STAGE(bufoff, gbase, voff) do { _Pragma("unroll") for (int _i = 0; _i < 2; ++_i) \
;         __builtin_amdgcn_global_load_lds((const unsigned*)((const char*)(gbase) + (voff)[_i]), (PG8_LAS unsigned*)(lds + (bufoff) + ldsw + _i * 8192), 16, 0, 0); } while (0)
; #define PG8_LDA(dst, b, h) do { _Pragma("unroll") for (int m = 0; m < 4; ++m) _Pragma("unroll") for (int k = 0; k < 2; ++k) dst[m][k] = *(const PG8_LAS bf16x8*)(lds + PG8_SA(b, h) + aoff + m * 2048 + k * 1024); } while (0)
; #define PG8_MMA(ai, bj, At, Bt) do { __builtin_amdgcn_s_setprio(1); _Pragma("unroll") for (int m = 0; m < 4; ++m) _Pragma("unroll") for (int n = 0; n < 2; ++n) _Pragma("unroll") for (int k = 0; k < 2; ++k) \
;         acc[ai][bj][m][n] = __builtin_amdgcn_mfma_f32_16x16x32_bf16(Bt[n][k], At[m][k], acc[ai][bj][m][n], 0, 0, 0); __builtin_amdgcn_s_setprio(0); } while (0)
; #define PG8_WAIT_V(n) asm volatile("s_waitcnt vmcnt(" #n ")" ::: "memory")
; #define PG8_WAIT_L(n) asm volatile("s_waitcnt lgkmcnt(" #n ")" ::: "memory")
; #define PG8_BAR __builtin_amdgcn_s_barrier()
; #define PG8_SCHED __builtin_amdgcn_sched_barrier(0)
; template <class Epi, class Sched, bool ALIGN_EPI = false, bool SP2 = false>
; __device__ __forceinline__ void gemm_phase(PG8_LAS unsigned char* lds, const Gemm g, const Sched& S, const Epi& E, const int tid) {
;     ...
;             PG8_LDA(At, 1, 1); PG8_STAGE(PG8_SB(1, 0), b3, voffB); PG8_STAGE(PG8_SB(1, 1), b3 + hstep, voffB); PG8_STAGE(PG8_SA(1, 0), a3, voffA);
;             PG8_WAIT_V(8); PG8_WAIT_L(0); PG8_BAR; PG8_MMA(1, 0, At, B0); PG8_MMA(1, 1, At, B1); PG8_BAR; PG8_SCHED;
;     __device__ __forceinline__ void operator()(const f32x4 (&acc)[2][2][4][2], const Unit& un, int wr, int wc, int fr, int fq) const {
;         const int rbase = un.pm * 256 + wr * 64 + fr, cw = un.pn * 256 + wc * 32 + 8 * fq;
;         const int slot = un.pm < (NLAT / 256) ? (un.pm >> 5) : 4; const float* sw = shw + (size_t)slot * DFF;
;         f32x4 s0[2], s1[2]; float rr[2][4];
; #pragma unroll
;         for (int bj = 0; bj < 2; ++bj) { s0[bj] = *(const f32x4*)(sw + cw + bj * 128); s1[bj] = *(const f32x4*)(sw + cw + bj * 128 + 4); }
; #pragma unroll
;         for (int ai = 0; ai < 2; ++ai)
; #pragma unroll
;             for (int m = 0; m < 4; ++m) rr[ai][m] = rs[rbase + ai * 128 + m * 16];
	s_setprio 1
	s_waitcnt lgkmcnt(0)
	v_mfma_f32_16x16x32_bf16 v[60:63], v[112:115], v[178:181], v[60:63]
	v_mfma_f32_16x16x32_bf16 v[56:59], v[120:123], v[178:181], v[56:59]
	v_mfma_f32_16x16x32_bf16 v[44:47], v[112:115], v[186:189], v[44:47]
	v_mfma_f32_16x16x32_bf16 v[40:43], v[120:123], v[186:189], v[40:43]
	v_mfma_f32_16x16x32_bf16 v[28:31], v[112:115], v[194:197], v[28:31]
	v_mfma_f32_16x16x32_bf16 v[24:27], v[120:123], v[194:197], v[24:27]
	v_mfma_f32_16x16x32_bf16 v[12:15], v[112:115], v[202:205], v[12:15]
	v_mfma_f32_16x16x32_bf16 v[8:11], v[120:123], v[202:205], v[8:11]
	v_mfma_f32_16x16x32_bf16 v[60:63], v[116:119], v[182:185], v[60:63]
	v_mfma_f32_16x16x32_bf16 v[56:59], v[124:127], v[182:185], v[56:59]
	v_mfma_f32_16x16x32_bf16 v[44:47], v[116:119], v[190:193], v[44:47]
	v_mfma_f32_16x16x32_bf16 v[40:43], v[124:127], v[190:193], v[40:43]
	v_mfma_f32_16x16x32_bf16 v[28:31], v[116:119], v[198:201], v[28:31]
	v_mfma_f32_16x16x32_bf16 v[24:27], v[124:127], v[198:201], v[24:27]
	v_mfma_f32_16x16x32_bf16 v[12:15], v[116:119], v[214:217], v[12:15]
	v_mfma_f32_16x16x32_bf16 v[8:11], v[124:127], v[214:217], v[8:11]
	v_mfma_f32_16x16x32_bf16 v[52:55], v[162:165], v[178:181], v[52:55]
	v_mfma_f32_16x16x32_bf16 v[48:51], v[170:173], v[178:181], v[48:51]
	v_mfma_f32_16x16x32_bf16 v[36:39], v[162:165], v[186:189], v[36:39]
	v_mfma_f32_16x16x32_bf16 v[32:35], v[170:173], v[186:189], v[32:35]
	v_mfma_f32_16x16x32_bf16 v[20:23], v[162:165], v[194:197], v[20:23]
	v_mfma_f32_16x16x32_bf16 v[16:19], v[170:173], v[194:197], v[16:19]
	v_mfma_f32_16x16x32_bf16 v[4:7], v[162:165], v[202:205], v[4:7]
	v_mfma_f32_16x16x32_bf16 v[0:3], v[170:173], v[202:205], v[0:3]
	v_mfma_f32_16x16x32_bf16 v[52:55], v[166:169], v[182:185], v[52:55]
	v_mfma_f32_16x16x32_bf16 v[48:51], v[174:177], v[182:185], v[48:51]
	v_mfma_f32_16x16x32_bf16 v[36:39], v[166:169], v[190:193], v[36:39]
	v_mfma_f32_16x16x32_bf16 v[32:35], v[174:177], v[190:193], v[32:35]
	v_mfma_f32_16x16x32_bf16 v[20:23], v[166:169], v[198:201], v[20:23]
	v_mfma_f32_16x16x32_bf16 v[16:19], v[174:177], v[198:201], v[16:19]
	v_mfma_f32_16x16x32_bf16 v[4:7], v[166:169], v[214:217], v[4:7]
	v_mfma_f32_16x16x32_bf16 v[0:3], v[174:177], v[214:217], v[0:3]
	s_setprio 0
	s_barrier
	s_add_i32 s56, s56, 2
	s_add_u32 s28, s28, 0x100
	s_addc_u32 s29, s29, 0
	s_add_u32 s54, s54, 0x100
	s_addc_u32 s55, s55, 0
	s_cmp_gt_u32 s56, 29
	s_cbranch_scc0 .LBB0_1479
	s_ashr_i32 s28, s24, 5
	s_ashr_i32 s29, s28, 31
	s_lshl_b64 s[28:29], s[28:29], 13
	s_cmpk_lt_i32 s24, 0x80
	s_cselect_b32 s29, s29, 0
	s_cselect_b32 s28, s28, 0x8000
	s_lshl_b64 s[28:29], s[28:29], 2
	v_lshl_or_b32 v174, s26, 8, v159
	s_add_u32 s28, s47, s28
	v_lshl_add_u32 v176, s24, 8, v155
	s_addc_u32 s29, s48, s29
	v_ashrrev_i32_e32 v175, 31, v174
	v_ashrrev_i32_e32 v177, 31, v176
	v_lshl_add_u64 v[116:117], v[174:175], 2, s[28:29]
	v_lshl_add_u64 v[178:179], v[176:177], 2, s[12:13]
	global_load_dwordx4 v[120:123], v[116:117], off offset:16
	global_load_dwordx4 v[124:127], v[116:117], off
	global_load_dwordx4 v[112:115], v[116:117], off offset:528
	s_nop 0
	global_load_dwordx4 v[116:119], v[116:117], off offset:512
	v_or_b32_e32 v172, 16, v176
	global_load_dword v180, v[178:179], off
	v_ashrrev_i32_e32 v173, 31, v172
	v_lshl_add_u64 v[162:163], v[172:173], 2, s[12:13]
	global_load_dword v170, v[162:163], off
	v_or_b32_e32 v168, 32, v176
	v_ashrrev_i32_e32 v169, 31, v168
	v_lshl_add_u64 v[162:163], v[168:169], 2, s[12:13]
	global_load_dword v166, v[162:163], off
	v_or_b32_e32 v164, 48, v176
	v_ashrrev_i32_e32 v165, 31, v164
	v_lshl_add_u64 v[162:163], v[164:165], 2, s[12:13]
	global_load_dword v162, v[162:163], off
	s_nop 0
	global_load_dword v160, v[178:179], off offset:512
	global_load_dword v158, v[178:179], off offset:576
	global_load_dword v156, v[178:179], off offset:640
	global_load_dword v154, v[178:179], off offset:704
	s_and_b64 vcc, exec, s[14:15]
	s_cbranch_vccz .LBB0_1482
	s_barrier

; #define PG8_STAGE(bufoff, gbase, voff) do { _Pragma("unroll") for (int _i = 0; _i < 2; ++_i) \
;         __builtin_amdgcn_global_load_lds((const unsigned*)((const char*)(gbase) + (voff)[_i]), (PG8_LAS unsigned*)(lds + (bufoff) + ldsw + _i * 8192), 16, 0, 0); } while (0)
; #define PG8_LDA(dst, b, h) do { _Pragma("unroll") for (int m = 0; m < 4; ++m) _Pragma("unroll") for (int k = 0; k < 2; ++k) dst[m][k] = *(const PG8_LAS bf16x8*)(lds + PG8_SA(b, h) + aoff + m * 2048 + k * 1024); } while (0)
; #define PG8_LDB(dst, b, h) do { _Pragma("unroll") for (int n = 0; n < 2; ++n) _Pragma("unroll") for (int k = 0; k < 2; ++k) dst[n][k] = *(const PG8_LAS bf16x8*)(lds + PG8_SB(b, h) + boff + n * 2048 + k * 1024); } while (0)
; #define PG8_MMA(ai, bj, At, Bt) do { __builtin_amdgcn_s_setprio(1); _Pragma("unroll") for (int m = 0; m < 4; ++m) _Pragma("unroll") for (int n = 0; n < 2; ++n) _Pragma("unroll") for (int k = 0; k < 2; ++k) \
;         acc[ai][bj][m][n] = __builtin_amdgcn_mfma_f32_16x16x32_bf16(Bt[n][k], At[m][k], acc[ai][bj][m][n], 0, 0, 0); __builtin_amdgcn_s_setprio(0); } while (0)
; #define PG8_WAIT_V(n) asm volatile("s_waitcnt vmcnt(" #n ")" ::: "memory")
; #define PG8_WAIT_L(n) asm volatile("s_waitcnt lgkmcnt(" #n ")" ::: "memory")
; #define PG8_BAR __builtin_amdgcn_s_barrier()
; #define PG8_SCHED __builtin_amdgcn_sched_barrier(0)
; template <class Epi, class Sched, bool ALIGN_EPI = false, bool SP2 = false>
; __device__ __forceinline__ void gemm_phase(PG8_LAS unsigned char* lds, const Gemm g, const Sched& S, const Epi& E, const int tid) {
;     ...
;             PG8_LDB(B0, 0, 0); PG8_LDB(B1, 0, 1); PG8_SCHED; PG8_LDA(At, 0, 0); PG8_STAGE(PG8_SA(1, 1), a1 + hstep, voffA);
;             PG8_WAIT_V(8); PG8_WAIT_L(0); PG8_BAR; PG8_MMA(0, 0, At, B0); PG8_MMA(0, 1, At, B1); PG8_BAR; PG8_SCHED;
;             PG8_LDA(At, 0, 1); PG8_STAGE(PG8_SB(0, 0), b2, voffB); PG8_STAGE(PG8_SB(0, 1), b2 + hstep, voffB); PG8_STAGE(PG8_SA(0, 0), a2, voffA);
;             PG8_WAIT_V(8); PG8_WAIT_L(0); PG8_BAR; PG8_MMA(1, 0, At, B0); PG8_MMA(1, 1, At, B1); PG8_BAR; PG8_SCHED;
.Lmy_nobar_1559:
	s_add_u32 s44, s42, 0xffe00080
	s_addc_u32 s45, s43, -1
	s_add_i32 s74, 0, 0x10000
	v_add_u32_e32 v132, s74, v252
	v_add_u32_e32 v156, s33, v252
	ds_read_b128 v[116:119], v132
	ds_read_b128 v[124:127], v132 offset:1024
	ds_read_b128 v[128:131], v132 offset:2048
	ds_read_b128 v[132:135], v132 offset:3072
	ds_read_b128 v[144:147], v156
	ds_read_b128 v[148:151], v156 offset:1024
	ds_read_b128 v[152:155], v156 offset:2048
	ds_read_b128 v[156:159], v156 offset:3072
	s_cmpk_eq_i32 s73, 0x7c
	s_cselect_b32 s47, s31, s45
	s_cselect_b32 s46, s39, s44
	s_cselect_b32 s45, s29, s72
	s_cselect_b32 s44, s41, s71
	v_lshl_add_u64 v[192:193], s[42:43], 0, v[220:221]
	s_add_i32 m0, s55, 0xc000
	ds_read_b128 v[160:163], v210
	ds_read_b128 v[164:167], v210 offset:1024
	ds_read_b128 v[168:171], v210 offset:2048
	ds_read_b128 v[172:175], v210 offset:3072
	ds_read_b128 v[176:179], v210 offset:4096
	ds_read_b128 v[180:183], v210 offset:5120
	ds_read_b128 v[184:187], v210 offset:6144
	ds_read_b128 v[188:191], v210 offset:7168
	global_load_lds_dwordx4 v[192:193], off
	v_lshl_add_u64 v[192:193], s[42:43], 0, v[222:223]
	s_add_i32 m0, s55, 0xe000
	s_nop 0
	global_load_lds_dwordx4 v[192:193], off
	s_waitcnt vmcnt(8)
	s_waitcnt lgkmcnt(0)
	s_barrier
	s_setprio 1
	s_waitcnt lgkmcnt(0)
	v_mfma_f32_16x16x32_bf16 v[140:143], v[116:119], v[160:163], 0
	v_mfma_f32_16x16x32_bf16 v[136:139], v[128:131], v[160:163], 0
	v_mfma_f32_16x16x32_bf16 v[108:111], v[116:119], v[168:171], 0
	v_mfma_f32_16x16x32_bf16 v[104:107], v[128:131], v[168:171], 0
	v_mfma_f32_16x16x32_bf16 v[92:95], v[116:119], v[176:179], 0
	v_mfma_f32_16x16x32_bf16 v[88:91], v[128:131], v[176:179], 0
	v_mfma_f32_16x16x32_bf16 v[76:79], v[116:119], v[184:187], 0
	v_mfma_f32_16x16x32_bf16 v[72:75], v[128:131], v[184:187], 0
	v_mfma_f32_16x16x32_bf16 v[140:143], v[124:127], v[164:167], v[140:143]
	v_mfma_f32_16x16x32_bf16 v[136:139], v[132:135], v[164:167], v[136:139]
	v_mfma_f32_16x16x32_bf16 v[108:111], v[124:127], v[172:175], v[108:111]
	v_mfma_f32_16x16x32_bf16 v[104:107], v[132:135], v[172:175], v[104:107]
	v_mfma_f32_16x16x32_bf16 v[92:95], v[124:127], v[180:183], v[92:95]
	v_mfma_f32_16x16x32_bf16 v[88:91], v[132:135], v[180:183], v[88:91]
	v_mfma_f32_16x16x32_bf16 v[76:79], v[124:127], v[188:191], v[76:79]
	v_mfma_f32_16x16x32_bf16 v[72:75], v[132:135], v[188:191], v[72:75]
	v_mfma_f32_16x16x32_bf16 v[120:123], v[144:147], v[160:163], 0
	v_mfma_f32_16x16x32_bf16 v[112:115], v[152:155], v[160:163], 0
	v_mfma_f32_16x16x32_bf16 v[100:103], v[144:147], v[168:171], 0
	v_mfma_f32_16x16x32_bf16 v[96:99], v[152:155], v[168:171], 0
	v_mfma_f32_16x16x32_bf16 v[84:87], v[144:147], v[176:179], 0
	v_mfma_f32_16x16x32_bf16 v[80:83], v[152:155], v[176:179], 0
	v_mfma_f32_16x16x32_bf16 v[68:71], v[144:147], v[184:187], 0
	v_mfma_f32_16x16x32_bf16 v[64:67], v[152:155], v[184:187], 0
	v_mfma_f32_16x16x32_bf16 v[120:123], v[148:151], v[164:167], v[120:123]
	v_mfma_f32_16x16x32_bf16 v[112:115], v[156:159], v[164:167], v[112:115]
	v_mfma_f32_16x16x32_bf16 v[100:103], v[148:151], v[172:175], v[100:103]
	v_mfma_f32_16x16x32_bf16 v[96:99], v[156:159], v[172:175], v[96:99]
	v_mfma_f32_16x16x32_bf16 v[84:87], v[148:151], v[180:183], v[84:87]
	v_mfma_f32_16x16x32_bf16 v[80:83], v[156:159], v[180:183], v[80:83]
	v_mfma_f32_16x16x32_bf16 v[68:71], v[148:151], v[188:191], v[68:71]
	v_mfma_f32_16x16x32_bf16 v[64:67], v[156:159], v[188:191], v[64:67]
	s_setprio 0
	s_barrier
	s_add_i32 s74, s74, s54
	v_lshl_add_u64 v[192:193], s[44:45], 0, v[208:209]
	s_mov_b32 m0, s74
	ds_read_b128 v[160:163], v210 offset:16384
	ds_read_b128 v[164:167], v210 offset:17408
	ds_read_b128 v[168:171], v210 offset:18432
	ds_read_b128 v[172:175], v210 offset:19456
	ds_read_b128 v[176:179], v210 offset:20480
	ds_read_b128 v[180:183], v210 offset:21504
	ds_read_b128 v[184:187], v210 offset:22528
	ds_read_b128 v[188:191], v210 offset:23552
	global_load_lds_dwordx4 v[192:193], off
	s_add_i32 m0, s74, 0x2000
	s_add_u32 s74, s44, 0x200000
	v_lshl_add_u64 v[194:195], s[44:45], 0, v[218:219]
	s_addc_u32 s75, s45, 0
	s_add_i32 s76, s33, s54
	global_load_lds_dwordx4 v[194:195], off
	v_lshl_add_u64 v[196:197], s[74:75], 0, v[208:209]
	s_mov_b32 m0, s76
	v_lshl_add_u64 v[198:199], s[46:47], 0, v[216:217]
	global_load_lds_dwordx4 v[196:197], off
	v_lshl_add_u64 v[196:197], s[74:75], 0, v[218:219]
	s_add_i32 m0, s76, 0x2000
	s_nop 0
	global_load_lds_dwordx4 v[196:197], off
	v_lshl_add_u64 v[196:197], s[46:47], 0, v[214:215]
	s_mov_b32 m0, s55
	s_nop 0
	global_load_lds_dwordx4 v[196:197], off
	s_mov_b32 m0, s56
	s_nop 0
	global_load_lds_dwordx4 v[198:199], off
	s_waitcnt vmcnt(8)
	s_waitcnt lgkmcnt(0)
	s_barrier
	s_setprio 1
	s_waitcnt lgkmcnt(0)
	v_mfma_f32_16x16x32_bf16 v[60:63], v[116:119], v[160:163], 0
	v_mfma_f32_16x16x32_bf16 v[56:59], v[128:131], v[160:163], 0
	v_mfma_f32_16x16x32_bf16 v[44:47], v[116:119], v[168:171], 0
	v_mfma_f32_16x16x32_bf16 v[40:43], v[128:131], v[168:171], 0
	v_mfma_f32_16x16x32_bf16 v[28:31], v[116:119], v[176:179], 0
	v_mfma_f32_16x16x32_bf16 v[24:27], v[128:131], v[176:179], 0
	v_mfma_f32_16x16x32_bf16 v[12:15], v[116:119], v[184:187], 0
	v_mfma_f32_16x16x32_bf16 v[8:11], v[128:131], v[184:187], 0
	v_mfma_f32_16x16x32_bf16 v[60:63], v[124:127], v[164:167], v[60:63]
	v_mfma_f32_16x16x32_bf16 v[56:59], v[132:135], v[164:167], v[56:59]
	v_mfma_f32_16x16x32_bf16 v[44:47], v[124:127], v[172:175], v[44:47]
	v_mfma_f32_16x16x32_bf16 v[40:43], v[132:135], v[172:175], v[40:43]
	v_mfma_f32_16x16x32_bf16 v[28:31], v[124:127], v[180:183], v[28:31]
	v_mfma_f32_16x16x32_bf16 v[24:27], v[132:135], v[180:183], v[24:27]
	v_mfma_f32_16x16x32_bf16 v[12:15], v[124:127], v[188:191], v[12:15]
	v_mfma_f32_16x16x32_bf16 v[8:11], v[132:135], v[188:191], v[8:11]
	v_mfma_f32_16x16x32_bf16 v[52:55], v[144:147], v[160:163], 0
	v_mfma_f32_16x16x32_bf16 v[48:51], v[152:155], v[160:163], 0
	v_mfma_f32_16x16x32_bf16 v[36:39], v[144:147], v[168:171], 0
	v_mfma_f32_16x16x32_bf16 v[32:35], v[152:155], v[168:171], 0
	v_mfma_f32_16x16x32_bf16 v[20:23], v[144:147], v[176:179], 0
	v_mfma_f32_16x16x32_bf16 v[16:19], v[152:155], v[176:179], 0
	v_mfma_f32_16x16x32_bf16 v[4:7], v[144:147], v[184:187], 0
	v_mfma_f32_16x16x32_bf16 v[0:3], v[152:155], v[184:187], 0
	v_mfma_f32_16x16x32_bf16 v[52:55], v[148:151], v[164:167], v[52:55]
	v_mfma_f32_16x16x32_bf16 v[48:51], v[156:159], v[164:167], v[48:51]
	v_mfma_f32_16x16x32_bf16 v[36:39], v[148:151], v[172:175], v[36:39]
	v_mfma_f32_16x16x32_bf16 v[32:35], v[156:159], v[172:175], v[32:35]
	v_mfma_f32_16x16x32_bf16 v[20:23], v[148:151], v[180:183], v[20:23]
	v_mfma_f32_16x16x32_bf16 v[16:19], v[156:159], v[180:183], v[16:19]
	v_mfma_f32_16x16x32_bf16 v[4:7], v[148:151], v[188:191], v[4:7]
	v_mfma_f32_16x16x32_bf16 v[0:3], v[156:159], v[188:191], v[0:3]
	s_setprio 0
	s_barrier
	s_branch .Lmy_mid_1559
; #define PG8_STAGE(bufoff, gbase, voff) do { _Pragma("unroll") for (int _i = 0; _i < 2; ++_i) \
;         __builtin_amdgcn_global_load_lds((const unsigned*)((const char*)(gbase) + (voff)[_i]), (PG8_LAS unsigned*)(lds + (bufoff) + ldsw + _i * 8192), 16, 0, 0); } while (0)
; #define PG8_LDA(dst, b, h) do { _Pragma("unroll") for (int m = 0; m < 4; ++m) _Pragma("unroll") for (int k = 0; k < 2; ++k) dst[m][k] = *(const PG8_LAS bf16x8*)(lds + PG8_SA(b, h) + aoff + m * 2048 + k * 1024); } while (0)
; #define PG8_LDB(dst, b, h) do { _Pragma("unroll") for (int n = 0; n < 2; ++n) _Pragma("unroll") for (int k = 0; k < 2; ++k) dst[n][k] = *(const PG8_LAS bf16x8*)(lds + PG8_SB(b, h) + boff + n * 2048 + k * 1024); } while (0)
; #define PG8_MMA(ai, bj, At, Bt) do { __builtin_amdgcn_s_setprio(1); _Pragma("unroll") for (int m = 0; m < 4; ++m) _Pragma("unroll") for (int n = 0; n < 2; ++n) _Pragma("unroll") for (int k = 0; k < 2; ++k) \
;         acc[ai][bj][m][n] = __builtin_amdgcn_mfma_f32_16x16x32_bf16(Bt[n][k], At[m][k], acc[ai][bj][m][n], 0, 0, 0); __builtin_amdgcn_s_setprio(0); } while (0)
; #define PG8_WAIT_V(n) asm volatile("s_waitcnt vmcnt(" #n ")" ::: "memory")
; #define PG8_WAIT_L(n) asm volatile("s_waitcnt lgkmcnt(" #n ")" ::: "memory")
; #define PG8_BAR __builtin_amdgcn_s_barrier()
; #define PG8_SCHED __builtin_amdgcn_sched_barrier(0)
; template <class Epi, class Sched, bool ALIGN_EPI = false, bool SP2 = false>
; __device__ __forceinline__ void gemm_phase(PG8_LAS unsigned char* lds, const Gemm g, const Sched& S, const Epi& E, const int tid) {
;     ...
;             PG8_LDB(B0, 0, 0); PG8_LDB(B1, 0, 1); PG8_SCHED; PG8_LDA(At, 0, 0); PG8_STAGE(PG8_SA(1, 1), a1 + hstep, voffA);
;             PG8_WAIT_V(8); PG8_WAIT_L(0); PG8_BAR; PG8_MMA(0, 0, At, B0); PG8_MMA(0, 1, At, B1); PG8_BAR; PG8_SCHED;
;             PG8_LDA(At, 0, 1); PG8_STAGE(PG8_SB(0, 0), b2, voffB); PG8_STAGE(PG8_SB(0, 1), b2 + hstep, voffB); PG8_STAGE(PG8_SA(0, 0), a2, voffA);
;             PG8_WAIT_V(8); PG8_WAIT_L(0); PG8_BAR; PG8_MMA(1, 0, At, B0); PG8_MMA(1, 1, At, B1); PG8_BAR; PG8_SCHED;
.LBB0_1559:
	s_add_u32 s44, s42, 0xffe00080
	s_addc_u32 s45, s43, -1
	s_add_i32 s74, 0, 0x10000
	v_add_u32_e32 v132, s74, v252
	v_add_u32_e32 v156, s33, v252
	ds_read_b128 v[116:119], v132
	ds_read_b128 v[124:127], v132 offset:1024
	ds_read_b128 v[128:131], v132 offset:2048
	ds_read_b128 v[132:135], v132 offset:3072
	ds_read_b128 v[144:147], v156
	ds_read_b128 v[148:151], v156 offset:1024
	ds_read_b128 v[152:155], v156 offset:2048
	ds_read_b128 v[156:159], v156 offset:3072
	s_cmpk_eq_i32 s73, 0x7c
	s_cselect_b32 s47, s31, s45
	s_cselect_b32 s46, s39, s44
	s_cselect_b32 s45, s29, s72
	s_cselect_b32 s44, s41, s71
	v_lshl_add_u64 v[192:193], s[42:43], 0, v[220:221]
	s_add_i32 m0, s55, 0xc000
	ds_read_b128 v[160:163], v210
	ds_read_b128 v[164:167], v210 offset:1024
	ds_read_b128 v[168:171], v210 offset:2048
	ds_read_b128 v[172:175], v210 offset:3072
	ds_read_b128 v[176:179], v210 offset:4096
	ds_read_b128 v[180:183], v210 offset:5120
	ds_read_b128 v[184:187], v210 offset:6144
	ds_read_b128 v[188:191], v210 offset:7168
	global_load_lds_dwordx4 v[192:193], off
	v_lshl_add_u64 v[192:193], s[42:43], 0, v[222:223]
	s_add_i32 m0, s55, 0xe000
	s_nop 0
	global_load_lds_dwordx4 v[192:193], off
	s_waitcnt vmcnt(8)
	s_waitcnt lgkmcnt(0)
	s_barrier
	s_setprio 1
	s_waitcnt lgkmcnt(0)
	v_mfma_f32_16x16x32_bf16 v[140:143], v[116:119], v[160:163], v[140:143]
	v_mfma_f32_16x16x32_bf16 v[136:139], v[128:131], v[160:163], v[136:139]
	v_mfma_f32_16x16x32_bf16 v[108:111], v[116:119], v[168:171], v[108:111]
	v_mfma_f32_16x16x32_bf16 v[104:107], v[128:131], v[168:171], v[104:107]
	v_mfma_f32_16x16x32_bf16 v[92:95], v[116:119], v[176:179], v[92:95]
	v_mfma_f32_16x16x32_bf16 v[88:91], v[128:131], v[176:179], v[88:91]
	v_mfma_f32_16x16x32_bf16 v[76:79], v[116:119], v[184:187], v[76:79]
	v_mfma_f32_16x16x32_bf16 v[72:75], v[128:131], v[184:187], v[72:75]
	v_mfma_f32_16x16x32_bf16 v[140:143], v[124:127], v[164:167], v[140:143]
	v_mfma_f32_16x16x32_bf16 v[136:139], v[132:135], v[164:167], v[136:139]
	v_mfma_f32_16x16x32_bf16 v[108:111], v[124:127], v[172:175], v[108:111]
	v_mfma_f32_16x16x32_bf16 v[104:107], v[132:135], v[172:175], v[104:107]
	v_mfma_f32_16x16x32_bf16 v[92:95], v[124:127], v[180:183], v[92:95]
	v_mfma_f32_16x16x32_bf16 v[88:91], v[132:135], v[180:183], v[88:91]
	v_mfma_f32_16x16x32_bf16 v[76:79], v[124:127], v[188:191], v[76:79]
	v_mfma_f32_16x16x32_bf16 v[72:75], v[132:135], v[188:191], v[72:75]
	v_mfma_f32_16x16x32_bf16 v[120:123], v[144:147], v[160:163], v[120:123]
	v_mfma_f32_16x16x32_bf16 v[112:115], v[152:155], v[160:163], v[112:115]
	v_mfma_f32_16x16x32_bf16 v[100:103], v[144:147], v[168:171], v[100:103]
	v_mfma_f32_16x16x32_bf16 v[96:99], v[152:155], v[168:171], v[96:99]
	v_mfma_f32_16x16x32_bf16 v[84:87], v[144:147], v[176:179], v[84:87]
	v_mfma_f32_16x16x32_bf16 v[80:83], v[152:155], v[176:179], v[80:83]
	v_mfma_f32_16x16x32_bf16 v[68:71], v[144:147], v[184:187], v[68:71]
	v_mfma_f32_16x16x32_bf16 v[64:67], v[152:155], v[184:187], v[64:67]
	v_mfma_f32_16x16x32_bf16 v[120:123], v[148:151], v[164:167], v[120:123]
	v_mfma_f32_16x16x32_bf16 v[112:115], v[156:159], v[164:167], v[112:115]
	v_mfma_f32_16x16x32_bf16 v[100:103], v[148:151], v[172:175], v[100:103]
	v_mfma_f32_16x16x32_bf16 v[96:99], v[156:159], v[172:175], v[96:99]
	v_mfma_f32_16x16x32_bf16 v[84:87], v[148:151], v[180:183], v[84:87]
	v_mfma_f32_16x16x32_bf16 v[80:83], v[156:159], v[180:183], v[80:83]
	v_mfma_f32_16x16x32_bf16 v[68:71], v[148:151], v[188:191], v[68:71]
	v_mfma_f32_16x16x32_bf16 v[64:67], v[156:159], v[188:191], v[64:67]
	s_setprio 0
	s_barrier
	s_add_i32 s74, s74, s54
	v_lshl_add_u64 v[192:193], s[44:45], 0, v[208:209]
	s_mov_b32 m0, s74
	ds_read_b128 v[160:163], v210 offset:16384
	ds_read_b128 v[164:167], v210 offset:17408
	ds_read_b128 v[168:171], v210 offset:18432
	ds_read_b128 v[172:175], v210 offset:19456
	ds_read_b128 v[176:179], v210 offset:20480
	ds_read_b128 v[180:183], v210 offset:21504
	ds_read_b128 v[184:187], v210 offset:22528
	ds_read_b128 v[188:191], v210 offset:23552
	global_load_lds_dwordx4 v[192:193], off
	s_add_i32 m0, s74, 0x2000
	s_add_u32 s74, s44, 0x200000
	v_lshl_add_u64 v[194:195], s[44:45], 0, v[218:219]
	s_addc_u32 s75, s45, 0
	s_add_i32 s76, s33, s54
	global_load_lds_dwordx4 v[194:195], off
	v_lshl_add_u64 v[196:197], s[74:75], 0, v[208:209]
	s_mov_b32 m0, s76
	v_lshl_add_u64 v[198:199], s[46:47], 0, v[216:217]
	global_load_lds_dwordx4 v[196:197], off
	v_lshl_add_u64 v[196:197], s[74:75], 0, v[218:219]
	s_add_i32 m0, s76, 0x2000
	s_nop 0
	global_load_lds_dwordx4 v[196:197], off
	v_lshl_add_u64 v[196:197], s[46:47], 0, v[214:215]
	s_mov_b32 m0, s55
	s_nop 0
	global_load_lds_dwordx4 v[196:197], off
	s_mov_b32 m0, s56
	s_nop 0
	global_load_lds_dwordx4 v[198:199], off
	s_waitcnt vmcnt(8)
	s_waitcnt lgkmcnt(0)
	s_barrier
	s_setprio 1
	s_waitcnt lgkmcnt(0)
	v_mfma_f32_16x16x32_bf16 v[60:63], v[116:119], v[160:163], v[60:63]
	v_mfma_f32_16x16x32_bf16 v[56:59], v[128:131], v[160:163], v[56:59]
	v_mfma_f32_16x16x32_bf16 v[44:47], v[116:119], v[168:171], v[44:47]
	v_mfma_f32_16x16x32_bf16 v[40:43], v[128:131], v[168:171], v[40:43]
	v_mfma_f32_16x16x32_bf16 v[28:31], v[116:119], v[176:179], v[28:31]
	v_mfma_f32_16x16x32_bf16 v[24:27], v[128:131], v[176:179], v[24:27]
	v_mfma_f32_16x16x32_bf16 v[12:15], v[116:119], v[184:187], v[12:15]
	v_mfma_f32_16x16x32_bf16 v[8:11], v[128:131], v[184:187], v[8:11]
	v_mfma_f32_16x16x32_bf16 v[60:63], v[124:127], v[164:167], v[60:63]
	v_mfma_f32_16x16x32_bf16 v[56:59], v[132:135], v[164:167], v[56:59]
	v_mfma_f32_16x16x32_bf16 v[44:47], v[124:127], v[172:175], v[44:47]
	v_mfma_f32_16x16x32_bf16 v[40:43], v[132:135], v[172:175], v[40:43]
	v_mfma_f32_16x16x32_bf16 v[28:31], v[124:127], v[180:183], v[28:31]
	v_mfma_f32_16x16x32_bf16 v[24:27], v[132:135], v[180:183], v[24:27]
	v_mfma_f32_16x16x32_bf16 v[12:15], v[124:127], v[188:191], v[12:15]
	v_mfma_f32_16x16x32_bf16 v[8:11], v[132:135], v[188:191], v[8:11]
	v_mfma_f32_16x16x32_bf16 v[52:55], v[144:147], v[160:163], v[52:55]
	v_mfma_f32_16x16x32_bf16 v[48:51], v[152:155], v[160:163], v[48:51]
	v_mfma_f32_16x16x32_bf16 v[36:39], v[144:147], v[168:171], v[36:39]
	v_mfma_f32_16x16x32_bf16 v[32:35], v[152:155], v[168:171], v[32:35]
	v_mfma_f32_16x16x32_bf16 v[20:23], v[144:147], v[176:179], v[20:23]
	v_mfma_f32_16x16x32_bf16 v[16:19], v[152:155], v[176:179], v[16:19]
	v_mfma_f32_16x16x32_bf16 v[4:7], v[144:147], v[184:187], v[4:7]
	v_mfma_f32_16x16x32_bf16 v[0:3], v[152:155], v[184:187], v[0:3]
	v_mfma_f32_16x16x32_bf16 v[52:55], v[148:151], v[164:167], v[52:55]
	v_mfma_f32_16x16x32_bf16 v[48:51], v[156:159], v[164:167], v[48:51]
	v_mfma_f32_16x16x32_bf16 v[36:39], v[148:151], v[172:175], v[36:39]
	v_mfma_f32_16x16x32_bf16 v[32:35], v[156:159], v[172:175], v[32:35]
	v_mfma_f32_16x16x32_bf16 v[20:23], v[148:151], v[180:183], v[20:23]
	v_mfma_f32_16x16x32_bf16 v[16:19], v[156:159], v[180:183], v[16:19]
	v_mfma_f32_16x16x32_bf16 v[4:7], v[148:151], v[188:191], v[4:7]
	v_mfma_f32_16x16x32_bf16 v[0:3], v[156:159], v[188:191], v[0:3]
	s_setprio 0
	s_barrier
; #define PG8_STAGE(bufoff, gbase, voff) do { _Pragma("unroll") for (int _i = 0; _i < 2; ++_i) \
;         __builtin_amdgcn_global_load_lds((const unsigned*)((const char*)(gbase) + (voff)[_i]), (PG8_LAS unsigned*)(lds + (bufoff) + ldsw + _i * 8192), 16, 0, 0); } while (0)
; #define PG8_LDA(dst, b, h) do { _Pragma("unroll") for (int m = 0; m < 4; ++m) _Pragma("unroll") for (int k = 0; k < 2; ++k) dst[m][k] = *(const PG8_LAS bf16x8*)(lds + PG8_SA(b, h) + aoff + m * 2048 + k * 1024); } while (0)
; #define PG8_LDB(dst, b, h) do { _Pragma("unroll") for (int n = 0; n < 2; ++n) _Pragma("unroll") for (int k = 0; k < 2; ++k) dst[n][k] = *(const PG8_LAS bf16x8*)(lds + PG8_SB(b, h) + boff + n * 2048 + k * 1024); } while (0)
; #define PG8_MMA(ai, bj, At, Bt) do { __builtin_amdgcn_s_setprio(1); _Pragma("unroll") for (int m = 0; m < 4; ++m) _Pragma("unroll") for (int n = 0; n < 2; ++n) _Pragma("unroll") for (int k = 0; k < 2; ++k) \
;         acc[ai][bj][m][n] = __builtin_amdgcn_mfma_f32_16x16x32_bf16(Bt[n][k], At[m][k], acc[ai][bj][m][n], 0, 0, 0); __builtin_amdgcn_s_setprio(0); } while (0)
; #define PG8_WAIT_V(n) asm volatile("s_waitcnt vmcnt(" #n ")" ::: "memory")
; #define PG8_WAIT_L(n) asm volatile("s_waitcnt lgkmcnt(" #n ")" ::: "memory")
; #define PG8_BAR __builtin_amdgcn_s_barrier()
; #define PG8_SCHED __builtin_amdgcn_sched_barrier(0)
; template <class Epi, class Sched, bool ALIGN_EPI = false, bool SP2 = false>
; __device__ __forceinline__ void gemm_phase(PG8_LAS unsigned char* lds, const Gemm g, const Sched& S, const Epi& E, const int tid) {
;     ...
;             PG8_LDB(B0, 1, 0); PG8_LDB(B1, 1, 1); PG8_SCHED; PG8_LDA(At, 1, 0); PG8_STAGE(PG8_SA(0, 1), a2 + hstep, voffA);
;             PG8_WAIT_V(8); PG8_WAIT_L(0); PG8_BAR; PG8_MMA(0, 0, At, B0); PG8_MMA(0, 1, At, B1); PG8_BAR; PG8_SCHED;
.Lmy_mid_1559:
	s_add_i32 s74, 0, 0x18000
	s_add_i32 s75, 0, 0x1c000
	v_add_u32_e32 v132, s74, v252
	v_add_u32_e32 v156, s75, v252
	ds_read_b128 v[116:119], v132
	ds_read_b128 v[124:127], v132 offset:1024
	ds_read_b128 v[128:131], v132 offset:2048
	ds_read_b128 v[132:135], v132 offset:3072
	ds_read_b128 v[144:147], v156
	ds_read_b128 v[148:151], v156 offset:1024
	ds_read_b128 v[152:155], v156 offset:2048
	ds_read_b128 v[156:159], v156 offset:3072
	s_add_u32 s46, s46, 0x200000
	s_addc_u32 s47, s47, 0
	s_mov_b32 m0, s57
	v_lshl_add_u64 v[200:201], s[46:47], 0, v[214:215]
	ds_read_b128 v[160:163], v210 offset:32768
	ds_read_b128 v[164:167], v210 offset:33792
	ds_read_b128 v[168:171], v210 offset:34816
	ds_read_b128 v[172:175], v210 offset:35840
	ds_read_b128 v[176:179], v210 offset:36864
	ds_read_b128 v[180:183], v210 offset:37888
	ds_read_b128 v[184:187], v210 offset:38912
	ds_read_b128 v[188:191], v210 offset:39936
	global_load_lds_dwordx4 v[200:201], off
	v_lshl_add_u64 v[200:201], s[46:47], 0, v[216:217]
	s_mov_b32 m0, s58
	s_nop 0
	global_load_lds_dwordx4 v[200:201], off
	s_waitcnt vmcnt(8)
	s_waitcnt lgkmcnt(0)
	s_barrier
	s_setprio 1
	s_waitcnt lgkmcnt(0)
	v_mfma_f32_16x16x32_bf16 v[140:143], v[116:119], v[160:163], v[140:143]
	v_mfma_f32_16x16x32_bf16 v[136:139], v[128:131], v[160:163], v[136:139]
	v_mfma_f32_16x16x32_bf16 v[108:111], v[116:119], v[168:171], v[108:111]
	v_mfma_f32_16x16x32_bf16 v[104:107], v[128:131], v[168:171], v[104:107]
	v_mfma_f32_16x16x32_bf16 v[92:95], v[116:119], v[176:179], v[92:95]
	v_mfma_f32_16x16x32_bf16 v[88:91], v[128:131], v[176:179], v[88:91]
	v_mfma_f32_16x16x32_bf16 v[76:79], v[116:119], v[184:187], v[76:79]
	v_mfma_f32_16x16x32_bf16 v[72:75], v[128:131], v[184:187], v[72:75]
	v_mfma_f32_16x16x32_bf16 v[140:143], v[124:127], v[164:167], v[140:143]
	v_mfma_f32_16x16x32_bf16 v[136:139], v[132:135], v[164:167], v[136:139]
	v_mfma_f32_16x16x32_bf16 v[108:111], v[124:127], v[172:175], v[108:111]
	v_mfma_f32_16x16x32_bf16 v[104:107], v[132:135], v[172:175], v[104:107]
	v_mfma_f32_16x16x32_bf16 v[92:95], v[124:127], v[180:183], v[92:95]
	v_mfma_f32_16x16x32_bf16 v[88:91], v[132:135], v[180:183], v[88:91]
	v_mfma_f32_16x16x32_bf16 v[76:79], v[124:127], v[188:191], v[76:79]
	v_mfma_f32_16x16x32_bf16 v[72:75], v[132:135], v[188:191], v[72:75]
	v_mfma_f32_16x16x32_bf16 v[120:123], v[144:147], v[160:163], v[120:123]
	v_mfma_f32_16x16x32_bf16 v[112:115], v[152:155], v[160:163], v[112:115]
	v_mfma_f32_16x16x32_bf16 v[100:103], v[144:147], v[168:171], v[100:103]
	v_mfma_f32_16x16x32_bf16 v[96:99], v[152:155], v[168:171], v[96:99]
	v_mfma_f32_16x16x32_bf16 v[84:87], v[144:147], v[176:179], v[84:87]
	v_mfma_f32_16x16x32_bf16 v[80:83], v[152:155], v[176:179], v[80:83]
	v_mfma_f32_16x16x32_bf16 v[68:71], v[144:147], v[184:187], v[68:71]
	v_mfma_f32_16x16x32_bf16 v[64:67], v[152:155], v[184:187], v[64:67]
	v_mfma_f32_16x16x32_bf16 v[120:123], v[148:151], v[164:167], v[120:123]
	v_mfma_f32_16x16x32_bf16 v[112:115], v[156:159], v[164:167], v[112:115]
	v_mfma_f32_16x16x32_bf16 v[100:103], v[148:151], v[172:175], v[100:103]
	v_mfma_f32_16x16x32_bf16 v[96:99], v[156:159], v[172:175], v[96:99]
	v_mfma_f32_16x16x32_bf16 v[84:87], v[148:151], v[180:183], v[84:87]
	v_mfma_f32_16x16x32_bf16 v[80:83], v[156:159], v[180:183], v[80:83]
	v_mfma_f32_16x16x32_bf16 v[68:71], v[148:151], v[188:191], v[68:71]
	v_mfma_f32_16x16x32_bf16 v[64:67], v[156:159], v[188:191], v[64:67]
	s_setprio 0
	s_barrier
; #define PG8_STAGE(bufoff, gbase, voff) do { _Pragma("unroll") for (int _i = 0; _i < 2; ++_i) \
;         __builtin_amdgcn_global_load_lds((const unsigned*)((const char*)(gbase) + (voff)[_i]), (PG8_LAS unsigned*)(lds + (bufoff) + ldsw + _i * 8192), 16, 0, 0); } while (0)
; #define PG8_LDA(dst, b, h) do { _Pragma("unroll") for (int m = 0; m < 4; ++m) _Pragma("unroll") for (int k = 0; k < 2; ++k) dst[m][k] = *(const PG8_LAS bf16x8*)(lds + PG8_SA(b, h) + aoff + m * 2048 + k * 1024); } while (0)
; #define PG8_MMA(ai, bj, At, Bt) do { __builtin_amdgcn_s_setprio(1); _Pragma("unroll") for (int m = 0; m < 4; ++m) _Pragma("unroll") for (int n = 0; n < 2; ++n) _Pragma("unroll") for (int k = 0; k < 2; ++k) \
;         acc[ai][bj][m][n] = __builtin_amdgcn_mfma_f32_16x16x32_bf16(Bt[n][k], At[m][k], acc[ai][bj][m][n], 0, 0, 0); __builtin_amdgcn_s_setprio(0); } while (0)
; #define PG8_WAIT_V(n) asm volatile("s_waitcnt vmcnt(" #n ")" ::: "memory")
; #define PG8_WAIT_L(n) asm volatile("s_waitcnt lgkmcnt(" #n ")" ::: "memory")
; #define PG8_BAR __builtin_amdgcn_s_barrier()
; #define PG8_SCHED __builtin_amdgcn_sched_barrier(0)
; template <class Epi, class Sched, bool ALIGN_EPI = false, bool SP2 = false>
; __device__ __forceinline__ void gemm_phase(PG8_LAS unsigned char* lds, const Gemm g, const Sched& S, const Epi& E, const int tid) {
;     ...
;             PG8_LDA(At, 1, 1); PG8_STAGE(PG8_SB(1, 0), b3, voffB); PG8_STAGE(PG8_SB(1, 1), b3 + hstep, voffB); PG8_STAGE(PG8_SA(1, 0), a3, voffA);
;             PG8_WAIT_V(8); PG8_WAIT_L(0); PG8_BAR; PG8_MMA(1, 0, At, B0); PG8_MMA(1, 1, At, B1); PG8_BAR; PG8_SCHED;
;     __device__ __forceinline__ void operator()(const f32x4 (&acc)[2][2][4][2], const Unit& un, int wr, int wc, int fr_, int fq_) const {
;         const int ln_ = lane_fresh(), fr = ln_ & 15, fq = ln_ >> 4; (void)fr_; (void)fq_;
;         const int rbase = un.pm * 256 + wr * 64 + fr, cw = un.pn * 256 + wc * 32 + 8 * fq;
;         const bool lat = un.pm < (NLAT / 256);
;         const int slot = lat ? (un.pm >> 5) : 4;
;         const float* src = lat ? srcl : srcc; float* dst = lat ? dstl : dstc; const int radj = lat ? 0 : NLAT;
;         const float* gp = modg + (size_t)slot * 12288; const float* sp2 = sc2 + (size_t)slot * 12288;
	s_add_i32 s46, s74, s54
	v_lshl_add_u64 v[192:193], v[192:193], 0, s[2:3]
	s_mov_b32 m0, s46
	ds_read_b128 v[160:163], v210 offset:49152
	ds_read_b128 v[164:167], v210 offset:50176
	ds_read_b128 v[168:171], v210 offset:51200
	ds_read_b128 v[172:175], v210 offset:52224
	ds_read_b128 v[176:179], v210 offset:53248
	ds_read_b128 v[180:183], v210 offset:54272
	ds_read_b128 v[184:187], v210 offset:55296
	ds_read_b128 v[188:191], v210 offset:56320
	global_load_lds_dwordx4 v[192:193], off
	s_add_i32 m0, s46, 0x2000
	s_add_u32 s44, s44, 0x200080
	v_lshl_add_u64 v[192:193], v[194:195], 0, s[2:3]
	s_addc_u32 s45, s45, 0
	s_add_i32 s46, s75, s54
	global_load_lds_dwordx4 v[192:193], off
	v_lshl_add_u64 v[192:193], s[44:45], 0, v[208:209]
	s_mov_b32 m0, s46
	s_nop 0
	global_load_lds_dwordx4 v[192:193], off
	v_lshl_add_u64 v[192:193], s[44:45], 0, v[218:219]
	s_add_i32 m0, s46, 0x2000
	s_nop 0
	global_load_lds_dwordx4 v[192:193], off
	v_lshl_add_u64 v[192:193], v[196:197], 0, s[2:3]
	s_mov_b32 m0, s66
	s_nop 0
	global_load_lds_dwordx4 v[192:193], off
	v_lshl_add_u64 v[192:193], v[198:199], 0, s[2:3]
	s_mov_b32 m0, s67
	s_nop 0
	global_load_lds_dwordx4 v[192:193], off
	s_waitcnt vmcnt(8)
	s_waitcnt lgkmcnt(0)
	s_barrier
	s_setprio 1
	s_waitcnt lgkmcnt(0)
	v_mfma_f32_16x16x32_bf16 v[60:63], v[116:119], v[160:163], v[60:63]
	v_mfma_f32_16x16x32_bf16 v[56:59], v[128:131], v[160:163], v[56:59]
	v_mfma_f32_16x16x32_bf16 v[44:47], v[116:119], v[168:171], v[44:47]
	v_mfma_f32_16x16x32_bf16 v[40:43], v[128:131], v[168:171], v[40:43]
	v_mfma_f32_16x16x32_bf16 v[28:31], v[116:119], v[176:179], v[28:31]
	v_mfma_f32_16x16x32_bf16 v[24:27], v[128:131], v[176:179], v[24:27]
	v_mfma_f32_16x16x32_bf16 v[12:15], v[116:119], v[184:187], v[12:15]
	v_mfma_f32_16x16x32_bf16 v[8:11], v[128:131], v[184:187], v[8:11]
	v_mfma_f32_16x16x32_bf16 v[60:63], v[124:127], v[164:167], v[60:63]
	v_mfma_f32_16x16x32_bf16 v[56:59], v[132:135], v[164:167], v[56:59]
	v_mfma_f32_16x16x32_bf16 v[44:47], v[124:127], v[172:175], v[44:47]
	v_mfma_f32_16x16x32_bf16 v[40:43], v[132:135], v[172:175], v[40:43]
	v_mfma_f32_16x16x32_bf16 v[28:31], v[124:127], v[180:183], v[28:31]
	v_mfma_f32_16x16x32_bf16 v[24:27], v[132:135], v[180:183], v[24:27]
	v_mfma_f32_16x16x32_bf16 v[12:15], v[124:127], v[188:191], v[12:15]
	v_mfma_f32_16x16x32_bf16 v[8:11], v[132:135], v[188:191], v[8:11]
	v_mfma_f32_16x16x32_bf16 v[52:55], v[144:147], v[160:163], v[52:55]
	v_mfma_f32_16x16x32_bf16 v[48:51], v[152:155], v[160:163], v[48:51]
	v_mfma_f32_16x16x32_bf16 v[36:39], v[144:147], v[168:171], v[36:39]
	v_mfma_f32_16x16x32_bf16 v[32:35], v[152:155], v[168:171], v[32:35]
	v_mfma_f32_16x16x32_bf16 v[20:23], v[144:147], v[176:179], v[20:23]
	v_mfma_f32_16x16x32_bf16 v[16:19], v[152:155], v[176:179], v[16:19]
	v_mfma_f32_16x16x32_bf16 v[4:7], v[144:147], v[184:187], v[4:7]
	v_mfma_f32_16x16x32_bf16 v[0:3], v[152:155], v[184:187], v[0:3]
	v_mfma_f32_16x16x32_bf16 v[52:55], v[148:151], v[164:167], v[52:55]
	v_mfma_f32_16x16x32_bf16 v[48:51], v[156:159], v[164:167], v[48:51]
	v_mfma_f32_16x16x32_bf16 v[36:39], v[148:151], v[172:175], v[36:39]
	v_mfma_f32_16x16x32_bf16 v[32:35], v[156:159], v[172:175], v[32:35]
	v_mfma_f32_16x16x32_bf16 v[20:23], v[148:151], v[180:183], v[20:23]
	v_mfma_f32_16x16x32_bf16 v[16:19], v[156:159], v[180:183], v[16:19]
	v_mfma_f32_16x16x32_bf16 v[4:7], v[148:151], v[188:191], v[4:7]
	v_mfma_f32_16x16x32_bf16 v[0:3], v[156:159], v[188:191], v[0:3]
	s_setprio 0
	s_barrier
	s_add_i32 s73, s73, 2
	s_add_u32 s42, s42, 0x100
	s_addc_u32 s43, s43, 0
	s_add_u32 s71, s71, 0x100
	s_addc_u32 s72, s72, 0
	s_cmpk_gt_u32 s73, 0x7d
	s_cbranch_scc0 .LBB0_1559
	s_cmpk_gt_i32 s40, 0x7f
	s_mov_b32 s71, 0x280000
	s_mov_b32 s72, 0x2c0000
	v_mbcnt_lo_u32_b32 v211, -1, 0
	v_mbcnt_hi_u32_b32 v211, -1, v211
	s_cbranch_scc1 .LBB0_1564
	s_ashr_i32 s29, s40, 5
	s_mul_hi_i32 s47, s29, 0x3000
	s_mul_i32 s46, s29, 0x3000
	s_mov_b32 s29, 0
	s_mov_b64 s[42:43], s[14:15]
	s_mov_b64 s[44:45], s[12:13]
	s_branch .LBB0_1565

; #define PG8_STAGE(bufoff, gbase, voff) do { _Pragma("unroll") for (int _i = 0; _i < 2; ++_i) \
;         __builtin_amdgcn_global_load_lds((const unsigned*)((const char*)(gbase) + (voff)[_i]), (PG8_LAS unsigned*)(lds + (bufoff) + ldsw + _i * 8192), 16, 0, 0); } while (0)
; #define PG8_LDA(dst, b, h) do { _Pragma("unroll") for (int m = 0; m < 4; ++m) _Pragma("unroll") for (int k = 0; k < 2; ++k) dst[m][k] = *(const PG8_LAS bf16x8*)(lds + PG8_SA(b, h) + aoff + m * 2048 + k * 1024); } while (0)
; #define PG8_LDB(dst, b, h) do { _Pragma("unroll") for (int n = 0; n < 2; ++n) _Pragma("unroll") for (int k = 0; k < 2; ++k) dst[n][k] = *(const PG8_LAS bf16x8*)(lds + PG8_SB(b, h) + boff + n * 2048 + k * 1024); } while (0)
; #define PG8_MMA(ai, bj, At, Bt) do { __builtin_amdgcn_s_setprio(1); _Pragma("unroll") for (int m = 0; m < 4; ++m) _Pragma("unroll") for (int n = 0; n < 2; ++n) _Pragma("unroll") for (int k = 0; k < 2; ++k) \
;         acc[ai][bj][m][n] = __builtin_amdgcn_mfma_f32_16x16x32_bf16(Bt[n][k], At[m][k], acc[ai][bj][m][n], 0, 0, 0); __builtin_amdgcn_s_setprio(0); } while (0)
; #define PG8_WAIT_V(n) asm volatile("s_waitcnt vmcnt(" #n ")" ::: "memory")
; #define PG8_WAIT_L(n) asm volatile("s_waitcnt lgkmcnt(" #n ")" ::: "memory")
; #define PG8_BAR __builtin_amdgcn_s_barrier()
; #define PG8_SCHED __builtin_amdgcn_sched_barrier(0)
; template <class Epi, class Sched, bool ALIGN_EPI = false, bool SP2 = false>
; __device__ __forceinline__ void gemm_phase(PG8_LAS unsigned char* lds, const Gemm g, const Sched& S, const Epi& E, const int tid) {
;     ...
;             PG8_LDB(B0, 0, 0); PG8_LDB(B1, 0, 1); PG8_SCHED; PG8_LDA(At, 0, 0); PG8_STAGE(PG8_SA(1, 1), a1 + hstep, voffA);
;             PG8_WAIT_V(8); PG8_WAIT_L(0); PG8_BAR; PG8_MMA(0, 0, At, B0); PG8_MMA(0, 1, At, B1); PG8_BAR; PG8_SCHED;
;             PG8_LDA(At, 0, 1); PG8_STAGE(PG8_SB(0, 0), b2, voffB); PG8_STAGE(PG8_SB(0, 1), b2 + hstep, voffB); PG8_STAGE(PG8_SA(0, 0), a2, voffA);
;             PG8_WAIT_V(8); PG8_WAIT_L(0); PG8_BAR; PG8_MMA(1, 0, At, B0); PG8_MMA(1, 1, At, B1); PG8_BAR; PG8_SCHED;
.Lmy_nobar_1604:
	s_add_u32 s34, s30, 0xffe00080
	s_addc_u32 s35, s31, -1
	s_add_i32 s61, 0, 0x10000
	v_add_u32_e32 v140, s61, v161
	v_add_u32_e32 v158, s33, v161
	ds_read_b128 v[128:131], v140
	ds_read_b128 v[132:135], v140 offset:1024
	ds_read_b128 v[136:139], v140 offset:2048
	ds_read_b128 v[140:143], v140 offset:3072
	ds_read_b128 v[154:157], v158
	ds_read_b128 v[164:167], v158 offset:1024
	ds_read_b128 v[168:171], v158 offset:2048
	ds_read_b128 v[172:175], v158 offset:3072
	s_cmpk_eq_i32 s60, 0x7c
	s_cselect_b32 s37, s23, s35
	s_cselect_b32 s36, s56, s34
	s_cselect_b32 s35, s21, s59
	s_cselect_b32 s34, s57, s58
	v_lshl_add_u64 v[158:159], s[30:31], 0, v[150:151]
	s_add_i32 m0, s29, 0xc000
	ds_read_b128 v[176:179], v163
	ds_read_b128 v[180:183], v163 offset:1024
	ds_read_b128 v[184:187], v163 offset:2048
	ds_read_b128 v[188:191], v163 offset:3072
	ds_read_b128 v[192:195], v163 offset:4096
	ds_read_b128 v[196:199], v163 offset:5120
	ds_read_b128 v[200:203], v163 offset:6144
	ds_read_b128 v[204:207], v163 offset:7168
	global_load_lds_dwordx4 v[158:159], off
	v_lshl_add_u64 v[158:159], s[30:31], 0, v[152:153]
	s_add_i32 m0, s29, 0xe000
	s_nop 0
	global_load_lds_dwordx4 v[158:159], off
	s_waitcnt vmcnt(8)
	s_waitcnt lgkmcnt(0)
	s_barrier
	s_setprio 1
	s_waitcnt lgkmcnt(0)
	v_mfma_f32_16x16x32_bf16 v[124:127], v[128:131], v[176:179], 0
	v_mfma_f32_16x16x32_bf16 v[120:123], v[136:139], v[176:179], 0
	v_mfma_f32_16x16x32_bf16 v[116:119], v[128:131], v[184:187], 0
	v_mfma_f32_16x16x32_bf16 v[112:115], v[136:139], v[184:187], 0
	v_mfma_f32_16x16x32_bf16 v[108:111], v[128:131], v[192:195], 0
	v_mfma_f32_16x16x32_bf16 v[100:103], v[136:139], v[192:195], 0
	v_mfma_f32_16x16x32_bf16 v[92:95], v[128:131], v[200:203], 0
	v_mfma_f32_16x16x32_bf16 v[72:75], v[136:139], v[200:203], 0
	v_mfma_f32_16x16x32_bf16 v[124:127], v[132:135], v[180:183], v[124:127]
	v_mfma_f32_16x16x32_bf16 v[120:123], v[140:143], v[180:183], v[120:123]
	v_mfma_f32_16x16x32_bf16 v[116:119], v[132:135], v[188:191], v[116:119]
	v_mfma_f32_16x16x32_bf16 v[112:115], v[140:143], v[188:191], v[112:115]
	v_mfma_f32_16x16x32_bf16 v[108:111], v[132:135], v[196:199], v[108:111]
	v_mfma_f32_16x16x32_bf16 v[100:103], v[140:143], v[196:199], v[100:103]
	v_mfma_f32_16x16x32_bf16 v[92:95], v[132:135], v[204:207], v[92:95]
	v_mfma_f32_16x16x32_bf16 v[72:75], v[140:143], v[204:207], v[72:75]
	v_mfma_f32_16x16x32_bf16 v[104:107], v[154:157], v[176:179], 0
	v_mfma_f32_16x16x32_bf16 v[96:99], v[168:171], v[176:179], 0
	v_mfma_f32_16x16x32_bf16 v[88:91], v[154:157], v[184:187], 0
	v_mfma_f32_16x16x32_bf16 v[84:87], v[168:171], v[184:187], 0
	v_mfma_f32_16x16x32_bf16 v[80:83], v[154:157], v[192:195], 0
	v_mfma_f32_16x16x32_bf16 v[76:79], v[168:171], v[192:195], 0
	v_mfma_f32_16x16x32_bf16 v[68:71], v[154:157], v[200:203], 0
	v_mfma_f32_16x16x32_bf16 v[64:67], v[168:171], v[200:203], 0
	v_mfma_f32_16x16x32_bf16 v[104:107], v[164:167], v[180:183], v[104:107]
	v_mfma_f32_16x16x32_bf16 v[96:99], v[172:175], v[180:183], v[96:99]
	v_mfma_f32_16x16x32_bf16 v[88:91], v[164:167], v[188:191], v[88:91]
	v_mfma_f32_16x16x32_bf16 v[84:87], v[172:175], v[188:191], v[84:87]
	v_mfma_f32_16x16x32_bf16 v[80:83], v[164:167], v[196:199], v[80:83]
	v_mfma_f32_16x16x32_bf16 v[76:79], v[172:175], v[196:199], v[76:79]
	v_mfma_f32_16x16x32_bf16 v[68:71], v[164:167], v[204:207], v[68:71]
	v_mfma_f32_16x16x32_bf16 v[64:67], v[172:175], v[204:207], v[64:67]
	s_setprio 0
	s_barrier
	s_add_i32 s61, s61, s45
	v_lshl_add_u64 v[158:159], s[34:35], 0, v[208:209]
	s_mov_b32 m0, s61
	ds_read_b128 v[176:179], v163 offset:16384
	ds_read_b128 v[180:183], v163 offset:17408
	ds_read_b128 v[184:187], v163 offset:18432
	ds_read_b128 v[188:191], v163 offset:19456
	ds_read_b128 v[192:195], v163 offset:20480
	ds_read_b128 v[196:199], v163 offset:21504
	ds_read_b128 v[200:203], v163 offset:22528
	ds_read_b128 v[204:207], v163 offset:23552
	global_load_lds_dwordx4 v[158:159], off
	s_add_i32 m0, s61, 0x2000
	s_add_u32 s62, s34, 0x200000
	v_lshl_add_u64 v[210:211], s[34:35], 0, v[148:149]
	s_addc_u32 s63, s35, 0
	s_add_i32 s61, s33, s45
	global_load_lds_dwordx4 v[210:211], off
	v_lshl_add_u64 v[212:213], s[62:63], 0, v[208:209]
	s_mov_b32 m0, s61
	v_lshl_add_u64 v[214:215], s[36:37], 0, v[146:147]
	global_load_lds_dwordx4 v[212:213], off
	v_lshl_add_u64 v[212:213], s[62:63], 0, v[148:149]
	s_add_i32 m0, s61, 0x2000
	s_nop 0
	global_load_lds_dwordx4 v[212:213], off
	v_lshl_add_u64 v[212:213], s[36:37], 0, v[144:145]
	s_mov_b32 m0, s29
	s_nop 0
	global_load_lds_dwordx4 v[212:213], off
	s_mov_b32 m0, s46
	s_nop 0
	global_load_lds_dwordx4 v[214:215], off
	s_waitcnt vmcnt(8)
	s_waitcnt lgkmcnt(0)
	s_barrier
	s_setprio 1
	s_waitcnt lgkmcnt(0)
	v_mfma_f32_16x16x32_bf16 v[60:63], v[128:131], v[176:179], 0
	v_mfma_f32_16x16x32_bf16 v[56:59], v[136:139], v[176:179], 0
	v_mfma_f32_16x16x32_bf16 v[52:55], v[128:131], v[184:187], 0
	v_mfma_f32_16x16x32_bf16 v[48:51], v[136:139], v[184:187], 0
	v_mfma_f32_16x16x32_bf16 v[44:47], v[128:131], v[192:195], 0
	v_mfma_f32_16x16x32_bf16 v[36:39], v[136:139], v[192:195], 0
	v_mfma_f32_16x16x32_bf16 v[20:23], v[128:131], v[200:203], 0
	v_mfma_f32_16x16x32_bf16 v[8:11], v[136:139], v[200:203], 0
	v_mfma_f32_16x16x32_bf16 v[60:63], v[132:135], v[180:183], v[60:63]
	v_mfma_f32_16x16x32_bf16 v[56:59], v[140:143], v[180:183], v[56:59]
	v_mfma_f32_16x16x32_bf16 v[52:55], v[132:135], v[188:191], v[52:55]
	v_mfma_f32_16x16x32_bf16 v[48:51], v[140:143], v[188:191], v[48:51]
	v_mfma_f32_16x16x32_bf16 v[44:47], v[132:135], v[196:199], v[44:47]
	v_mfma_f32_16x16x32_bf16 v[36:39], v[140:143], v[196:199], v[36:39]
	v_mfma_f32_16x16x32_bf16 v[20:23], v[132:135], v[204:207], v[20:23]
	v_mfma_f32_16x16x32_bf16 v[8:11], v[140:143], v[204:207], v[8:11]
	v_mfma_f32_16x16x32_bf16 v[40:43], v[154:157], v[176:179], 0
	v_mfma_f32_16x16x32_bf16 v[32:35], v[168:171], v[176:179], 0
	v_mfma_f32_16x16x32_bf16 v[28:31], v[154:157], v[184:187], 0
	v_mfma_f32_16x16x32_bf16 v[24:27], v[168:171], v[184:187], 0
	v_mfma_f32_16x16x32_bf16 v[16:19], v[154:157], v[192:195], 0
	v_mfma_f32_16x16x32_bf16 v[12:15], v[168:171], v[192:195], 0
	v_mfma_f32_16x16x32_bf16 v[4:7], v[154:157], v[200:203], 0
	v_mfma_f32_16x16x32_bf16 v[0:3], v[168:171], v[200:203], 0
	v_mfma_f32_16x16x32_bf16 v[40:43], v[164:167], v[180:183], v[40:43]
	v_mfma_f32_16x16x32_bf16 v[32:35], v[172:175], v[180:183], v[32:35]
	v_mfma_f32_16x16x32_bf16 v[28:31], v[164:167], v[188:191], v[28:31]
	v_mfma_f32_16x16x32_bf16 v[24:27], v[172:175], v[188:191], v[24:27]
	v_mfma_f32_16x16x32_bf16 v[16:19], v[164:167], v[196:199], v[16:19]
	v_mfma_f32_16x16x32_bf16 v[12:15], v[172:175], v[196:199], v[12:15]
	v_mfma_f32_16x16x32_bf16 v[4:7], v[164:167], v[204:207], v[4:7]
	v_mfma_f32_16x16x32_bf16 v[0:3], v[172:175], v[204:207], v[0:3]
	s_setprio 0
	s_barrier
	s_branch .Lmy_mid_1604
; #define PG8_STAGE(bufoff, gbase, voff) do { _Pragma("unroll") for (int _i = 0; _i < 2; ++_i) \
;         __builtin_amdgcn_global_load_lds((const unsigned*)((const char*)(gbase) + (voff)[_i]), (PG8_LAS unsigned*)(lds + (bufoff) + ldsw + _i * 8192), 16, 0, 0); } while (0)
; #define PG8_LDA(dst, b, h) do { _Pragma("unroll") for (int m = 0; m < 4; ++m) _Pragma("unroll") for (int k = 0; k < 2; ++k) dst[m][k] = *(const PG8_LAS bf16x8*)(lds + PG8_SA(b, h) + aoff + m * 2048 + k * 1024); } while (0)
; #define PG8_LDB(dst, b, h) do { _Pragma("unroll") for (int n = 0; n < 2; ++n) _Pragma("unroll") for (int k = 0; k < 2; ++k) dst[n][k] = *(const PG8_LAS bf16x8*)(lds + PG8_SB(b, h) + boff + n * 2048 + k * 1024); } while (0)
; #define PG8_MMA(ai, bj, At, Bt) do { __builtin_amdgcn_s_setprio(1); _Pragma("unroll") for (int m = 0; m < 4; ++m) _Pragma("unroll") for (int n = 0; n < 2; ++n) _Pragma("unroll") for (int k = 0; k < 2; ++k) \
;         acc[ai][bj][m][n] = __builtin_amdgcn_mfma_f32_16x16x32_bf16(Bt[n][k], At[m][k], acc[ai][bj][m][n], 0, 0, 0); __builtin_amdgcn_s_setprio(0); } while (0)
; #define PG8_WAIT_V(n) asm volatile("s_waitcnt vmcnt(" #n ")" ::: "memory")
; #define PG8_WAIT_L(n) asm volatile("s_waitcnt lgkmcnt(" #n ")" ::: "memory")
; #define PG8_BAR __builtin_amdgcn_s_barrier()
; #define PG8_SCHED __builtin_amdgcn_sched_barrier(0)
; template <class Epi, class Sched, bool ALIGN_EPI = false, bool SP2 = false>
; __device__ __forceinline__ void gemm_phase(PG8_LAS unsigned char* lds, const Gemm g, const Sched& S, const Epi& E, const int tid) {
;     ...
;             PG8_LDB(B0, 0, 0); PG8_LDB(B1, 0, 1); PG8_SCHED; PG8_LDA(At, 0, 0); PG8_STAGE(PG8_SA(1, 1), a1 + hstep, voffA);
;             PG8_WAIT_V(8); PG8_WAIT_L(0); PG8_BAR; PG8_MMA(0, 0, At, B0); PG8_MMA(0, 1, At, B1); PG8_BAR; PG8_SCHED;
;             PG8_LDA(At, 0, 1); PG8_STAGE(PG8_SB(0, 0), b2, voffB); PG8_STAGE(PG8_SB(0, 1), b2 + hstep, voffB); PG8_STAGE(PG8_SA(0, 0), a2, voffA);
;             PG8_WAIT_V(8); PG8_WAIT_L(0); PG8_BAR; PG8_MMA(1, 0, At, B0); PG8_MMA(1, 1, At, B1); PG8_BAR; PG8_SCHED;
.LBB0_1604:
	s_add_u32 s34, s30, 0xffe00080
	s_addc_u32 s35, s31, -1
	s_add_i32 s61, 0, 0x10000
	v_add_u32_e32 v140, s61, v161
	v_add_u32_e32 v158, s33, v161
	ds_read_b128 v[128:131], v140
	ds_read_b128 v[132:135], v140 offset:1024
	ds_read_b128 v[136:139], v140 offset:2048
	ds_read_b128 v[140:143], v140 offset:3072
	ds_read_b128 v[154:157], v158
	ds_read_b128 v[164:167], v158 offset:1024
	ds_read_b128 v[168:171], v158 offset:2048
	ds_read_b128 v[172:175], v158 offset:3072
	s_cmpk_eq_i32 s60, 0x7c
	s_cselect_b32 s37, s23, s35
	s_cselect_b32 s36, s56, s34
	s_cselect_b32 s35, s21, s59
	s_cselect_b32 s34, s57, s58
	v_lshl_add_u64 v[158:159], s[30:31], 0, v[150:151]
	s_add_i32 m0, s29, 0xc000
	ds_read_b128 v[176:179], v163
	ds_read_b128 v[180:183], v163 offset:1024
	ds_read_b128 v[184:187], v163 offset:2048
	ds_read_b128 v[188:191], v163 offset:3072
	ds_read_b128 v[192:195], v163 offset:4096
	ds_read_b128 v[196:199], v163 offset:5120
	ds_read_b128 v[200:203], v163 offset:6144
	ds_read_b128 v[204:207], v163 offset:7168
	global_load_lds_dwordx4 v[158:159], off
	v_lshl_add_u64 v[158:159], s[30:31], 0, v[152:153]
	s_add_i32 m0, s29, 0xe000
	s_nop 0
	global_load_lds_dwordx4 v[158:159], off
	s_waitcnt vmcnt(8)
	s_waitcnt lgkmcnt(0)
	s_barrier
	s_setprio 1
	s_waitcnt lgkmcnt(0)
	v_mfma_f32_16x16x32_bf16 v[124:127], v[128:131], v[176:179], v[124:127]
	v_mfma_f32_16x16x32_bf16 v[120:123], v[136:139], v[176:179], v[120:123]
	v_mfma_f32_16x16x32_bf16 v[116:119], v[128:131], v[184:187], v[116:119]
	v_mfma_f32_16x16x32_bf16 v[112:115], v[136:139], v[184:187], v[112:115]
	v_mfma_f32_16x16x32_bf16 v[108:111], v[128:131], v[192:195], v[108:111]
	v_mfma_f32_16x16x32_bf16 v[100:103], v[136:139], v[192:195], v[100:103]
	v_mfma_f32_16x16x32_bf16 v[92:95], v[128:131], v[200:203], v[92:95]
	v_mfma_f32_16x16x32_bf16 v[72:75], v[136:139], v[200:203], v[72:75]
	v_mfma_f32_16x16x32_bf16 v[124:127], v[132:135], v[180:183], v[124:127]
	v_mfma_f32_16x16x32_bf16 v[120:123], v[140:143], v[180:183], v[120:123]
	v_mfma_f32_16x16x32_bf16 v[116:119], v[132:135], v[188:191], v[116:119]
	v_mfma_f32_16x16x32_bf16 v[112:115], v[140:143], v[188:191], v[112:115]
	v_mfma_f32_16x16x32_bf16 v[108:111], v[132:135], v[196:199], v[108:111]
	v_mfma_f32_16x16x32_bf16 v[100:103], v[140:143], v[196:199], v[100:103]
	v_mfma_f32_16x16x32_bf16 v[92:95], v[132:135], v[204:207], v[92:95]
	v_mfma_f32_16x16x32_bf16 v[72:75], v[140:143], v[204:207], v[72:75]
	v_mfma_f32_16x16x32_bf16 v[104:107], v[154:157], v[176:179], v[104:107]
	v_mfma_f32_16x16x32_bf16 v[96:99], v[168:171], v[176:179], v[96:99]
	v_mfma_f32_16x16x32_bf16 v[88:91], v[154:157], v[184:187], v[88:91]
	v_mfma_f32_16x16x32_bf16 v[84:87], v[168:171], v[184:187], v[84:87]
	v_mfma_f32_16x16x32_bf16 v[80:83], v[154:157], v[192:195], v[80:83]
	v_mfma_f32_16x16x32_bf16 v[76:79], v[168:171], v[192:195], v[76:79]
	v_mfma_f32_16x16x32_bf16 v[68:71], v[154:157], v[200:203], v[68:71]
	v_mfma_f32_16x16x32_bf16 v[64:67], v[168:171], v[200:203], v[64:67]
	v_mfma_f32_16x16x32_bf16 v[104:107], v[164:167], v[180:183], v[104:107]
	v_mfma_f32_16x16x32_bf16 v[96:99], v[172:175], v[180:183], v[96:99]
	v_mfma_f32_16x16x32_bf16 v[88:91], v[164:167], v[188:191], v[88:91]
	v_mfma_f32_16x16x32_bf16 v[84:87], v[172:175], v[188:191], v[84:87]
	v_mfma_f32_16x16x32_bf16 v[80:83], v[164:167], v[196:199], v[80:83]
	v_mfma_f32_16x16x32_bf16 v[76:79], v[172:175], v[196:199], v[76:79]
	v_mfma_f32_16x16x32_bf16 v[68:71], v[164:167], v[204:207], v[68:71]
	v_mfma_f32_16x16x32_bf16 v[64:67], v[172:175], v[204:207], v[64:67]
	s_setprio 0
	s_barrier
	s_add_i32 s61, s61, s45
	v_lshl_add_u64 v[158:159], s[34:35], 0, v[208:209]
	s_mov_b32 m0, s61
	ds_read_b128 v[176:179], v163 offset:16384
	ds_read_b128 v[180:183], v163 offset:17408
	ds_read_b128 v[184:187], v163 offset:18432
	ds_read_b128 v[188:191], v163 offset:19456
	ds_read_b128 v[192:195], v163 offset:20480
	ds_read_b128 v[196:199], v163 offset:21504
	ds_read_b128 v[200:203], v163 offset:22528
	ds_read_b128 v[204:207], v163 offset:23552
	global_load_lds_dwordx4 v[158:159], off
	s_add_i32 m0, s61, 0x2000
	s_add_u32 s62, s34, 0x200000
	v_lshl_add_u64 v[210:211], s[34:35], 0, v[148:149]
	s_addc_u32 s63, s35, 0
	s_add_i32 s61, s33, s45
	global_load_lds_dwordx4 v[210:211], off
	v_lshl_add_u64 v[212:213], s[62:63], 0, v[208:209]
	s_mov_b32 m0, s61
	v_lshl_add_u64 v[214:215], s[36:37], 0, v[146:147]
	global_load_lds_dwordx4 v[212:213], off
	v_lshl_add_u64 v[212:213], s[62:63], 0, v[148:149]
	s_add_i32 m0, s61, 0x2000
	s_nop 0
	global_load_lds_dwordx4 v[212:213], off
	v_lshl_add_u64 v[212:213], s[36:37], 0, v[144:145]
	s_mov_b32 m0, s29
	s_nop 0
	global_load_lds_dwordx4 v[212:213], off
	s_mov_b32 m0, s46
	s_nop 0
	global_load_lds_dwordx4 v[214:215], off
	s_waitcnt vmcnt(8)
	s_waitcnt lgkmcnt(0)
	s_barrier
	s_setprio 1
	s_waitcnt lgkmcnt(0)
	v_mfma_f32_16x16x32_bf16 v[60:63], v[128:131], v[176:179], v[60:63]
	v_mfma_f32_16x16x32_bf16 v[56:59], v[136:139], v[176:179], v[56:59]
	v_mfma_f32_16x16x32_bf16 v[52:55], v[128:131], v[184:187], v[52:55]
	v_mfma_f32_16x16x32_bf16 v[48:51], v[136:139], v[184:187], v[48:51]
	v_mfma_f32_16x16x32_bf16 v[44:47], v[128:131], v[192:195], v[44:47]
	v_mfma_f32_16x16x32_bf16 v[36:39], v[136:139], v[192:195], v[36:39]
	v_mfma_f32_16x16x32_bf16 v[20:23], v[128:131], v[200:203], v[20:23]
	v_mfma_f32_16x16x32_bf16 v[8:11], v[136:139], v[200:203], v[8:11]
	v_mfma_f32_16x16x32_bf16 v[60:63], v[132:135], v[180:183], v[60:63]
	v_mfma_f32_16x16x32_bf16 v[56:59], v[140:143], v[180:183], v[56:59]
	v_mfma_f32_16x16x32_bf16 v[52:55], v[132:135], v[188:191], v[52:55]
	v_mfma_f32_16x16x32_bf16 v[48:51], v[140:143], v[188:191], v[48:51]
	v_mfma_f32_16x16x32_bf16 v[44:47], v[132:135], v[196:199], v[44:47]
	v_mfma_f32_16x16x32_bf16 v[36:39], v[140:143], v[196:199], v[36:39]
	v_mfma_f32_16x16x32_bf16 v[20:23], v[132:135], v[204:207], v[20:23]
	v_mfma_f32_16x16x32_bf16 v[8:11], v[140:143], v[204:207], v[8:11]
	v_mfma_f32_16x16x32_bf16 v[40:43], v[154:157], v[176:179], v[40:43]
	v_mfma_f32_16x16x32_bf16 v[32:35], v[168:171], v[176:179], v[32:35]
	v_mfma_f32_16x16x32_bf16 v[28:31], v[154:157], v[184:187], v[28:31]
	v_mfma_f32_16x16x32_bf16 v[24:27], v[168:171], v[184:187], v[24:27]
	v_mfma_f32_16x16x32_bf16 v[16:19], v[154:157], v[192:195], v[16:19]
	v_mfma_f32_16x16x32_bf16 v[12:15], v[168:171], v[192:195], v[12:15]
	v_mfma_f32_16x16x32_bf16 v[4:7], v[154:157], v[200:203], v[4:7]
	v_mfma_f32_16x16x32_bf16 v[0:3], v[168:171], v[200:203], v[0:3]
	v_mfma_f32_16x16x32_bf16 v[40:43], v[164:167], v[180:183], v[40:43]
	v_mfma_f32_16x16x32_bf16 v[32:35], v[172:175], v[180:183], v[32:35]
	v_mfma_f32_16x16x32_bf16 v[28:31], v[164:167], v[188:191], v[28:31]
	v_mfma_f32_16x16x32_bf16 v[24:27], v[172:175], v[188:191], v[24:27]
	v_mfma_f32_16x16x32_bf16 v[16:19], v[164:167], v[196:199], v[16:19]
	v_mfma_f32_16x16x32_bf16 v[12:15], v[172:175], v[196:199], v[12:15]
	v_mfma_f32_16x16x32_bf16 v[4:7], v[164:167], v[204:207], v[4:7]
	v_mfma_f32_16x16x32_bf16 v[0:3], v[172:175], v[204:207], v[0:3]
	s_setprio 0
	s_barrier
; #define PG8_STAGE(bufoff, gbase, voff) do { _Pragma("unroll") for (int _i = 0; _i < 2; ++_i) \
;         __builtin_amdgcn_global_load_lds((const unsigned*)((const char*)(gbase) + (voff)[_i]), (PG8_LAS unsigned*)(lds + (bufoff) + ldsw + _i * 8192), 16, 0, 0); } while (0)
; #define PG8_LDA(dst, b, h) do { _Pragma("unroll") for (int m = 0; m < 4; ++m) _Pragma("unroll") for (int k = 0; k < 2; ++k) dst[m][k] = *(const PG8_LAS bf16x8*)(lds + PG8_SA(b, h) + aoff + m * 2048 + k * 1024); } while (0)
; #define PG8_LDB(dst, b, h) do { _Pragma("unroll") for (int n = 0; n < 2; ++n) _Pragma("unroll") for (int k = 0; k < 2; ++k) dst[n][k] = *(const PG8_LAS bf16x8*)(lds + PG8_SB(b, h) + boff + n * 2048 + k * 1024); } while (0)
; #define PG8_MMA(ai, bj, At, Bt) do { __builtin_amdgcn_s_setprio(1); _Pragma("unroll") for (int m = 0; m < 4; ++m) _Pragma("unroll") for (int n = 0; n < 2; ++n) _Pragma("unroll") for (int k = 0; k < 2; ++k) \
;         acc[ai][bj][m][n] = __builtin_amdgcn_mfma_f32_16x16x32_bf16(Bt[n][k], At[m][k], acc[ai][bj][m][n], 0, 0, 0); __builtin_amdgcn_s_setprio(0); } while (0)
; #define PG8_WAIT_V(n) asm volatile("s_waitcnt vmcnt(" #n ")" ::: "memory")
; #define PG8_WAIT_L(n) asm volatile("s_waitcnt lgkmcnt(" #n ")" ::: "memory")
; #define PG8_BAR __builtin_amdgcn_s_barrier()
; #define PG8_SCHED __builtin_amdgcn_sched_barrier(0)
; template <class Epi, class Sched, bool ALIGN_EPI = false, bool SP2 = false>
; __device__ __forceinline__ void gemm_phase(PG8_LAS unsigned char* lds, const Gemm g, const Sched& S, const Epi& E, const int tid) {
;     ...
;             PG8_LDB(B0, 1, 0); PG8_LDB(B1, 1, 1); PG8_SCHED; PG8_LDA(At, 1, 0); PG8_STAGE(PG8_SA(0, 1), a2 + hstep, voffA);
;             PG8_WAIT_V(8); PG8_WAIT_L(0); PG8_BAR; PG8_MMA(0, 0, At, B0); PG8_MMA(0, 1, At, B1); PG8_BAR; PG8_SCHED;
.Lmy_mid_1604:
	s_add_i32 s61, 0, 0x18000
	s_add_i32 s62, 0, 0x1c000
	v_add_u32_e32 v140, s61, v161
	v_add_u32_e32 v172, s62, v161
	ds_read_b128 v[128:131], v140
	ds_read_b128 v[132:135], v140 offset:1024
	ds_read_b128 v[136:139], v140 offset:2048
	ds_read_b128 v[140:143], v140 offset:3072
	ds_read_b128 v[154:157], v172
	ds_read_b128 v[164:167], v172 offset:1024
	ds_read_b128 v[168:171], v172 offset:2048
	ds_read_b128 v[172:175], v172 offset:3072
	s_add_u32 s36, s36, 0x200000
	s_addc_u32 s37, s37, 0
	s_mov_b32 m0, s47
	v_lshl_add_u64 v[216:217], s[36:37], 0, v[144:145]
	ds_read_b128 v[176:179], v163 offset:32768
	ds_read_b128 v[180:183], v163 offset:33792
	ds_read_b128 v[184:187], v163 offset:34816
	ds_read_b128 v[188:191], v163 offset:35840
	ds_read_b128 v[192:195], v163 offset:36864
	ds_read_b128 v[196:199], v163 offset:37888
	ds_read_b128 v[200:203], v163 offset:38912
	ds_read_b128 v[204:207], v163 offset:39936
	global_load_lds_dwordx4 v[216:217], off
	v_lshl_add_u64 v[216:217], s[36:37], 0, v[146:147]
	s_mov_b32 m0, s48
	s_nop 0
	global_load_lds_dwordx4 v[216:217], off
	s_waitcnt vmcnt(8)
	s_waitcnt lgkmcnt(0)
	s_barrier
	s_setprio 1
	s_waitcnt lgkmcnt(0)
	v_mfma_f32_16x16x32_bf16 v[124:127], v[128:131], v[176:179], v[124:127]
	v_mfma_f32_16x16x32_bf16 v[120:123], v[136:139], v[176:179], v[120:123]
	v_mfma_f32_16x16x32_bf16 v[116:119], v[128:131], v[184:187], v[116:119]
	v_mfma_f32_16x16x32_bf16 v[112:115], v[136:139], v[184:187], v[112:115]
	v_mfma_f32_16x16x32_bf16 v[108:111], v[128:131], v[192:195], v[108:111]
	v_mfma_f32_16x16x32_bf16 v[100:103], v[136:139], v[192:195], v[100:103]
	v_mfma_f32_16x16x32_bf16 v[92:95], v[128:131], v[200:203], v[92:95]
	v_mfma_f32_16x16x32_bf16 v[72:75], v[136:139], v[200:203], v[72:75]
	v_mfma_f32_16x16x32_bf16 v[124:127], v[132:135], v[180:183], v[124:127]
	v_mfma_f32_16x16x32_bf16 v[120:123], v[140:143], v[180:183], v[120:123]
	v_mfma_f32_16x16x32_bf16 v[116:119], v[132:135], v[188:191], v[116:119]
	v_mfma_f32_16x16x32_bf16 v[112:115], v[140:143], v[188:191], v[112:115]
	v_mfma_f32_16x16x32_bf16 v[108:111], v[132:135], v[196:199], v[108:111]
	v_mfma_f32_16x16x32_bf16 v[100:103], v[140:143], v[196:199], v[100:103]
	v_mfma_f32_16x16x32_bf16 v[92:95], v[132:135], v[204:207], v[92:95]
	v_mfma_f32_16x16x32_bf16 v[72:75], v[140:143], v[204:207], v[72:75]
	v_mfma_f32_16x16x32_bf16 v[104:107], v[154:157], v[176:179], v[104:107]
	v_mfma_f32_16x16x32_bf16 v[96:99], v[168:171], v[176:179], v[96:99]
	v_mfma_f32_16x16x32_bf16 v[88:91], v[154:157], v[184:187], v[88:91]
	v_mfma_f32_16x16x32_bf16 v[84:87], v[168:171], v[184:187], v[84:87]
	v_mfma_f32_16x16x32_bf16 v[80:83], v[154:157], v[192:195], v[80:83]
	v_mfma_f32_16x16x32_bf16 v[76:79], v[168:171], v[192:195], v[76:79]
	v_mfma_f32_16x16x32_bf16 v[68:71], v[154:157], v[200:203], v[68:71]
	v_mfma_f32_16x16x32_bf16 v[64:67], v[168:171], v[200:203], v[64:67]
	v_mfma_f32_16x16x32_bf16 v[104:107], v[164:167], v[180:183], v[104:107]
	v_mfma_f32_16x16x32_bf16 v[96:99], v[172:175], v[180:183], v[96:99]
	v_mfma_f32_16x16x32_bf16 v[88:91], v[164:167], v[188:191], v[88:91]
	v_mfma_f32_16x16x32_bf16 v[84:87], v[172:175], v[188:191], v[84:87]
	v_mfma_f32_16x16x32_bf16 v[80:83], v[164:167], v[196:199], v[80:83]
	v_mfma_f32_16x16x32_bf16 v[76:79], v[172:175], v[196:199], v[76:79]
	v_mfma_f32_16x16x32_bf16 v[68:71], v[164:167], v[204:207], v[68:71]
	v_mfma_f32_16x16x32_bf16 v[64:67], v[172:175], v[204:207], v[64:67]
	s_setprio 0
	s_barrier
; #define PG8_STAGE(bufoff, gbase, voff) do { _Pragma("unroll") for (int _i = 0; _i < 2; ++_i) \
;         __builtin_amdgcn_global_load_lds((const unsigned*)((const char*)(gbase) + (voff)[_i]), (PG8_LAS unsigned*)(lds + (bufoff) + ldsw + _i * 8192), 16, 0, 0); } while (0)
; #define PG8_LDA(dst, b, h) do { _Pragma("unroll") for (int m = 0; m < 4; ++m) _Pragma("unroll") for (int k = 0; k < 2; ++k) dst[m][k] = *(const PG8_LAS bf16x8*)(lds + PG8_SA(b, h) + aoff + m * 2048 + k * 1024); } while (0)
; #define PG8_MMA(ai, bj, At, Bt) do { __builtin_amdgcn_s_setprio(1); _Pragma("unroll") for (int m = 0; m < 4; ++m) _Pragma("unroll") for (int n = 0; n < 2; ++n) _Pragma("unroll") for (int k = 0; k < 2; ++k) \
;         acc[ai][bj][m][n] = __builtin_amdgcn_mfma_f32_16x16x32_bf16(Bt[n][k], At[m][k], acc[ai][bj][m][n], 0, 0, 0); __builtin_amdgcn_s_setprio(0); } while (0)
; #define PG8_WAIT_V(n) asm volatile("s_waitcnt vmcnt(" #n ")" ::: "memory")
; #define PG8_WAIT_L(n) asm volatile("s_waitcnt lgkmcnt(" #n ")" ::: "memory")
; #define PG8_BAR __builtin_amdgcn_s_barrier()
; #define PG8_SCHED __builtin_amdgcn_sched_barrier(0)
; template <class Epi, class Sched, bool ALIGN_EPI = false, bool SP2 = false>
; __device__ __forceinline__ void gemm_phase(PG8_LAS unsigned char* lds, const Gemm g, const Sched& S, const Epi& E, const int tid) {
;     ...
;             PG8_LDA(At, 1, 1); PG8_STAGE(PG8_SB(1, 0), b3, voffB); PG8_STAGE(PG8_SB(1, 1), b3 + hstep, voffB); PG8_STAGE(PG8_SA(1, 0), a3, voffA);
;             PG8_WAIT_V(8); PG8_WAIT_L(0); PG8_BAR; PG8_MMA(1, 0, At, B0); PG8_MMA(1, 1, At, B1); PG8_BAR; PG8_SCHED;
	s_add_i32 s36, s61, s45
	v_lshl_add_u64 v[158:159], v[158:159], 0, s[2:3]
	s_mov_b32 m0, s36
	ds_read_b128 v[176:179], v163 offset:49152
	ds_read_b128 v[180:183], v163 offset:50176
	ds_read_b128 v[184:187], v163 offset:51200
	ds_read_b128 v[188:191], v163 offset:52224
	ds_read_b128 v[192:195], v163 offset:53248
	ds_read_b128 v[196:199], v163 offset:54272
	ds_read_b128 v[200:203], v163 offset:55296
	ds_read_b128 v[204:207], v163 offset:56320
	global_load_lds_dwordx4 v[158:159], off
	s_add_i32 m0, s36, 0x2000
	s_add_u32 s34, s34, 0x200080
	v_lshl_add_u64 v[158:159], v[210:211], 0, s[2:3]
	s_addc_u32 s35, s35, 0
	s_add_i32 s36, s62, s45
	global_load_lds_dwordx4 v[158:159], off
	v_lshl_add_u64 v[158:159], s[34:35], 0, v[208:209]
	s_mov_b32 m0, s36
	s_nop 0
	global_load_lds_dwordx4 v[158:159], off
	v_lshl_add_u64 v[158:159], s[34:35], 0, v[148:149]
	s_add_i32 m0, s36, 0x2000
	s_nop 0
	global_load_lds_dwordx4 v[158:159], off
	v_lshl_add_u64 v[158:159], v[212:213], 0, s[2:3]
	s_mov_b32 m0, s51
	s_nop 0
	global_load_lds_dwordx4 v[158:159], off
	v_lshl_add_u64 v[158:159], v[214:215], 0, s[2:3]
	s_mov_b32 m0, s52
	s_nop 0
	global_load_lds_dwordx4 v[158:159], off
	s_waitcnt vmcnt(8)
	s_waitcnt lgkmcnt(0)
	s_barrier
	s_setprio 1
	s_waitcnt lgkmcnt(0)
	v_mfma_f32_16x16x32_bf16 v[60:63], v[128:131], v[176:179], v[60:63]
	v_mfma_f32_16x16x32_bf16 v[56:59], v[136:139], v[176:179], v[56:59]
	v_mfma_f32_16x16x32_bf16 v[52:55], v[128:131], v[184:187], v[52:55]
	v_mfma_f32_16x16x32_bf16 v[48:51], v[136:139], v[184:187], v[48:51]
	v_mfma_f32_16x16x32_bf16 v[44:47], v[128:131], v[192:195], v[44:47]
	v_mfma_f32_16x16x32_bf16 v[36:39], v[136:139], v[192:195], v[36:39]
	v_mfma_f32_16x16x32_bf16 v[20:23], v[128:131], v[200:203], v[20:23]
	v_mfma_f32_16x16x32_bf16 v[8:11], v[136:139], v[200:203], v[8:11]
	v_mfma_f32_16x16x32_bf16 v[60:63], v[132:135], v[180:183], v[60:63]
	v_mfma_f32_16x16x32_bf16 v[56:59], v[140:143], v[180:183], v[56:59]
	v_mfma_f32_16x16x32_bf16 v[52:55], v[132:135], v[188:191], v[52:55]
	v_mfma_f32_16x16x32_bf16 v[48:51], v[140:143], v[188:191], v[48:51]
	v_mfma_f32_16x16x32_bf16 v[44:47], v[132:135], v[196:199], v[44:47]
	v_mfma_f32_16x16x32_bf16 v[36:39], v[140:143], v[196:199], v[36:39]
	v_mfma_f32_16x16x32_bf16 v[20:23], v[132:135], v[204:207], v[20:23]
	v_mfma_f32_16x16x32_bf16 v[8:11], v[140:143], v[204:207], v[8:11]
	v_mfma_f32_16x16x32_bf16 v[40:43], v[154:157], v[176:179], v[40:43]
	v_mfma_f32_16x16x32_bf16 v[32:35], v[168:171], v[176:179], v[32:35]
	v_mfma_f32_16x16x32_bf16 v[28:31], v[154:157], v[184:187], v[28:31]
	v_mfma_f32_16x16x32_bf16 v[24:27], v[168:171], v[184:187], v[24:27]
	v_mfma_f32_16x16x32_bf16 v[16:19], v[154:157], v[192:195], v[16:19]
	v_mfma_f32_16x16x32_bf16 v[12:15], v[168:171], v[192:195], v[12:15]
	v_mfma_f32_16x16x32_bf16 v[4:7], v[154:157], v[200:203], v[4:7]
	v_mfma_f32_16x16x32_bf16 v[0:3], v[168:171], v[200:203], v[0:3]
	v_mfma_f32_16x16x32_bf16 v[40:43], v[164:167], v[180:183], v[40:43]
	v_mfma_f32_16x16x32_bf16 v[32:35], v[172:175], v[180:183], v[32:35]
	v_mfma_f32_16x16x32_bf16 v[28:31], v[164:167], v[188:191], v[28:31]
	v_mfma_f32_16x16x32_bf16 v[24:27], v[172:175], v[188:191], v[24:27]
	v_mfma_f32_16x16x32_bf16 v[16:19], v[164:167], v[196:199], v[16:19]
	v_mfma_f32_16x16x32_bf16 v[12:15], v[172:175], v[196:199], v[12:15]
	v_mfma_f32_16x16x32_bf16 v[4:7], v[164:167], v[204:207], v[4:7]
	v_mfma_f32_16x16x32_bf16 v[0:3], v[172:175], v[204:207], v[0:3]
	s_setprio 0
	s_barrier
	s_add_i32 s60, s60, 2
	s_add_u32 s30, s30, 0x100
	s_addc_u32 s31, s31, 0
	s_add_u32 s58, s58, 0x100
	s_addc_u32 s59, s59, 0
	s_cmpk_gt_u32 s60, 0x7d
	s_cbranch_scc0 .LBB0_1604
	s_and_b64 vcc, exec, s[8:9]
	s_cbranch_vccz .LBB0_1607
	s_barrier

; #define PG8_STAGE(bufoff, gbase, voff) do { _Pragma("unroll") for (int _i = 0; _i < 2; ++_i) \
;         __builtin_amdgcn_global_load_lds((const unsigned*)((const char*)(gbase) + (voff)[_i]), (PG8_LAS unsigned*)(lds + (bufoff) + ldsw + _i * 8192), 16, 0, 0); } while (0)
; #define PG8_LDA(dst, b, h) do { _Pragma("unroll") for (int m = 0; m < 4; ++m) _Pragma("unroll") for (int k = 0; k < 2; ++k) dst[m][k] = *(const PG8_LAS bf16x8*)(lds + PG8_SA(b, h) + aoff + m * 2048 + k * 1024); } while (0)
; #define PG8_LDB(dst, b, h) do { _Pragma("unroll") for (int n = 0; n < 2; ++n) _Pragma("unroll") for (int k = 0; k < 2; ++k) dst[n][k] = *(const PG8_LAS bf16x8*)(lds + PG8_SB(b, h) + boff + n * 2048 + k * 1024); } while (0)
; #define PG8_WAIT_V(n) asm volatile("s_waitcnt vmcnt(" #n ")" ::: "memory")
; #define PG8_WAIT_L(n) asm volatile("s_waitcnt lgkmcnt(" #n ")" ::: "memory")
; #define PG8_BAR __builtin_amdgcn_s_barrier()
; #define PG8_SCHED __builtin_amdgcn_sched_barrier(0)
; template <class Epi, class Sched, bool ALIGN_EPI = false, bool SP2 = false>
; __device__ __forceinline__ void gemm_phase(PG8_LAS unsigned char* lds, const Gemm g, const Sched& S, const Epi& E, const int tid) {
;     ...
;         const char* nA = has_next ? (const char*)g.A + (size_t)nxt.pm * tstep + (size_t)nxt.kb * g.sA : cA; const char* nB = has_next ? (const char*)g.Bt + (size_t)nxt.pn * tstep + (size_t)nxt.kb * g.sB : cB;
;         for (int t = 0; t < nt; t += 2) {
;             const bool last = (t == nt - 2);
;             const char* a1 = cA + (size_t)(t + 1) * kstep;
;             const char* a2 = last ? nA : cA + (size_t)(t + 2) * kstep; const char* b2 = last ? nB : cB + (size_t)(t + 2) * kstep;
;             const char* a3 = a2 + kstep; const char* b3 = b2 + kstep;
;             if (last && has_next) S.a_ready(nxt);
;             if constexpr (SP2) {
;             PG8_LDB(B0, 0, 0); PG8_LDB(B1, 0, 1); PG8_SCHED; PG8_LDA(At, 0, 0); PG8_STAGE(PG8_SA(1, 1), a1 + hstep, voffA);
;             PG8_WAIT_V(8); PG8_WAIT_L(0); PG8_BAR; PG8_MMA(0, 0, At, B0); PG8_MMA(0, 1, At, B1); PG8_BAR; PG8_SCHED;
;             PG8_LDA(At, 0, 1); PG8_STAGE(PG8_SB(0, 0), b2, voffB); PG8_STAGE(PG8_SB(0, 1), b2 + hstep, voffB); PG8_STAGE(PG8_SA(0, 0), a2, voffA);
;             PG8_WAIT_V(8); PG8_WAIT_L(0); PG8_BAR; PG8_MMA(1, 0, At, B0); PG8_MMA(1, 1, At, B1); PG8_BAR; PG8_SCHED;
.LBB0_1619:
	s_add_u32 s14, s12, 0x100
	s_addc_u32 s15, s13, 0
	s_cmp_lg_u32 s34, 28
	s_cselect_b32 s16, s14, 0
	s_cselect_b32 s17, s15, 0
	s_add_u32 s18, s8, s16
	s_addc_u32 s19, s9, s17
	s_add_i32 s35, 0, 0x10000
	v_add_u32_e32 v154, s35, v140
	v_add_u32_e32 v170, s33, v140
	ds_read_b128 v[142:145], v154
	ds_read_b128 v[146:149], v154 offset:1024
	ds_read_b128 v[150:153], v154 offset:2048
	ds_read_b128 v[154:157], v154 offset:3072
	ds_read_b128 v[158:161], v170
	ds_read_b128 v[162:165], v170 offset:1024
	ds_read_b128 v[166:169], v170 offset:2048
	ds_read_b128 v[170:173], v170 offset:3072
	s_add_u32 s16, s4, s16
	s_addc_u32 s17, s5, s17
	v_lshl_add_u64 v[206:207], v[134:135], 0, s[12:13]
	s_add_i32 m0, s1, 0xc000
	ds_read_b128 v[174:177], v141
	ds_read_b128 v[178:181], v141 offset:1024
	ds_read_b128 v[182:185], v141 offset:2048
	ds_read_b128 v[186:189], v141 offset:3072
	ds_read_b128 v[190:193], v141 offset:4096
	ds_read_b128 v[194:197], v141 offset:5120
	ds_read_b128 v[198:201], v141 offset:6144
	ds_read_b128 v[202:205], v141 offset:7168
	global_load_lds_dwordx4 v[206:207], off
	v_lshl_add_u64 v[206:207], v[136:137], 0, s[12:13]
	s_add_i32 m0, s1, 0xe000
	s_nop 0
	global_load_lds_dwordx4 v[206:207], off
	s_waitcnt vmcnt(8)
	s_waitcnt lgkmcnt(0)
	s_barrier
	s_setprio 1
	s_waitcnt lgkmcnt(0)
	v_mfma_f32_16x16x32_bf16 v[124:127], v[142:145], v[174:177], v[124:127]
	v_mfma_f32_16x16x32_bf16 v[120:123], v[150:153], v[174:177], v[120:123]
	v_mfma_f32_16x16x32_bf16 v[116:119], v[142:145], v[182:185], v[116:119]
	v_mfma_f32_16x16x32_bf16 v[112:115], v[150:153], v[182:185], v[112:115]
	v_mfma_f32_16x16x32_bf16 v[104:107], v[142:145], v[190:193], v[104:107]
	v_mfma_f32_16x16x32_bf16 v[96:99], v[150:153], v[190:193], v[96:99]
	v_mfma_f32_16x16x32_bf16 v[88:91], v[142:145], v[198:201], v[88:91]
	v_mfma_f32_16x16x32_bf16 v[80:83], v[150:153], v[198:201], v[80:83]
	v_mfma_f32_16x16x32_bf16 v[124:127], v[146:149], v[178:181], v[124:127]
	v_mfma_f32_16x16x32_bf16 v[120:123], v[154:157], v[178:181], v[120:123]
	v_mfma_f32_16x16x32_bf16 v[116:119], v[146:149], v[186:189], v[116:119]
	v_mfma_f32_16x16x32_bf16 v[112:115], v[154:157], v[186:189], v[112:115]
	v_mfma_f32_16x16x32_bf16 v[104:107], v[146:149], v[194:197], v[104:107]
	v_mfma_f32_16x16x32_bf16 v[96:99], v[154:157], v[194:197], v[96:99]
	v_mfma_f32_16x16x32_bf16 v[88:91], v[146:149], v[202:205], v[88:91]
	v_mfma_f32_16x16x32_bf16 v[80:83], v[154:157], v[202:205], v[80:83]
	v_mfma_f32_16x16x32_bf16 v[108:111], v[158:161], v[174:177], v[108:111]
	v_mfma_f32_16x16x32_bf16 v[100:103], v[166:169], v[174:177], v[100:103]
	v_mfma_f32_16x16x32_bf16 v[92:95], v[158:161], v[182:185], v[92:95]
	v_mfma_f32_16x16x32_bf16 v[84:87], v[166:169], v[182:185], v[84:87]
	v_mfma_f32_16x16x32_bf16 v[76:79], v[158:161], v[190:193], v[76:79]
	v_mfma_f32_16x16x32_bf16 v[72:75], v[166:169], v[190:193], v[72:75]
	v_mfma_f32_16x16x32_bf16 v[68:71], v[158:161], v[198:201], v[68:71]
	v_mfma_f32_16x16x32_bf16 v[64:67], v[166:169], v[198:201], v[64:67]
	v_mfma_f32_16x16x32_bf16 v[108:111], v[162:165], v[178:181], v[108:111]
	v_mfma_f32_16x16x32_bf16 v[100:103], v[170:173], v[178:181], v[100:103]
	v_mfma_f32_16x16x32_bf16 v[92:95], v[162:165], v[186:189], v[92:95]
	v_mfma_f32_16x16x32_bf16 v[84:87], v[170:173], v[186:189], v[84:87]
	v_mfma_f32_16x16x32_bf16 v[76:79], v[162:165], v[194:197], v[76:79]
	v_mfma_f32_16x16x32_bf16 v[72:75], v[170:173], v[194:197], v[72:75]
	v_mfma_f32_16x16x32_bf16 v[68:71], v[162:165], v[202:205], v[68:71]
	v_mfma_f32_16x16x32_bf16 v[64:67], v[170:173], v[202:205], v[64:67]
	s_setprio 0
	s_barrier
	s_add_i32 s12, s35, s23
	v_lshl_add_u64 v[206:207], s[16:17], 0, v[208:209]
	s_mov_b32 m0, s12
	ds_read_b128 v[174:177], v141 offset:16384
	ds_read_b128 v[178:181], v141 offset:17408
	ds_read_b128 v[182:185], v141 offset:18432
	ds_read_b128 v[186:189], v141 offset:19456
	ds_read_b128 v[190:193], v141 offset:20480
	ds_read_b128 v[194:197], v141 offset:21504
	ds_read_b128 v[198:201], v141 offset:22528
	ds_read_b128 v[202:205], v141 offset:23552
	global_load_lds_dwordx4 v[206:207], off
	s_add_i32 m0, s12, 0x2000
	s_add_u32 s12, s16, 0x200000
	v_lshl_add_u64 v[210:211], s[16:17], 0, v[128:129]
	s_addc_u32 s13, s17, 0
	s_add_i32 s35, s33, s23
	global_load_lds_dwordx4 v[210:211], off
	v_lshl_add_u64 v[212:213], s[12:13], 0, v[208:209]
	s_mov_b32 m0, s35
	v_lshl_add_u64 v[214:215], s[18:19], 0, v[130:131]
	global_load_lds_dwordx4 v[212:213], off
	v_lshl_add_u64 v[212:213], s[12:13], 0, v[128:129]
	s_add_i32 m0, s35, 0x2000
	s_nop 0
	global_load_lds_dwordx4 v[212:213], off
	v_lshl_add_u64 v[212:213], s[18:19], 0, v[132:133]
	s_mov_b32 m0, s1
	s_nop 0
	global_load_lds_dwordx4 v[212:213], off
	s_mov_b32 m0, s25
	s_nop 0
	global_load_lds_dwordx4 v[214:215], off
	s_waitcnt vmcnt(8)
	s_waitcnt lgkmcnt(0)
	s_barrier
; #define PG8_STAGE(bufoff, gbase, voff) do { _Pragma("unroll") for (int _i = 0; _i < 2; ++_i) \
;         __builtin_amdgcn_global_load_lds((const unsigned*)((const char*)(gbase) + (voff)[_i]), (PG8_LAS unsigned*)(lds + (bufoff) + ldsw + _i * 8192), 16, 0, 0); } while (0)
; #define PG8_LDA(dst, b, h) do { _Pragma("unroll") for (int m = 0; m < 4; ++m) _Pragma("unroll") for (int k = 0; k < 2; ++k) dst[m][k] = *(const PG8_LAS bf16x8*)(lds + PG8_SA(b, h) + aoff + m * 2048 + k * 1024); } while (0)
; #define PG8_LDB(dst, b, h) do { _Pragma("unroll") for (int n = 0; n < 2; ++n) _Pragma("unroll") for (int k = 0; k < 2; ++k) dst[n][k] = *(const PG8_LAS bf16x8*)(lds + PG8_SB(b, h) + boff + n * 2048 + k * 1024); } while (0)
; #define PG8_MMA(ai, bj, At, Bt) do { __builtin_amdgcn_s_setprio(1); _Pragma("unroll") for (int m = 0; m < 4; ++m) _Pragma("unroll") for (int n = 0; n < 2; ++n) _Pragma("unroll") for (int k = 0; k < 2; ++k) \
;         acc[ai][bj][m][n] = __builtin_amdgcn_mfma_f32_16x16x32_bf16(Bt[n][k], At[m][k], acc[ai][bj][m][n], 0, 0, 0); __builtin_amdgcn_s_setprio(0); } while (0)
; #define PG8_WAIT_V(n) asm volatile("s_waitcnt vmcnt(" #n ")" ::: "memory")
; #define PG8_WAIT_L(n) asm volatile("s_waitcnt lgkmcnt(" #n ")" ::: "memory")
; #define PG8_BAR __builtin_amdgcn_s_barrier()
; #define PG8_SCHED __builtin_amdgcn_sched_barrier(0)
; template <class Epi, class Sched, bool ALIGN_EPI = false, bool SP2 = false>
; __device__ __forceinline__ void gemm_phase(PG8_LAS unsigned char* lds, const Gemm g, const Sched& S, const Epi& E, const int tid) {
;     ...
;             PG8_WAIT_V(8); PG8_WAIT_L(0); PG8_BAR; PG8_MMA(1, 0, At, B0); PG8_MMA(1, 1, At, B1); PG8_BAR; PG8_SCHED;
;             PG8_LDB(B0, 1, 0); PG8_LDB(B1, 1, 1); PG8_SCHED; PG8_LDA(At, 1, 0); PG8_STAGE(PG8_SA(0, 1), a2 + hstep, voffA);
;             PG8_WAIT_V(8); PG8_WAIT_L(0); PG8_BAR; PG8_MMA(0, 0, At, B0); PG8_MMA(0, 1, At, B1); PG8_BAR; PG8_SCHED;
	s_setprio 1
	s_waitcnt lgkmcnt(0)
	v_mfma_f32_16x16x32_bf16 v[60:63], v[142:145], v[174:177], v[60:63]
	v_mfma_f32_16x16x32_bf16 v[56:59], v[150:153], v[174:177], v[56:59]
	v_mfma_f32_16x16x32_bf16 v[52:55], v[142:145], v[182:185], v[52:55]
	v_mfma_f32_16x16x32_bf16 v[48:51], v[150:153], v[182:185], v[48:51]
	v_mfma_f32_16x16x32_bf16 v[36:39], v[142:145], v[190:193], v[36:39]
	v_mfma_f32_16x16x32_bf16 v[32:35], v[150:153], v[190:193], v[32:35]
	v_mfma_f32_16x16x32_bf16 v[20:23], v[142:145], v[198:201], v[20:23]
	v_mfma_f32_16x16x32_bf16 v[16:19], v[150:153], v[198:201], v[16:19]
	v_mfma_f32_16x16x32_bf16 v[60:63], v[146:149], v[178:181], v[60:63]
	v_mfma_f32_16x16x32_bf16 v[56:59], v[154:157], v[178:181], v[56:59]
	v_mfma_f32_16x16x32_bf16 v[52:55], v[146:149], v[186:189], v[52:55]
	v_mfma_f32_16x16x32_bf16 v[48:51], v[154:157], v[186:189], v[48:51]
	v_mfma_f32_16x16x32_bf16 v[36:39], v[146:149], v[194:197], v[36:39]
	v_mfma_f32_16x16x32_bf16 v[32:35], v[154:157], v[194:197], v[32:35]
	v_mfma_f32_16x16x32_bf16 v[20:23], v[146:149], v[202:205], v[20:23]
	v_mfma_f32_16x16x32_bf16 v[16:19], v[154:157], v[202:205], v[16:19]
	v_mfma_f32_16x16x32_bf16 v[44:47], v[158:161], v[174:177], v[44:47]
	v_mfma_f32_16x16x32_bf16 v[40:43], v[166:169], v[174:177], v[40:43]
	v_mfma_f32_16x16x32_bf16 v[28:31], v[158:161], v[182:185], v[28:31]
	v_mfma_f32_16x16x32_bf16 v[24:27], v[166:169], v[182:185], v[24:27]
	v_mfma_f32_16x16x32_bf16 v[12:15], v[158:161], v[190:193], v[12:15]
	v_mfma_f32_16x16x32_bf16 v[8:11], v[166:169], v[190:193], v[8:11]
	v_mfma_f32_16x16x32_bf16 v[4:7], v[158:161], v[198:201], v[4:7]
	v_mfma_f32_16x16x32_bf16 v[0:3], v[166:169], v[198:201], v[0:3]
	v_mfma_f32_16x16x32_bf16 v[44:47], v[162:165], v[178:181], v[44:47]
	v_mfma_f32_16x16x32_bf16 v[40:43], v[170:173], v[178:181], v[40:43]
	v_mfma_f32_16x16x32_bf16 v[28:31], v[162:165], v[186:189], v[28:31]
	v_mfma_f32_16x16x32_bf16 v[24:27], v[170:173], v[186:189], v[24:27]
	v_mfma_f32_16x16x32_bf16 v[12:15], v[162:165], v[194:197], v[12:15]
	v_mfma_f32_16x16x32_bf16 v[8:11], v[170:173], v[194:197], v[8:11]
	v_mfma_f32_16x16x32_bf16 v[4:7], v[162:165], v[202:205], v[4:7]
	v_mfma_f32_16x16x32_bf16 v[0:3], v[170:173], v[202:205], v[0:3]
	s_setprio 0
	s_barrier
	s_add_i32 s35, 0, 0x18000
	s_add_i32 s36, 0, 0x1c000
	v_add_u32_e32 v154, s35, v140
	v_add_u32_e32 v170, s36, v140
	ds_read_b128 v[142:145], v154
	ds_read_b128 v[146:149], v154 offset:1024
	ds_read_b128 v[150:153], v154 offset:2048
	ds_read_b128 v[154:157], v154 offset:3072
	ds_read_b128 v[158:161], v170
	ds_read_b128 v[162:165], v170 offset:1024
	ds_read_b128 v[166:169], v170 offset:2048
	ds_read_b128 v[170:173], v170 offset:3072
	s_add_u32 s12, s18, 0x200000
	s_addc_u32 s13, s19, 0
	s_mov_b32 m0, s26
	v_lshl_add_u64 v[216:217], s[12:13], 0, v[132:133]
	ds_read_b128 v[174:177], v141 offset:32768
	ds_read_b128 v[178:181], v141 offset:33792
	ds_read_b128 v[182:185], v141 offset:34816
	ds_read_b128 v[186:189], v141 offset:35840
	ds_read_b128 v[190:193], v141 offset:36864
	ds_read_b128 v[194:197], v141 offset:37888
	ds_read_b128 v[198:201], v141 offset:38912
	ds_read_b128 v[202:205], v141 offset:39936
	global_load_lds_dwordx4 v[216:217], off
	v_lshl_add_u64 v[216:217], s[12:13], 0, v[130:131]
	s_mov_b32 m0, s27
	s_nop 0
	global_load_lds_dwordx4 v[216:217], off
	s_waitcnt vmcnt(8)
	s_waitcnt lgkmcnt(0)
	s_barrier
	s_setprio 1
	s_waitcnt lgkmcnt(0)
	v_mfma_f32_16x16x32_bf16 v[124:127], v[142:145], v[174:177], v[124:127]
	v_mfma_f32_16x16x32_bf16 v[120:123], v[150:153], v[174:177], v[120:123]
	v_mfma_f32_16x16x32_bf16 v[116:119], v[142:145], v[182:185], v[116:119]
	v_mfma_f32_16x16x32_bf16 v[112:115], v[150:153], v[182:185], v[112:115]
	v_mfma_f32_16x16x32_bf16 v[104:107], v[142:145], v[190:193], v[104:107]
	v_mfma_f32_16x16x32_bf16 v[96:99], v[150:153], v[190:193], v[96:99]
	v_mfma_f32_16x16x32_bf16 v[88:91], v[142:145], v[198:201], v[88:91]
	v_mfma_f32_16x16x32_bf16 v[80:83], v[150:153], v[198:201], v[80:83]
	v_mfma_f32_16x16x32_bf16 v[124:127], v[146:149], v[178:181], v[124:127]
	v_mfma_f32_16x16x32_bf16 v[120:123], v[154:157], v[178:181], v[120:123]
	v_mfma_f32_16x16x32_bf16 v[116:119], v[146:149], v[186:189], v[116:119]
	v_mfma_f32_16x16x32_bf16 v[112:115], v[154:157], v[186:189], v[112:115]
	v_mfma_f32_16x16x32_bf16 v[104:107], v[146:149], v[194:197], v[104:107]
	v_mfma_f32_16x16x32_bf16 v[96:99], v[154:157], v[194:197], v[96:99]
	v_mfma_f32_16x16x32_bf16 v[88:91], v[146:149], v[202:205], v[88:91]
	v_mfma_f32_16x16x32_bf16 v[80:83], v[154:157], v[202:205], v[80:83]
	v_mfma_f32_16x16x32_bf16 v[108:111], v[158:161], v[174:177], v[108:111]
	v_mfma_f32_16x16x32_bf16 v[100:103], v[166:169], v[174:177], v[100:103]
	v_mfma_f32_16x16x32_bf16 v[92:95], v[158:161], v[182:185], v[92:95]
	v_mfma_f32_16x16x32_bf16 v[84:87], v[166:169], v[182:185], v[84:87]
	v_mfma_f32_16x16x32_bf16 v[76:79], v[158:161], v[190:193], v[76:79]
	v_mfma_f32_16x16x32_bf16 v[72:75], v[166:169], v[190:193], v[72:75]
	v_mfma_f32_16x16x32_bf16 v[68:71], v[158:161], v[198:201], v[68:71]
	v_mfma_f32_16x16x32_bf16 v[64:67], v[166:169], v[198:201], v[64:67]
	v_mfma_f32_16x16x32_bf16 v[108:111], v[162:165], v[178:181], v[108:111]
	v_mfma_f32_16x16x32_bf16 v[100:103], v[170:173], v[178:181], v[100:103]
	v_mfma_f32_16x16x32_bf16 v[92:95], v[162:165], v[186:189], v[92:95]
	v_mfma_f32_16x16x32_bf16 v[84:87], v[170:173], v[186:189], v[84:87]
	v_mfma_f32_16x16x32_bf16 v[76:79], v[162:165], v[194:197], v[76:79]
	v_mfma_f32_16x16x32_bf16 v[72:75], v[170:173], v[194:197], v[72:75]
	v_mfma_f32_16x16x32_bf16 v[68:71], v[162:165], v[202:205], v[68:71]
	v_mfma_f32_16x16x32_bf16 v[64:67], v[170:173], v[202:205], v[64:67]
	s_setprio 0
	s_barrier
; #define PG8_STAGE(bufoff, gbase, voff) do { _Pragma("unroll") for (int _i = 0; _i < 2; ++_i) \
;         __builtin_amdgcn_global_load_lds((const unsigned*)((const char*)(gbase) + (voff)[_i]), (PG8_LAS unsigned*)(lds + (bufoff) + ldsw + _i * 8192), 16, 0, 0); } while (0)
; #define PG8_LDA(dst, b, h) do { _Pragma("unroll") for (int m = 0; m < 4; ++m) _Pragma("unroll") for (int k = 0; k < 2; ++k) dst[m][k] = *(const PG8_LAS bf16x8*)(lds + PG8_SA(b, h) + aoff + m * 2048 + k * 1024); } while (0)
; #define PG8_MMA(ai, bj, At, Bt) do { __builtin_amdgcn_s_setprio(1); _Pragma("unroll") for (int m = 0; m < 4; ++m) _Pragma("unroll") for (int n = 0; n < 2; ++n) _Pragma("unroll") for (int k = 0; k < 2; ++k) \
;         acc[ai][bj][m][n] = __builtin_amdgcn_mfma_f32_16x16x32_bf16(Bt[n][k], At[m][k], acc[ai][bj][m][n], 0, 0, 0); __builtin_amdgcn_s_setprio(0); } while (0)
; #define PG8_WAIT_V(n) asm volatile("s_waitcnt vmcnt(" #n ")" ::: "memory")
; #define PG8_WAIT_L(n) asm volatile("s_waitcnt lgkmcnt(" #n ")" ::: "memory")
; #define PG8_BAR __builtin_amdgcn_s_barrier()
; #define PG8_SCHED __builtin_amdgcn_sched_barrier(0)
; template <class Epi, class Sched, bool ALIGN_EPI = false, bool SP2 = false>
; __device__ __forceinline__ void gemm_phase(PG8_LAS unsigned char* lds, const Gemm g, const Sched& S, const Epi& E, const int tid) {
;     ...
;             PG8_LDA(At, 1, 1); PG8_STAGE(PG8_SB(1, 0), b3, voffB); PG8_STAGE(PG8_SB(1, 1), b3 + hstep, voffB); PG8_STAGE(PG8_SA(1, 0), a3, voffA);
;             PG8_WAIT_V(8); PG8_WAIT_L(0); PG8_BAR; PG8_MMA(1, 0, At, B0); PG8_MMA(1, 1, At, B1); PG8_BAR; PG8_SCHED;
	s_add_i32 s12, s35, s23
	v_lshl_add_u64 v[206:207], v[206:207], 0, s[2:3]
	s_mov_b32 m0, s12
	ds_read_b128 v[174:177], v141 offset:49152
	ds_read_b128 v[178:181], v141 offset:50176
	ds_read_b128 v[182:185], v141 offset:51200
	ds_read_b128 v[186:189], v141 offset:52224
	ds_read_b128 v[190:193], v141 offset:53248
	ds_read_b128 v[194:197], v141 offset:54272
	ds_read_b128 v[198:201], v141 offset:55296
	ds_read_b128 v[202:205], v141 offset:56320
	global_load_lds_dwordx4 v[206:207], off
	s_add_i32 m0, s12, 0x2000
	s_add_u32 s12, s16, 0x200080
	v_lshl_add_u64 v[206:207], v[210:211], 0, s[2:3]
	s_addc_u32 s13, s17, 0
	s_add_i32 s16, s36, s23
	global_load_lds_dwordx4 v[206:207], off
	v_lshl_add_u64 v[206:207], s[12:13], 0, v[208:209]
	s_mov_b32 m0, s16
	s_nop 0
	global_load_lds_dwordx4 v[206:207], off
	v_lshl_add_u64 v[206:207], s[12:13], 0, v[128:129]
	s_add_i32 m0, s16, 0x2000
	s_nop 0
	global_load_lds_dwordx4 v[206:207], off
	v_lshl_add_u64 v[206:207], v[212:213], 0, s[2:3]
	s_mov_b32 m0, s30
	s_nop 0
	global_load_lds_dwordx4 v[206:207], off
	v_lshl_add_u64 v[206:207], v[214:215], 0, s[2:3]
	s_mov_b32 m0, s31
	s_nop 0
	global_load_lds_dwordx4 v[206:207], off
	s_waitcnt vmcnt(8)
	s_waitcnt lgkmcnt(0)
	s_barrier
	s_setprio 1
	s_waitcnt lgkmcnt(0)
	v_mfma_f32_16x16x32_bf16 v[60:63], v[142:145], v[174:177], v[60:63]
	v_mfma_f32_16x16x32_bf16 v[56:59], v[150:153], v[174:177], v[56:59]
	v_mfma_f32_16x16x32_bf16 v[52:55], v[142:145], v[182:185], v[52:55]
	v_mfma_f32_16x16x32_bf16 v[48:51], v[150:153], v[182:185], v[48:51]
	v_mfma_f32_16x16x32_bf16 v[36:39], v[142:145], v[190:193], v[36:39]
	v_mfma_f32_16x16x32_bf16 v[32:35], v[150:153], v[190:193], v[32:35]
	v_mfma_f32_16x16x32_bf16 v[20:23], v[142:145], v[198:201], v[20:23]
	v_mfma_f32_16x16x32_bf16 v[16:19], v[150:153], v[198:201], v[16:19]
	v_mfma_f32_16x16x32_bf16 v[60:63], v[146:149], v[178:181], v[60:63]
	v_mfma_f32_16x16x32_bf16 v[56:59], v[154:157], v[178:181], v[56:59]
	v_mfma_f32_16x16x32_bf16 v[52:55], v[146:149], v[186:189], v[52:55]
	v_mfma_f32_16x16x32_bf16 v[48:51], v[154:157], v[186:189], v[48:51]
	v_mfma_f32_16x16x32_bf16 v[36:39], v[146:149], v[194:197], v[36:39]
	v_mfma_f32_16x16x32_bf16 v[32:35], v[154:157], v[194:197], v[32:35]
	v_mfma_f32_16x16x32_bf16 v[20:23], v[146:149], v[202:205], v[20:23]
	v_mfma_f32_16x16x32_bf16 v[16:19], v[154:157], v[202:205], v[16:19]
	v_mfma_f32_16x16x32_bf16 v[44:47], v[158:161], v[174:177], v[44:47]
	v_mfma_f32_16x16x32_bf16 v[40:43], v[166:169], v[174:177], v[40:43]
	v_mfma_f32_16x16x32_bf16 v[28:31], v[158:161], v[182:185], v[28:31]
	v_mfma_f32_16x16x32_bf16 v[24:27], v[166:169], v[182:185], v[24:27]
	v_mfma_f32_16x16x32_bf16 v[12:15], v[158:161], v[190:193], v[12:15]
	v_mfma_f32_16x16x32_bf16 v[8:11], v[166:169], v[190:193], v[8:11]
	v_mfma_f32_16x16x32_bf16 v[4:7], v[158:161], v[198:201], v[4:7]
	v_mfma_f32_16x16x32_bf16 v[0:3], v[166:169], v[198:201], v[0:3]
	v_mfma_f32_16x16x32_bf16 v[44:47], v[162:165], v[178:181], v[44:47]
	v_mfma_f32_16x16x32_bf16 v[40:43], v[170:173], v[178:181], v[40:43]
	v_mfma_f32_16x16x32_bf16 v[28:31], v[162:165], v[186:189], v[28:31]
	v_mfma_f32_16x16x32_bf16 v[24:27], v[170:173], v[186:189], v[24:27]
	v_mfma_f32_16x16x32_bf16 v[12:15], v[162:165], v[194:197], v[12:15]
	v_mfma_f32_16x16x32_bf16 v[8:11], v[170:173], v[194:197], v[8:11]
	v_mfma_f32_16x16x32_bf16 v[4:7], v[162:165], v[202:205], v[4:7]
	v_mfma_f32_16x16x32_bf16 v[0:3], v[170:173], v[202:205], v[0:3]
	s_setprio 0
	s_barrier
	s_add_i32 s34, s34, 2
	s_cmp_gt_u32 s34, 29
	s_mov_b64 s[12:13], s[14:15]
	s_cbranch_scc0 .LBB0_1619
	s_cmpk_lt_u32 s22, 0x100
	s_movk_i32 s30, 0x41
	s_cbranch_scc0 .LBB0_1622
	s_barrier
